# loop-edge edits: GEMM loop back edge taken before the closing barrier (barrier = loop head, own copy on the exit path), next iteration scalar address arithmetic and post-barrier address ops moved in f
# baseline (speedup 1.0000x reference)
.Lm4ap_31:
	s_waitcnt lgkmcnt(0)
	s_barrier
	s_nop 0
	v_mfma_f32_16x16x32_bf16 v[124:127], v[128:131], v[162:165], 0
	v_mfma_f32_16x16x32_bf16 v[120:123], v[136:139], v[162:165], 0
	v_mfma_f32_16x16x32_bf16 v[108:111], v[128:131], v[170:173], 0
	v_mfma_f32_16x16x32_bf16 v[104:107], v[136:139], v[170:173], 0
	v_mfma_f32_16x16x32_bf16 v[96:99], v[128:131], v[178:181], 0
	v_mfma_f32_16x16x32_bf16 v[88:91], v[136:139], v[178:181], 0
	v_mfma_f32_16x16x32_bf16 v[84:87], v[128:131], v[194:197], 0
	v_mfma_f32_16x16x32_bf16 v[80:83], v[136:139], v[194:197], 0
	v_mfma_f32_16x16x32_bf16 v[124:127], v[132:135], v[166:169], v[124:127]
	v_mfma_f32_16x16x32_bf16 v[120:123], v[146:149], v[166:169], v[120:123]
	v_mfma_f32_16x16x32_bf16 v[108:111], v[132:135], v[174:177], v[108:111]
	v_mfma_f32_16x16x32_bf16 v[104:107], v[146:149], v[174:177], v[104:107]
	v_mfma_f32_16x16x32_bf16 v[96:99], v[132:135], v[182:185], v[96:99]
	v_mfma_f32_16x16x32_bf16 v[88:91], v[146:149], v[182:185], v[88:91]
	v_mfma_f32_16x16x32_bf16 v[84:87], v[132:135], v[210:213], v[84:87]
	v_mfma_f32_16x16x32_bf16 v[80:83], v[146:149], v[210:213], v[80:83]
	v_mfma_f32_16x16x32_bf16 v[116:119], v[214:217], v[162:165], 0
	v_mfma_f32_16x16x32_bf16 v[112:115], v[222:225], v[162:165], 0
	v_mfma_f32_16x16x32_bf16 v[100:103], v[214:217], v[170:173], 0
	v_mfma_f32_16x16x32_bf16 v[92:95], v[222:225], v[170:173], 0
	v_mfma_f32_16x16x32_bf16 v[76:79], v[214:217], v[178:181], 0
	v_mfma_f32_16x16x32_bf16 v[72:75], v[222:225], v[178:181], 0
	v_mfma_f32_16x16x32_bf16 v[68:71], v[214:217], v[194:197], 0
	v_mfma_f32_16x16x32_bf16 v[64:67], v[222:225], v[194:197], 0
	v_mfma_f32_16x16x32_bf16 v[116:119], v[218:221], v[166:169], v[116:119]
	v_mfma_f32_16x16x32_bf16 v[112:115], v[226:229], v[166:169], v[112:115]
	v_mfma_f32_16x16x32_bf16 v[100:103], v[218:221], v[174:177], v[100:103]
	v_mfma_f32_16x16x32_bf16 v[92:95], v[226:229], v[174:177], v[92:95]
	v_mfma_f32_16x16x32_bf16 v[76:79], v[218:221], v[182:185], v[76:79]
	v_mfma_f32_16x16x32_bf16 v[72:75], v[226:229], v[182:185], v[72:75]
	v_mfma_f32_16x16x32_bf16 v[68:71], v[218:221], v[210:213], v[68:71]
	v_mfma_f32_16x16x32_bf16 v[64:67], v[226:229], v[210:213], v[64:67]
	s_add_i32 s6, s6, s57
	v_lshl_add_u64 v[230:231], s[48:49], 0, v[140:141]
	s_mov_b32 m0, s6
	s_barrier
	s_nop 0
	global_load_lds_dwordx4 v[230:231], off
	v_lshl_add_u64 v[232:233], s[48:49], 0, v[150:151]
	s_add_i32 m0, s6, 0x2000
	s_nop 0
	global_load_lds_dwordx4 v[232:233], off
	s_mov_b32 m0, s58
	v_lshl_add_u64 v[234:235], s[52:53], 0, v[154:155]
	ds_read_b128 v[162:165], v208 offset:16384
	ds_read_b128 v[166:169], v208 offset:17408
	ds_read_b128 v[170:173], v208 offset:18432
	ds_read_b128 v[174:177], v208 offset:19456
	ds_read_b128 v[178:181], v208 offset:20480
	ds_read_b128 v[182:185], v208 offset:21504
	ds_read_b128 v[194:197], v208 offset:22528
	ds_read_b128 v[210:213], v208 offset:23552
	global_load_lds_dwordx4 v[234:235], off
	v_lshl_add_u64 v[236:237], s[52:53], 0, v[152:153]
	s_mov_b32 m0, s59
	s_nop 0
	global_load_lds_dwordx4 v[236:237], off
	s_add_u32 s50, s48, 0xb0000
	s_addc_u32 s51, s49, 0
	s_add_i32 s6, s19, s57
	v_lshl_add_u64 v[250:251], s[50:51], 0, v[140:141]
	s_mov_b32 m0, s6
	s_nop 0
	global_load_lds_dwordx4 v[250:251], off
	v_lshl_add_u64 v[250:251], s[50:51], 0, v[150:151]
	s_add_i32 m0, s6, 0x2000
	s_nop 0
	global_load_lds_dwordx4 v[250:251], off
	s_waitcnt vmcnt(40)
	s_cmp_lg_u32 s100, 0
	s_cbranch_scc1 .Lm4bp_31
	s_waitcnt vmcnt(8)
.Lm4bp_31:
	s_waitcnt lgkmcnt(0)
	s_mov_b32 s100, 0
	s_barrier
	v_mfma_f32_16x16x32_bf16 v[60:63], v[128:131], v[162:165], 0
	v_mfma_f32_16x16x32_bf16 v[56:59], v[136:139], v[162:165], 0
	v_mfma_f32_16x16x32_bf16 v[48:51], v[128:131], v[170:173], 0
	v_mfma_f32_16x16x32_bf16 v[40:43], v[136:139], v[170:173], 0
	v_mfma_f32_16x16x32_bf16 v[32:35], v[128:131], v[178:181], 0
	v_mfma_f32_16x16x32_bf16 v[24:27], v[136:139], v[178:181], 0
	v_mfma_f32_16x16x32_bf16 v[16:19], v[128:131], v[194:197], 0
	v_mfma_f32_16x16x32_bf16 v[8:11], v[136:139], v[194:197], 0
	v_mfma_f32_16x16x32_bf16 v[60:63], v[132:135], v[166:169], v[60:63]
	v_mfma_f32_16x16x32_bf16 v[56:59], v[146:149], v[166:169], v[56:59]
	v_mfma_f32_16x16x32_bf16 v[48:51], v[132:135], v[174:177], v[48:51]
	v_mfma_f32_16x16x32_bf16 v[40:43], v[146:149], v[174:177], v[40:43]
	v_mfma_f32_16x16x32_bf16 v[32:35], v[132:135], v[182:185], v[32:35]
	v_mfma_f32_16x16x32_bf16 v[24:27], v[146:149], v[182:185], v[24:27]
	v_mfma_f32_16x16x32_bf16 v[16:19], v[132:135], v[210:213], v[16:19]
	v_mfma_f32_16x16x32_bf16 v[8:11], v[146:149], v[210:213], v[8:11]
	v_mfma_f32_16x16x32_bf16 v[52:55], v[214:217], v[162:165], 0
	v_mfma_f32_16x16x32_bf16 v[44:47], v[222:225], v[162:165], 0
	v_mfma_f32_16x16x32_bf16 v[36:39], v[214:217], v[170:173], 0
	v_mfma_f32_16x16x32_bf16 v[28:31], v[222:225], v[170:173], 0
	v_mfma_f32_16x16x32_bf16 v[20:23], v[214:217], v[178:181], 0
	v_mfma_f32_16x16x32_bf16 v[12:15], v[222:225], v[178:181], 0
	v_mfma_f32_16x16x32_bf16 v[4:7], v[214:217], v[194:197], 0
	v_mfma_f32_16x16x32_bf16 v[0:3], v[222:225], v[194:197], 0
	v_mfma_f32_16x16x32_bf16 v[52:55], v[218:221], v[166:169], v[52:55]
	v_mfma_f32_16x16x32_bf16 v[44:47], v[226:229], v[166:169], v[44:47]
	v_mfma_f32_16x16x32_bf16 v[36:39], v[218:221], v[174:177], v[36:39]
	v_mfma_f32_16x16x32_bf16 v[28:31], v[226:229], v[174:177], v[28:31]
	v_mfma_f32_16x16x32_bf16 v[20:23], v[218:221], v[182:185], v[20:23]
	v_mfma_f32_16x16x32_bf16 v[12:15], v[226:229], v[182:185], v[12:15]
	v_mfma_f32_16x16x32_bf16 v[4:7], v[218:221], v[210:213], v[4:7]
	v_mfma_f32_16x16x32_bf16 v[0:3], v[226:229], v[210:213], v[0:3]
	s_add_i32 s6, 0, 0x18000
	s_barrier
	v_add_u32_e32 v146, s6, v206
	ds_read_b128 v[128:131], v146
	ds_read_b128 v[132:135], v146 offset:1024
	ds_read_b128 v[136:139], v146 offset:2048
	ds_read_b128 v[146:149], v146 offset:3072
	s_add_u32 s50, s52, 0xb0000
	s_addc_u32 s51, s53, 0
	s_mov_b32 m0, s68
	v_lshl_add_u64 v[214:215], s[50:51], 0, v[154:155]
	ds_read_b128 v[162:165], v208 offset:32768
	ds_read_b128 v[166:169], v208 offset:33792
	ds_read_b128 v[170:173], v208 offset:34816
	ds_read_b128 v[174:177], v208 offset:35840
	ds_read_b128 v[178:181], v208 offset:36864
	ds_read_b128 v[182:185], v208 offset:37888
	ds_read_b128 v[194:197], v208 offset:38912
	ds_read_b128 v[210:213], v208 offset:39936
	global_load_lds_dwordx4 v[214:215], off
	v_lshl_add_u64 v[214:215], s[50:51], 0, v[152:153]
	s_mov_b32 m0, s69
	s_nop 0
	global_load_lds_dwordx4 v[214:215], off
	s_add_i32 s19, 0, 0x1c000
	v_add_u32_e32 v192, s19, v206
	ds_read_b128 v[214:217], v192
	ds_read_b128 v[218:221], v192 offset:1024
	ds_read_b128 v[222:225], v192 offset:2048
	ds_read_b128 v[226:229], v192 offset:3072
	s_waitcnt vmcnt(8)
	s_waitcnt lgkmcnt(0)
	s_barrier
	v_mfma_f32_16x16x32_bf16 v[124:127], v[128:131], v[162:165], v[124:127]
	v_mfma_f32_16x16x32_bf16 v[120:123], v[136:139], v[162:165], v[120:123]
	v_mfma_f32_16x16x32_bf16 v[108:111], v[128:131], v[170:173], v[108:111]
	v_mfma_f32_16x16x32_bf16 v[104:107], v[136:139], v[170:173], v[104:107]
	v_mfma_f32_16x16x32_bf16 v[96:99], v[128:131], v[178:181], v[96:99]
	v_mfma_f32_16x16x32_bf16 v[88:91], v[136:139], v[178:181], v[88:91]
	v_mfma_f32_16x16x32_bf16 v[84:87], v[128:131], v[194:197], v[84:87]
	v_mfma_f32_16x16x32_bf16 v[80:83], v[136:139], v[194:197], v[80:83]
	v_mfma_f32_16x16x32_bf16 v[124:127], v[132:135], v[166:169], v[124:127]
	v_mfma_f32_16x16x32_bf16 v[120:123], v[146:149], v[166:169], v[120:123]
	v_mfma_f32_16x16x32_bf16 v[108:111], v[132:135], v[174:177], v[108:111]
	v_mfma_f32_16x16x32_bf16 v[104:107], v[146:149], v[174:177], v[104:107]
	v_mfma_f32_16x16x32_bf16 v[96:99], v[132:135], v[182:185], v[96:99]
	v_mfma_f32_16x16x32_bf16 v[88:91], v[146:149], v[182:185], v[88:91]
	v_mfma_f32_16x16x32_bf16 v[84:87], v[132:135], v[210:213], v[84:87]
	v_mfma_f32_16x16x32_bf16 v[80:83], v[146:149], v[210:213], v[80:83]
	v_mfma_f32_16x16x32_bf16 v[116:119], v[214:217], v[162:165], v[116:119]
	v_mfma_f32_16x16x32_bf16 v[112:115], v[222:225], v[162:165], v[112:115]
	v_mfma_f32_16x16x32_bf16 v[100:103], v[214:217], v[170:173], v[100:103]
	v_mfma_f32_16x16x32_bf16 v[92:95], v[222:225], v[170:173], v[92:95]
	v_mfma_f32_16x16x32_bf16 v[76:79], v[214:217], v[178:181], v[76:79]
	v_mfma_f32_16x16x32_bf16 v[72:75], v[222:225], v[178:181], v[72:75]
	v_mfma_f32_16x16x32_bf16 v[68:71], v[214:217], v[194:197], v[68:71]
	v_mfma_f32_16x16x32_bf16 v[64:67], v[222:225], v[194:197], v[64:67]
	v_mfma_f32_16x16x32_bf16 v[116:119], v[218:221], v[166:169], v[116:119]
	v_mfma_f32_16x16x32_bf16 v[112:115], v[226:229], v[166:169], v[112:115]
	v_mfma_f32_16x16x32_bf16 v[100:103], v[218:221], v[174:177], v[100:103]
	v_mfma_f32_16x16x32_bf16 v[92:95], v[226:229], v[174:177], v[92:95]
	v_mfma_f32_16x16x32_bf16 v[76:79], v[218:221], v[182:185], v[76:79]
	v_mfma_f32_16x16x32_bf16 v[72:75], v[226:229], v[182:185], v[72:75]
	v_mfma_f32_16x16x32_bf16 v[68:71], v[218:221], v[210:213], v[68:71]
	v_mfma_f32_16x16x32_bf16 v[64:67], v[226:229], v[210:213], v[64:67]
	s_add_i32 s6, s6, s57
	v_lshl_add_u64 v[230:231], v[230:231], 0, s[36:37]
	s_mov_b32 m0, s6
	s_barrier
	s_nop 0
	global_load_lds_dwordx4 v[230:231], off
	v_lshl_add_u64 v[230:231], v[232:233], 0, s[36:37]
	s_add_i32 m0, s6, 0x2000
	s_nop 0
	global_load_lds_dwordx4 v[230:231], off
	s_mov_b32 m0, s70
	v_lshl_add_u64 v[230:231], v[234:235], 0, s[36:37]
	ds_read_b128 v[162:165], v208 offset:49152
	ds_read_b128 v[166:169], v208 offset:50176
	ds_read_b128 v[170:173], v208 offset:51200
	ds_read_b128 v[174:177], v208 offset:52224
	ds_read_b128 v[178:181], v208 offset:53248
	ds_read_b128 v[182:185], v208 offset:54272
	ds_read_b128 v[194:197], v208 offset:55296
	ds_read_b128 v[210:213], v208 offset:56320
	global_load_lds_dwordx4 v[230:231], off
	v_lshl_add_u64 v[230:231], v[236:237], 0, s[36:37]
	s_mov_b32 m0, s71
	s_nop 0
	global_load_lds_dwordx4 v[230:231], off
	s_add_u32 s48, s48, 0xb0080
	s_addc_u32 s49, s49, 0
	s_add_i32 s6, s19, s57
	v_lshl_add_u64 v[250:251], s[48:49], 0, v[140:141]
	s_mov_b32 m0, s6
	s_nop 0
	global_load_lds_dwordx4 v[250:251], off
	v_lshl_add_u64 v[250:251], s[48:49], 0, v[150:151]
	s_add_i32 m0, s6, 0x2000
	s_nop 0
	global_load_lds_dwordx4 v[250:251], off
	s_waitcnt vmcnt(8)
	s_waitcnt lgkmcnt(0)
	s_barrier
	v_mfma_f32_16x16x32_bf16 v[60:63], v[128:131], v[162:165], v[60:63]
	v_mfma_f32_16x16x32_bf16 v[56:59], v[136:139], v[162:165], v[56:59]
	v_mfma_f32_16x16x32_bf16 v[48:51], v[128:131], v[170:173], v[48:51]
	v_mfma_f32_16x16x32_bf16 v[40:43], v[136:139], v[170:173], v[40:43]
	v_mfma_f32_16x16x32_bf16 v[32:35], v[128:131], v[178:181], v[32:35]
	v_mfma_f32_16x16x32_bf16 v[24:27], v[136:139], v[178:181], v[24:27]
	v_mfma_f32_16x16x32_bf16 v[16:19], v[128:131], v[194:197], v[16:19]
	v_mfma_f32_16x16x32_bf16 v[8:11], v[136:139], v[194:197], v[8:11]
	v_mfma_f32_16x16x32_bf16 v[60:63], v[132:135], v[166:169], v[60:63]
	v_mfma_f32_16x16x32_bf16 v[56:59], v[146:149], v[166:169], v[56:59]
	v_mfma_f32_16x16x32_bf16 v[48:51], v[132:135], v[174:177], v[48:51]
	v_mfma_f32_16x16x32_bf16 v[40:43], v[146:149], v[174:177], v[40:43]
	v_mfma_f32_16x16x32_bf16 v[32:35], v[132:135], v[182:185], v[32:35]
	v_mfma_f32_16x16x32_bf16 v[24:27], v[146:149], v[182:185], v[24:27]
	v_mfma_f32_16x16x32_bf16 v[16:19], v[132:135], v[210:213], v[16:19]
	v_mfma_f32_16x16x32_bf16 v[8:11], v[146:149], v[210:213], v[8:11]
	v_mfma_f32_16x16x32_bf16 v[52:55], v[214:217], v[162:165], v[52:55]
	v_mfma_f32_16x16x32_bf16 v[44:47], v[222:225], v[162:165], v[44:47]
	v_mfma_f32_16x16x32_bf16 v[36:39], v[214:217], v[170:173], v[36:39]
	v_mfma_f32_16x16x32_bf16 v[28:31], v[222:225], v[170:173], v[28:31]
	v_mfma_f32_16x16x32_bf16 v[20:23], v[214:217], v[178:181], v[20:23]
	v_mfma_f32_16x16x32_bf16 v[12:15], v[222:225], v[178:181], v[12:15]
	v_mfma_f32_16x16x32_bf16 v[4:7], v[214:217], v[194:197], v[4:7]
	v_mfma_f32_16x16x32_bf16 v[0:3], v[222:225], v[194:197], v[0:3]
	v_mfma_f32_16x16x32_bf16 v[52:55], v[218:221], v[166:169], v[52:55]
	v_mfma_f32_16x16x32_bf16 v[44:47], v[226:229], v[166:169], v[44:47]
	v_mfma_f32_16x16x32_bf16 v[36:39], v[218:221], v[174:177], v[36:39]
	v_mfma_f32_16x16x32_bf16 v[28:31], v[226:229], v[174:177], v[28:31]
	v_mfma_f32_16x16x32_bf16 v[20:23], v[218:221], v[182:185], v[20:23]
	v_mfma_f32_16x16x32_bf16 v[12:15], v[226:229], v[182:185], v[12:15]
	v_mfma_f32_16x16x32_bf16 v[4:7], v[218:221], v[210:213], v[4:7]
	v_mfma_f32_16x16x32_bf16 v[0:3], v[226:229], v[210:213], v[0:3]
	s_add_i32 s12, s12, 2
	s_add_u32 s10, s10, 0x100
	s_addc_u32 s11, s11, 0
	s_cmp_gt_u32 s12, 41
	s_mov_b64 s[50:51], s[46:47]
	s_add_u32 s46, s50, 0x100
	s_addc_u32 s47, s51, 0
	s_add_i32 s6, 0, 0x10000
	s_cmp_eq_u32 s12, 40
	s_cselect_b32 s53, s31, s47
	s_cselect_b32 s52, s30, s46
	s_cselect_b32 s49, s35, s11
	s_cselect_b32 s48, s34, s10
my_head_31:
	s_barrier
.LBB0_31:
	v_add_u32_e32 v146, s6, v206
	ds_read_b128 v[128:131], v146
	ds_read_b128 v[132:135], v146 offset:1024
	ds_read_b128 v[136:139], v146 offset:2048
	ds_read_b128 v[146:149], v146 offset:3072
	v_lshl_add_u64 v[214:215], s[50:51], 0, v[158:159]
	s_add_i32 m0, s58, 0xc000
	ds_read_b128 v[162:165], v208
	ds_read_b128 v[166:169], v208 offset:1024
	ds_read_b128 v[170:173], v208 offset:2048
	ds_read_b128 v[174:177], v208 offset:3072
	ds_read_b128 v[178:181], v208 offset:4096
	ds_read_b128 v[182:185], v208 offset:5120
	ds_read_b128 v[194:197], v208 offset:6144
	ds_read_b128 v[210:213], v208 offset:7168
	global_load_lds_dwordx4 v[214:215], off
	v_lshl_add_u64 v[214:215], s[50:51], 0, v[160:161]
	s_add_i32 m0, s58, 0xe000
	s_nop 0
	global_load_lds_dwordx4 v[214:215], off
	s_add_i32 s19, 0, 0x14000
	v_add_u32_e32 v192, s19, v206
	ds_read_b128 v[214:217], v192
	ds_read_b128 v[218:221], v192 offset:1024
	ds_read_b128 v[222:225], v192 offset:2048
	ds_read_b128 v[226:229], v192 offset:3072
	s_nop 0
	s_waitcnt vmcnt(8)
	s_waitcnt lgkmcnt(0)
	s_barrier
	v_mfma_f32_16x16x32_bf16 v[124:127], v[128:131], v[162:165], v[124:127]
	v_mfma_f32_16x16x32_bf16 v[120:123], v[136:139], v[162:165], v[120:123]
	v_mfma_f32_16x16x32_bf16 v[108:111], v[128:131], v[170:173], v[108:111]
	v_mfma_f32_16x16x32_bf16 v[104:107], v[136:139], v[170:173], v[104:107]
	v_mfma_f32_16x16x32_bf16 v[96:99], v[128:131], v[178:181], v[96:99]
	v_mfma_f32_16x16x32_bf16 v[88:91], v[136:139], v[178:181], v[88:91]
	v_mfma_f32_16x16x32_bf16 v[84:87], v[128:131], v[194:197], v[84:87]
	v_mfma_f32_16x16x32_bf16 v[80:83], v[136:139], v[194:197], v[80:83]
	v_mfma_f32_16x16x32_bf16 v[124:127], v[132:135], v[166:169], v[124:127]
	v_mfma_f32_16x16x32_bf16 v[120:123], v[146:149], v[166:169], v[120:123]
	v_mfma_f32_16x16x32_bf16 v[108:111], v[132:135], v[174:177], v[108:111]
	v_mfma_f32_16x16x32_bf16 v[104:107], v[146:149], v[174:177], v[104:107]
	v_mfma_f32_16x16x32_bf16 v[96:99], v[132:135], v[182:185], v[96:99]
	v_mfma_f32_16x16x32_bf16 v[88:91], v[146:149], v[182:185], v[88:91]
	v_mfma_f32_16x16x32_bf16 v[84:87], v[132:135], v[210:213], v[84:87]
	v_mfma_f32_16x16x32_bf16 v[80:83], v[146:149], v[210:213], v[80:83]
	v_mfma_f32_16x16x32_bf16 v[116:119], v[214:217], v[162:165], v[116:119]
	v_mfma_f32_16x16x32_bf16 v[112:115], v[222:225], v[162:165], v[112:115]
	v_mfma_f32_16x16x32_bf16 v[100:103], v[214:217], v[170:173], v[100:103]
	v_mfma_f32_16x16x32_bf16 v[92:95], v[222:225], v[170:173], v[92:95]
	v_mfma_f32_16x16x32_bf16 v[76:79], v[214:217], v[178:181], v[76:79]
	v_mfma_f32_16x16x32_bf16 v[72:75], v[222:225], v[178:181], v[72:75]
	v_mfma_f32_16x16x32_bf16 v[68:71], v[214:217], v[194:197], v[68:71]
	v_mfma_f32_16x16x32_bf16 v[64:67], v[222:225], v[194:197], v[64:67]
	v_mfma_f32_16x16x32_bf16 v[116:119], v[218:221], v[166:169], v[116:119]
	v_mfma_f32_16x16x32_bf16 v[112:115], v[226:229], v[166:169], v[112:115]
	v_mfma_f32_16x16x32_bf16 v[100:103], v[218:221], v[174:177], v[100:103]
	v_mfma_f32_16x16x32_bf16 v[92:95], v[226:229], v[174:177], v[92:95]
	v_mfma_f32_16x16x32_bf16 v[76:79], v[218:221], v[182:185], v[76:79]
	v_mfma_f32_16x16x32_bf16 v[72:75], v[226:229], v[182:185], v[72:75]
	v_mfma_f32_16x16x32_bf16 v[68:71], v[218:221], v[210:213], v[68:71]
	v_mfma_f32_16x16x32_bf16 v[64:67], v[226:229], v[210:213], v[64:67]
	s_add_i32 s6, s6, s57
	v_lshl_add_u64 v[230:231], s[48:49], 0, v[140:141]
	s_mov_b32 m0, s6
	s_barrier
	s_nop 0
	global_load_lds_dwordx4 v[230:231], off
	v_lshl_add_u64 v[232:233], s[48:49], 0, v[150:151]
	s_add_i32 m0, s6, 0x2000
	s_nop 0
	global_load_lds_dwordx4 v[232:233], off
	s_mov_b32 m0, s58
	v_lshl_add_u64 v[234:235], s[52:53], 0, v[154:155]
	ds_read_b128 v[162:165], v208 offset:16384
	ds_read_b128 v[166:169], v208 offset:17408
	ds_read_b128 v[170:173], v208 offset:18432
	ds_read_b128 v[174:177], v208 offset:19456
	ds_read_b128 v[178:181], v208 offset:20480
	ds_read_b128 v[182:185], v208 offset:21504
	ds_read_b128 v[194:197], v208 offset:22528
	ds_read_b128 v[210:213], v208 offset:23552
	global_load_lds_dwordx4 v[234:235], off
	v_lshl_add_u64 v[236:237], s[52:53], 0, v[152:153]
	s_mov_b32 m0, s59
	s_nop 0
	global_load_lds_dwordx4 v[236:237], off
	s_add_u32 s50, s48, 0xb0000
	s_addc_u32 s51, s49, 0
	s_add_i32 s6, s19, s57
	v_lshl_add_u64 v[250:251], s[50:51], 0, v[140:141]
	s_mov_b32 m0, s6
	s_nop 0
	global_load_lds_dwordx4 v[250:251], off
	v_lshl_add_u64 v[250:251], s[50:51], 0, v[150:151]
	s_add_i32 m0, s6, 0x2000
	s_nop 0
	global_load_lds_dwordx4 v[250:251], off
	s_waitcnt vmcnt(8)
	s_waitcnt lgkmcnt(0)
	s_barrier
	v_mfma_f32_16x16x32_bf16 v[60:63], v[128:131], v[162:165], v[60:63]
	v_mfma_f32_16x16x32_bf16 v[56:59], v[136:139], v[162:165], v[56:59]
	v_mfma_f32_16x16x32_bf16 v[48:51], v[128:131], v[170:173], v[48:51]
	v_mfma_f32_16x16x32_bf16 v[40:43], v[136:139], v[170:173], v[40:43]
	v_mfma_f32_16x16x32_bf16 v[32:35], v[128:131], v[178:181], v[32:35]
	v_mfma_f32_16x16x32_bf16 v[24:27], v[136:139], v[178:181], v[24:27]
	v_mfma_f32_16x16x32_bf16 v[16:19], v[128:131], v[194:197], v[16:19]
	v_mfma_f32_16x16x32_bf16 v[8:11], v[136:139], v[194:197], v[8:11]
	v_mfma_f32_16x16x32_bf16 v[60:63], v[132:135], v[166:169], v[60:63]
	v_mfma_f32_16x16x32_bf16 v[56:59], v[146:149], v[166:169], v[56:59]
	v_mfma_f32_16x16x32_bf16 v[48:51], v[132:135], v[174:177], v[48:51]
	v_mfma_f32_16x16x32_bf16 v[40:43], v[146:149], v[174:177], v[40:43]
	v_mfma_f32_16x16x32_bf16 v[32:35], v[132:135], v[182:185], v[32:35]
	v_mfma_f32_16x16x32_bf16 v[24:27], v[146:149], v[182:185], v[24:27]
	v_mfma_f32_16x16x32_bf16 v[16:19], v[132:135], v[210:213], v[16:19]
	v_mfma_f32_16x16x32_bf16 v[8:11], v[146:149], v[210:213], v[8:11]
	v_mfma_f32_16x16x32_bf16 v[52:55], v[214:217], v[162:165], v[52:55]
	v_mfma_f32_16x16x32_bf16 v[44:47], v[222:225], v[162:165], v[44:47]
	v_mfma_f32_16x16x32_bf16 v[36:39], v[214:217], v[170:173], v[36:39]
	v_mfma_f32_16x16x32_bf16 v[28:31], v[222:225], v[170:173], v[28:31]
	v_mfma_f32_16x16x32_bf16 v[20:23], v[214:217], v[178:181], v[20:23]
	v_mfma_f32_16x16x32_bf16 v[12:15], v[222:225], v[178:181], v[12:15]
	v_mfma_f32_16x16x32_bf16 v[4:7], v[214:217], v[194:197], v[4:7]
	v_mfma_f32_16x16x32_bf16 v[0:3], v[222:225], v[194:197], v[0:3]
	v_mfma_f32_16x16x32_bf16 v[52:55], v[218:221], v[166:169], v[52:55]
	v_mfma_f32_16x16x32_bf16 v[44:47], v[226:229], v[166:169], v[44:47]
	v_mfma_f32_16x16x32_bf16 v[36:39], v[218:221], v[174:177], v[36:39]
	v_mfma_f32_16x16x32_bf16 v[28:31], v[226:229], v[174:177], v[28:31]
	v_mfma_f32_16x16x32_bf16 v[20:23], v[218:221], v[182:185], v[20:23]
	v_mfma_f32_16x16x32_bf16 v[12:15], v[226:229], v[182:185], v[12:15]
	v_mfma_f32_16x16x32_bf16 v[4:7], v[218:221], v[210:213], v[4:7]
	v_mfma_f32_16x16x32_bf16 v[0:3], v[226:229], v[210:213], v[0:3]
	s_add_i32 s6, 0, 0x18000
	s_barrier
	v_add_u32_e32 v146, s6, v206
	ds_read_b128 v[128:131], v146
	ds_read_b128 v[132:135], v146 offset:1024
	ds_read_b128 v[136:139], v146 offset:2048
	ds_read_b128 v[146:149], v146 offset:3072
	s_add_u32 s50, s52, 0xb0000
	s_addc_u32 s51, s53, 0
	s_mov_b32 m0, s68
	v_lshl_add_u64 v[214:215], s[50:51], 0, v[154:155]
	ds_read_b128 v[162:165], v208 offset:32768
	ds_read_b128 v[166:169], v208 offset:33792
	ds_read_b128 v[170:173], v208 offset:34816
	ds_read_b128 v[174:177], v208 offset:35840
	ds_read_b128 v[178:181], v208 offset:36864
	ds_read_b128 v[182:185], v208 offset:37888
	ds_read_b128 v[194:197], v208 offset:38912
	ds_read_b128 v[210:213], v208 offset:39936
	global_load_lds_dwordx4 v[214:215], off
	v_lshl_add_u64 v[214:215], s[50:51], 0, v[152:153]
	s_mov_b32 m0, s69
	s_nop 0
	global_load_lds_dwordx4 v[214:215], off
	s_add_i32 s19, 0, 0x1c000
	v_add_u32_e32 v192, s19, v206
	ds_read_b128 v[214:217], v192
	ds_read_b128 v[218:221], v192 offset:1024
	ds_read_b128 v[222:225], v192 offset:2048
	ds_read_b128 v[226:229], v192 offset:3072
	s_waitcnt vmcnt(8)
	s_waitcnt lgkmcnt(0)
	s_barrier
	v_mfma_f32_16x16x32_bf16 v[124:127], v[128:131], v[162:165], v[124:127]
	v_mfma_f32_16x16x32_bf16 v[120:123], v[136:139], v[162:165], v[120:123]
	v_mfma_f32_16x16x32_bf16 v[108:111], v[128:131], v[170:173], v[108:111]
	v_mfma_f32_16x16x32_bf16 v[104:107], v[136:139], v[170:173], v[104:107]
	v_mfma_f32_16x16x32_bf16 v[96:99], v[128:131], v[178:181], v[96:99]
	v_mfma_f32_16x16x32_bf16 v[88:91], v[136:139], v[178:181], v[88:91]
	v_mfma_f32_16x16x32_bf16 v[84:87], v[128:131], v[194:197], v[84:87]
	v_mfma_f32_16x16x32_bf16 v[80:83], v[136:139], v[194:197], v[80:83]
	v_mfma_f32_16x16x32_bf16 v[124:127], v[132:135], v[166:169], v[124:127]
	v_mfma_f32_16x16x32_bf16 v[120:123], v[146:149], v[166:169], v[120:123]
	v_mfma_f32_16x16x32_bf16 v[108:111], v[132:135], v[174:177], v[108:111]
	v_mfma_f32_16x16x32_bf16 v[104:107], v[146:149], v[174:177], v[104:107]
	v_mfma_f32_16x16x32_bf16 v[96:99], v[132:135], v[182:185], v[96:99]
	v_mfma_f32_16x16x32_bf16 v[88:91], v[146:149], v[182:185], v[88:91]
	v_mfma_f32_16x16x32_bf16 v[84:87], v[132:135], v[210:213], v[84:87]
	v_mfma_f32_16x16x32_bf16 v[80:83], v[146:149], v[210:213], v[80:83]
	v_mfma_f32_16x16x32_bf16 v[116:119], v[214:217], v[162:165], v[116:119]
	v_mfma_f32_16x16x32_bf16 v[112:115], v[222:225], v[162:165], v[112:115]
	v_mfma_f32_16x16x32_bf16 v[100:103], v[214:217], v[170:173], v[100:103]
	v_mfma_f32_16x16x32_bf16 v[92:95], v[222:225], v[170:173], v[92:95]
	v_mfma_f32_16x16x32_bf16 v[76:79], v[214:217], v[178:181], v[76:79]
	v_mfma_f32_16x16x32_bf16 v[72:75], v[222:225], v[178:181], v[72:75]
	v_mfma_f32_16x16x32_bf16 v[68:71], v[214:217], v[194:197], v[68:71]
	v_mfma_f32_16x16x32_bf16 v[64:67], v[222:225], v[194:197], v[64:67]
	v_mfma_f32_16x16x32_bf16 v[116:119], v[218:221], v[166:169], v[116:119]
	v_mfma_f32_16x16x32_bf16 v[112:115], v[226:229], v[166:169], v[112:115]
	v_mfma_f32_16x16x32_bf16 v[100:103], v[218:221], v[174:177], v[100:103]
	v_mfma_f32_16x16x32_bf16 v[92:95], v[226:229], v[174:177], v[92:95]
	v_mfma_f32_16x16x32_bf16 v[76:79], v[218:221], v[182:185], v[76:79]
	v_mfma_f32_16x16x32_bf16 v[72:75], v[226:229], v[182:185], v[72:75]
	v_mfma_f32_16x16x32_bf16 v[68:71], v[218:221], v[210:213], v[68:71]
	v_mfma_f32_16x16x32_bf16 v[64:67], v[226:229], v[210:213], v[64:67]
	s_add_i32 s6, s6, s57
	v_lshl_add_u64 v[230:231], v[230:231], 0, s[36:37]
	s_mov_b32 m0, s6
	s_barrier
	s_nop 0
	global_load_lds_dwordx4 v[230:231], off
	v_lshl_add_u64 v[230:231], v[232:233], 0, s[36:37]
	s_add_i32 m0, s6, 0x2000
	s_nop 0
	global_load_lds_dwordx4 v[230:231], off
	s_mov_b32 m0, s70
	v_lshl_add_u64 v[230:231], v[234:235], 0, s[36:37]
	ds_read_b128 v[162:165], v208 offset:49152
	ds_read_b128 v[166:169], v208 offset:50176
	ds_read_b128 v[170:173], v208 offset:51200
	ds_read_b128 v[174:177], v208 offset:52224
	ds_read_b128 v[178:181], v208 offset:53248
	ds_read_b128 v[182:185], v208 offset:54272
	ds_read_b128 v[194:197], v208 offset:55296
	ds_read_b128 v[210:213], v208 offset:56320
	global_load_lds_dwordx4 v[230:231], off
	v_lshl_add_u64 v[230:231], v[236:237], 0, s[36:37]
	s_mov_b32 m0, s71
	s_nop 0
	global_load_lds_dwordx4 v[230:231], off
	s_add_u32 s48, s48, 0xb0080
	s_addc_u32 s49, s49, 0
	s_add_i32 s6, s19, s57
	v_lshl_add_u64 v[250:251], s[48:49], 0, v[140:141]
	s_mov_b32 m0, s6
	s_nop 0
	global_load_lds_dwordx4 v[250:251], off
	v_lshl_add_u64 v[250:251], s[48:49], 0, v[150:151]
	s_add_i32 m0, s6, 0x2000
	s_nop 0
	global_load_lds_dwordx4 v[250:251], off
	s_waitcnt vmcnt(8)
	s_waitcnt lgkmcnt(0)
	s_barrier
	v_mfma_f32_16x16x32_bf16 v[60:63], v[128:131], v[162:165], v[60:63]
	v_mfma_f32_16x16x32_bf16 v[56:59], v[136:139], v[162:165], v[56:59]
	v_mfma_f32_16x16x32_bf16 v[48:51], v[128:131], v[170:173], v[48:51]
	v_mfma_f32_16x16x32_bf16 v[40:43], v[136:139], v[170:173], v[40:43]
	v_mfma_f32_16x16x32_bf16 v[32:35], v[128:131], v[178:181], v[32:35]
	v_mfma_f32_16x16x32_bf16 v[24:27], v[136:139], v[178:181], v[24:27]
	v_mfma_f32_16x16x32_bf16 v[16:19], v[128:131], v[194:197], v[16:19]
	v_mfma_f32_16x16x32_bf16 v[8:11], v[136:139], v[194:197], v[8:11]
	v_mfma_f32_16x16x32_bf16 v[60:63], v[132:135], v[166:169], v[60:63]
	v_mfma_f32_16x16x32_bf16 v[56:59], v[146:149], v[166:169], v[56:59]
	v_mfma_f32_16x16x32_bf16 v[48:51], v[132:135], v[174:177], v[48:51]
	v_mfma_f32_16x16x32_bf16 v[40:43], v[146:149], v[174:177], v[40:43]
	v_mfma_f32_16x16x32_bf16 v[32:35], v[132:135], v[182:185], v[32:35]
	v_mfma_f32_16x16x32_bf16 v[24:27], v[146:149], v[182:185], v[24:27]
	v_mfma_f32_16x16x32_bf16 v[16:19], v[132:135], v[210:213], v[16:19]
	v_mfma_f32_16x16x32_bf16 v[8:11], v[146:149], v[210:213], v[8:11]
	v_mfma_f32_16x16x32_bf16 v[52:55], v[214:217], v[162:165], v[52:55]
	v_mfma_f32_16x16x32_bf16 v[44:47], v[222:225], v[162:165], v[44:47]
	v_mfma_f32_16x16x32_bf16 v[36:39], v[214:217], v[170:173], v[36:39]
	v_mfma_f32_16x16x32_bf16 v[28:31], v[222:225], v[170:173], v[28:31]
	v_mfma_f32_16x16x32_bf16 v[20:23], v[214:217], v[178:181], v[20:23]
	v_mfma_f32_16x16x32_bf16 v[12:15], v[222:225], v[178:181], v[12:15]
	v_mfma_f32_16x16x32_bf16 v[4:7], v[214:217], v[194:197], v[4:7]
	v_mfma_f32_16x16x32_bf16 v[0:3], v[222:225], v[194:197], v[0:3]
	v_mfma_f32_16x16x32_bf16 v[52:55], v[218:221], v[166:169], v[52:55]
	v_mfma_f32_16x16x32_bf16 v[44:47], v[226:229], v[166:169], v[44:47]
	v_mfma_f32_16x16x32_bf16 v[36:39], v[218:221], v[174:177], v[36:39]
	v_mfma_f32_16x16x32_bf16 v[28:31], v[226:229], v[174:177], v[28:31]
	v_mfma_f32_16x16x32_bf16 v[20:23], v[218:221], v[182:185], v[20:23]
	v_mfma_f32_16x16x32_bf16 v[12:15], v[226:229], v[182:185], v[12:15]
	v_mfma_f32_16x16x32_bf16 v[4:7], v[218:221], v[210:213], v[4:7]
	v_mfma_f32_16x16x32_bf16 v[0:3], v[226:229], v[210:213], v[0:3]
	s_add_i32 s12, s12, 2
	s_add_u32 s10, s10, 0x100
	s_addc_u32 s11, s11, 0
	s_cmp_gt_u32 s12, 41
	s_mov_b64 s[50:51], s[46:47]
	s_cbranch_scc1 my_exit_31
	s_add_u32 s46, s50, 0x100
	s_addc_u32 s47, s51, 0
	s_add_i32 s6, 0, 0x10000
	s_cmp_eq_u32 s12, 40
	s_cselect_b32 s53, s31, s47
	s_cselect_b32 s52, s30, s46
	s_cselect_b32 s49, s35, s11
	s_cselect_b32 s48, s34, s10
	s_branch my_head_31
my_exit_31:
	s_barrier
	s_mov_b32 s100, 1
	s_ashr_i32 s39, s38, 31
	v_lshl_or_b32 v128, s81, 8, v207
	s_lshl_b64 s[10:11], s[38:39], 8
	v_ashrrev_i32_e32 v129, 31, v128
	v_lshl_add_u64 v[168:169], s[10:11], 0, v[156:157]
	v_lshlrev_b64 v[170:171], 1, v[128:129]
	v_lshl_add_u64 v[174:175], s[4:5], 0, v[170:171]
	v_lshlrev_b64 v[172:173], 11, v[168:169]
	v_lshl_add_u64 v[128:129], v[174:175], 0, v[172:173]
	global_load_dwordx4 v[146:149], v[128:129], off
	global_load_dwordx4 v[182:185], v[128:129], off offset:256
	v_or_b32_e32 v166, 16, v168
	v_mov_b32_e32 v167, v169
	v_lshlrev_b64 v[176:177], 11, v[166:167]
	v_lshl_add_u64 v[128:129], v[174:175], 0, v[176:177]
	global_load_dwordx4 v[194:197], v[128:129], off
	global_load_dwordx4 v[210:213], v[128:129], off offset:256
	v_or_b32_e32 v164, 32, v168
	v_mov_b32_e32 v165, v169
	v_or_b32_e32 v162, 48, v168
	v_mov_b32_e32 v163, v169
	v_lshlrev_b64 v[180:181], 11, v[164:165]
	v_lshlrev_b64 v[178:179], 11, v[162:163]
	v_lshl_add_u64 v[128:129], v[174:175], 0, v[180:181]
	v_lshl_add_u64 v[130:131], v[174:175], 0, v[178:179]
	global_load_dwordx4 v[214:217], v[128:129], off
	global_load_dwordx4 v[136:139], v[128:129], off offset:256
	global_load_dwordx4 v[132:135], v[130:131], off
	s_nop 0
	global_load_dwordx4 v[128:131], v[130:131], off offset:256
	s_mov_b64 s[10:11], 0x90
	v_lshl_add_u64 v[172:173], s[28:29], 0, v[172:173]
	v_lshl_add_u64 v[172:173], v[172:173], 0, v[170:171]
	s_waitcnt vmcnt(0)
	v_lshlrev_b32_e32 v218, 16, v146
	v_and_b32_e32 v219, 0xffff0000, v146
	v_lshlrev_b32_e32 v220, 16, v148
	v_and_b32_e32 v221, 0xffff0000, v148
	v_lshlrev_b32_e32 v146, 16, v147
	v_and_b32_e32 v147, 0xffff0000, v147
	v_lshlrev_b32_e32 v222, 16, v182
	v_and_b32_e32 v223, 0xffff0000, v182
	v_lshlrev_b32_e32 v224, 16, v184
	v_and_b32_e32 v225, 0xffff0000, v184
	v_lshlrev_b32_e32 v182, 16, v183
	v_and_b32_e32 v183, 0xffff0000, v183
	v_pk_fma_f32 v[124:125], v[124:125], 0.5, v[218:219] op_sel_hi:[1,0,1]
	v_pk_fma_f32 v[120:121], v[120:121], 0.5, v[220:221] op_sel_hi:[1,0,1]
	v_pk_fma_f32 v[126:127], v[126:127], 0.5, v[146:147] op_sel_hi:[1,0,1]
	v_pk_fma_f32 v[116:117], v[116:117], 0.5, v[222:223] op_sel_hi:[1,0,1]
	v_pk_fma_f32 v[146:147], v[112:113], 0.5, v[224:225] op_sel_hi:[1,0,1]
	v_pk_fma_f32 v[118:119], v[118:119], 0.5, v[182:183] op_sel_hi:[1,0,1]
	v_pk_mul_f32 v[220:221], v[124:125], v[124:125]
	v_pk_mul_f32 v[222:223], v[126:127], v[126:127]
	v_cvt_pk_bf16_f32 v112, v124, v125
	v_cvt_pk_bf16_f32 v113, v126, v127
	v_pk_mul_f32 v[124:125], v[116:117], v[116:117]
	v_pk_mul_f32 v[126:127], v[118:119], v[118:119]
	v_pk_mul_f32 v[228:229], v[146:147], v[146:147]
	v_cvt_pk_bf16_f32 v116, v116, v117
	v_cvt_pk_bf16_f32 v117, v118, v119
	v_cvt_pk_bf16_f32 v118, v146, v147
	v_add_f32_e32 v146, v220, v221
	v_add_f32_e32 v146, v222, v146
	v_lshlrev_b32_e32 v148, 16, v149
	v_and_b32_e32 v149, 0xffff0000, v149
	v_pk_mul_f32 v[224:225], v[120:121], v[120:121]
	v_add_f32_e32 v146, v223, v146
	v_pk_fma_f32 v[122:123], v[122:123], 0.5, v[148:149] op_sel_hi:[1,0,1]
	v_add_f32_e32 v146, v224, v146
	v_pk_mul_f32 v[226:227], v[122:123], v[122:123]
	v_add_f32_e32 v146, v225, v146
	v_add_f32_e32 v146, v226, v146
	v_add_f32_e32 v146, v227, v146
	v_add_f32_e32 v124, v124, v146
	v_add_f32_e32 v124, v125, v124
	v_add_f32_e32 v124, v126, v124
	v_lshlrev_b32_e32 v184, 16, v185
	v_and_b32_e32 v185, 0xffff0000, v185
	v_add_f32_e32 v124, v127, v124
	v_pk_fma_f32 v[148:149], v[114:115], 0.5, v[184:185] op_sel_hi:[1,0,1]
	v_add_f32_e32 v124, v228, v124
	v_pk_mul_f32 v[230:231], v[148:149], v[148:149]
	v_add_f32_e32 v124, v229, v124
	v_add_f32_e32 v124, v230, v124
	v_add_f32_e32 v209, v231, v124
	v_lshlrev_b32_e32 v124, 16, v212
	v_and_b32_e32 v125, 0xffff0000, v212
	v_pk_fma_f32 v[124:125], v[92:93], 0.5, v[124:125] op_sel_hi:[1,0,1]
	v_lshlrev_b32_e32 v92, 16, v211
	v_and_b32_e32 v93, 0xffff0000, v211
	v_pk_fma_f32 v[102:103], v[102:103], 0.5, v[92:93] op_sel_hi:[1,0,1]
	v_lshlrev_b32_e32 v92, 16, v213
	v_and_b32_e32 v93, 0xffff0000, v213
	v_pk_fma_f32 v[126:127], v[94:95], 0.5, v[92:93] op_sel_hi:[1,0,1]
	v_lshlrev_b32_e32 v92, 16, v214
	v_and_b32_e32 v93, 0xffff0000, v214
	v_pk_fma_f32 v[92:93], v[96:97], 0.5, v[92:93] op_sel_hi:[1,0,1]
	v_lshlrev_b32_e32 v96, 16, v217
	v_and_b32_e32 v97, 0xffff0000, v217
	v_lshlrev_b32_e32 v94, 16, v216
	v_and_b32_e32 v95, 0xffff0000, v216
	v_pk_fma_f32 v[90:91], v[90:91], 0.5, v[96:97] op_sel_hi:[1,0,1]
	v_lshlrev_b32_e32 v96, 16, v136
	v_and_b32_e32 v97, 0xffff0000, v136
	v_lshlrev_b32_e32 v182, 16, v194
	v_and_b32_e32 v183, 0xffff0000, v194
	v_pk_fma_f32 v[88:89], v[88:89], 0.5, v[94:95] op_sel_hi:[1,0,1]
	v_lshlrev_b32_e32 v94, 16, v215
	v_and_b32_e32 v95, 0xffff0000, v215
	v_pk_fma_f32 v[96:97], v[76:77], 0.5, v[96:97] op_sel_hi:[1,0,1]
	v_lshl_add_u64 v[76:77], v[168:169], 0, s[36:37]
	v_lshlrev_b32_e32 v184, 16, v196
	v_and_b32_e32 v185, 0xffff0000, v196
	v_cvt_pk_bf16_f32 v114, v120, v121
	v_pk_fma_f32 v[120:121], v[108:109], 0.5, v[182:183] op_sel_hi:[1,0,1]
	v_pk_fma_f32 v[94:95], v[98:99], 0.5, v[94:95] op_sel_hi:[1,0,1]
	v_lshlrev_b64 v[182:183], 11, v[76:77]
	v_lshlrev_b32_e32 v98, 16, v138
	v_and_b32_e32 v99, 0xffff0000, v138
	v_pk_fma_f32 v[108:109], v[104:105], 0.5, v[184:185] op_sel_hi:[1,0,1]
	v_lshl_add_u64 v[184:185], v[174:175], 0, v[182:183]
	v_pk_fma_f32 v[98:99], v[72:73], 0.5, v[98:99] op_sel_hi:[1,0,1]
	v_lshlrev_b32_e32 v72, 16, v137
	v_and_b32_e32 v73, 0xffff0000, v137
	v_lshlrev_b32_e32 v218, 16, v210
	v_and_b32_e32 v219, 0xffff0000, v210
	global_load_dwordx4 v[210:213], v[184:185], off
	v_pk_fma_f32 v[136:137], v[78:79], 0.5, v[72:73] op_sel_hi:[1,0,1]
	v_lshlrev_b32_e32 v72, 16, v139
	v_and_b32_e32 v73, 0xffff0000, v139
	v_pk_fma_f32 v[138:139], v[74:75], 0.5, v[72:73] op_sel_hi:[1,0,1]
	v_lshlrev_b32_e32 v72, 16, v132
	v_and_b32_e32 v73, 0xffff0000, v132
	v_pk_fma_f32 v[74:75], v[84:85], 0.5, v[72:73] op_sel_hi:[1,0,1]
	v_lshlrev_b32_e32 v72, 16, v134
	v_and_b32_e32 v73, 0xffff0000, v134
	v_pk_fma_f32 v[78:79], v[80:81], 0.5, v[72:73] op_sel_hi:[1,0,1]
	v_lshlrev_b32_e32 v72, 16, v133
	v_and_b32_e32 v73, 0xffff0000, v133
	v_pk_fma_f32 v[100:101], v[100:101], 0.5, v[218:219] op_sel_hi:[1,0,1]
	global_load_dwordx4 v[218:221], v[184:185], off offset:256
	v_pk_fma_f32 v[80:81], v[86:87], 0.5, v[72:73] op_sel_hi:[1,0,1]
	v_lshlrev_b32_e32 v72, 16, v135
	v_and_b32_e32 v73, 0xffff0000, v135
	v_pk_fma_f32 v[82:83], v[82:83], 0.5, v[72:73] op_sel_hi:[1,0,1]
	v_lshl_add_u64 v[72:73], v[168:169], 0, s[10:11]
	v_lshlrev_b64 v[132:133], 11, v[72:73]
	v_lshl_add_u64 v[134:135], v[174:175], 0, v[132:133]
	v_lshlrev_b32_e32 v84, 16, v128
	v_and_b32_e32 v85, 0xffff0000, v128
	global_load_dwordx4 v[226:229], v[134:135], off
	global_load_dwordx4 v[234:237], v[134:135], off offset:256
	v_pk_fma_f32 v[84:85], v[68:69], 0.5, v[84:85] op_sel_hi:[1,0,1]
	v_lshlrev_b32_e32 v68, 16, v130
	v_and_b32_e32 v69, 0xffff0000, v130
	v_pk_fma_f32 v[86:87], v[64:65], 0.5, v[68:69] op_sel_hi:[1,0,1]
	v_lshlrev_b32_e32 v64, 16, v129
	v_and_b32_e32 v65, 0xffff0000, v129
	s_mov_b64 s[10:11], 0xa0
	v_pk_fma_f32 v[128:129], v[70:71], 0.5, v[64:65] op_sel_hi:[1,0,1]
	v_lshl_add_u64 v[70:71], v[168:169], 0, s[10:11]
	s_mov_b64 s[10:11], 0xb0
	v_lshlrev_b32_e32 v64, 16, v131
	v_and_b32_e32 v65, 0xffff0000, v131
	v_lshlrev_b64 v[134:135], 11, v[70:71]
	v_lshl_add_u64 v[68:69], v[168:169], 0, s[10:11]
	v_pk_fma_f32 v[130:131], v[66:67], 0.5, v[64:65] op_sel_hi:[1,0,1]
	v_lshl_add_u64 v[64:65], v[174:175], 0, v[134:135]
	v_lshlrev_b64 v[184:185], 11, v[68:69]
	global_load_dwordx4 v[238:241], v[64:65], off
	global_load_dwordx4 v[242:245], v[64:65], off offset:256
	v_lshl_add_u64 v[64:65], v[174:175], 0, v[184:185]
	global_load_dwordx4 v[246:249], v[64:65], off
	s_nop 0
	global_load_dwordx4 v[64:67], v[64:65], off offset:256
	v_lshlrev_b32_e32 v194, 16, v195
	v_and_b32_e32 v195, 0xffff0000, v195
	v_lshlrev_b32_e32 v196, 16, v197
	v_and_b32_e32 v197, 0xffff0000, v197
	v_cvt_pk_bf16_f32 v115, v122, v123
	v_cvt_pk_bf16_f32 v119, v148, v149
	v_pk_fma_f32 v[122:123], v[110:111], 0.5, v[194:195] op_sel_hi:[1,0,1]
	v_pk_fma_f32 v[110:111], v[106:107], 0.5, v[196:197] op_sel_hi:[1,0,1]
	global_store_dwordx4 v[172:173], v[112:115], off
	global_store_dwordx4 v[172:173], v[116:119], off offset:256
	v_cvt_pk_bf16_f32 v104, v120, v121
	v_lshl_add_u64 v[112:113], s[28:29], 0, v[176:177]
	v_cvt_pk_bf16_f32 v105, v122, v123
	v_cvt_pk_bf16_f32 v106, v108, v109
	v_cvt_pk_bf16_f32 v107, v110, v111
	v_lshl_add_u64 v[112:113], v[112:113], 0, v[170:171]
	v_cvt_pk_bf16_f32 v146, v100, v101
	v_cvt_pk_bf16_f32 v147, v102, v103
	v_cvt_pk_bf16_f32 v148, v124, v125
	v_cvt_pk_bf16_f32 v149, v126, v127
	global_store_dwordx4 v[112:113], v[104:107], off
	global_store_dwordx4 v[112:113], v[146:149], off offset:256
	v_cvt_pk_bf16_f32 v194, v92, v93
	v_lshl_add_u64 v[104:105], s[28:29], 0, v[180:181]
	v_cvt_pk_bf16_f32 v195, v94, v95
	v_cvt_pk_bf16_f32 v196, v88, v89
	v_cvt_pk_bf16_f32 v197, v90, v91
	v_lshl_add_u64 v[104:105], v[104:105], 0, v[170:171]
	v_cvt_pk_bf16_f32 v214, v96, v97
	v_cvt_pk_bf16_f32 v215, v136, v137
	v_cvt_pk_bf16_f32 v216, v98, v99
	v_cvt_pk_bf16_f32 v217, v138, v139
	global_store_dwordx4 v[104:105], v[194:197], off
	global_store_dwordx4 v[104:105], v[214:217], off offset:256
	v_lshl_add_u64 v[104:105], s[28:29], 0, v[178:179]
	v_cvt_pk_bf16_f32 v222, v74, v75
	v_cvt_pk_bf16_f32 v223, v80, v81
	v_cvt_pk_bf16_f32 v224, v78, v79
	v_cvt_pk_bf16_f32 v225, v82, v83
	v_lshl_add_u64 v[104:105], v[104:105], 0, v[170:171]
	v_cvt_pk_bf16_f32 v230, v84, v85
	v_cvt_pk_bf16_f32 v231, v128, v129
	v_cvt_pk_bf16_f32 v232, v86, v87
	v_cvt_pk_bf16_f32 v233, v130, v131
	global_store_dwordx4 v[104:105], v[222:225], off
	global_store_dwordx4 v[104:105], v[230:233], off offset:256
	s_waitcnt vmcnt(0)
	v_lshlrev_b32_e32 v104, 16, v210
	v_and_b32_e32 v105, 0xffff0000, v210
	v_pk_fma_f32 v[60:61], v[60:61], 0.5, v[104:105] op_sel_hi:[1,0,1]
	v_lshlrev_b32_e32 v104, 16, v212
	v_and_b32_e32 v105, 0xffff0000, v212
	v_pk_fma_f32 v[56:57], v[56:57], 0.5, v[104:105] op_sel_hi:[1,0,1]
	v_lshlrev_b32_e32 v104, 16, v211
	v_and_b32_e32 v105, 0xffff0000, v211
	v_pk_fma_f32 v[62:63], v[62:63], 0.5, v[104:105] op_sel_hi:[1,0,1]
	v_lshlrev_b32_e32 v104, 16, v213
	v_and_b32_e32 v105, 0xffff0000, v213
	v_pk_fma_f32 v[58:59], v[58:59], 0.5, v[104:105] op_sel_hi:[1,0,1]
	v_lshlrev_b32_e32 v104, 16, v218
	v_and_b32_e32 v105, 0xffff0000, v218
	v_pk_fma_f32 v[52:53], v[52:53], 0.5, v[104:105] op_sel_hi:[1,0,1]
	v_lshlrev_b32_e32 v104, 16, v220
	v_and_b32_e32 v105, 0xffff0000, v220
	v_pk_fma_f32 v[104:105], v[44:45], 0.5, v[104:105] op_sel_hi:[1,0,1]
	v_lshlrev_b32_e32 v44, 16, v219
	v_and_b32_e32 v45, 0xffff0000, v219
	v_pk_fma_f32 v[54:55], v[54:55], 0.5, v[44:45] op_sel_hi:[1,0,1]
	v_lshlrev_b32_e32 v44, 16, v221
	v_and_b32_e32 v45, 0xffff0000, v221
	v_pk_fma_f32 v[106:107], v[46:47], 0.5, v[44:45] op_sel_hi:[1,0,1]
	v_lshlrev_b32_e32 v44, 16, v226
	v_and_b32_e32 v45, 0xffff0000, v226
	v_pk_fma_f32 v[44:45], v[48:49], 0.5, v[44:45] op_sel_hi:[1,0,1]
	v_lshlrev_b32_e32 v48, 16, v229
	v_and_b32_e32 v49, 0xffff0000, v229
	v_pk_fma_f32 v[42:43], v[42:43], 0.5, v[48:49] op_sel_hi:[1,0,1]
	v_lshlrev_b32_e32 v48, 16, v234
	v_and_b32_e32 v49, 0xffff0000, v234
	v_pk_fma_f32 v[36:37], v[36:37], 0.5, v[48:49] op_sel_hi:[1,0,1]
	v_lshlrev_b32_e32 v48, 16, v236
	v_and_b32_e32 v49, 0xffff0000, v236
	v_lshlrev_b32_e32 v46, 16, v228
	v_and_b32_e32 v47, 0xffff0000, v228
	v_pk_fma_f32 v[48:49], v[28:29], 0.5, v[48:49] op_sel_hi:[1,0,1]
	v_lshlrev_b32_e32 v28, 16, v235
	v_and_b32_e32 v29, 0xffff0000, v235
	v_pk_fma_f32 v[40:41], v[40:41], 0.5, v[46:47] op_sel_hi:[1,0,1]
	v_lshlrev_b32_e32 v46, 16, v227
	v_and_b32_e32 v47, 0xffff0000, v227
	v_pk_fma_f32 v[38:39], v[38:39], 0.5, v[28:29] op_sel_hi:[1,0,1]
	v_lshlrev_b32_e32 v28, 16, v237
	v_and_b32_e32 v29, 0xffff0000, v237
	v_pk_fma_f32 v[46:47], v[50:51], 0.5, v[46:47] op_sel_hi:[1,0,1]
	v_pk_fma_f32 v[50:51], v[30:31], 0.5, v[28:29] op_sel_hi:[1,0,1]
	v_lshlrev_b32_e32 v28, 16, v238
	v_and_b32_e32 v29, 0xffff0000, v238
	v_lshlrev_b32_e32 v180, 16, v64
	v_and_b32_e32 v181, 0xffff0000, v64
	v_pk_fma_f32 v[28:29], v[32:33], 0.5, v[28:29] op_sel_hi:[1,0,1]
	v_lshlrev_b32_e32 v32, 16, v241
	v_and_b32_e32 v33, 0xffff0000, v241
	v_pk_fma_f32 v[4:5], v[4:5], 0.5, v[180:181] op_sel_hi:[1,0,1]
	v_lshlrev_b32_e32 v180, 16, v66
	v_and_b32_e32 v181, 0xffff0000, v66
	v_pk_fma_f32 v[26:27], v[26:27], 0.5, v[32:33] op_sel_hi:[1,0,1]
	v_lshlrev_b32_e32 v32, 16, v242
	v_and_b32_e32 v33, 0xffff0000, v242
	v_pk_fma_f32 v[0:1], v[0:1], 0.5, v[180:181] op_sel_hi:[1,0,1]
	v_lshl_add_u64 v[180:181], s[28:29], 0, v[182:183]
	v_cvt_pk_bf16_f32 v112, v60, v61
	v_cvt_pk_bf16_f32 v113, v62, v63
	v_cvt_pk_bf16_f32 v114, v56, v57
	v_cvt_pk_bf16_f32 v115, v58, v59
	v_pk_fma_f32 v[20:21], v[20:21], 0.5, v[32:33] op_sel_hi:[1,0,1]
	v_lshlrev_b32_e32 v32, 16, v244
	v_and_b32_e32 v33, 0xffff0000, v244
	v_lshl_add_u64 v[180:181], v[180:181], 0, v[170:171]
	v_cvt_pk_bf16_f32 v116, v52, v53
	v_cvt_pk_bf16_f32 v117, v54, v55
	v_cvt_pk_bf16_f32 v118, v104, v105
	v_cvt_pk_bf16_f32 v119, v106, v107
	v_lshlrev_b32_e32 v30, 16, v240
	v_and_b32_e32 v31, 0xffff0000, v240
	v_pk_fma_f32 v[32:33], v[12:13], 0.5, v[32:33] op_sel_hi:[1,0,1]
	v_lshlrev_b32_e32 v12, 16, v243
	v_and_b32_e32 v13, 0xffff0000, v243
	global_store_dwordx4 v[180:181], v[112:115], off
	global_store_dwordx4 v[180:181], v[116:119], off offset:256
	v_cvt_pk_bf16_f32 v146, v44, v45
	v_lshl_add_u64 v[112:113], s[28:29], 0, v[132:133]
	v_cvt_pk_bf16_f32 v147, v46, v47
	v_cvt_pk_bf16_f32 v148, v40, v41
	v_cvt_pk_bf16_f32 v149, v42, v43
	v_pk_fma_f32 v[24:25], v[24:25], 0.5, v[30:31] op_sel_hi:[1,0,1]
	v_lshlrev_b32_e32 v30, 16, v239
	v_and_b32_e32 v31, 0xffff0000, v239
	v_pk_fma_f32 v[22:23], v[22:23], 0.5, v[12:13] op_sel_hi:[1,0,1]
	v_lshlrev_b32_e32 v12, 16, v245
	v_and_b32_e32 v13, 0xffff0000, v245
	v_lshl_add_u64 v[112:113], v[112:113], 0, v[170:171]
	v_cvt_pk_bf16_f32 v172, v36, v37
	v_cvt_pk_bf16_f32 v173, v38, v39
	v_cvt_pk_bf16_f32 v174, v48, v49
	v_cvt_pk_bf16_f32 v175, v50, v51
	v_pk_fma_f32 v[30:31], v[34:35], 0.5, v[30:31] op_sel_hi:[1,0,1]
	v_pk_fma_f32 v[34:35], v[14:15], 0.5, v[12:13] op_sel_hi:[1,0,1]
	v_lshlrev_b32_e32 v12, 16, v246
	v_and_b32_e32 v13, 0xffff0000, v246
	v_lshlrev_b32_e32 v14, 16, v248
	v_and_b32_e32 v15, 0xffff0000, v248
	global_store_dwordx4 v[112:113], v[146:149], off
	global_store_dwordx4 v[112:113], v[172:175], off offset:256
	v_lshl_add_u64 v[112:113], s[28:29], 0, v[134:135]
	v_cvt_pk_bf16_f32 v176, v28, v29
	v_cvt_pk_bf16_f32 v177, v30, v31
	v_cvt_pk_bf16_f32 v178, v24, v25
	v_cvt_pk_bf16_f32 v179, v26, v27
	v_pk_fma_f32 v[12:13], v[16:17], 0.5, v[12:13] op_sel_hi:[1,0,1]
	v_pk_fma_f32 v[8:9], v[8:9], 0.5, v[14:15] op_sel_hi:[1,0,1]
	v_lshlrev_b32_e32 v14, 16, v247
	v_and_b32_e32 v15, 0xffff0000, v247
	v_lshlrev_b32_e32 v16, 16, v249
	v_and_b32_e32 v17, 0xffff0000, v249
	v_lshlrev_b32_e32 v64, 16, v65
	v_and_b32_e32 v65, 0xffff0000, v65
	v_lshl_add_u64 v[112:113], v[112:113], 0, v[170:171]
	v_cvt_pk_bf16_f32 v194, v20, v21
	v_cvt_pk_bf16_f32 v195, v22, v23
	v_cvt_pk_bf16_f32 v196, v32, v33
	v_cvt_pk_bf16_f32 v197, v34, v35
	v_pk_fma_f32 v[14:15], v[18:19], 0.5, v[14:15] op_sel_hi:[1,0,1]
	v_pk_fma_f32 v[10:11], v[10:11], 0.5, v[16:17] op_sel_hi:[1,0,1]
	v_pk_fma_f32 v[6:7], v[6:7], 0.5, v[64:65] op_sel_hi:[1,0,1]
	v_lshlrev_b32_e32 v64, 16, v67
	v_and_b32_e32 v65, 0xffff0000, v67
	global_store_dwordx4 v[112:113], v[176:179], off
	global_store_dwordx4 v[112:113], v[194:197], off offset:256
	v_lshl_add_u64 v[112:113], s[28:29], 0, v[184:185]
	v_cvt_pk_bf16_f32 v16, v12, v13
	v_cvt_pk_bf16_f32 v17, v14, v15
	v_cvt_pk_bf16_f32 v18, v8, v9
	v_cvt_pk_bf16_f32 v19, v10, v11
	v_pk_fma_f32 v[2:3], v[2:3], 0.5, v[64:65] op_sel_hi:[1,0,1]
	v_lshl_add_u64 v[112:113], v[112:113], 0, v[170:171]
	v_cvt_pk_bf16_f32 v64, v4, v5
	v_cvt_pk_bf16_f32 v65, v6, v7
	v_cvt_pk_bf16_f32 v66, v0, v1
	v_cvt_pk_bf16_f32 v67, v2, v3
	global_store_dwordx4 v[112:113], v[16:19], off
	global_store_dwordx4 v[112:113], v[64:67], off offset:256
	s_lshl_b32 s10, s81, 2
	v_and_b32_e32 v17, 64, v188
	v_xor_b32_e32 v16, 16, v188
	v_add_u32_e32 v17, 64, v17
	v_cmp_lt_i32_e32 vcc, v16, v17
	v_xor_b32_e32 v18, 32, v188
	s_ashr_i32 s11, s10, 31
	v_cndmask_b32_e32 v16, v188, v16, vcc
	v_lshlrev_b32_e32 v16, 2, v16
	ds_bpermute_b32 v19, v16, v209
	v_cmp_lt_i32_e32 vcc, v18, v17
	s_lshl_b64 s[10:11], s[10:11], 2
	s_add_u32 s38, s73, s10
	v_cndmask_b32_e32 v17, v188, v18, vcc
	v_lshlrev_b32_e32 v17, 2, v17
	s_waitcnt lgkmcnt(0)
	v_add_f32_e32 v18, v209, v19
	ds_bpermute_b32 v19, v17, v18
	s_addc_u32 s39, s74, s11
	s_and_saveexec_b64 s[46:47], s[42:43]
	s_cbranch_execz .LBB0_34
	s_waitcnt lgkmcnt(0)
	v_add_f32_e32 v64, v18, v19
	v_lshlrev_b64 v[18:19], 6, v[168:169]
	v_lshl_add_u64 v[18:19], s[38:39], 0, v[18:19]
	global_store_dword v[18:19], v64, off

.Lm4ap_77:
	s_waitcnt lgkmcnt(0)
	s_barrier
	v_mfma_f32_16x16x32_bf16 v[124:127], v[158:161], v[174:177], 0
	v_mfma_f32_16x16x32_bf16 v[120:123], v[166:169], v[174:177], 0
	v_mfma_f32_16x16x32_bf16 v[116:119], v[158:161], v[182:185], 0
	v_mfma_f32_16x16x32_bf16 v[112:115], v[166:169], v[182:185], 0
	v_mfma_f32_16x16x32_bf16 v[108:111], v[158:161], v[210:213], 0
	v_mfma_f32_16x16x32_bf16 v[104:107], v[166:169], v[210:213], 0
	v_mfma_f32_16x16x32_bf16 v[100:103], v[158:161], v[218:221], 0
	v_mfma_f32_16x16x32_bf16 v[96:99], v[166:169], v[218:221], 0
	v_mfma_f32_16x16x32_bf16 v[124:127], v[162:165], v[178:181], v[124:127]
	v_mfma_f32_16x16x32_bf16 v[120:123], v[170:173], v[178:181], v[120:123]
	v_mfma_f32_16x16x32_bf16 v[116:119], v[162:165], v[206:209], v[116:119]
	v_mfma_f32_16x16x32_bf16 v[112:115], v[170:173], v[206:209], v[112:115]
	v_mfma_f32_16x16x32_bf16 v[108:111], v[162:165], v[214:217], v[108:111]
	v_mfma_f32_16x16x32_bf16 v[104:107], v[170:173], v[214:217], v[104:107]
	v_mfma_f32_16x16x32_bf16 v[100:103], v[162:165], v[222:225], v[100:103]
	v_mfma_f32_16x16x32_bf16 v[96:99], v[170:173], v[222:225], v[96:99]
	v_mfma_f32_16x16x32_bf16 v[92:95], v[226:229], v[174:177], 0
	v_mfma_f32_16x16x32_bf16 v[88:91], v[234:237], v[174:177], 0
	v_mfma_f32_16x16x32_bf16 v[84:87], v[226:229], v[182:185], 0
	v_mfma_f32_16x16x32_bf16 v[80:83], v[234:237], v[182:185], 0
	v_mfma_f32_16x16x32_bf16 v[76:79], v[226:229], v[210:213], 0
	v_mfma_f32_16x16x32_bf16 v[72:75], v[234:237], v[210:213], 0
	v_mfma_f32_16x16x32_bf16 v[68:71], v[226:229], v[218:221], 0
	v_mfma_f32_16x16x32_bf16 v[64:67], v[234:237], v[218:221], 0
	v_mfma_f32_16x16x32_bf16 v[92:95], v[230:233], v[178:181], v[92:95]
	v_mfma_f32_16x16x32_bf16 v[88:91], v[238:241], v[178:181], v[88:91]
	v_mfma_f32_16x16x32_bf16 v[84:87], v[230:233], v[206:209], v[84:87]
	v_mfma_f32_16x16x32_bf16 v[80:83], v[238:241], v[206:209], v[80:83]
	v_mfma_f32_16x16x32_bf16 v[76:79], v[230:233], v[214:217], v[76:79]
	v_mfma_f32_16x16x32_bf16 v[72:75], v[238:241], v[214:217], v[72:75]
	v_mfma_f32_16x16x32_bf16 v[68:71], v[230:233], v[222:225], v[68:71]
	v_mfma_f32_16x16x32_bf16 v[64:67], v[238:241], v[222:225], v[64:67]
	s_add_i32 s19, s82, s59
	v_lshl_add_u64 v[146:147], s[52:53], 0, v[140:141]
	s_mov_b32 m0, s19
	v_lshl_add_u64 v[148:149], s[52:53], 0, v[132:133]
	s_barrier
	global_load_lds_dwordx4 v[146:147], off
	s_add_i32 m0, s19, 0x2000
	s_nop 0
	global_load_lds_dwordx4 v[148:149], off
	s_mov_b32 m0, s68
	v_lshl_add_u64 v[194:195], s[54:55], 0, v[128:129]
	ds_read_b128 v[174:177], v157 offset:16384
	ds_read_b128 v[178:181], v157 offset:17408
	ds_read_b128 v[182:185], v157 offset:18432
	ds_read_b128 v[206:209], v157 offset:19456
	ds_read_b128 v[210:213], v157 offset:20480
	ds_read_b128 v[214:217], v157 offset:21504
	ds_read_b128 v[218:221], v157 offset:22528
	ds_read_b128 v[222:225], v157 offset:23552
	global_load_lds_dwordx4 v[194:195], off
	v_lshl_add_u64 v[196:197], s[54:55], 0, v[130:131]
	s_mov_b32 m0, s69
	s_nop 0
	global_load_lds_dwordx4 v[196:197], off
	s_add_u32 s82, s52, 0x40000
	s_addc_u32 s83, s53, 0
	s_add_i32 s6, s6, s59
	v_lshl_add_u64 v[250:251], s[82:83], 0, v[140:141]
	s_mov_b32 m0, s6
	s_nop 0
	global_load_lds_dwordx4 v[250:251], off
	v_lshl_add_u64 v[250:251], s[82:83], 0, v[132:133]
	s_add_i32 m0, s6, 0x2000
	s_nop 0
	global_load_lds_dwordx4 v[250:251], off
	s_waitcnt vmcnt(16)
	s_cmp_lg_u32 s100, 0
	s_cbranch_scc1 .Lm4bp_77
	s_waitcnt vmcnt(8)
.Lm4bp_77:
	s_waitcnt lgkmcnt(0)
	s_mov_b32 s100, 0
	s_barrier
	s_nop 0
	v_mfma_f32_16x16x32_bf16 v[60:63], v[158:161], v[174:177], 0
	v_mfma_f32_16x16x32_bf16 v[56:59], v[166:169], v[174:177], 0
	v_mfma_f32_16x16x32_bf16 v[52:55], v[158:161], v[182:185], 0
	v_mfma_f32_16x16x32_bf16 v[48:51], v[166:169], v[182:185], 0
	v_mfma_f32_16x16x32_bf16 v[44:47], v[158:161], v[210:213], 0
	v_mfma_f32_16x16x32_bf16 v[40:43], v[166:169], v[210:213], 0
	v_mfma_f32_16x16x32_bf16 v[36:39], v[158:161], v[218:221], 0
	v_mfma_f32_16x16x32_bf16 v[32:35], v[166:169], v[218:221], 0
	v_mfma_f32_16x16x32_bf16 v[60:63], v[162:165], v[178:181], v[60:63]
	v_mfma_f32_16x16x32_bf16 v[56:59], v[170:173], v[178:181], v[56:59]
	v_mfma_f32_16x16x32_bf16 v[52:55], v[162:165], v[206:209], v[52:55]
	v_mfma_f32_16x16x32_bf16 v[48:51], v[170:173], v[206:209], v[48:51]
	v_mfma_f32_16x16x32_bf16 v[44:47], v[162:165], v[214:217], v[44:47]
	v_mfma_f32_16x16x32_bf16 v[40:43], v[170:173], v[214:217], v[40:43]
	v_mfma_f32_16x16x32_bf16 v[36:39], v[162:165], v[222:225], v[36:39]
	v_mfma_f32_16x16x32_bf16 v[32:35], v[170:173], v[222:225], v[32:35]
	v_mfma_f32_16x16x32_bf16 v[28:31], v[226:229], v[174:177], 0
	v_mfma_f32_16x16x32_bf16 v[24:27], v[234:237], v[174:177], 0
	v_mfma_f32_16x16x32_bf16 v[20:23], v[226:229], v[182:185], 0
	v_mfma_f32_16x16x32_bf16 v[16:19], v[234:237], v[182:185], 0
	v_mfma_f32_16x16x32_bf16 v[12:15], v[226:229], v[210:213], 0
	v_mfma_f32_16x16x32_bf16 v[8:11], v[234:237], v[210:213], 0
	v_mfma_f32_16x16x32_bf16 v[4:7], v[226:229], v[218:221], 0
	v_mfma_f32_16x16x32_bf16 v[0:3], v[234:237], v[218:221], 0
	v_mfma_f32_16x16x32_bf16 v[28:31], v[230:233], v[178:181], v[28:31]
	v_mfma_f32_16x16x32_bf16 v[24:27], v[238:241], v[178:181], v[24:27]
	v_mfma_f32_16x16x32_bf16 v[20:23], v[230:233], v[206:209], v[20:23]
	v_mfma_f32_16x16x32_bf16 v[16:19], v[238:241], v[206:209], v[16:19]
	v_mfma_f32_16x16x32_bf16 v[12:15], v[230:233], v[214:217], v[12:15]
	v_mfma_f32_16x16x32_bf16 v[8:11], v[238:241], v[214:217], v[8:11]
	v_mfma_f32_16x16x32_bf16 v[4:7], v[230:233], v[222:225], v[4:7]
	v_mfma_f32_16x16x32_bf16 v[0:3], v[238:241], v[222:225], v[0:3]
	s_add_i32 s6, 0, 0x18000
	s_barrier
	v_add_u32_e32 v170, s6, v154
	ds_read_b128 v[158:161], v170
	ds_read_b128 v[162:165], v170 offset:1024
	ds_read_b128 v[166:169], v170 offset:2048
	ds_read_b128 v[170:173], v170 offset:3072
	s_add_u32 s54, s54, 0x40000
	s_addc_u32 s55, s55, 0
	s_mov_b32 m0, s70
	v_lshl_add_u64 v[226:227], s[54:55], 0, v[128:129]
	ds_read_b128 v[174:177], v157 offset:32768
	ds_read_b128 v[178:181], v157 offset:33792
	ds_read_b128 v[182:185], v157 offset:34816
	ds_read_b128 v[206:209], v157 offset:35840
	ds_read_b128 v[210:213], v157 offset:36864
	ds_read_b128 v[214:217], v157 offset:37888
	ds_read_b128 v[218:221], v157 offset:38912
	ds_read_b128 v[222:225], v157 offset:39936
	global_load_lds_dwordx4 v[226:227], off
	v_lshl_add_u64 v[226:227], s[54:55], 0, v[130:131]
	s_mov_b32 m0, s71
	s_nop 0
	global_load_lds_dwordx4 v[226:227], off
	s_add_i32 s19, 0, 0x1c000
	v_add_u32_e32 v192, s19, v154
	ds_read_b128 v[226:229], v192
	ds_read_b128 v[230:233], v192 offset:1024
	ds_read_b128 v[234:237], v192 offset:2048
	ds_read_b128 v[238:241], v192 offset:3072
	s_waitcnt vmcnt(8)
	s_waitcnt lgkmcnt(0)
	s_barrier
	v_mfma_f32_16x16x32_bf16 v[124:127], v[158:161], v[174:177], v[124:127]
	v_mfma_f32_16x16x32_bf16 v[120:123], v[166:169], v[174:177], v[120:123]
	v_mfma_f32_16x16x32_bf16 v[116:119], v[158:161], v[182:185], v[116:119]
	v_mfma_f32_16x16x32_bf16 v[112:115], v[166:169], v[182:185], v[112:115]
	v_mfma_f32_16x16x32_bf16 v[108:111], v[158:161], v[210:213], v[108:111]
	v_mfma_f32_16x16x32_bf16 v[104:107], v[166:169], v[210:213], v[104:107]
	v_mfma_f32_16x16x32_bf16 v[100:103], v[158:161], v[218:221], v[100:103]
	v_mfma_f32_16x16x32_bf16 v[96:99], v[166:169], v[218:221], v[96:99]
	v_mfma_f32_16x16x32_bf16 v[124:127], v[162:165], v[178:181], v[124:127]
	v_mfma_f32_16x16x32_bf16 v[120:123], v[170:173], v[178:181], v[120:123]
	v_mfma_f32_16x16x32_bf16 v[116:119], v[162:165], v[206:209], v[116:119]
	v_mfma_f32_16x16x32_bf16 v[112:115], v[170:173], v[206:209], v[112:115]
	v_mfma_f32_16x16x32_bf16 v[108:111], v[162:165], v[214:217], v[108:111]
	v_mfma_f32_16x16x32_bf16 v[104:107], v[170:173], v[214:217], v[104:107]
	v_mfma_f32_16x16x32_bf16 v[100:103], v[162:165], v[222:225], v[100:103]
	v_mfma_f32_16x16x32_bf16 v[96:99], v[170:173], v[222:225], v[96:99]
	v_mfma_f32_16x16x32_bf16 v[92:95], v[226:229], v[174:177], v[92:95]
	v_mfma_f32_16x16x32_bf16 v[88:91], v[234:237], v[174:177], v[88:91]
	v_mfma_f32_16x16x32_bf16 v[84:87], v[226:229], v[182:185], v[84:87]
	v_mfma_f32_16x16x32_bf16 v[80:83], v[234:237], v[182:185], v[80:83]
	v_mfma_f32_16x16x32_bf16 v[76:79], v[226:229], v[210:213], v[76:79]
	v_mfma_f32_16x16x32_bf16 v[72:75], v[234:237], v[210:213], v[72:75]
	v_mfma_f32_16x16x32_bf16 v[68:71], v[226:229], v[218:221], v[68:71]
	v_mfma_f32_16x16x32_bf16 v[64:67], v[234:237], v[218:221], v[64:67]
	v_mfma_f32_16x16x32_bf16 v[92:95], v[230:233], v[178:181], v[92:95]
	v_mfma_f32_16x16x32_bf16 v[88:91], v[238:241], v[178:181], v[88:91]
	v_mfma_f32_16x16x32_bf16 v[84:87], v[230:233], v[206:209], v[84:87]
	v_mfma_f32_16x16x32_bf16 v[80:83], v[238:241], v[206:209], v[80:83]
	v_mfma_f32_16x16x32_bf16 v[76:79], v[230:233], v[214:217], v[76:79]
	v_mfma_f32_16x16x32_bf16 v[72:75], v[238:241], v[214:217], v[72:75]
	v_mfma_f32_16x16x32_bf16 v[68:71], v[230:233], v[222:225], v[68:71]
	v_mfma_f32_16x16x32_bf16 v[64:67], v[238:241], v[222:225], v[64:67]
	s_add_i32 s6, s6, s59
	v_lshl_add_u64 v[146:147], v[146:147], 0, s[36:37]
	s_mov_b32 m0, s6
	s_barrier
	s_nop 0
	global_load_lds_dwordx4 v[146:147], off
	v_lshl_add_u64 v[146:147], v[148:149], 0, s[36:37]
	s_add_i32 m0, s6, 0x2000
	s_nop 0
	global_load_lds_dwordx4 v[146:147], off
	s_mov_b32 m0, s72
	v_lshl_add_u64 v[146:147], v[194:195], 0, s[36:37]
	ds_read_b128 v[174:177], v157 offset:49152
	ds_read_b128 v[178:181], v157 offset:50176
	ds_read_b128 v[182:185], v157 offset:51200
	ds_read_b128 v[206:209], v157 offset:52224
	ds_read_b128 v[210:213], v157 offset:53248
	ds_read_b128 v[214:217], v157 offset:54272
	ds_read_b128 v[218:221], v157 offset:55296
	ds_read_b128 v[222:225], v157 offset:56320
	global_load_lds_dwordx4 v[146:147], off
	v_lshl_add_u64 v[146:147], v[196:197], 0, s[36:37]
	s_mov_b32 m0, s73
	s_nop 0
	global_load_lds_dwordx4 v[146:147], off
	s_add_u32 s52, s52, 0x40080
	s_addc_u32 s53, s53, 0
	s_add_i32 s6, s19, s59
	v_lshl_add_u64 v[146:147], s[52:53], 0, v[140:141]
	s_mov_b32 m0, s6
	s_nop 0
	global_load_lds_dwordx4 v[146:147], off
	v_lshl_add_u64 v[146:147], s[52:53], 0, v[132:133]
	s_add_i32 m0, s6, 0x2000
	s_nop 0
	global_load_lds_dwordx4 v[146:147], off
	s_waitcnt vmcnt(8)
	s_waitcnt lgkmcnt(0)
	s_barrier
	v_mfma_f32_16x16x32_bf16 v[60:63], v[158:161], v[174:177], v[60:63]
	v_mfma_f32_16x16x32_bf16 v[56:59], v[166:169], v[174:177], v[56:59]
	v_mfma_f32_16x16x32_bf16 v[52:55], v[158:161], v[182:185], v[52:55]
	v_mfma_f32_16x16x32_bf16 v[48:51], v[166:169], v[182:185], v[48:51]
	v_mfma_f32_16x16x32_bf16 v[44:47], v[158:161], v[210:213], v[44:47]
	v_mfma_f32_16x16x32_bf16 v[40:43], v[166:169], v[210:213], v[40:43]
	v_mfma_f32_16x16x32_bf16 v[36:39], v[158:161], v[218:221], v[36:39]
	v_mfma_f32_16x16x32_bf16 v[32:35], v[166:169], v[218:221], v[32:35]
	v_mfma_f32_16x16x32_bf16 v[60:63], v[162:165], v[178:181], v[60:63]
	v_mfma_f32_16x16x32_bf16 v[56:59], v[170:173], v[178:181], v[56:59]
	v_mfma_f32_16x16x32_bf16 v[52:55], v[162:165], v[206:209], v[52:55]
	v_mfma_f32_16x16x32_bf16 v[48:51], v[170:173], v[206:209], v[48:51]
	v_mfma_f32_16x16x32_bf16 v[44:47], v[162:165], v[214:217], v[44:47]
	v_mfma_f32_16x16x32_bf16 v[40:43], v[170:173], v[214:217], v[40:43]
	v_mfma_f32_16x16x32_bf16 v[36:39], v[162:165], v[222:225], v[36:39]
	v_mfma_f32_16x16x32_bf16 v[32:35], v[170:173], v[222:225], v[32:35]
	v_mfma_f32_16x16x32_bf16 v[28:31], v[226:229], v[174:177], v[28:31]
	v_mfma_f32_16x16x32_bf16 v[24:27], v[234:237], v[174:177], v[24:27]
	v_mfma_f32_16x16x32_bf16 v[20:23], v[226:229], v[182:185], v[20:23]
	v_mfma_f32_16x16x32_bf16 v[16:19], v[234:237], v[182:185], v[16:19]
	v_mfma_f32_16x16x32_bf16 v[12:15], v[226:229], v[210:213], v[12:15]
	v_mfma_f32_16x16x32_bf16 v[8:11], v[234:237], v[210:213], v[8:11]
	v_mfma_f32_16x16x32_bf16 v[4:7], v[226:229], v[218:221], v[4:7]
	v_mfma_f32_16x16x32_bf16 v[0:3], v[234:237], v[218:221], v[0:3]
	v_mfma_f32_16x16x32_bf16 v[28:31], v[230:233], v[178:181], v[28:31]
	v_mfma_f32_16x16x32_bf16 v[24:27], v[238:241], v[178:181], v[24:27]
	v_mfma_f32_16x16x32_bf16 v[20:23], v[230:233], v[206:209], v[20:23]
	v_mfma_f32_16x16x32_bf16 v[16:19], v[238:241], v[206:209], v[16:19]
	v_mfma_f32_16x16x32_bf16 v[12:15], v[230:233], v[214:217], v[12:15]
	v_mfma_f32_16x16x32_bf16 v[8:11], v[238:241], v[214:217], v[8:11]
	v_mfma_f32_16x16x32_bf16 v[4:7], v[230:233], v[222:225], v[4:7]
	v_mfma_f32_16x16x32_bf16 v[0:3], v[238:241], v[222:225], v[0:3]
	s_add_i32 s81, s81, 2
	s_add_u32 s50, s50, 0x100
	s_addc_u32 s51, s51, 0
	s_cmp_gt_u32 s81, 13
	s_add_u32 s6, s26, s50
	s_addc_u32 s19, s27, s51
	s_add_u32 s6, s6, 0x100
	s_addc_u32 s19, s19, 0
	s_add_u32 s23, s10, s50
	s_addc_u32 s52, s11, s51
	s_add_i32 s82, 0, 0x10000
	s_cmpk_eq_i32 s50, 0x700
	s_cselect_b32 s55, s12, s19
	s_cselect_b32 s54, s31, s6
	s_cselect_b32 s53, s35, s52
	s_cselect_b32 s52, s39, s23
my_head_77:
	s_barrier
.LBB0_77:
	v_add_u32_e32 v146, s82, v154
	ds_read_b128 v[158:161], v146
	ds_read_b128 v[162:165], v146 offset:1024
	ds_read_b128 v[166:169], v146 offset:2048
	ds_read_b128 v[170:173], v146 offset:3072
	v_lshl_add_u64 v[146:147], v[150:151], 0, s[50:51]
	s_add_i32 m0, s68, 0xc000
	ds_read_b128 v[174:177], v157
	ds_read_b128 v[178:181], v157 offset:1024
	ds_read_b128 v[182:185], v157 offset:2048
	ds_read_b128 v[206:209], v157 offset:3072
	ds_read_b128 v[210:213], v157 offset:4096
	ds_read_b128 v[214:217], v157 offset:5120
	ds_read_b128 v[218:221], v157 offset:6144
	ds_read_b128 v[222:225], v157 offset:7168
	global_load_lds_dwordx4 v[146:147], off
	v_lshl_add_u64 v[146:147], v[152:153], 0, s[50:51]
	s_add_i32 m0, s68, 0xe000
	s_nop 0
	global_load_lds_dwordx4 v[146:147], off
	s_add_i32 s6, 0, 0x14000
	v_add_u32_e32 v146, s6, v154
	ds_read_b128 v[226:229], v146
	ds_read_b128 v[230:233], v146 offset:1024
	ds_read_b128 v[234:237], v146 offset:2048
	ds_read_b128 v[238:241], v146 offset:3072
	s_waitcnt vmcnt(8)
	s_waitcnt lgkmcnt(0)
	s_barrier
	v_mfma_f32_16x16x32_bf16 v[124:127], v[158:161], v[174:177], v[124:127]
	v_mfma_f32_16x16x32_bf16 v[120:123], v[166:169], v[174:177], v[120:123]
	v_mfma_f32_16x16x32_bf16 v[116:119], v[158:161], v[182:185], v[116:119]
	v_mfma_f32_16x16x32_bf16 v[112:115], v[166:169], v[182:185], v[112:115]
	v_mfma_f32_16x16x32_bf16 v[108:111], v[158:161], v[210:213], v[108:111]
	v_mfma_f32_16x16x32_bf16 v[104:107], v[166:169], v[210:213], v[104:107]
	v_mfma_f32_16x16x32_bf16 v[100:103], v[158:161], v[218:221], v[100:103]
	v_mfma_f32_16x16x32_bf16 v[96:99], v[166:169], v[218:221], v[96:99]
	v_mfma_f32_16x16x32_bf16 v[124:127], v[162:165], v[178:181], v[124:127]
	v_mfma_f32_16x16x32_bf16 v[120:123], v[170:173], v[178:181], v[120:123]
	v_mfma_f32_16x16x32_bf16 v[116:119], v[162:165], v[206:209], v[116:119]
	v_mfma_f32_16x16x32_bf16 v[112:115], v[170:173], v[206:209], v[112:115]
	v_mfma_f32_16x16x32_bf16 v[108:111], v[162:165], v[214:217], v[108:111]
	v_mfma_f32_16x16x32_bf16 v[104:107], v[170:173], v[214:217], v[104:107]
	v_mfma_f32_16x16x32_bf16 v[100:103], v[162:165], v[222:225], v[100:103]
	v_mfma_f32_16x16x32_bf16 v[96:99], v[170:173], v[222:225], v[96:99]
	v_mfma_f32_16x16x32_bf16 v[92:95], v[226:229], v[174:177], v[92:95]
	v_mfma_f32_16x16x32_bf16 v[88:91], v[234:237], v[174:177], v[88:91]
	v_mfma_f32_16x16x32_bf16 v[84:87], v[226:229], v[182:185], v[84:87]
	v_mfma_f32_16x16x32_bf16 v[80:83], v[234:237], v[182:185], v[80:83]
	v_mfma_f32_16x16x32_bf16 v[76:79], v[226:229], v[210:213], v[76:79]
	v_mfma_f32_16x16x32_bf16 v[72:75], v[234:237], v[210:213], v[72:75]
	v_mfma_f32_16x16x32_bf16 v[68:71], v[226:229], v[218:221], v[68:71]
	v_mfma_f32_16x16x32_bf16 v[64:67], v[234:237], v[218:221], v[64:67]
	v_mfma_f32_16x16x32_bf16 v[92:95], v[230:233], v[178:181], v[92:95]
	v_mfma_f32_16x16x32_bf16 v[88:91], v[238:241], v[178:181], v[88:91]
	v_mfma_f32_16x16x32_bf16 v[84:87], v[230:233], v[206:209], v[84:87]
	v_mfma_f32_16x16x32_bf16 v[80:83], v[238:241], v[206:209], v[80:83]
	v_mfma_f32_16x16x32_bf16 v[76:79], v[230:233], v[214:217], v[76:79]
	v_mfma_f32_16x16x32_bf16 v[72:75], v[238:241], v[214:217], v[72:75]
	v_mfma_f32_16x16x32_bf16 v[68:71], v[230:233], v[222:225], v[68:71]
	v_mfma_f32_16x16x32_bf16 v[64:67], v[238:241], v[222:225], v[64:67]
	s_add_i32 s19, s82, s59
	v_lshl_add_u64 v[146:147], s[52:53], 0, v[140:141]
	s_mov_b32 m0, s19
	v_lshl_add_u64 v[148:149], s[52:53], 0, v[132:133]
	s_barrier
	global_load_lds_dwordx4 v[146:147], off
	s_add_i32 m0, s19, 0x2000
	s_nop 0
	global_load_lds_dwordx4 v[148:149], off
	s_mov_b32 m0, s68
	v_lshl_add_u64 v[194:195], s[54:55], 0, v[128:129]
	ds_read_b128 v[174:177], v157 offset:16384
	ds_read_b128 v[178:181], v157 offset:17408
	ds_read_b128 v[182:185], v157 offset:18432
	ds_read_b128 v[206:209], v157 offset:19456
	ds_read_b128 v[210:213], v157 offset:20480
	ds_read_b128 v[214:217], v157 offset:21504
	ds_read_b128 v[218:221], v157 offset:22528
	ds_read_b128 v[222:225], v157 offset:23552
	global_load_lds_dwordx4 v[194:195], off
	v_lshl_add_u64 v[196:197], s[54:55], 0, v[130:131]
	s_mov_b32 m0, s69
	s_nop 0
	global_load_lds_dwordx4 v[196:197], off
	s_add_u32 s82, s52, 0x40000
	s_addc_u32 s83, s53, 0
	s_add_i32 s6, s6, s59
	v_lshl_add_u64 v[250:251], s[82:83], 0, v[140:141]
	s_mov_b32 m0, s6
	s_nop 0
	global_load_lds_dwordx4 v[250:251], off
	v_lshl_add_u64 v[250:251], s[82:83], 0, v[132:133]
	s_add_i32 m0, s6, 0x2000
	s_nop 0
	global_load_lds_dwordx4 v[250:251], off
	s_nop 0
	s_waitcnt vmcnt(8)
	s_waitcnt lgkmcnt(0)
	s_barrier
	v_mfma_f32_16x16x32_bf16 v[60:63], v[158:161], v[174:177], v[60:63]
	v_mfma_f32_16x16x32_bf16 v[56:59], v[166:169], v[174:177], v[56:59]
	v_mfma_f32_16x16x32_bf16 v[52:55], v[158:161], v[182:185], v[52:55]
	v_mfma_f32_16x16x32_bf16 v[48:51], v[166:169], v[182:185], v[48:51]
	v_mfma_f32_16x16x32_bf16 v[44:47], v[158:161], v[210:213], v[44:47]
	v_mfma_f32_16x16x32_bf16 v[40:43], v[166:169], v[210:213], v[40:43]
	v_mfma_f32_16x16x32_bf16 v[36:39], v[158:161], v[218:221], v[36:39]
	v_mfma_f32_16x16x32_bf16 v[32:35], v[166:169], v[218:221], v[32:35]
	v_mfma_f32_16x16x32_bf16 v[60:63], v[162:165], v[178:181], v[60:63]
	v_mfma_f32_16x16x32_bf16 v[56:59], v[170:173], v[178:181], v[56:59]
	v_mfma_f32_16x16x32_bf16 v[52:55], v[162:165], v[206:209], v[52:55]
	v_mfma_f32_16x16x32_bf16 v[48:51], v[170:173], v[206:209], v[48:51]
	v_mfma_f32_16x16x32_bf16 v[44:47], v[162:165], v[214:217], v[44:47]
	v_mfma_f32_16x16x32_bf16 v[40:43], v[170:173], v[214:217], v[40:43]
	v_mfma_f32_16x16x32_bf16 v[36:39], v[162:165], v[222:225], v[36:39]
	v_mfma_f32_16x16x32_bf16 v[32:35], v[170:173], v[222:225], v[32:35]
	v_mfma_f32_16x16x32_bf16 v[28:31], v[226:229], v[174:177], v[28:31]
	v_mfma_f32_16x16x32_bf16 v[24:27], v[234:237], v[174:177], v[24:27]
	v_mfma_f32_16x16x32_bf16 v[20:23], v[226:229], v[182:185], v[20:23]
	v_mfma_f32_16x16x32_bf16 v[16:19], v[234:237], v[182:185], v[16:19]
	v_mfma_f32_16x16x32_bf16 v[12:15], v[226:229], v[210:213], v[12:15]
	v_mfma_f32_16x16x32_bf16 v[8:11], v[234:237], v[210:213], v[8:11]
	v_mfma_f32_16x16x32_bf16 v[4:7], v[226:229], v[218:221], v[4:7]
	v_mfma_f32_16x16x32_bf16 v[0:3], v[234:237], v[218:221], v[0:3]
	v_mfma_f32_16x16x32_bf16 v[28:31], v[230:233], v[178:181], v[28:31]
	v_mfma_f32_16x16x32_bf16 v[24:27], v[238:241], v[178:181], v[24:27]
	v_mfma_f32_16x16x32_bf16 v[20:23], v[230:233], v[206:209], v[20:23]
	v_mfma_f32_16x16x32_bf16 v[16:19], v[238:241], v[206:209], v[16:19]
	v_mfma_f32_16x16x32_bf16 v[12:15], v[230:233], v[214:217], v[12:15]
	v_mfma_f32_16x16x32_bf16 v[8:11], v[238:241], v[214:217], v[8:11]
	v_mfma_f32_16x16x32_bf16 v[4:7], v[230:233], v[222:225], v[4:7]
	v_mfma_f32_16x16x32_bf16 v[0:3], v[238:241], v[222:225], v[0:3]
	s_add_i32 s6, 0, 0x18000
	s_barrier
	v_add_u32_e32 v170, s6, v154
	ds_read_b128 v[158:161], v170
	ds_read_b128 v[162:165], v170 offset:1024
	ds_read_b128 v[166:169], v170 offset:2048
	ds_read_b128 v[170:173], v170 offset:3072
	s_add_u32 s54, s54, 0x40000
	s_addc_u32 s55, s55, 0
	s_mov_b32 m0, s70
	v_lshl_add_u64 v[226:227], s[54:55], 0, v[128:129]
	ds_read_b128 v[174:177], v157 offset:32768
	ds_read_b128 v[178:181], v157 offset:33792
	ds_read_b128 v[182:185], v157 offset:34816
	ds_read_b128 v[206:209], v157 offset:35840
	ds_read_b128 v[210:213], v157 offset:36864
	ds_read_b128 v[214:217], v157 offset:37888
	ds_read_b128 v[218:221], v157 offset:38912
	ds_read_b128 v[222:225], v157 offset:39936
	global_load_lds_dwordx4 v[226:227], off
	v_lshl_add_u64 v[226:227], s[54:55], 0, v[130:131]
	s_mov_b32 m0, s71
	s_nop 0
	global_load_lds_dwordx4 v[226:227], off
	s_add_i32 s19, 0, 0x1c000
	v_add_u32_e32 v192, s19, v154
	ds_read_b128 v[226:229], v192
	ds_read_b128 v[230:233], v192 offset:1024
	ds_read_b128 v[234:237], v192 offset:2048
	ds_read_b128 v[238:241], v192 offset:3072
	s_waitcnt vmcnt(8)
	s_waitcnt lgkmcnt(0)
	s_barrier
	v_mfma_f32_16x16x32_bf16 v[124:127], v[158:161], v[174:177], v[124:127]
	v_mfma_f32_16x16x32_bf16 v[120:123], v[166:169], v[174:177], v[120:123]
	v_mfma_f32_16x16x32_bf16 v[116:119], v[158:161], v[182:185], v[116:119]
	v_mfma_f32_16x16x32_bf16 v[112:115], v[166:169], v[182:185], v[112:115]
	v_mfma_f32_16x16x32_bf16 v[108:111], v[158:161], v[210:213], v[108:111]
	v_mfma_f32_16x16x32_bf16 v[104:107], v[166:169], v[210:213], v[104:107]
	v_mfma_f32_16x16x32_bf16 v[100:103], v[158:161], v[218:221], v[100:103]
	v_mfma_f32_16x16x32_bf16 v[96:99], v[166:169], v[218:221], v[96:99]
	v_mfma_f32_16x16x32_bf16 v[124:127], v[162:165], v[178:181], v[124:127]
	v_mfma_f32_16x16x32_bf16 v[120:123], v[170:173], v[178:181], v[120:123]
	v_mfma_f32_16x16x32_bf16 v[116:119], v[162:165], v[206:209], v[116:119]
	v_mfma_f32_16x16x32_bf16 v[112:115], v[170:173], v[206:209], v[112:115]
	v_mfma_f32_16x16x32_bf16 v[108:111], v[162:165], v[214:217], v[108:111]
	v_mfma_f32_16x16x32_bf16 v[104:107], v[170:173], v[214:217], v[104:107]
	v_mfma_f32_16x16x32_bf16 v[100:103], v[162:165], v[222:225], v[100:103]
	v_mfma_f32_16x16x32_bf16 v[96:99], v[170:173], v[222:225], v[96:99]
	v_mfma_f32_16x16x32_bf16 v[92:95], v[226:229], v[174:177], v[92:95]
	v_mfma_f32_16x16x32_bf16 v[88:91], v[234:237], v[174:177], v[88:91]
	v_mfma_f32_16x16x32_bf16 v[84:87], v[226:229], v[182:185], v[84:87]
	v_mfma_f32_16x16x32_bf16 v[80:83], v[234:237], v[182:185], v[80:83]
	v_mfma_f32_16x16x32_bf16 v[76:79], v[226:229], v[210:213], v[76:79]
	v_mfma_f32_16x16x32_bf16 v[72:75], v[234:237], v[210:213], v[72:75]
	v_mfma_f32_16x16x32_bf16 v[68:71], v[226:229], v[218:221], v[68:71]
	v_mfma_f32_16x16x32_bf16 v[64:67], v[234:237], v[218:221], v[64:67]
	v_mfma_f32_16x16x32_bf16 v[92:95], v[230:233], v[178:181], v[92:95]
	v_mfma_f32_16x16x32_bf16 v[88:91], v[238:241], v[178:181], v[88:91]
	v_mfma_f32_16x16x32_bf16 v[84:87], v[230:233], v[206:209], v[84:87]
	v_mfma_f32_16x16x32_bf16 v[80:83], v[238:241], v[206:209], v[80:83]
	v_mfma_f32_16x16x32_bf16 v[76:79], v[230:233], v[214:217], v[76:79]
	v_mfma_f32_16x16x32_bf16 v[72:75], v[238:241], v[214:217], v[72:75]
	v_mfma_f32_16x16x32_bf16 v[68:71], v[230:233], v[222:225], v[68:71]
	v_mfma_f32_16x16x32_bf16 v[64:67], v[238:241], v[222:225], v[64:67]
	s_add_i32 s6, s6, s59
	v_lshl_add_u64 v[146:147], v[146:147], 0, s[36:37]
	s_mov_b32 m0, s6
	s_barrier
	s_nop 0
	global_load_lds_dwordx4 v[146:147], off
	v_lshl_add_u64 v[146:147], v[148:149], 0, s[36:37]
	s_add_i32 m0, s6, 0x2000
	s_nop 0
	global_load_lds_dwordx4 v[146:147], off
	s_mov_b32 m0, s72
	v_lshl_add_u64 v[146:147], v[194:195], 0, s[36:37]
	ds_read_b128 v[174:177], v157 offset:49152
	ds_read_b128 v[178:181], v157 offset:50176
	ds_read_b128 v[182:185], v157 offset:51200
	ds_read_b128 v[206:209], v157 offset:52224
	ds_read_b128 v[210:213], v157 offset:53248
	ds_read_b128 v[214:217], v157 offset:54272
	ds_read_b128 v[218:221], v157 offset:55296
	ds_read_b128 v[222:225], v157 offset:56320
	global_load_lds_dwordx4 v[146:147], off
	v_lshl_add_u64 v[146:147], v[196:197], 0, s[36:37]
	s_mov_b32 m0, s73
	s_nop 0
	global_load_lds_dwordx4 v[146:147], off
	s_add_u32 s52, s52, 0x40080
	s_addc_u32 s53, s53, 0
	s_add_i32 s6, s19, s59
	v_lshl_add_u64 v[146:147], s[52:53], 0, v[140:141]
	s_mov_b32 m0, s6
	s_nop 0
	global_load_lds_dwordx4 v[146:147], off
	v_lshl_add_u64 v[146:147], s[52:53], 0, v[132:133]
	s_add_i32 m0, s6, 0x2000
	s_nop 0
	global_load_lds_dwordx4 v[146:147], off
	s_waitcnt vmcnt(8)
	s_waitcnt lgkmcnt(0)
	s_barrier
	v_mfma_f32_16x16x32_bf16 v[60:63], v[158:161], v[174:177], v[60:63]
	v_mfma_f32_16x16x32_bf16 v[56:59], v[166:169], v[174:177], v[56:59]
	v_mfma_f32_16x16x32_bf16 v[52:55], v[158:161], v[182:185], v[52:55]
	v_mfma_f32_16x16x32_bf16 v[48:51], v[166:169], v[182:185], v[48:51]
	v_mfma_f32_16x16x32_bf16 v[44:47], v[158:161], v[210:213], v[44:47]
	v_mfma_f32_16x16x32_bf16 v[40:43], v[166:169], v[210:213], v[40:43]
	v_mfma_f32_16x16x32_bf16 v[36:39], v[158:161], v[218:221], v[36:39]
	v_mfma_f32_16x16x32_bf16 v[32:35], v[166:169], v[218:221], v[32:35]
	v_mfma_f32_16x16x32_bf16 v[60:63], v[162:165], v[178:181], v[60:63]
	v_mfma_f32_16x16x32_bf16 v[56:59], v[170:173], v[178:181], v[56:59]
	v_mfma_f32_16x16x32_bf16 v[52:55], v[162:165], v[206:209], v[52:55]
	v_mfma_f32_16x16x32_bf16 v[48:51], v[170:173], v[206:209], v[48:51]
	v_mfma_f32_16x16x32_bf16 v[44:47], v[162:165], v[214:217], v[44:47]
	v_mfma_f32_16x16x32_bf16 v[40:43], v[170:173], v[214:217], v[40:43]
	v_mfma_f32_16x16x32_bf16 v[36:39], v[162:165], v[222:225], v[36:39]
	v_mfma_f32_16x16x32_bf16 v[32:35], v[170:173], v[222:225], v[32:35]
	v_mfma_f32_16x16x32_bf16 v[28:31], v[226:229], v[174:177], v[28:31]
	v_mfma_f32_16x16x32_bf16 v[24:27], v[234:237], v[174:177], v[24:27]
	v_mfma_f32_16x16x32_bf16 v[20:23], v[226:229], v[182:185], v[20:23]
	v_mfma_f32_16x16x32_bf16 v[16:19], v[234:237], v[182:185], v[16:19]
	v_mfma_f32_16x16x32_bf16 v[12:15], v[226:229], v[210:213], v[12:15]
	v_mfma_f32_16x16x32_bf16 v[8:11], v[234:237], v[210:213], v[8:11]
	v_mfma_f32_16x16x32_bf16 v[4:7], v[226:229], v[218:221], v[4:7]
	v_mfma_f32_16x16x32_bf16 v[0:3], v[234:237], v[218:221], v[0:3]
	v_mfma_f32_16x16x32_bf16 v[28:31], v[230:233], v[178:181], v[28:31]
	v_mfma_f32_16x16x32_bf16 v[24:27], v[238:241], v[178:181], v[24:27]
	v_mfma_f32_16x16x32_bf16 v[20:23], v[230:233], v[206:209], v[20:23]
	v_mfma_f32_16x16x32_bf16 v[16:19], v[238:241], v[206:209], v[16:19]
	v_mfma_f32_16x16x32_bf16 v[12:15], v[230:233], v[214:217], v[12:15]
	v_mfma_f32_16x16x32_bf16 v[8:11], v[238:241], v[214:217], v[8:11]
	v_mfma_f32_16x16x32_bf16 v[4:7], v[230:233], v[222:225], v[4:7]
	v_mfma_f32_16x16x32_bf16 v[0:3], v[238:241], v[222:225], v[0:3]
	s_add_i32 s81, s81, 2
	s_add_u32 s50, s50, 0x100
	s_addc_u32 s51, s51, 0
	s_cmp_gt_u32 s81, 13
	s_cbranch_scc1 my_exit_77
	s_add_u32 s6, s26, s50
	s_addc_u32 s19, s27, s51
	s_add_u32 s6, s6, 0x100
	s_addc_u32 s19, s19, 0
	s_add_u32 s23, s10, s50
	s_addc_u32 s52, s11, s51
	s_add_i32 s82, 0, 0x10000
	s_cmpk_eq_i32 s50, 0x700
	s_cselect_b32 s55, s12, s19
	s_cselect_b32 s54, s31, s6
	s_cselect_b32 s53, s35, s52
	s_cselect_b32 s52, s39, s23
	s_branch my_head_77
my_exit_77:
	s_barrier
	s_mov_b32 s100, 1
	v_lshl_add_u32 v158, s75, 10, v155
	ds_read2_b32 v[146:147], v158 offset1:16
	s_add_u32 s50, s10, 0xffffff00
	s_addc_u32 s51, s11, -1
	s_ashr_i32 s31, s30, 31
	s_lshl_b64 s[10:11], s[30:31], 8
	s_waitcnt lgkmcnt(0)
	v_mul_f32_e32 v184, 0xbfb8aa3b, v146
	v_mul_f32_e32 v206, v146, v146
	v_pk_mul_f32 v[168:169], v[124:125], v[184:185] op_sel_hi:[1,0]
	v_pk_mul_f32 v[170:171], v[126:127], v[184:185] op_sel_hi:[1,0]
	v_pk_mul_f32 v[172:173], v[120:121], v[184:185] op_sel_hi:[1,0]
	v_pk_mul_f32 v[174:175], v[122:123], v[184:185] op_sel_hi:[1,0]
	v_exp_f32_e32 v168, v168
	v_exp_f32_e32 v169, v169
	v_exp_f32_e32 v170, v170
	v_exp_f32_e32 v171, v171
	v_exp_f32_e32 v172, v172
	v_exp_f32_e32 v173, v173
	v_exp_f32_e32 v174, v174
	v_exp_f32_e32 v175, v175
	v_pk_mul_f32 v[176:177], v[124:125], v[92:93]
	v_pk_mul_f32 v[178:179], v[126:127], v[94:95]
	v_pk_mul_f32 v[180:181], v[120:121], v[88:89]
	v_pk_mul_f32 v[182:183], v[122:123], v[90:91]
	v_pk_add_f32 v[168:169], v[168:169], 1.0 op_sel_hi:[1,0]
	v_pk_add_f32 v[170:171], v[170:171], 1.0 op_sel_hi:[1,0]
	v_pk_add_f32 v[172:173], v[172:173], 1.0 op_sel_hi:[1,0]
	v_pk_add_f32 v[174:175], v[174:175], 1.0 op_sel_hi:[1,0]
	v_rcp_f32_e32 v168, v168
	v_rcp_f32_e32 v169, v169
	v_rcp_f32_e32 v170, v170
	v_rcp_f32_e32 v171, v171
	v_rcp_f32_e32 v172, v172
	v_rcp_f32_e32 v173, v173
	v_rcp_f32_e32 v174, v174
	v_rcp_f32_e32 v175, v175
	v_pk_mul_f32 v[176:177], v[176:177], v[206:207] op_sel_hi:[1,0]
	v_pk_mul_f32 v[178:179], v[178:179], v[206:207] op_sel_hi:[1,0]
	v_pk_mul_f32 v[180:181], v[180:181], v[206:207] op_sel_hi:[1,0]
	v_pk_mul_f32 v[182:183], v[182:183], v[206:207] op_sel_hi:[1,0]
	v_pk_mul_f32 v[176:177], v[176:177], v[168:169]
	v_pk_mul_f32 v[178:179], v[178:179], v[170:171]
	v_pk_mul_f32 v[180:181], v[180:181], v[172:173]
	v_pk_mul_f32 v[182:183], v[182:183], v[174:175]
	v_cvt_pk_bf16_f32 v160, v176, v177
	v_cvt_pk_bf16_f32 v161, v178, v179
	v_cvt_pk_bf16_f32 v162, v180, v181
	v_cvt_pk_bf16_f32 v163, v182, v183
	v_lshl_add_u64 v[152:153], v[134:135], 0, s[10:11]
	s_movk_i32 s6, 0x1600
	v_lshl_or_b32 v150, s74, 7, v156
	v_ashrrev_i32_e32 v151, 31, v150
	s_nop 1
	v_mov_b64_e32 v[148:149], s[28:29]
	v_mad_u64_u32 v[148:149], s[10:11], v152, s6, v[148:149]
	v_mov_b32_e32 v146, v149
	v_mad_u64_u32 v[152:153], s[10:11], v153, s6, v[146:147]
	v_mov_b32_e32 v149, v152
	v_mov_b32_e32 v146, v147
	v_lshl_add_u64 v[150:151], v[150:151], 1, v[148:149]
	global_store_dwordx4 v[150:151], v[160:163], off
	v_mul_f32_e32 v184, 0xbfb8aa3b, v146
	v_mul_f32_e32 v206, v146, v146
	v_pk_mul_f32 v[168:169], v[116:117], v[184:185] op_sel_hi:[1,0]
	v_pk_mul_f32 v[170:171], v[118:119], v[184:185] op_sel_hi:[1,0]
	v_pk_mul_f32 v[172:173], v[112:113], v[184:185] op_sel_hi:[1,0]
	v_pk_mul_f32 v[174:175], v[114:115], v[184:185] op_sel_hi:[1,0]
	v_exp_f32_e32 v168, v168
	v_exp_f32_e32 v169, v169
	v_exp_f32_e32 v170, v170
	v_exp_f32_e32 v171, v171
	v_exp_f32_e32 v172, v172
	v_exp_f32_e32 v173, v173
	v_exp_f32_e32 v174, v174
	v_exp_f32_e32 v175, v175
	v_pk_mul_f32 v[176:177], v[116:117], v[84:85]
	v_pk_mul_f32 v[178:179], v[118:119], v[86:87]
	v_pk_mul_f32 v[180:181], v[112:113], v[80:81]
	v_pk_mul_f32 v[182:183], v[114:115], v[82:83]
	v_pk_add_f32 v[168:169], v[168:169], 1.0 op_sel_hi:[1,0]
	v_pk_add_f32 v[170:171], v[170:171], 1.0 op_sel_hi:[1,0]
	v_pk_add_f32 v[172:173], v[172:173], 1.0 op_sel_hi:[1,0]
	v_pk_add_f32 v[174:175], v[174:175], 1.0 op_sel_hi:[1,0]
	v_rcp_f32_e32 v168, v168
	v_rcp_f32_e32 v169, v169
	v_rcp_f32_e32 v170, v170
	v_rcp_f32_e32 v171, v171
	v_rcp_f32_e32 v172, v172
	v_rcp_f32_e32 v173, v173
	v_rcp_f32_e32 v174, v174
	v_rcp_f32_e32 v175, v175
	v_pk_mul_f32 v[176:177], v[176:177], v[206:207] op_sel_hi:[1,0]
	v_pk_mul_f32 v[178:179], v[178:179], v[206:207] op_sel_hi:[1,0]
	v_pk_mul_f32 v[180:181], v[180:181], v[206:207] op_sel_hi:[1,0]
	v_pk_mul_f32 v[182:183], v[182:183], v[206:207] op_sel_hi:[1,0]
	v_pk_mul_f32 v[176:177], v[176:177], v[168:169]
	v_pk_mul_f32 v[178:179], v[178:179], v[170:171]
	v_pk_mul_f32 v[180:181], v[180:181], v[172:173]
	v_pk_mul_f32 v[182:183], v[182:183], v[174:175]
	v_cvt_pk_bf16_f32 v160, v176, v177
	v_cvt_pk_bf16_f32 v161, v178, v179
	v_cvt_pk_bf16_f32 v162, v180, v181
	v_cvt_pk_bf16_f32 v163, v182, v183
	s_mov_b32 s6, 0x16000
	s_nop 1
	v_add_co_u32_e32 v146, vcc, s6, v150
	s_nop 0
	v_addc_co_u32_e32 v147, vcc, 0, v151, vcc
	global_store_dwordx4 v[146:147], v[160:163], off
	ds_read2_b32 v[146:147], v158 offset0:32 offset1:48
	s_mov_b32 s6, 0x2c000
	s_waitcnt lgkmcnt(0)
	v_mul_f32_e32 v184, 0xbfb8aa3b, v146
	v_mul_f32_e32 v206, v146, v146
	v_pk_mul_f32 v[168:169], v[108:109], v[184:185] op_sel_hi:[1,0]
	v_pk_mul_f32 v[170:171], v[110:111], v[184:185] op_sel_hi:[1,0]
	v_pk_mul_f32 v[172:173], v[104:105], v[184:185] op_sel_hi:[1,0]
	v_pk_mul_f32 v[174:175], v[106:107], v[184:185] op_sel_hi:[1,0]
	v_exp_f32_e32 v168, v168
	v_exp_f32_e32 v169, v169
	v_exp_f32_e32 v170, v170
	v_exp_f32_e32 v171, v171
	v_exp_f32_e32 v172, v172
	v_exp_f32_e32 v173, v173
	v_exp_f32_e32 v174, v174
	v_exp_f32_e32 v175, v175
	v_pk_mul_f32 v[176:177], v[108:109], v[76:77]
	v_pk_mul_f32 v[178:179], v[110:111], v[78:79]
	v_pk_mul_f32 v[180:181], v[104:105], v[72:73]
	v_pk_mul_f32 v[182:183], v[106:107], v[74:75]
	v_pk_add_f32 v[168:169], v[168:169], 1.0 op_sel_hi:[1,0]
	v_pk_add_f32 v[170:171], v[170:171], 1.0 op_sel_hi:[1,0]
	v_pk_add_f32 v[172:173], v[172:173], 1.0 op_sel_hi:[1,0]
	v_pk_add_f32 v[174:175], v[174:175], 1.0 op_sel_hi:[1,0]
	v_rcp_f32_e32 v168, v168
	v_rcp_f32_e32 v169, v169
	v_rcp_f32_e32 v170, v170
	v_rcp_f32_e32 v171, v171
	v_rcp_f32_e32 v172, v172
	v_rcp_f32_e32 v173, v173
	v_rcp_f32_e32 v174, v174
	v_rcp_f32_e32 v175, v175
	v_pk_mul_f32 v[176:177], v[176:177], v[206:207] op_sel_hi:[1,0]
	v_pk_mul_f32 v[178:179], v[178:179], v[206:207] op_sel_hi:[1,0]
	v_pk_mul_f32 v[180:181], v[180:181], v[206:207] op_sel_hi:[1,0]
	v_pk_mul_f32 v[182:183], v[182:183], v[206:207] op_sel_hi:[1,0]
	v_pk_mul_f32 v[176:177], v[176:177], v[168:169]
	v_pk_mul_f32 v[178:179], v[178:179], v[170:171]
	v_pk_mul_f32 v[180:181], v[180:181], v[172:173]
	v_pk_mul_f32 v[182:183], v[182:183], v[174:175]
	v_cvt_pk_bf16_f32 v160, v176, v177
	v_cvt_pk_bf16_f32 v161, v178, v179
	v_cvt_pk_bf16_f32 v162, v180, v181
	v_cvt_pk_bf16_f32 v163, v182, v183
	s_nop 1
	v_mov_b32_e32 v146, v147
	v_add_co_u32_e32 v148, vcc, s6, v150
	v_addc_co_u32_e32 v149, vcc, 0, v151, vcc
	global_store_dwordx4 v[148:149], v[160:163], off
	v_mul_f32_e32 v184, 0xbfb8aa3b, v146
	v_mul_f32_e32 v206, v146, v146
	v_pk_mul_f32 v[168:169], v[100:101], v[184:185] op_sel_hi:[1,0]
	v_pk_mul_f32 v[170:171], v[102:103], v[184:185] op_sel_hi:[1,0]
	v_pk_mul_f32 v[172:173], v[96:97], v[184:185] op_sel_hi:[1,0]
	v_pk_mul_f32 v[174:175], v[98:99], v[184:185] op_sel_hi:[1,0]
	v_exp_f32_e32 v168, v168
	v_exp_f32_e32 v169, v169
	v_exp_f32_e32 v170, v170
	v_exp_f32_e32 v171, v171
	v_exp_f32_e32 v172, v172
	v_exp_f32_e32 v173, v173
	v_exp_f32_e32 v174, v174
	v_exp_f32_e32 v175, v175
	v_pk_mul_f32 v[176:177], v[100:101], v[68:69]
	v_pk_mul_f32 v[178:179], v[102:103], v[70:71]
	v_pk_mul_f32 v[180:181], v[96:97], v[64:65]
	v_pk_mul_f32 v[182:183], v[98:99], v[66:67]
	v_pk_add_f32 v[168:169], v[168:169], 1.0 op_sel_hi:[1,0]
	v_pk_add_f32 v[170:171], v[170:171], 1.0 op_sel_hi:[1,0]
	v_pk_add_f32 v[172:173], v[172:173], 1.0 op_sel_hi:[1,0]
	v_pk_add_f32 v[174:175], v[174:175], 1.0 op_sel_hi:[1,0]
	v_rcp_f32_e32 v168, v168
	v_rcp_f32_e32 v169, v169
	v_rcp_f32_e32 v170, v170
	v_rcp_f32_e32 v171, v171
	v_rcp_f32_e32 v172, v172
	v_rcp_f32_e32 v173, v173
	v_rcp_f32_e32 v174, v174
	v_rcp_f32_e32 v175, v175
	v_pk_mul_f32 v[176:177], v[176:177], v[206:207] op_sel_hi:[1,0]
	v_pk_mul_f32 v[178:179], v[178:179], v[206:207] op_sel_hi:[1,0]
	v_pk_mul_f32 v[180:181], v[180:181], v[206:207] op_sel_hi:[1,0]
	v_pk_mul_f32 v[182:183], v[182:183], v[206:207] op_sel_hi:[1,0]
	v_pk_mul_f32 v[176:177], v[176:177], v[168:169]
	v_pk_mul_f32 v[178:179], v[178:179], v[170:171]
	v_pk_mul_f32 v[180:181], v[180:181], v[172:173]
	v_pk_mul_f32 v[182:183], v[182:183], v[174:175]
	v_cvt_pk_bf16_f32 v160, v176, v177
	v_cvt_pk_bf16_f32 v161, v178, v179
	v_cvt_pk_bf16_f32 v162, v180, v181
	v_cvt_pk_bf16_f32 v163, v182, v183
	s_mov_b32 s6, 0x42000
	s_nop 1
	v_add_co_u32_e32 v146, vcc, s6, v150
	s_nop 0
	v_addc_co_u32_e32 v147, vcc, 0, v151, vcc
	global_store_dwordx4 v[146:147], v[160:163], off
	ds_read2_b32 v[146:147], v158 offset0:128 offset1:144
	s_mov_b32 s6, 0xb0000
	s_waitcnt lgkmcnt(0)
	v_mul_f32_e32 v184, 0xbfb8aa3b, v146
	v_mul_f32_e32 v206, v146, v146
	v_pk_mul_f32 v[168:169], v[60:61], v[184:185] op_sel_hi:[1,0]
	v_pk_mul_f32 v[170:171], v[62:63], v[184:185] op_sel_hi:[1,0]
	v_pk_mul_f32 v[172:173], v[56:57], v[184:185] op_sel_hi:[1,0]
	v_pk_mul_f32 v[174:175], v[58:59], v[184:185] op_sel_hi:[1,0]
	v_exp_f32_e32 v168, v168
	v_exp_f32_e32 v169, v169
	v_exp_f32_e32 v170, v170
	v_exp_f32_e32 v171, v171
	v_exp_f32_e32 v172, v172
	v_exp_f32_e32 v173, v173
	v_exp_f32_e32 v174, v174
	v_exp_f32_e32 v175, v175
	v_pk_mul_f32 v[176:177], v[60:61], v[28:29]
	v_pk_mul_f32 v[178:179], v[62:63], v[30:31]
	v_pk_mul_f32 v[180:181], v[56:57], v[24:25]
	v_pk_mul_f32 v[182:183], v[58:59], v[26:27]
	v_pk_add_f32 v[168:169], v[168:169], 1.0 op_sel_hi:[1,0]
	v_pk_add_f32 v[170:171], v[170:171], 1.0 op_sel_hi:[1,0]
	v_pk_add_f32 v[172:173], v[172:173], 1.0 op_sel_hi:[1,0]
	v_pk_add_f32 v[174:175], v[174:175], 1.0 op_sel_hi:[1,0]
	v_rcp_f32_e32 v168, v168
	v_rcp_f32_e32 v169, v169
	v_rcp_f32_e32 v170, v170
	v_rcp_f32_e32 v171, v171
	v_rcp_f32_e32 v172, v172
	v_rcp_f32_e32 v173, v173
	v_rcp_f32_e32 v174, v174
	v_rcp_f32_e32 v175, v175
	v_pk_mul_f32 v[176:177], v[176:177], v[206:207] op_sel_hi:[1,0]
	v_pk_mul_f32 v[178:179], v[178:179], v[206:207] op_sel_hi:[1,0]
	v_pk_mul_f32 v[180:181], v[180:181], v[206:207] op_sel_hi:[1,0]
	v_pk_mul_f32 v[182:183], v[182:183], v[206:207] op_sel_hi:[1,0]
	v_pk_mul_f32 v[176:177], v[176:177], v[168:169]
	v_pk_mul_f32 v[178:179], v[178:179], v[170:171]
	v_pk_mul_f32 v[180:181], v[180:181], v[172:173]
	v_pk_mul_f32 v[182:183], v[182:183], v[174:175]
	v_cvt_pk_bf16_f32 v160, v176, v177
	v_cvt_pk_bf16_f32 v161, v178, v179
	v_cvt_pk_bf16_f32 v162, v180, v181
	v_cvt_pk_bf16_f32 v163, v182, v183
	s_nop 1
	v_mov_b32_e32 v146, v147
	v_add_co_u32_e32 v148, vcc, s6, v150
	v_addc_co_u32_e32 v149, vcc, 0, v151, vcc
	global_store_dwordx4 v[148:149], v[160:163], off
	v_mul_f32_e32 v184, 0xbfb8aa3b, v146
	v_mul_f32_e32 v206, v146, v146
	v_pk_mul_f32 v[168:169], v[52:53], v[184:185] op_sel_hi:[1,0]
	v_pk_mul_f32 v[170:171], v[54:55], v[184:185] op_sel_hi:[1,0]
	v_pk_mul_f32 v[172:173], v[48:49], v[184:185] op_sel_hi:[1,0]
	v_pk_mul_f32 v[174:175], v[50:51], v[184:185] op_sel_hi:[1,0]
	v_exp_f32_e32 v168, v168
	v_exp_f32_e32 v169, v169
	v_exp_f32_e32 v170, v170
	v_exp_f32_e32 v171, v171
	v_exp_f32_e32 v172, v172
	v_exp_f32_e32 v173, v173
	v_exp_f32_e32 v174, v174
	v_exp_f32_e32 v175, v175
	v_pk_mul_f32 v[176:177], v[52:53], v[20:21]
	v_pk_mul_f32 v[178:179], v[54:55], v[22:23]
	v_pk_mul_f32 v[180:181], v[48:49], v[16:17]
	v_pk_mul_f32 v[182:183], v[50:51], v[18:19]
	v_pk_add_f32 v[168:169], v[168:169], 1.0 op_sel_hi:[1,0]
	v_pk_add_f32 v[170:171], v[170:171], 1.0 op_sel_hi:[1,0]
	v_pk_add_f32 v[172:173], v[172:173], 1.0 op_sel_hi:[1,0]
	v_pk_add_f32 v[174:175], v[174:175], 1.0 op_sel_hi:[1,0]
	v_rcp_f32_e32 v168, v168
	v_rcp_f32_e32 v169, v169
	v_rcp_f32_e32 v170, v170
	v_rcp_f32_e32 v171, v171
	v_rcp_f32_e32 v172, v172
	v_rcp_f32_e32 v173, v173
	v_rcp_f32_e32 v174, v174
	v_rcp_f32_e32 v175, v175
	v_pk_mul_f32 v[176:177], v[176:177], v[206:207] op_sel_hi:[1,0]
	v_pk_mul_f32 v[178:179], v[178:179], v[206:207] op_sel_hi:[1,0]
	v_pk_mul_f32 v[180:181], v[180:181], v[206:207] op_sel_hi:[1,0]
	v_pk_mul_f32 v[182:183], v[182:183], v[206:207] op_sel_hi:[1,0]
	v_pk_mul_f32 v[176:177], v[176:177], v[168:169]
	v_pk_mul_f32 v[178:179], v[178:179], v[170:171]
	v_pk_mul_f32 v[180:181], v[180:181], v[172:173]
	v_pk_mul_f32 v[182:183], v[182:183], v[174:175]
	v_cvt_pk_bf16_f32 v160, v176, v177
	v_cvt_pk_bf16_f32 v161, v178, v179
	v_cvt_pk_bf16_f32 v162, v180, v181
	v_cvt_pk_bf16_f32 v163, v182, v183
	s_mov_b32 s6, 0xc6000
	s_nop 1
	v_add_co_u32_e32 v146, vcc, s6, v150
	s_nop 0
	v_addc_co_u32_e32 v147, vcc, 0, v151, vcc
	global_store_dwordx4 v[146:147], v[160:163], off
	ds_read2_b32 v[146:147], v158 offset0:160 offset1:176
	s_mov_b32 s6, 0xdc000
	s_waitcnt lgkmcnt(0)
	v_mul_f32_e32 v184, 0xbfb8aa3b, v146
	v_mul_f32_e32 v206, v146, v146
	v_pk_mul_f32 v[168:169], v[44:45], v[184:185] op_sel_hi:[1,0]
	v_pk_mul_f32 v[170:171], v[46:47], v[184:185] op_sel_hi:[1,0]
	v_pk_mul_f32 v[172:173], v[40:41], v[184:185] op_sel_hi:[1,0]
	v_pk_mul_f32 v[174:175], v[42:43], v[184:185] op_sel_hi:[1,0]
	v_exp_f32_e32 v168, v168
	v_exp_f32_e32 v169, v169
	v_exp_f32_e32 v170, v170
	v_exp_f32_e32 v171, v171
	v_exp_f32_e32 v172, v172
	v_exp_f32_e32 v173, v173
	v_exp_f32_e32 v174, v174
	v_exp_f32_e32 v175, v175
	v_pk_mul_f32 v[176:177], v[44:45], v[12:13]
	v_pk_mul_f32 v[178:179], v[46:47], v[14:15]
	v_pk_mul_f32 v[180:181], v[40:41], v[8:9]
	v_pk_mul_f32 v[182:183], v[42:43], v[10:11]
	v_pk_add_f32 v[168:169], v[168:169], 1.0 op_sel_hi:[1,0]
	v_pk_add_f32 v[170:171], v[170:171], 1.0 op_sel_hi:[1,0]
	v_pk_add_f32 v[172:173], v[172:173], 1.0 op_sel_hi:[1,0]
	v_pk_add_f32 v[174:175], v[174:175], 1.0 op_sel_hi:[1,0]
	v_rcp_f32_e32 v168, v168
	v_rcp_f32_e32 v169, v169
	v_rcp_f32_e32 v170, v170
	v_rcp_f32_e32 v171, v171
	v_rcp_f32_e32 v172, v172
	v_rcp_f32_e32 v173, v173
	v_rcp_f32_e32 v174, v174
	v_rcp_f32_e32 v175, v175
	v_pk_mul_f32 v[176:177], v[176:177], v[206:207] op_sel_hi:[1,0]
	v_pk_mul_f32 v[178:179], v[178:179], v[206:207] op_sel_hi:[1,0]
	v_pk_mul_f32 v[180:181], v[180:181], v[206:207] op_sel_hi:[1,0]
	v_pk_mul_f32 v[182:183], v[182:183], v[206:207] op_sel_hi:[1,0]
	v_pk_mul_f32 v[176:177], v[176:177], v[168:169]
	v_pk_mul_f32 v[178:179], v[178:179], v[170:171]
	v_pk_mul_f32 v[180:181], v[180:181], v[172:173]
	v_pk_mul_f32 v[182:183], v[182:183], v[174:175]
	v_cvt_pk_bf16_f32 v158, v176, v177
	v_cvt_pk_bf16_f32 v159, v178, v179
	v_cvt_pk_bf16_f32 v160, v180, v181
	v_cvt_pk_bf16_f32 v161, v182, v183
	s_nop 1
	v_mov_b32_e32 v146, v147
	v_add_co_u32_e32 v148, vcc, s6, v150
	v_addc_co_u32_e32 v149, vcc, 0, v151, vcc
	global_store_dwordx4 v[148:149], v[158:161], off
	v_mul_f32_e32 v184, 0xbfb8aa3b, v146
	v_mul_f32_e32 v206, v146, v146
	v_pk_mul_f32 v[168:169], v[36:37], v[184:185] op_sel_hi:[1,0]
	v_pk_mul_f32 v[170:171], v[38:39], v[184:185] op_sel_hi:[1,0]
	v_pk_mul_f32 v[172:173], v[32:33], v[184:185] op_sel_hi:[1,0]
	v_pk_mul_f32 v[174:175], v[34:35], v[184:185] op_sel_hi:[1,0]
	v_exp_f32_e32 v168, v168
	v_exp_f32_e32 v169, v169
	v_exp_f32_e32 v170, v170
	v_exp_f32_e32 v171, v171
	v_exp_f32_e32 v172, v172
	v_exp_f32_e32 v173, v173
	v_exp_f32_e32 v174, v174
	v_exp_f32_e32 v175, v175
	v_pk_mul_f32 v[176:177], v[36:37], v[4:5]
	v_pk_mul_f32 v[178:179], v[38:39], v[6:7]
	v_pk_mul_f32 v[180:181], v[32:33], v[0:1]
	v_pk_mul_f32 v[182:183], v[34:35], v[2:3]
	v_pk_add_f32 v[168:169], v[168:169], 1.0 op_sel_hi:[1,0]
	v_pk_add_f32 v[170:171], v[170:171], 1.0 op_sel_hi:[1,0]
	v_pk_add_f32 v[172:173], v[172:173], 1.0 op_sel_hi:[1,0]
	v_pk_add_f32 v[174:175], v[174:175], 1.0 op_sel_hi:[1,0]
	v_rcp_f32_e32 v168, v168
	v_rcp_f32_e32 v169, v169
	v_rcp_f32_e32 v170, v170
	v_rcp_f32_e32 v171, v171
	v_rcp_f32_e32 v172, v172
	v_rcp_f32_e32 v173, v173
	v_rcp_f32_e32 v174, v174
	v_rcp_f32_e32 v175, v175
	v_pk_mul_f32 v[176:177], v[176:177], v[206:207] op_sel_hi:[1,0]
	v_pk_mul_f32 v[178:179], v[178:179], v[206:207] op_sel_hi:[1,0]
	v_pk_mul_f32 v[180:181], v[180:181], v[206:207] op_sel_hi:[1,0]
	v_pk_mul_f32 v[182:183], v[182:183], v[206:207] op_sel_hi:[1,0]
	v_pk_mul_f32 v[176:177], v[176:177], v[168:169]
	v_pk_mul_f32 v[178:179], v[178:179], v[170:171]
	v_pk_mul_f32 v[180:181], v[180:181], v[172:173]
	v_pk_mul_f32 v[182:183], v[182:183], v[174:175]
	v_cvt_pk_bf16_f32 v158, v176, v177
	v_cvt_pk_bf16_f32 v159, v178, v179
	v_cvt_pk_bf16_f32 v160, v180, v181
	v_cvt_pk_bf16_f32 v161, v182, v183
	s_nop 1
	v_add_co_u32_e32 v146, vcc, 0xf2000, v150
	s_nop 0
	v_addc_co_u32_e32 v147, vcc, 0, v151, vcc
	s_andn2_b64 vcc, exec, s[44:45]
	global_store_dwordx4 v[146:147], v[158:161], off
	s_cbranch_vccz .LBB0_73
	s_mov_b64 s[46:47], s[50:51]
	s_andn2_b64 vcc, exec, s[42:43]
	s_mov_b64 s[50:51], s[46:47]
	s_cbranch_vccnz .LBB0_74

.Lm4ap_103:
	s_waitcnt lgkmcnt(0)
	s_barrier
	v_mfma_f32_16x16x32_bf16 v[124:127], v[128:131], v[162:165], 0
	v_mfma_f32_16x16x32_bf16 v[120:123], v[136:139], v[162:165], 0
	v_mfma_f32_16x16x32_bf16 v[108:111], v[128:131], v[170:173], 0
	v_mfma_f32_16x16x32_bf16 v[104:107], v[136:139], v[170:173], 0
	v_mfma_f32_16x16x32_bf16 v[96:99], v[128:131], v[178:181], 0
	v_mfma_f32_16x16x32_bf16 v[88:91], v[136:139], v[178:181], 0
	v_mfma_f32_16x16x32_bf16 v[84:87], v[128:131], v[194:197], 0
	v_mfma_f32_16x16x32_bf16 v[80:83], v[136:139], v[194:197], 0
	v_mfma_f32_16x16x32_bf16 v[124:127], v[132:135], v[166:169], v[124:127]
	v_mfma_f32_16x16x32_bf16 v[120:123], v[146:149], v[166:169], v[120:123]
	v_mfma_f32_16x16x32_bf16 v[108:111], v[132:135], v[174:177], v[108:111]
	v_mfma_f32_16x16x32_bf16 v[104:107], v[146:149], v[174:177], v[104:107]
	v_mfma_f32_16x16x32_bf16 v[96:99], v[132:135], v[182:185], v[96:99]
	v_mfma_f32_16x16x32_bf16 v[88:91], v[146:149], v[182:185], v[88:91]
	v_mfma_f32_16x16x32_bf16 v[84:87], v[132:135], v[210:213], v[84:87]
	v_mfma_f32_16x16x32_bf16 v[80:83], v[146:149], v[210:213], v[80:83]
	v_mfma_f32_16x16x32_bf16 v[116:119], v[214:217], v[162:165], 0
	v_mfma_f32_16x16x32_bf16 v[112:115], v[222:225], v[162:165], 0
	v_mfma_f32_16x16x32_bf16 v[100:103], v[214:217], v[170:173], 0
	v_mfma_f32_16x16x32_bf16 v[92:95], v[222:225], v[170:173], 0
	v_mfma_f32_16x16x32_bf16 v[76:79], v[214:217], v[178:181], 0
	v_mfma_f32_16x16x32_bf16 v[72:75], v[222:225], v[178:181], 0
	v_mfma_f32_16x16x32_bf16 v[68:71], v[214:217], v[194:197], 0
	v_mfma_f32_16x16x32_bf16 v[64:67], v[222:225], v[194:197], 0
	v_mfma_f32_16x16x32_bf16 v[116:119], v[218:221], v[166:169], v[116:119]
	v_mfma_f32_16x16x32_bf16 v[112:115], v[226:229], v[166:169], v[112:115]
	v_mfma_f32_16x16x32_bf16 v[100:103], v[218:221], v[174:177], v[100:103]
	v_mfma_f32_16x16x32_bf16 v[92:95], v[226:229], v[174:177], v[92:95]
	v_mfma_f32_16x16x32_bf16 v[76:79], v[218:221], v[182:185], v[76:79]
	v_mfma_f32_16x16x32_bf16 v[72:75], v[226:229], v[182:185], v[72:75]
	v_mfma_f32_16x16x32_bf16 v[68:71], v[218:221], v[210:213], v[68:71]
	v_mfma_f32_16x16x32_bf16 v[64:67], v[226:229], v[210:213], v[64:67]
	s_add_i32 s19, s23, s71
	v_lshl_add_u64 v[192:193], s[58:59], 0, v[140:141]
	s_mov_b32 m0, s19
	v_lshl_add_u64 v[230:231], s[58:59], 0, v[150:151]
	s_barrier
	global_load_lds_dwordx4 v[192:193], off
	s_add_i32 m0, s19, 0x2000
	s_nop 0
	global_load_lds_dwordx4 v[230:231], off
	s_mov_b32 m0, s72
	v_lshl_add_u64 v[232:233], s[68:69], 0, v[154:155]
	ds_read_b128 v[162:165], v208 offset:16384
	ds_read_b128 v[166:169], v208 offset:17408
	ds_read_b128 v[170:173], v208 offset:18432
	ds_read_b128 v[174:177], v208 offset:19456
	ds_read_b128 v[178:181], v208 offset:20480
	ds_read_b128 v[182:185], v208 offset:21504
	ds_read_b128 v[194:197], v208 offset:22528
	ds_read_b128 v[210:213], v208 offset:23552
	global_load_lds_dwordx4 v[232:233], off
	v_lshl_add_u64 v[234:235], s[68:69], 0, v[152:153]
	s_mov_b32 m0, s73
	s_nop 0
	global_load_lds_dwordx4 v[234:235], off
	s_add_u32 s86, s58, 0x40000
	s_addc_u32 s87, s59, 0
	s_add_i32 s6, s6, s71
	v_lshl_add_u64 v[250:251], s[86:87], 0, v[140:141]
	s_mov_b32 m0, s6
	s_nop 0
	global_load_lds_dwordx4 v[250:251], off
	v_lshl_add_u64 v[250:251], s[86:87], 0, v[150:151]
	s_add_i32 m0, s6, 0x2000
	s_nop 0
	global_load_lds_dwordx4 v[250:251], off
	s_waitcnt vmcnt(40)
	s_cmp_lg_u32 s100, 0
	s_cbranch_scc1 .Lm4bp_103
	s_waitcnt vmcnt(8)
.Lm4bp_103:
	s_waitcnt lgkmcnt(0)
	s_mov_b32 s100, 0
	s_barrier
	s_nop 0
	v_mfma_f32_16x16x32_bf16 v[60:63], v[128:131], v[162:165], 0
	v_mfma_f32_16x16x32_bf16 v[56:59], v[136:139], v[162:165], 0
	v_mfma_f32_16x16x32_bf16 v[48:51], v[128:131], v[170:173], 0
	v_mfma_f32_16x16x32_bf16 v[40:43], v[136:139], v[170:173], 0
	v_mfma_f32_16x16x32_bf16 v[32:35], v[128:131], v[178:181], 0
	v_mfma_f32_16x16x32_bf16 v[24:27], v[136:139], v[178:181], 0
	v_mfma_f32_16x16x32_bf16 v[16:19], v[128:131], v[194:197], 0
	v_mfma_f32_16x16x32_bf16 v[8:11], v[136:139], v[194:197], 0
	v_mfma_f32_16x16x32_bf16 v[60:63], v[132:135], v[166:169], v[60:63]
	v_mfma_f32_16x16x32_bf16 v[56:59], v[146:149], v[166:169], v[56:59]
	v_mfma_f32_16x16x32_bf16 v[48:51], v[132:135], v[174:177], v[48:51]
	v_mfma_f32_16x16x32_bf16 v[40:43], v[146:149], v[174:177], v[40:43]
	v_mfma_f32_16x16x32_bf16 v[32:35], v[132:135], v[182:185], v[32:35]
	v_mfma_f32_16x16x32_bf16 v[24:27], v[146:149], v[182:185], v[24:27]
	v_mfma_f32_16x16x32_bf16 v[16:19], v[132:135], v[210:213], v[16:19]
	v_mfma_f32_16x16x32_bf16 v[8:11], v[146:149], v[210:213], v[8:11]
	v_mfma_f32_16x16x32_bf16 v[52:55], v[214:217], v[162:165], 0
	v_mfma_f32_16x16x32_bf16 v[44:47], v[222:225], v[162:165], 0
	v_mfma_f32_16x16x32_bf16 v[36:39], v[214:217], v[170:173], 0
	v_mfma_f32_16x16x32_bf16 v[28:31], v[222:225], v[170:173], 0
	v_mfma_f32_16x16x32_bf16 v[20:23], v[214:217], v[178:181], 0
	v_mfma_f32_16x16x32_bf16 v[12:15], v[222:225], v[178:181], 0
	v_mfma_f32_16x16x32_bf16 v[4:7], v[214:217], v[194:197], 0
	v_mfma_f32_16x16x32_bf16 v[0:3], v[222:225], v[194:197], 0
	v_mfma_f32_16x16x32_bf16 v[52:55], v[218:221], v[166:169], v[52:55]
	v_mfma_f32_16x16x32_bf16 v[44:47], v[226:229], v[166:169], v[44:47]
	v_mfma_f32_16x16x32_bf16 v[36:39], v[218:221], v[174:177], v[36:39]
	v_mfma_f32_16x16x32_bf16 v[28:31], v[226:229], v[174:177], v[28:31]
	v_mfma_f32_16x16x32_bf16 v[20:23], v[218:221], v[182:185], v[20:23]
	v_mfma_f32_16x16x32_bf16 v[12:15], v[226:229], v[182:185], v[12:15]
	v_mfma_f32_16x16x32_bf16 v[4:7], v[218:221], v[210:213], v[4:7]
	v_mfma_f32_16x16x32_bf16 v[0:3], v[226:229], v[210:213], v[0:3]
	s_add_i32 s6, 0, 0x18000
	s_barrier
	v_add_u32_e32 v146, s6, v206
	ds_read_b128 v[128:131], v146
	ds_read_b128 v[132:135], v146 offset:1024
	ds_read_b128 v[136:139], v146 offset:2048
	ds_read_b128 v[146:149], v146 offset:3072
	s_add_u32 s68, s68, 0x40000
	s_addc_u32 s69, s69, 0
	s_mov_b32 m0, s74
	v_lshl_add_u64 v[214:215], s[68:69], 0, v[154:155]
	ds_read_b128 v[162:165], v208 offset:32768
	ds_read_b128 v[166:169], v208 offset:33792
	ds_read_b128 v[170:173], v208 offset:34816
	ds_read_b128 v[174:177], v208 offset:35840
	ds_read_b128 v[178:181], v208 offset:36864
	ds_read_b128 v[182:185], v208 offset:37888
	ds_read_b128 v[194:197], v208 offset:38912
	ds_read_b128 v[210:213], v208 offset:39936
	global_load_lds_dwordx4 v[214:215], off
	v_lshl_add_u64 v[214:215], s[68:69], 0, v[152:153]
	s_mov_b32 m0, s75
	s_nop 0
	global_load_lds_dwordx4 v[214:215], off
	s_add_i32 s19, 0, 0x1c000
	v_add_u32_e32 v209, s19, v206
	ds_read_b128 v[214:217], v209
	ds_read_b128 v[218:221], v209 offset:1024
	ds_read_b128 v[222:225], v209 offset:2048
	ds_read_b128 v[226:229], v209 offset:3072
	s_waitcnt vmcnt(8)
	s_waitcnt lgkmcnt(0)
	s_barrier
	v_mfma_f32_16x16x32_bf16 v[124:127], v[128:131], v[162:165], v[124:127]
	v_mfma_f32_16x16x32_bf16 v[120:123], v[136:139], v[162:165], v[120:123]
	v_mfma_f32_16x16x32_bf16 v[108:111], v[128:131], v[170:173], v[108:111]
	v_mfma_f32_16x16x32_bf16 v[104:107], v[136:139], v[170:173], v[104:107]
	v_mfma_f32_16x16x32_bf16 v[96:99], v[128:131], v[178:181], v[96:99]
	v_mfma_f32_16x16x32_bf16 v[88:91], v[136:139], v[178:181], v[88:91]
	v_mfma_f32_16x16x32_bf16 v[84:87], v[128:131], v[194:197], v[84:87]
	v_mfma_f32_16x16x32_bf16 v[80:83], v[136:139], v[194:197], v[80:83]
	v_mfma_f32_16x16x32_bf16 v[124:127], v[132:135], v[166:169], v[124:127]
	v_mfma_f32_16x16x32_bf16 v[120:123], v[146:149], v[166:169], v[120:123]
	v_mfma_f32_16x16x32_bf16 v[108:111], v[132:135], v[174:177], v[108:111]
	v_mfma_f32_16x16x32_bf16 v[104:107], v[146:149], v[174:177], v[104:107]
	v_mfma_f32_16x16x32_bf16 v[96:99], v[132:135], v[182:185], v[96:99]
	v_mfma_f32_16x16x32_bf16 v[88:91], v[146:149], v[182:185], v[88:91]
	v_mfma_f32_16x16x32_bf16 v[84:87], v[132:135], v[210:213], v[84:87]
	v_mfma_f32_16x16x32_bf16 v[80:83], v[146:149], v[210:213], v[80:83]
	v_mfma_f32_16x16x32_bf16 v[116:119], v[214:217], v[162:165], v[116:119]
	v_mfma_f32_16x16x32_bf16 v[112:115], v[222:225], v[162:165], v[112:115]
	v_mfma_f32_16x16x32_bf16 v[100:103], v[214:217], v[170:173], v[100:103]
	v_mfma_f32_16x16x32_bf16 v[92:95], v[222:225], v[170:173], v[92:95]
	v_mfma_f32_16x16x32_bf16 v[76:79], v[214:217], v[178:181], v[76:79]
	v_mfma_f32_16x16x32_bf16 v[72:75], v[222:225], v[178:181], v[72:75]
	v_mfma_f32_16x16x32_bf16 v[68:71], v[214:217], v[194:197], v[68:71]
	v_mfma_f32_16x16x32_bf16 v[64:67], v[222:225], v[194:197], v[64:67]
	v_mfma_f32_16x16x32_bf16 v[116:119], v[218:221], v[166:169], v[116:119]
	v_mfma_f32_16x16x32_bf16 v[112:115], v[226:229], v[166:169], v[112:115]
	v_mfma_f32_16x16x32_bf16 v[100:103], v[218:221], v[174:177], v[100:103]
	v_mfma_f32_16x16x32_bf16 v[92:95], v[226:229], v[174:177], v[92:95]
	v_mfma_f32_16x16x32_bf16 v[76:79], v[218:221], v[182:185], v[76:79]
	v_mfma_f32_16x16x32_bf16 v[72:75], v[226:229], v[182:185], v[72:75]
	v_mfma_f32_16x16x32_bf16 v[68:71], v[218:221], v[210:213], v[68:71]
	v_mfma_f32_16x16x32_bf16 v[64:67], v[226:229], v[210:213], v[64:67]
	s_add_i32 s6, s6, s71
	v_lshl_add_u64 v[192:193], v[192:193], 0, s[36:37]
	s_mov_b32 m0, s6
	s_barrier
	s_nop 0
	global_load_lds_dwordx4 v[192:193], off
	v_lshl_add_u64 v[192:193], v[230:231], 0, s[36:37]
	s_add_i32 m0, s6, 0x2000
	s_nop 0
	global_load_lds_dwordx4 v[192:193], off
	s_mov_b32 m0, s80
	v_lshl_add_u64 v[192:193], v[232:233], 0, s[36:37]
	ds_read_b128 v[162:165], v208 offset:49152
	ds_read_b128 v[166:169], v208 offset:50176
	ds_read_b128 v[170:173], v208 offset:51200
	ds_read_b128 v[174:177], v208 offset:52224
	ds_read_b128 v[178:181], v208 offset:53248
	ds_read_b128 v[182:185], v208 offset:54272
	ds_read_b128 v[194:197], v208 offset:55296
	ds_read_b128 v[210:213], v208 offset:56320
	global_load_lds_dwordx4 v[192:193], off
	v_lshl_add_u64 v[192:193], v[234:235], 0, s[36:37]
	s_mov_b32 m0, s81
	s_nop 0
	global_load_lds_dwordx4 v[192:193], off
	s_add_u32 s58, s58, 0x40080
	s_addc_u32 s59, s59, 0
	s_add_i32 s6, s19, s71
	v_lshl_add_u64 v[250:251], s[58:59], 0, v[140:141]
	s_mov_b32 m0, s6
	s_nop 0
	global_load_lds_dwordx4 v[250:251], off
	v_lshl_add_u64 v[250:251], s[58:59], 0, v[150:151]
	s_add_i32 m0, s6, 0x2000
	s_nop 0
	global_load_lds_dwordx4 v[250:251], off
	s_waitcnt vmcnt(8)
	s_waitcnt lgkmcnt(0)
	s_barrier
	v_mfma_f32_16x16x32_bf16 v[60:63], v[128:131], v[162:165], v[60:63]
	v_mfma_f32_16x16x32_bf16 v[56:59], v[136:139], v[162:165], v[56:59]
	v_mfma_f32_16x16x32_bf16 v[48:51], v[128:131], v[170:173], v[48:51]
	v_mfma_f32_16x16x32_bf16 v[40:43], v[136:139], v[170:173], v[40:43]
	v_mfma_f32_16x16x32_bf16 v[32:35], v[128:131], v[178:181], v[32:35]
	v_mfma_f32_16x16x32_bf16 v[24:27], v[136:139], v[178:181], v[24:27]
	v_mfma_f32_16x16x32_bf16 v[16:19], v[128:131], v[194:197], v[16:19]
	v_mfma_f32_16x16x32_bf16 v[8:11], v[136:139], v[194:197], v[8:11]
	v_mfma_f32_16x16x32_bf16 v[60:63], v[132:135], v[166:169], v[60:63]
	v_mfma_f32_16x16x32_bf16 v[56:59], v[146:149], v[166:169], v[56:59]
	v_mfma_f32_16x16x32_bf16 v[48:51], v[132:135], v[174:177], v[48:51]
	v_mfma_f32_16x16x32_bf16 v[40:43], v[146:149], v[174:177], v[40:43]
	v_mfma_f32_16x16x32_bf16 v[32:35], v[132:135], v[182:185], v[32:35]
	v_mfma_f32_16x16x32_bf16 v[24:27], v[146:149], v[182:185], v[24:27]
	v_mfma_f32_16x16x32_bf16 v[16:19], v[132:135], v[210:213], v[16:19]
	v_mfma_f32_16x16x32_bf16 v[8:11], v[146:149], v[210:213], v[8:11]
	v_mfma_f32_16x16x32_bf16 v[52:55], v[214:217], v[162:165], v[52:55]
	v_mfma_f32_16x16x32_bf16 v[44:47], v[222:225], v[162:165], v[44:47]
	v_mfma_f32_16x16x32_bf16 v[36:39], v[214:217], v[170:173], v[36:39]
	v_mfma_f32_16x16x32_bf16 v[28:31], v[222:225], v[170:173], v[28:31]
	v_mfma_f32_16x16x32_bf16 v[20:23], v[214:217], v[178:181], v[20:23]
	v_mfma_f32_16x16x32_bf16 v[12:15], v[222:225], v[178:181], v[12:15]
	v_mfma_f32_16x16x32_bf16 v[4:7], v[214:217], v[194:197], v[4:7]
	v_mfma_f32_16x16x32_bf16 v[0:3], v[222:225], v[194:197], v[0:3]
	v_mfma_f32_16x16x32_bf16 v[52:55], v[218:221], v[166:169], v[52:55]
	v_mfma_f32_16x16x32_bf16 v[44:47], v[226:229], v[166:169], v[44:47]
	v_mfma_f32_16x16x32_bf16 v[36:39], v[218:221], v[174:177], v[36:39]
	v_mfma_f32_16x16x32_bf16 v[28:31], v[226:229], v[174:177], v[28:31]
	v_mfma_f32_16x16x32_bf16 v[20:23], v[218:221], v[182:185], v[20:23]
	v_mfma_f32_16x16x32_bf16 v[12:15], v[226:229], v[182:185], v[12:15]
	v_mfma_f32_16x16x32_bf16 v[4:7], v[218:221], v[210:213], v[4:7]
	v_mfma_f32_16x16x32_bf16 v[0:3], v[226:229], v[210:213], v[0:3]
	s_add_i32 s12, s12, 2
	s_add_u32 s54, s54, 0x100
	s_addc_u32 s55, s55, 0
	s_add_u32 s10, s10, 0x100
	s_addc_u32 s11, s11, 0
	s_cmp_gt_u32 s12, 13
	s_add_u32 s6, s54, 0xfffc0080
	s_addc_u32 s19, s55, -1
	s_add_i32 s23, 0, 0x10000
	s_cmp_eq_u32 s12, 12
	s_cselect_b32 s69, s47, s19
	s_cselect_b32 s68, s46, s6
	s_cselect_b32 s59, s49, s11
	s_cselect_b32 s58, s48, s10
my_head_103:
	s_barrier
.LBB0_103:
	v_add_u32_e32 v146, s23, v206
	ds_read_b128 v[128:131], v146
	ds_read_b128 v[132:135], v146 offset:1024
	ds_read_b128 v[136:139], v146 offset:2048
	ds_read_b128 v[146:149], v146 offset:3072
	v_lshl_add_u64 v[192:193], s[54:55], 0, v[158:159]
	s_add_i32 m0, s72, 0xc000
	ds_read_b128 v[162:165], v208
	ds_read_b128 v[166:169], v208 offset:1024
	ds_read_b128 v[170:173], v208 offset:2048
	ds_read_b128 v[174:177], v208 offset:3072
	ds_read_b128 v[178:181], v208 offset:4096
	ds_read_b128 v[182:185], v208 offset:5120
	ds_read_b128 v[194:197], v208 offset:6144
	ds_read_b128 v[210:213], v208 offset:7168
	global_load_lds_dwordx4 v[192:193], off
	v_lshl_add_u64 v[192:193], s[54:55], 0, v[160:161]
	s_add_i32 m0, s72, 0xe000
	s_nop 0
	global_load_lds_dwordx4 v[192:193], off
	s_add_i32 s6, 0, 0x14000
	v_add_u32_e32 v192, s6, v206
	ds_read_b128 v[214:217], v192
	ds_read_b128 v[218:221], v192 offset:1024
	ds_read_b128 v[222:225], v192 offset:2048
	ds_read_b128 v[226:229], v192 offset:3072
	s_nop 0
	s_waitcnt vmcnt(8)
	s_waitcnt lgkmcnt(0)
	s_barrier
	v_mfma_f32_16x16x32_bf16 v[124:127], v[128:131], v[162:165], v[124:127]
	v_mfma_f32_16x16x32_bf16 v[120:123], v[136:139], v[162:165], v[120:123]
	v_mfma_f32_16x16x32_bf16 v[108:111], v[128:131], v[170:173], v[108:111]
	v_mfma_f32_16x16x32_bf16 v[104:107], v[136:139], v[170:173], v[104:107]
	v_mfma_f32_16x16x32_bf16 v[96:99], v[128:131], v[178:181], v[96:99]
	v_mfma_f32_16x16x32_bf16 v[88:91], v[136:139], v[178:181], v[88:91]
	v_mfma_f32_16x16x32_bf16 v[84:87], v[128:131], v[194:197], v[84:87]
	v_mfma_f32_16x16x32_bf16 v[80:83], v[136:139], v[194:197], v[80:83]
	v_mfma_f32_16x16x32_bf16 v[124:127], v[132:135], v[166:169], v[124:127]
	v_mfma_f32_16x16x32_bf16 v[120:123], v[146:149], v[166:169], v[120:123]
	v_mfma_f32_16x16x32_bf16 v[108:111], v[132:135], v[174:177], v[108:111]
	v_mfma_f32_16x16x32_bf16 v[104:107], v[146:149], v[174:177], v[104:107]
	v_mfma_f32_16x16x32_bf16 v[96:99], v[132:135], v[182:185], v[96:99]
	v_mfma_f32_16x16x32_bf16 v[88:91], v[146:149], v[182:185], v[88:91]
	v_mfma_f32_16x16x32_bf16 v[84:87], v[132:135], v[210:213], v[84:87]
	v_mfma_f32_16x16x32_bf16 v[80:83], v[146:149], v[210:213], v[80:83]
	v_mfma_f32_16x16x32_bf16 v[116:119], v[214:217], v[162:165], v[116:119]
	v_mfma_f32_16x16x32_bf16 v[112:115], v[222:225], v[162:165], v[112:115]
	v_mfma_f32_16x16x32_bf16 v[100:103], v[214:217], v[170:173], v[100:103]
	v_mfma_f32_16x16x32_bf16 v[92:95], v[222:225], v[170:173], v[92:95]
	v_mfma_f32_16x16x32_bf16 v[76:79], v[214:217], v[178:181], v[76:79]
	v_mfma_f32_16x16x32_bf16 v[72:75], v[222:225], v[178:181], v[72:75]
	v_mfma_f32_16x16x32_bf16 v[68:71], v[214:217], v[194:197], v[68:71]
	v_mfma_f32_16x16x32_bf16 v[64:67], v[222:225], v[194:197], v[64:67]
	v_mfma_f32_16x16x32_bf16 v[116:119], v[218:221], v[166:169], v[116:119]
	v_mfma_f32_16x16x32_bf16 v[112:115], v[226:229], v[166:169], v[112:115]
	v_mfma_f32_16x16x32_bf16 v[100:103], v[218:221], v[174:177], v[100:103]
	v_mfma_f32_16x16x32_bf16 v[92:95], v[226:229], v[174:177], v[92:95]
	v_mfma_f32_16x16x32_bf16 v[76:79], v[218:221], v[182:185], v[76:79]
	v_mfma_f32_16x16x32_bf16 v[72:75], v[226:229], v[182:185], v[72:75]
	v_mfma_f32_16x16x32_bf16 v[68:71], v[218:221], v[210:213], v[68:71]
	v_mfma_f32_16x16x32_bf16 v[64:67], v[226:229], v[210:213], v[64:67]
	s_add_i32 s19, s23, s71
	v_lshl_add_u64 v[192:193], s[58:59], 0, v[140:141]
	s_mov_b32 m0, s19
	v_lshl_add_u64 v[230:231], s[58:59], 0, v[150:151]
	s_barrier
	global_load_lds_dwordx4 v[192:193], off
	s_add_i32 m0, s19, 0x2000
	s_nop 0
	global_load_lds_dwordx4 v[230:231], off
	s_mov_b32 m0, s72
	v_lshl_add_u64 v[232:233], s[68:69], 0, v[154:155]
	ds_read_b128 v[162:165], v208 offset:16384
	ds_read_b128 v[166:169], v208 offset:17408
	ds_read_b128 v[170:173], v208 offset:18432
	ds_read_b128 v[174:177], v208 offset:19456
	ds_read_b128 v[178:181], v208 offset:20480
	ds_read_b128 v[182:185], v208 offset:21504
	ds_read_b128 v[194:197], v208 offset:22528
	ds_read_b128 v[210:213], v208 offset:23552
	global_load_lds_dwordx4 v[232:233], off
	v_lshl_add_u64 v[234:235], s[68:69], 0, v[152:153]
	s_mov_b32 m0, s73
	s_nop 0
	global_load_lds_dwordx4 v[234:235], off
	s_add_u32 s86, s58, 0x40000
	s_addc_u32 s87, s59, 0
	s_add_i32 s6, s6, s71
	v_lshl_add_u64 v[250:251], s[86:87], 0, v[140:141]
	s_mov_b32 m0, s6
	s_nop 0
	global_load_lds_dwordx4 v[250:251], off
	v_lshl_add_u64 v[250:251], s[86:87], 0, v[150:151]
	s_add_i32 m0, s6, 0x2000
	s_nop 0
	global_load_lds_dwordx4 v[250:251], off
	s_nop 0
	s_waitcnt vmcnt(8)
	s_waitcnt lgkmcnt(0)
	s_barrier
	v_mfma_f32_16x16x32_bf16 v[60:63], v[128:131], v[162:165], v[60:63]
	v_mfma_f32_16x16x32_bf16 v[56:59], v[136:139], v[162:165], v[56:59]
	v_mfma_f32_16x16x32_bf16 v[48:51], v[128:131], v[170:173], v[48:51]
	v_mfma_f32_16x16x32_bf16 v[40:43], v[136:139], v[170:173], v[40:43]
	v_mfma_f32_16x16x32_bf16 v[32:35], v[128:131], v[178:181], v[32:35]
	v_mfma_f32_16x16x32_bf16 v[24:27], v[136:139], v[178:181], v[24:27]
	v_mfma_f32_16x16x32_bf16 v[16:19], v[128:131], v[194:197], v[16:19]
	v_mfma_f32_16x16x32_bf16 v[8:11], v[136:139], v[194:197], v[8:11]
	v_mfma_f32_16x16x32_bf16 v[60:63], v[132:135], v[166:169], v[60:63]
	v_mfma_f32_16x16x32_bf16 v[56:59], v[146:149], v[166:169], v[56:59]
	v_mfma_f32_16x16x32_bf16 v[48:51], v[132:135], v[174:177], v[48:51]
	v_mfma_f32_16x16x32_bf16 v[40:43], v[146:149], v[174:177], v[40:43]
	v_mfma_f32_16x16x32_bf16 v[32:35], v[132:135], v[182:185], v[32:35]
	v_mfma_f32_16x16x32_bf16 v[24:27], v[146:149], v[182:185], v[24:27]
	v_mfma_f32_16x16x32_bf16 v[16:19], v[132:135], v[210:213], v[16:19]
	v_mfma_f32_16x16x32_bf16 v[8:11], v[146:149], v[210:213], v[8:11]
	v_mfma_f32_16x16x32_bf16 v[52:55], v[214:217], v[162:165], v[52:55]
	v_mfma_f32_16x16x32_bf16 v[44:47], v[222:225], v[162:165], v[44:47]
	v_mfma_f32_16x16x32_bf16 v[36:39], v[214:217], v[170:173], v[36:39]
	v_mfma_f32_16x16x32_bf16 v[28:31], v[222:225], v[170:173], v[28:31]
	v_mfma_f32_16x16x32_bf16 v[20:23], v[214:217], v[178:181], v[20:23]
	v_mfma_f32_16x16x32_bf16 v[12:15], v[222:225], v[178:181], v[12:15]
	v_mfma_f32_16x16x32_bf16 v[4:7], v[214:217], v[194:197], v[4:7]
	v_mfma_f32_16x16x32_bf16 v[0:3], v[222:225], v[194:197], v[0:3]
	v_mfma_f32_16x16x32_bf16 v[52:55], v[218:221], v[166:169], v[52:55]
	v_mfma_f32_16x16x32_bf16 v[44:47], v[226:229], v[166:169], v[44:47]
	v_mfma_f32_16x16x32_bf16 v[36:39], v[218:221], v[174:177], v[36:39]
	v_mfma_f32_16x16x32_bf16 v[28:31], v[226:229], v[174:177], v[28:31]
	v_mfma_f32_16x16x32_bf16 v[20:23], v[218:221], v[182:185], v[20:23]
	v_mfma_f32_16x16x32_bf16 v[12:15], v[226:229], v[182:185], v[12:15]
	v_mfma_f32_16x16x32_bf16 v[4:7], v[218:221], v[210:213], v[4:7]
	v_mfma_f32_16x16x32_bf16 v[0:3], v[226:229], v[210:213], v[0:3]
	s_add_i32 s6, 0, 0x18000
	s_barrier
	v_add_u32_e32 v146, s6, v206
	ds_read_b128 v[128:131], v146
	ds_read_b128 v[132:135], v146 offset:1024
	ds_read_b128 v[136:139], v146 offset:2048
	ds_read_b128 v[146:149], v146 offset:3072
	s_add_u32 s68, s68, 0x40000
	s_addc_u32 s69, s69, 0
	s_mov_b32 m0, s74
	v_lshl_add_u64 v[214:215], s[68:69], 0, v[154:155]
	ds_read_b128 v[162:165], v208 offset:32768
	ds_read_b128 v[166:169], v208 offset:33792
	ds_read_b128 v[170:173], v208 offset:34816
	ds_read_b128 v[174:177], v208 offset:35840
	ds_read_b128 v[178:181], v208 offset:36864
	ds_read_b128 v[182:185], v208 offset:37888
	ds_read_b128 v[194:197], v208 offset:38912
	ds_read_b128 v[210:213], v208 offset:39936
	global_load_lds_dwordx4 v[214:215], off
	v_lshl_add_u64 v[214:215], s[68:69], 0, v[152:153]
	s_mov_b32 m0, s75
	s_nop 0
	global_load_lds_dwordx4 v[214:215], off
	s_add_i32 s19, 0, 0x1c000
	v_add_u32_e32 v209, s19, v206
	ds_read_b128 v[214:217], v209
	ds_read_b128 v[218:221], v209 offset:1024
	ds_read_b128 v[222:225], v209 offset:2048
	ds_read_b128 v[226:229], v209 offset:3072
	s_waitcnt vmcnt(8)
	s_waitcnt lgkmcnt(0)
	s_barrier
	v_mfma_f32_16x16x32_bf16 v[124:127], v[128:131], v[162:165], v[124:127]
	v_mfma_f32_16x16x32_bf16 v[120:123], v[136:139], v[162:165], v[120:123]
	v_mfma_f32_16x16x32_bf16 v[108:111], v[128:131], v[170:173], v[108:111]
	v_mfma_f32_16x16x32_bf16 v[104:107], v[136:139], v[170:173], v[104:107]
	v_mfma_f32_16x16x32_bf16 v[96:99], v[128:131], v[178:181], v[96:99]
	v_mfma_f32_16x16x32_bf16 v[88:91], v[136:139], v[178:181], v[88:91]
	v_mfma_f32_16x16x32_bf16 v[84:87], v[128:131], v[194:197], v[84:87]
	v_mfma_f32_16x16x32_bf16 v[80:83], v[136:139], v[194:197], v[80:83]
	v_mfma_f32_16x16x32_bf16 v[124:127], v[132:135], v[166:169], v[124:127]
	v_mfma_f32_16x16x32_bf16 v[120:123], v[146:149], v[166:169], v[120:123]
	v_mfma_f32_16x16x32_bf16 v[108:111], v[132:135], v[174:177], v[108:111]
	v_mfma_f32_16x16x32_bf16 v[104:107], v[146:149], v[174:177], v[104:107]
	v_mfma_f32_16x16x32_bf16 v[96:99], v[132:135], v[182:185], v[96:99]
	v_mfma_f32_16x16x32_bf16 v[88:91], v[146:149], v[182:185], v[88:91]
	v_mfma_f32_16x16x32_bf16 v[84:87], v[132:135], v[210:213], v[84:87]
	v_mfma_f32_16x16x32_bf16 v[80:83], v[146:149], v[210:213], v[80:83]
	v_mfma_f32_16x16x32_bf16 v[116:119], v[214:217], v[162:165], v[116:119]
	v_mfma_f32_16x16x32_bf16 v[112:115], v[222:225], v[162:165], v[112:115]
	v_mfma_f32_16x16x32_bf16 v[100:103], v[214:217], v[170:173], v[100:103]
	v_mfma_f32_16x16x32_bf16 v[92:95], v[222:225], v[170:173], v[92:95]
	v_mfma_f32_16x16x32_bf16 v[76:79], v[214:217], v[178:181], v[76:79]
	v_mfma_f32_16x16x32_bf16 v[72:75], v[222:225], v[178:181], v[72:75]
	v_mfma_f32_16x16x32_bf16 v[68:71], v[214:217], v[194:197], v[68:71]
	v_mfma_f32_16x16x32_bf16 v[64:67], v[222:225], v[194:197], v[64:67]
	v_mfma_f32_16x16x32_bf16 v[116:119], v[218:221], v[166:169], v[116:119]
	v_mfma_f32_16x16x32_bf16 v[112:115], v[226:229], v[166:169], v[112:115]
	v_mfma_f32_16x16x32_bf16 v[100:103], v[218:221], v[174:177], v[100:103]
	v_mfma_f32_16x16x32_bf16 v[92:95], v[226:229], v[174:177], v[92:95]
	v_mfma_f32_16x16x32_bf16 v[76:79], v[218:221], v[182:185], v[76:79]
	v_mfma_f32_16x16x32_bf16 v[72:75], v[226:229], v[182:185], v[72:75]
	v_mfma_f32_16x16x32_bf16 v[68:71], v[218:221], v[210:213], v[68:71]
	v_mfma_f32_16x16x32_bf16 v[64:67], v[226:229], v[210:213], v[64:67]
	s_add_i32 s6, s6, s71
	v_lshl_add_u64 v[192:193], v[192:193], 0, s[36:37]
	s_mov_b32 m0, s6
	s_barrier
	s_nop 0
	global_load_lds_dwordx4 v[192:193], off
	v_lshl_add_u64 v[192:193], v[230:231], 0, s[36:37]
	s_add_i32 m0, s6, 0x2000
	s_nop 0
	global_load_lds_dwordx4 v[192:193], off
	s_mov_b32 m0, s80
	v_lshl_add_u64 v[192:193], v[232:233], 0, s[36:37]
	ds_read_b128 v[162:165], v208 offset:49152
	ds_read_b128 v[166:169], v208 offset:50176
	ds_read_b128 v[170:173], v208 offset:51200
	ds_read_b128 v[174:177], v208 offset:52224
	ds_read_b128 v[178:181], v208 offset:53248
	ds_read_b128 v[182:185], v208 offset:54272
	ds_read_b128 v[194:197], v208 offset:55296
	ds_read_b128 v[210:213], v208 offset:56320
	global_load_lds_dwordx4 v[192:193], off
	v_lshl_add_u64 v[192:193], v[234:235], 0, s[36:37]
	s_mov_b32 m0, s81
	s_nop 0
	global_load_lds_dwordx4 v[192:193], off
	s_add_u32 s58, s58, 0x40080
	s_addc_u32 s59, s59, 0
	s_add_i32 s6, s19, s71
	v_lshl_add_u64 v[250:251], s[58:59], 0, v[140:141]
	s_mov_b32 m0, s6
	s_nop 0
	global_load_lds_dwordx4 v[250:251], off
	v_lshl_add_u64 v[250:251], s[58:59], 0, v[150:151]
	s_add_i32 m0, s6, 0x2000
	s_nop 0
	global_load_lds_dwordx4 v[250:251], off
	s_waitcnt vmcnt(8)
	s_waitcnt lgkmcnt(0)
	s_barrier
	v_mfma_f32_16x16x32_bf16 v[60:63], v[128:131], v[162:165], v[60:63]
	v_mfma_f32_16x16x32_bf16 v[56:59], v[136:139], v[162:165], v[56:59]
	v_mfma_f32_16x16x32_bf16 v[48:51], v[128:131], v[170:173], v[48:51]
	v_mfma_f32_16x16x32_bf16 v[40:43], v[136:139], v[170:173], v[40:43]
	v_mfma_f32_16x16x32_bf16 v[32:35], v[128:131], v[178:181], v[32:35]
	v_mfma_f32_16x16x32_bf16 v[24:27], v[136:139], v[178:181], v[24:27]
	v_mfma_f32_16x16x32_bf16 v[16:19], v[128:131], v[194:197], v[16:19]
	v_mfma_f32_16x16x32_bf16 v[8:11], v[136:139], v[194:197], v[8:11]
	v_mfma_f32_16x16x32_bf16 v[60:63], v[132:135], v[166:169], v[60:63]
	v_mfma_f32_16x16x32_bf16 v[56:59], v[146:149], v[166:169], v[56:59]
	v_mfma_f32_16x16x32_bf16 v[48:51], v[132:135], v[174:177], v[48:51]
	v_mfma_f32_16x16x32_bf16 v[40:43], v[146:149], v[174:177], v[40:43]
	v_mfma_f32_16x16x32_bf16 v[32:35], v[132:135], v[182:185], v[32:35]
	v_mfma_f32_16x16x32_bf16 v[24:27], v[146:149], v[182:185], v[24:27]
	v_mfma_f32_16x16x32_bf16 v[16:19], v[132:135], v[210:213], v[16:19]
	v_mfma_f32_16x16x32_bf16 v[8:11], v[146:149], v[210:213], v[8:11]
	v_mfma_f32_16x16x32_bf16 v[52:55], v[214:217], v[162:165], v[52:55]
	v_mfma_f32_16x16x32_bf16 v[44:47], v[222:225], v[162:165], v[44:47]
	v_mfma_f32_16x16x32_bf16 v[36:39], v[214:217], v[170:173], v[36:39]
	v_mfma_f32_16x16x32_bf16 v[28:31], v[222:225], v[170:173], v[28:31]
	v_mfma_f32_16x16x32_bf16 v[20:23], v[214:217], v[178:181], v[20:23]
	v_mfma_f32_16x16x32_bf16 v[12:15], v[222:225], v[178:181], v[12:15]
	v_mfma_f32_16x16x32_bf16 v[4:7], v[214:217], v[194:197], v[4:7]
	v_mfma_f32_16x16x32_bf16 v[0:3], v[222:225], v[194:197], v[0:3]
	v_mfma_f32_16x16x32_bf16 v[52:55], v[218:221], v[166:169], v[52:55]
	v_mfma_f32_16x16x32_bf16 v[44:47], v[226:229], v[166:169], v[44:47]
	v_mfma_f32_16x16x32_bf16 v[36:39], v[218:221], v[174:177], v[36:39]
	v_mfma_f32_16x16x32_bf16 v[28:31], v[226:229], v[174:177], v[28:31]
	v_mfma_f32_16x16x32_bf16 v[20:23], v[218:221], v[182:185], v[20:23]
	v_mfma_f32_16x16x32_bf16 v[12:15], v[226:229], v[182:185], v[12:15]
	v_mfma_f32_16x16x32_bf16 v[4:7], v[218:221], v[210:213], v[4:7]
	v_mfma_f32_16x16x32_bf16 v[0:3], v[226:229], v[210:213], v[0:3]
	s_add_i32 s12, s12, 2
	s_add_u32 s54, s54, 0x100
	s_addc_u32 s55, s55, 0
	s_add_u32 s10, s10, 0x100
	s_addc_u32 s11, s11, 0
	s_cmp_gt_u32 s12, 13
	s_cbranch_scc1 my_exit_103
	s_add_u32 s6, s54, 0xfffc0080
	s_addc_u32 s19, s55, -1
	s_add_i32 s23, 0, 0x10000
	s_cmp_eq_u32 s12, 12
	s_cselect_b32 s69, s47, s19
	s_cselect_b32 s68, s46, s6
	s_cselect_b32 s59, s49, s11
	s_cselect_b32 s58, s48, s10
	s_branch my_head_103
my_exit_103:
	s_barrier
	s_mov_b32 s100, 1
	s_ashr_i32 s51, s50, 31
	s_ashr_i32 s53, s52, 31
	s_lshl_b64 s[10:11], s[50:51], 13
	s_lshl_b64 s[50:51], s[52:53], 8
	s_add_u32 s10, s50, s10
	v_lshl_or_b32 v128, s85, 8, v207
	s_addc_u32 s11, s51, s11
	v_ashrrev_i32_e32 v129, 31, v128
	v_lshl_add_u64 v[168:169], s[10:11], 0, v[156:157]
	v_lshlrev_b64 v[170:171], 1, v[128:129]
	v_lshl_add_u64 v[174:175], s[26:27], 0, v[170:171]
	v_lshlrev_b64 v[172:173], 11, v[168:169]
	v_or_b32_e32 v166, 16, v168
	v_mov_b32_e32 v167, v169
	v_lshl_add_u64 v[128:129], v[174:175], 0, v[172:173]
	v_lshlrev_b64 v[176:177], 11, v[166:167]
	global_load_dwordx4 v[146:149], v[128:129], off
	global_load_dwordx4 v[182:185], v[128:129], off offset:256
	v_lshl_add_u64 v[128:129], v[174:175], 0, v[176:177]
	global_load_dwordx4 v[194:197], v[128:129], off
	global_load_dwordx4 v[210:213], v[128:129], off offset:256
	v_or_b32_e32 v164, 32, v168
	v_mov_b32_e32 v165, v169
	v_or_b32_e32 v162, 48, v168
	v_mov_b32_e32 v163, v169
	v_lshlrev_b64 v[180:181], 11, v[164:165]
	v_lshlrev_b64 v[178:179], 11, v[162:163]
	v_lshl_add_u64 v[128:129], v[174:175], 0, v[180:181]
	v_lshl_add_u64 v[130:131], v[174:175], 0, v[178:179]
	global_load_dwordx4 v[214:217], v[128:129], off
	global_load_dwordx4 v[136:139], v[128:129], off offset:256
	global_load_dwordx4 v[132:135], v[130:131], off
	s_nop 0
	global_load_dwordx4 v[128:131], v[130:131], off offset:256
	s_mov_b64 s[10:11], 0x90
	v_lshl_add_u64 v[172:173], s[28:29], 0, v[172:173]
	v_lshl_add_u64 v[172:173], v[172:173], 0, v[170:171]
	s_waitcnt vmcnt(0)
	v_lshlrev_b32_e32 v192, 16, v146
	v_and_b32_e32 v193, 0xffff0000, v146
	v_lshlrev_b32_e32 v218, 16, v148
	v_and_b32_e32 v219, 0xffff0000, v148
	v_lshlrev_b32_e32 v146, 16, v147
	v_and_b32_e32 v147, 0xffff0000, v147
	v_lshlrev_b32_e32 v148, 16, v149
	v_and_b32_e32 v149, 0xffff0000, v149
	v_lshlrev_b32_e32 v220, 16, v182
	v_and_b32_e32 v221, 0xffff0000, v182
	v_lshlrev_b32_e32 v222, 16, v184
	v_and_b32_e32 v223, 0xffff0000, v184
	v_lshlrev_b32_e32 v182, 16, v183
	v_and_b32_e32 v183, 0xffff0000, v183
	v_lshlrev_b32_e32 v184, 16, v185
	v_and_b32_e32 v185, 0xffff0000, v185
	v_pk_add_f32 v[124:125], v[124:125], v[192:193]
	v_pk_add_f32 v[126:127], v[126:127], v[146:147]
	v_pk_add_f32 v[122:123], v[122:123], v[148:149]
	v_pk_add_f32 v[116:117], v[116:117], v[220:221]
	v_pk_add_f32 v[146:147], v[112:113], v[222:223]
	v_pk_add_f32 v[118:119], v[118:119], v[182:183]
	v_pk_add_f32 v[148:149], v[114:115], v[184:185]
	v_lshlrev_b32_e32 v182, 16, v194
	v_and_b32_e32 v183, 0xffff0000, v194
	v_lshlrev_b32_e32 v184, 16, v196
	v_and_b32_e32 v185, 0xffff0000, v196
	v_lshlrev_b32_e32 v192, 16, v195
	v_and_b32_e32 v193, 0xffff0000, v195
	v_lshlrev_b32_e32 v194, 16, v197
	v_and_b32_e32 v195, 0xffff0000, v197
	v_pk_mul_f32 v[196:197], v[124:125], v[124:125]
	v_pk_add_f32 v[120:121], v[120:121], v[218:219]
	v_pk_mul_f32 v[218:219], v[126:127], v[126:127]
	v_cvt_pk_bf16_f32 v112, v124, v125
	v_cvt_pk_bf16_f32 v113, v126, v127
	v_pk_mul_f32 v[124:125], v[116:117], v[116:117]
	v_pk_mul_f32 v[126:127], v[118:119], v[118:119]
	v_pk_mul_f32 v[224:225], v[146:147], v[146:147]
	v_cvt_pk_bf16_f32 v116, v116, v117
	v_cvt_pk_bf16_f32 v117, v118, v119
	v_cvt_pk_bf16_f32 v118, v146, v147
	v_add_f32_e32 v146, v196, v197
	v_add_f32_e32 v146, v218, v146
	v_pk_mul_f32 v[220:221], v[120:121], v[120:121]
	v_add_f32_e32 v146, v219, v146
	v_add_f32_e32 v146, v220, v146
	v_pk_mul_f32 v[222:223], v[122:123], v[122:123]
	v_add_f32_e32 v146, v221, v146
	v_add_f32_e32 v146, v222, v146
	v_add_f32_e32 v146, v223, v146
	v_add_f32_e32 v124, v124, v146
	v_add_f32_e32 v124, v125, v124
	v_add_f32_e32 v124, v126, v124
	v_add_f32_e32 v124, v127, v124
	v_add_f32_e32 v124, v224, v124
	v_pk_mul_f32 v[226:227], v[148:149], v[148:149]
	v_add_f32_e32 v124, v225, v124
	v_add_f32_e32 v124, v226, v124
	v_add_f32_e32 v209, v227, v124
	v_lshlrev_b32_e32 v124, 16, v210
	v_and_b32_e32 v125, 0xffff0000, v210
	v_pk_add_f32 v[100:101], v[100:101], v[124:125]
	v_lshlrev_b32_e32 v124, 16, v212
	v_and_b32_e32 v125, 0xffff0000, v212
	v_pk_add_f32 v[124:125], v[92:93], v[124:125]
	v_lshlrev_b32_e32 v92, 16, v211
	v_and_b32_e32 v93, 0xffff0000, v211
	v_pk_add_f32 v[102:103], v[102:103], v[92:93]
	v_lshlrev_b32_e32 v92, 16, v213
	v_and_b32_e32 v93, 0xffff0000, v213
	v_pk_add_f32 v[126:127], v[94:95], v[92:93]
	v_lshlrev_b32_e32 v92, 16, v214
	v_and_b32_e32 v93, 0xffff0000, v214
	v_pk_add_f32 v[92:93], v[96:97], v[92:93]
	v_lshlrev_b32_e32 v96, 16, v217
	v_and_b32_e32 v97, 0xffff0000, v217
	v_lshlrev_b32_e32 v94, 16, v216
	v_and_b32_e32 v95, 0xffff0000, v216
	v_pk_add_f32 v[90:91], v[90:91], v[96:97]
	v_lshlrev_b32_e32 v96, 16, v136
	v_and_b32_e32 v97, 0xffff0000, v136
	v_pk_add_f32 v[88:89], v[88:89], v[94:95]
	v_lshlrev_b32_e32 v94, 16, v215
	v_and_b32_e32 v95, 0xffff0000, v215
	v_pk_add_f32 v[96:97], v[76:77], v[96:97]
	v_lshl_add_u64 v[76:77], v[168:169], 0, s[36:37]
	v_cvt_pk_bf16_f32 v114, v120, v121
	v_pk_add_f32 v[120:121], v[108:109], v[182:183]
	v_pk_add_f32 v[94:95], v[98:99], v[94:95]
	v_lshlrev_b64 v[182:183], 11, v[76:77]
	v_lshlrev_b32_e32 v98, 16, v138
	v_and_b32_e32 v99, 0xffff0000, v138
	v_pk_add_f32 v[108:109], v[104:105], v[184:185]
	v_lshl_add_u64 v[184:185], v[174:175], 0, v[182:183]
	v_pk_add_f32 v[98:99], v[72:73], v[98:99]
	v_lshlrev_b32_e32 v72, 16, v137
	v_and_b32_e32 v73, 0xffff0000, v137
	global_load_dwordx4 v[210:213], v[184:185], off
	global_load_dwordx4 v[218:221], v[184:185], off offset:256
	v_pk_add_f32 v[136:137], v[78:79], v[72:73]
	v_lshlrev_b32_e32 v72, 16, v139
	v_and_b32_e32 v73, 0xffff0000, v139
	v_pk_add_f32 v[138:139], v[74:75], v[72:73]
	v_lshlrev_b32_e32 v72, 16, v132
	v_and_b32_e32 v73, 0xffff0000, v132
	v_pk_add_f32 v[74:75], v[84:85], v[72:73]
	v_lshlrev_b32_e32 v72, 16, v134
	v_and_b32_e32 v73, 0xffff0000, v134
	v_pk_add_f32 v[78:79], v[80:81], v[72:73]
	v_lshlrev_b32_e32 v72, 16, v133
	v_and_b32_e32 v73, 0xffff0000, v133
	v_pk_add_f32 v[80:81], v[86:87], v[72:73]
	v_lshlrev_b32_e32 v72, 16, v135
	v_and_b32_e32 v73, 0xffff0000, v135
	v_pk_add_f32 v[82:83], v[82:83], v[72:73]
	v_lshl_add_u64 v[72:73], v[168:169], 0, s[10:11]
	v_lshlrev_b64 v[132:133], 11, v[72:73]
	v_lshl_add_u64 v[134:135], v[174:175], 0, v[132:133]
	v_lshlrev_b32_e32 v84, 16, v128
	v_and_b32_e32 v85, 0xffff0000, v128
	global_load_dwordx4 v[226:229], v[134:135], off
	global_load_dwordx4 v[234:237], v[134:135], off offset:256
	v_pk_add_f32 v[84:85], v[68:69], v[84:85]
	v_lshlrev_b32_e32 v68, 16, v130
	v_and_b32_e32 v69, 0xffff0000, v130
	v_pk_add_f32 v[86:87], v[64:65], v[68:69]
	v_lshlrev_b32_e32 v64, 16, v129
	v_and_b32_e32 v65, 0xffff0000, v129
	s_mov_b64 s[10:11], 0xa0
	v_pk_add_f32 v[128:129], v[70:71], v[64:65]
	v_lshl_add_u64 v[70:71], v[168:169], 0, s[10:11]
	s_mov_b64 s[10:11], 0xb0
	v_lshlrev_b32_e32 v64, 16, v131
	v_and_b32_e32 v65, 0xffff0000, v131
	v_lshlrev_b64 v[134:135], 11, v[70:71]
	v_lshl_add_u64 v[68:69], v[168:169], 0, s[10:11]
	v_pk_add_f32 v[130:131], v[66:67], v[64:65]
	v_lshl_add_u64 v[64:65], v[174:175], 0, v[134:135]
	v_lshlrev_b64 v[184:185], 11, v[68:69]
	global_load_dwordx4 v[238:241], v[64:65], off
	global_load_dwordx4 v[242:245], v[64:65], off offset:256
	v_lshl_add_u64 v[64:65], v[174:175], 0, v[184:185]
	global_load_dwordx4 v[246:249], v[64:65], off
	s_nop 0
	global_load_dwordx4 v[64:67], v[64:65], off offset:256
	v_cvt_pk_bf16_f32 v115, v122, v123
	v_cvt_pk_bf16_f32 v119, v148, v149
	v_pk_add_f32 v[110:111], v[110:111], v[192:193]
	v_pk_add_f32 v[122:123], v[106:107], v[194:195]
	global_store_dwordx4 v[172:173], v[112:115], off
	global_store_dwordx4 v[172:173], v[116:119], off offset:256
	v_cvt_pk_bf16_f32 v104, v120, v121
	v_lshl_add_u64 v[112:113], s[28:29], 0, v[176:177]
	v_cvt_pk_bf16_f32 v105, v110, v111
	v_cvt_pk_bf16_f32 v106, v108, v109
	v_cvt_pk_bf16_f32 v107, v122, v123
	v_lshl_add_u64 v[112:113], v[112:113], 0, v[170:171]
	v_cvt_pk_bf16_f32 v146, v100, v101
	v_cvt_pk_bf16_f32 v147, v102, v103
	v_cvt_pk_bf16_f32 v148, v124, v125
	v_cvt_pk_bf16_f32 v149, v126, v127
	global_store_dwordx4 v[112:113], v[104:107], off
	global_store_dwordx4 v[112:113], v[146:149], off offset:256
	v_cvt_pk_bf16_f32 v194, v92, v93
	v_lshl_add_u64 v[104:105], s[28:29], 0, v[180:181]
	v_cvt_pk_bf16_f32 v195, v94, v95
	v_cvt_pk_bf16_f32 v196, v88, v89
	v_cvt_pk_bf16_f32 v197, v90, v91
	v_lshl_add_u64 v[104:105], v[104:105], 0, v[170:171]
	v_cvt_pk_bf16_f32 v214, v96, v97
	v_cvt_pk_bf16_f32 v215, v136, v137
	v_cvt_pk_bf16_f32 v216, v98, v99
	v_cvt_pk_bf16_f32 v217, v138, v139
	global_store_dwordx4 v[104:105], v[194:197], off
	global_store_dwordx4 v[104:105], v[214:217], off offset:256
	v_lshl_add_u64 v[104:105], s[28:29], 0, v[178:179]
	v_cvt_pk_bf16_f32 v222, v74, v75
	v_cvt_pk_bf16_f32 v223, v80, v81
	v_cvt_pk_bf16_f32 v224, v78, v79
	v_cvt_pk_bf16_f32 v225, v82, v83
	v_lshl_add_u64 v[104:105], v[104:105], 0, v[170:171]
	v_cvt_pk_bf16_f32 v230, v84, v85
	v_cvt_pk_bf16_f32 v231, v128, v129
	v_cvt_pk_bf16_f32 v232, v86, v87
	v_cvt_pk_bf16_f32 v233, v130, v131
	global_store_dwordx4 v[104:105], v[222:225], off
	global_store_dwordx4 v[104:105], v[230:233], off offset:256
	s_waitcnt vmcnt(0)
	v_lshlrev_b32_e32 v104, 16, v210
	v_and_b32_e32 v105, 0xffff0000, v210
	v_pk_add_f32 v[60:61], v[60:61], v[104:105]
	v_lshlrev_b32_e32 v104, 16, v212
	v_and_b32_e32 v105, 0xffff0000, v212
	v_pk_add_f32 v[56:57], v[56:57], v[104:105]
	v_lshlrev_b32_e32 v104, 16, v211
	v_and_b32_e32 v105, 0xffff0000, v211
	v_pk_add_f32 v[62:63], v[62:63], v[104:105]
	v_lshlrev_b32_e32 v104, 16, v213
	v_and_b32_e32 v105, 0xffff0000, v213
	v_pk_add_f32 v[58:59], v[58:59], v[104:105]
	v_lshlrev_b32_e32 v104, 16, v218
	v_and_b32_e32 v105, 0xffff0000, v218
	v_pk_add_f32 v[52:53], v[52:53], v[104:105]
	v_lshlrev_b32_e32 v104, 16, v220
	v_and_b32_e32 v105, 0xffff0000, v220
	v_pk_add_f32 v[104:105], v[44:45], v[104:105]
	v_lshlrev_b32_e32 v44, 16, v219
	v_and_b32_e32 v45, 0xffff0000, v219
	v_pk_add_f32 v[54:55], v[54:55], v[44:45]
	v_lshlrev_b32_e32 v44, 16, v221
	v_and_b32_e32 v45, 0xffff0000, v221
	v_pk_add_f32 v[106:107], v[46:47], v[44:45]
	v_lshlrev_b32_e32 v44, 16, v226
	v_and_b32_e32 v45, 0xffff0000, v226
	v_pk_add_f32 v[44:45], v[48:49], v[44:45]
	v_lshlrev_b32_e32 v48, 16, v229
	v_and_b32_e32 v49, 0xffff0000, v229
	v_pk_add_f32 v[42:43], v[42:43], v[48:49]
	v_lshlrev_b32_e32 v48, 16, v234
	v_and_b32_e32 v49, 0xffff0000, v234
	v_pk_add_f32 v[36:37], v[36:37], v[48:49]
	v_lshlrev_b32_e32 v48, 16, v236
	v_and_b32_e32 v49, 0xffff0000, v236
	v_lshlrev_b32_e32 v46, 16, v228
	v_and_b32_e32 v47, 0xffff0000, v228
	v_pk_add_f32 v[48:49], v[28:29], v[48:49]
	v_lshlrev_b32_e32 v28, 16, v235
	v_and_b32_e32 v29, 0xffff0000, v235
	v_pk_add_f32 v[40:41], v[40:41], v[46:47]
	v_lshlrev_b32_e32 v46, 16, v227
	v_and_b32_e32 v47, 0xffff0000, v227
	v_pk_add_f32 v[38:39], v[38:39], v[28:29]
	v_lshlrev_b32_e32 v28, 16, v237
	v_and_b32_e32 v29, 0xffff0000, v237
	v_pk_add_f32 v[46:47], v[50:51], v[46:47]
	v_pk_add_f32 v[50:51], v[30:31], v[28:29]
	v_lshlrev_b32_e32 v28, 16, v238
	v_and_b32_e32 v29, 0xffff0000, v238
	v_lshlrev_b32_e32 v180, 16, v64
	v_and_b32_e32 v181, 0xffff0000, v64
	v_pk_add_f32 v[28:29], v[32:33], v[28:29]
	v_lshlrev_b32_e32 v32, 16, v241
	v_and_b32_e32 v33, 0xffff0000, v241
	v_pk_add_f32 v[4:5], v[4:5], v[180:181]
	v_lshlrev_b32_e32 v180, 16, v66
	v_and_b32_e32 v181, 0xffff0000, v66
	v_pk_add_f32 v[26:27], v[26:27], v[32:33]
	v_lshlrev_b32_e32 v32, 16, v242
	v_and_b32_e32 v33, 0xffff0000, v242
	v_pk_add_f32 v[0:1], v[0:1], v[180:181]
	v_lshl_add_u64 v[180:181], s[28:29], 0, v[182:183]
	v_cvt_pk_bf16_f32 v112, v60, v61
	v_cvt_pk_bf16_f32 v113, v62, v63
	v_cvt_pk_bf16_f32 v114, v56, v57
	v_cvt_pk_bf16_f32 v115, v58, v59
	v_pk_add_f32 v[20:21], v[20:21], v[32:33]
	v_lshlrev_b32_e32 v32, 16, v244
	v_and_b32_e32 v33, 0xffff0000, v244
	v_lshl_add_u64 v[180:181], v[180:181], 0, v[170:171]
	v_cvt_pk_bf16_f32 v116, v52, v53
	v_cvt_pk_bf16_f32 v117, v54, v55
	v_cvt_pk_bf16_f32 v118, v104, v105
	v_cvt_pk_bf16_f32 v119, v106, v107
	v_lshlrev_b32_e32 v30, 16, v240
	v_and_b32_e32 v31, 0xffff0000, v240
	v_pk_add_f32 v[32:33], v[12:13], v[32:33]
	v_lshlrev_b32_e32 v12, 16, v243
	v_and_b32_e32 v13, 0xffff0000, v243
	global_store_dwordx4 v[180:181], v[112:115], off
	global_store_dwordx4 v[180:181], v[116:119], off offset:256
	v_cvt_pk_bf16_f32 v146, v44, v45
	v_lshl_add_u64 v[112:113], s[28:29], 0, v[132:133]
	v_cvt_pk_bf16_f32 v147, v46, v47
	v_cvt_pk_bf16_f32 v148, v40, v41
	v_cvt_pk_bf16_f32 v149, v42, v43
	v_pk_add_f32 v[24:25], v[24:25], v[30:31]
	v_lshlrev_b32_e32 v30, 16, v239
	v_and_b32_e32 v31, 0xffff0000, v239
	v_pk_add_f32 v[22:23], v[22:23], v[12:13]
	v_lshlrev_b32_e32 v12, 16, v245
	v_and_b32_e32 v13, 0xffff0000, v245
	v_lshl_add_u64 v[112:113], v[112:113], 0, v[170:171]
	v_cvt_pk_bf16_f32 v172, v36, v37
	v_cvt_pk_bf16_f32 v173, v38, v39
	v_cvt_pk_bf16_f32 v174, v48, v49
	v_cvt_pk_bf16_f32 v175, v50, v51
	v_pk_add_f32 v[30:31], v[34:35], v[30:31]
	v_pk_add_f32 v[34:35], v[14:15], v[12:13]
	v_lshlrev_b32_e32 v12, 16, v246
	v_and_b32_e32 v13, 0xffff0000, v246
	v_lshlrev_b32_e32 v14, 16, v248
	v_and_b32_e32 v15, 0xffff0000, v248
	global_store_dwordx4 v[112:113], v[146:149], off
	global_store_dwordx4 v[112:113], v[172:175], off offset:256
	v_lshl_add_u64 v[112:113], s[28:29], 0, v[134:135]
	v_cvt_pk_bf16_f32 v176, v28, v29
	v_cvt_pk_bf16_f32 v177, v30, v31
	v_cvt_pk_bf16_f32 v178, v24, v25
	v_cvt_pk_bf16_f32 v179, v26, v27
	v_pk_add_f32 v[12:13], v[16:17], v[12:13]
	v_pk_add_f32 v[8:9], v[8:9], v[14:15]
	v_lshlrev_b32_e32 v14, 16, v247
	v_and_b32_e32 v15, 0xffff0000, v247
	v_lshlrev_b32_e32 v16, 16, v249
	v_and_b32_e32 v17, 0xffff0000, v249
	v_lshlrev_b32_e32 v64, 16, v65
	v_and_b32_e32 v65, 0xffff0000, v65
	v_lshl_add_u64 v[112:113], v[112:113], 0, v[170:171]
	v_cvt_pk_bf16_f32 v194, v20, v21
	v_cvt_pk_bf16_f32 v195, v22, v23
	v_cvt_pk_bf16_f32 v196, v32, v33
	v_cvt_pk_bf16_f32 v197, v34, v35
	v_pk_add_f32 v[14:15], v[18:19], v[14:15]
	v_pk_add_f32 v[10:11], v[10:11], v[16:17]
	v_pk_add_f32 v[6:7], v[6:7], v[64:65]
	v_lshlrev_b32_e32 v64, 16, v67
	v_and_b32_e32 v65, 0xffff0000, v67
	global_store_dwordx4 v[112:113], v[176:179], off
	global_store_dwordx4 v[112:113], v[194:197], off offset:256
	v_lshl_add_u64 v[112:113], s[28:29], 0, v[184:185]
	v_cvt_pk_bf16_f32 v16, v12, v13
	v_cvt_pk_bf16_f32 v17, v14, v15
	v_cvt_pk_bf16_f32 v18, v8, v9
	v_cvt_pk_bf16_f32 v19, v10, v11
	v_pk_add_f32 v[2:3], v[2:3], v[64:65]
	v_lshl_add_u64 v[112:113], v[112:113], 0, v[170:171]
	v_cvt_pk_bf16_f32 v64, v4, v5
	v_cvt_pk_bf16_f32 v65, v6, v7
	v_cvt_pk_bf16_f32 v66, v0, v1
	v_cvt_pk_bf16_f32 v67, v2, v3
	global_store_dwordx4 v[112:113], v[16:19], off
	global_store_dwordx4 v[112:113], v[64:67], off offset:256
	s_lshl_b32 s10, s85, 2
	v_and_b32_e32 v17, 64, v188
	v_xor_b32_e32 v16, 16, v188
	v_add_u32_e32 v17, 64, v17
	v_cmp_lt_i32_e32 vcc, v16, v17
	v_xor_b32_e32 v18, 32, v188
	s_ashr_i32 s11, s10, 31
	v_cndmask_b32_e32 v16, v188, v16, vcc
	v_lshlrev_b32_e32 v16, 2, v16
	ds_bpermute_b32 v19, v16, v209
	v_cmp_lt_i32_e32 vcc, v18, v17
	s_lshl_b64 s[10:11], s[10:11], 2
	s_add_u32 s50, s83, s10
	v_cndmask_b32_e32 v17, v188, v18, vcc
	v_lshlrev_b32_e32 v17, 2, v17
	s_waitcnt lgkmcnt(0)
	v_add_f32_e32 v18, v209, v19
	ds_bpermute_b32 v19, v17, v18
	s_addc_u32 s51, s84, s11
	s_and_saveexec_b64 s[52:53], s[42:43]
	s_cbranch_execz .LBB0_106
	s_waitcnt lgkmcnt(0)
	v_add_f32_e32 v64, v18, v19
	v_lshlrev_b64 v[18:19], 6, v[168:169]
	v_lshl_add_u64 v[18:19], s[50:51], 0, v[18:19]
	global_store_dword v[18:19], v64, off

.LBB0_192:
	s_add_u32 s6, s26, s54
	s_addc_u32 s11, s27, s55
	s_add_u32 s6, s6, 0x100
	s_addc_u32 s11, s11, 0
	s_add_u32 s12, s29, s54
	s_addc_u32 s19, s31, s55
	s_add_i32 s23, 0, 0x10000
	v_add_u32_e32 v169, s23, v156
	ds_read_b128 v[146:149], v169
	ds_read_b128 v[170:173], v169 offset:1024
	ds_read_b128 v[174:177], v169 offset:2048
	ds_read_b128 v[178:181], v169 offset:3072
	s_cmpk_eq_i32 s54, 0x700
	s_cselect_b32 s69, s53, s11
	s_cselect_b32 s68, s52, s6
	s_cselect_b32 s59, s49, s19
	s_cselect_b32 s58, s48, s12
	v_lshl_add_u64 v[230:231], v[152:153], 0, s[54:55]
	s_add_i32 m0, s72, 0xc000
	ds_read_b128 v[182:185], v168
	ds_read_b128 v[194:197], v168 offset:1024
	ds_read_b128 v[206:209], v168 offset:2048
	ds_read_b128 v[210:213], v168 offset:3072
	ds_read_b128 v[214:217], v168 offset:4096
	ds_read_b128 v[218:221], v168 offset:5120
	ds_read_b128 v[222:225], v168 offset:6144
	ds_read_b128 v[226:229], v168 offset:7168
	global_load_lds_dwordx4 v[230:231], off
	v_lshl_add_u64 v[230:231], v[154:155], 0, s[54:55]
	s_add_i32 m0, s72, 0xe000
	s_nop 0
	global_load_lds_dwordx4 v[230:231], off
	s_waitcnt lgkmcnt(8)
	s_barrier
	s_setprio 1
	s_waitcnt lgkmcnt(7)
	v_mfma_f32_16x16x32_bf16 v[16:19], v[146:149], v[182:185], v[16:19]
	v_mfma_f32_16x16x32_bf16 v[20:23], v[174:177], v[182:185], v[20:23]
	s_waitcnt lgkmcnt(5)
	v_mfma_f32_16x16x32_bf16 v[40:43], v[146:149], v[206:209], v[40:43]
	v_mfma_f32_16x16x32_bf16 v[32:35], v[174:177], v[206:209], v[32:35]
	s_waitcnt lgkmcnt(3)
	v_mfma_f32_16x16x32_bf16 v[64:67], v[146:149], v[214:217], v[64:67]
	v_mfma_f32_16x16x32_bf16 v[56:59], v[174:177], v[214:217], v[56:59]
	s_waitcnt lgkmcnt(1)
	v_mfma_f32_16x16x32_bf16 v[88:91], v[146:149], v[222:225], v[88:91]
	v_mfma_f32_16x16x32_bf16 v[80:83], v[174:177], v[222:225], v[80:83]
	v_mfma_f32_16x16x32_bf16 v[16:19], v[170:173], v[194:197], v[16:19]
	v_mfma_f32_16x16x32_bf16 v[20:23], v[178:181], v[194:197], v[20:23]
	v_mfma_f32_16x16x32_bf16 v[40:43], v[170:173], v[210:213], v[40:43]
	v_mfma_f32_16x16x32_bf16 v[32:35], v[178:181], v[210:213], v[32:35]
	v_mfma_f32_16x16x32_bf16 v[64:67], v[170:173], v[218:221], v[64:67]
	v_mfma_f32_16x16x32_bf16 v[56:59], v[178:181], v[218:221], v[56:59]
	s_waitcnt lgkmcnt(0)
	v_mfma_f32_16x16x32_bf16 v[88:91], v[170:173], v[226:229], v[88:91]
	v_mfma_f32_16x16x32_bf16 v[80:83], v[178:181], v[226:229], v[80:83]
	s_setprio 0
	s_barrier
	s_add_i32 s6, 0, 0x14000
	s_add_i32 s11, s23, s71
	v_add_u32_e32 v169, s6, v156
	v_lshl_add_u64 v[246:247], s[58:59], 0, v[130:131]
	s_mov_b32 m0, s11
	ds_read_b128 v[230:233], v169
	ds_read_b128 v[234:237], v169 offset:1024
	ds_read_b128 v[238:241], v169 offset:2048
	ds_read_b128 v[242:245], v169 offset:3072
	global_load_lds_dwordx4 v[246:247], off
	v_lshl_add_u64 v[248:249], s[58:59], 0, v[134:135]
	s_add_i32 m0, s11, 0x2000
	s_nop 0
	global_load_lds_dwordx4 v[248:249], off
	s_barrier
	s_setprio 1
	s_waitcnt lgkmcnt(3)
	v_mfma_f32_16x16x32_bf16 v[0:3], v[230:233], v[182:185], v[0:3]
	s_waitcnt lgkmcnt(1)
	v_mfma_f32_16x16x32_bf16 v[4:7], v[238:241], v[182:185], v[4:7]
	v_mfma_f32_16x16x32_bf16 v[8:11], v[230:233], v[206:209], v[8:11]
	v_mfma_f32_16x16x32_bf16 v[12:15], v[238:241], v[206:209], v[12:15]
	v_mfma_f32_16x16x32_bf16 v[24:27], v[230:233], v[214:217], v[24:27]
	v_mfma_f32_16x16x32_bf16 v[28:31], v[238:241], v[214:217], v[28:31]
	v_mfma_f32_16x16x32_bf16 v[48:51], v[230:233], v[222:225], v[48:51]
	v_mfma_f32_16x16x32_bf16 v[52:55], v[238:241], v[222:225], v[52:55]
	v_mfma_f32_16x16x32_bf16 v[0:3], v[234:237], v[194:197], v[0:3]
	s_waitcnt lgkmcnt(0)
	v_mfma_f32_16x16x32_bf16 v[4:7], v[242:245], v[194:197], v[4:7]
	v_mfma_f32_16x16x32_bf16 v[8:11], v[234:237], v[210:213], v[8:11]
	v_mfma_f32_16x16x32_bf16 v[12:15], v[242:245], v[210:213], v[12:15]
	v_mfma_f32_16x16x32_bf16 v[24:27], v[234:237], v[218:221], v[24:27]
	v_mfma_f32_16x16x32_bf16 v[28:31], v[242:245], v[218:221], v[28:31]
	v_mfma_f32_16x16x32_bf16 v[48:51], v[234:237], v[226:229], v[48:51]
	v_mfma_f32_16x16x32_bf16 v[52:55], v[242:245], v[226:229], v[52:55]
	s_setprio 0
	s_mov_b32 m0, s72
	v_lshl_add_u64 v[250:251], s[68:69], 0, v[128:129]
	s_barrier
	ds_read_b128 v[182:185], v168 offset:16384
	ds_read_b128 v[194:197], v168 offset:17408
	ds_read_b128 v[206:209], v168 offset:18432
	ds_read_b128 v[210:213], v168 offset:19456
	ds_read_b128 v[214:217], v168 offset:20480
	ds_read_b128 v[218:221], v168 offset:21504
	ds_read_b128 v[222:225], v168 offset:22528
	ds_read_b128 v[226:229], v168 offset:23552
	global_load_lds_dwordx4 v[250:251], off
	v_lshl_add_u64 v[192:193], s[68:69], 0, v[132:133]
	s_mov_b32 m0, s73
	s_nop 0
	global_load_lds_dwordx4 v[192:193], off
	s_barrier
	s_setprio 1
	s_waitcnt lgkmcnt(7)
	v_mfma_f32_16x16x32_bf16 v[76:79], v[146:149], v[182:185], v[76:79]
	v_mfma_f32_16x16x32_bf16 v[72:75], v[174:177], v[182:185], v[72:75]
	s_waitcnt lgkmcnt(5)
	v_mfma_f32_16x16x32_bf16 v[100:103], v[146:149], v[206:209], v[100:103]
	v_mfma_f32_16x16x32_bf16 v[96:99], v[174:177], v[206:209], v[96:99]
	s_waitcnt lgkmcnt(3)
	v_mfma_f32_16x16x32_bf16 v[116:119], v[146:149], v[214:217], v[116:119]
	v_mfma_f32_16x16x32_bf16 v[112:115], v[174:177], v[214:217], v[112:115]
	s_waitcnt lgkmcnt(1)
	v_mfma_f32_16x16x32_bf16 v[124:127], v[146:149], v[222:225], v[124:127]
	v_mfma_f32_16x16x32_bf16 v[120:123], v[174:177], v[222:225], v[120:123]
	v_mfma_f32_16x16x32_bf16 v[76:79], v[170:173], v[194:197], v[76:79]
	v_mfma_f32_16x16x32_bf16 v[72:75], v[178:181], v[194:197], v[72:75]
	v_mfma_f32_16x16x32_bf16 v[100:103], v[170:173], v[210:213], v[100:103]
	v_mfma_f32_16x16x32_bf16 v[96:99], v[178:181], v[210:213], v[96:99]
	v_mfma_f32_16x16x32_bf16 v[116:119], v[170:173], v[218:221], v[116:119]
	v_mfma_f32_16x16x32_bf16 v[112:115], v[178:181], v[218:221], v[112:115]
	s_waitcnt lgkmcnt(0)
	v_mfma_f32_16x16x32_bf16 v[124:127], v[170:173], v[226:229], v[124:127]
	v_mfma_f32_16x16x32_bf16 v[120:123], v[178:181], v[226:229], v[120:123]
	s_setprio 0
	s_barrier
	s_add_u32 s88, s58, 0x40000
	s_addc_u32 s89, s59, 0
	s_add_i32 s6, s6, s71
	v_lshl_add_u64 v[146:147], s[88:89], 0, v[130:131]
	s_mov_b32 m0, s6
	s_nop 0
	global_load_lds_dwordx4 v[146:147], off
	v_lshl_add_u64 v[146:147], s[88:89], 0, v[134:135]
	s_add_i32 m0, s6, 0x2000
	s_nop 0
	global_load_lds_dwordx4 v[146:147], off
	s_nop 0
	s_waitcnt vmcnt(6)
	s_barrier
	s_setprio 1
	v_mfma_f32_16x16x32_bf16 v[36:39], v[230:233], v[182:185], v[36:39]
	v_mfma_f32_16x16x32_bf16 v[44:47], v[238:241], v[182:185], v[44:47]
	v_mfma_f32_16x16x32_bf16 v[60:63], v[230:233], v[206:209], v[60:63]
	v_mfma_f32_16x16x32_bf16 v[68:71], v[238:241], v[206:209], v[68:71]
	v_mfma_f32_16x16x32_bf16 v[84:87], v[230:233], v[214:217], v[84:87]
	v_mfma_f32_16x16x32_bf16 v[92:95], v[238:241], v[214:217], v[92:95]
	v_mfma_f32_16x16x32_bf16 v[108:111], v[230:233], v[222:225], v[108:111]
	v_mfma_f32_16x16x32_bf16 v[104:107], v[238:241], v[222:225], v[104:107]
	v_mfma_f32_16x16x32_bf16 v[36:39], v[234:237], v[194:197], v[36:39]
	v_mfma_f32_16x16x32_bf16 v[44:47], v[242:245], v[194:197], v[44:47]
	v_mfma_f32_16x16x32_bf16 v[60:63], v[234:237], v[210:213], v[60:63]
	v_mfma_f32_16x16x32_bf16 v[68:71], v[242:245], v[210:213], v[68:71]
	v_mfma_f32_16x16x32_bf16 v[84:87], v[234:237], v[218:221], v[84:87]
	v_mfma_f32_16x16x32_bf16 v[92:95], v[242:245], v[218:221], v[92:95]
	v_mfma_f32_16x16x32_bf16 v[108:111], v[234:237], v[226:229], v[108:111]
	v_mfma_f32_16x16x32_bf16 v[104:107], v[242:245], v[226:229], v[104:107]
	s_setprio 0
	s_add_i32 s6, 0, 0x18000
	v_add_u32_e32 v169, s6, v156
	s_barrier
	ds_read_b128 v[146:149], v169
	ds_read_b128 v[170:173], v169 offset:1024
	ds_read_b128 v[174:177], v169 offset:2048
	ds_read_b128 v[178:181], v169 offset:3072
	s_add_u32 s68, s68, 0x40000
	s_addc_u32 s69, s69, 0
	s_mov_b32 m0, s74
	v_lshl_add_u64 v[230:231], s[68:69], 0, v[128:129]
	ds_read_b128 v[182:185], v168 offset:32768
	ds_read_b128 v[194:197], v168 offset:33792
	ds_read_b128 v[206:209], v168 offset:34816
	ds_read_b128 v[210:213], v168 offset:35840
	ds_read_b128 v[214:217], v168 offset:36864
	ds_read_b128 v[218:221], v168 offset:37888
	ds_read_b128 v[222:225], v168 offset:38912
	ds_read_b128 v[226:229], v168 offset:39936
	global_load_lds_dwordx4 v[230:231], off
	v_lshl_add_u64 v[230:231], s[68:69], 0, v[132:133]
	s_mov_b32 m0, s75
	s_nop 0
	global_load_lds_dwordx4 v[230:231], off
	s_waitcnt lgkmcnt(8)
	s_barrier
	s_setprio 1
	s_waitcnt lgkmcnt(7)
	v_mfma_f32_16x16x32_bf16 v[16:19], v[146:149], v[182:185], v[16:19]
	v_mfma_f32_16x16x32_bf16 v[20:23], v[174:177], v[182:185], v[20:23]
	s_waitcnt lgkmcnt(5)
	v_mfma_f32_16x16x32_bf16 v[40:43], v[146:149], v[206:209], v[40:43]
	v_mfma_f32_16x16x32_bf16 v[32:35], v[174:177], v[206:209], v[32:35]
	s_waitcnt lgkmcnt(3)
	v_mfma_f32_16x16x32_bf16 v[64:67], v[146:149], v[214:217], v[64:67]
	v_mfma_f32_16x16x32_bf16 v[56:59], v[174:177], v[214:217], v[56:59]
	s_waitcnt lgkmcnt(1)
	v_mfma_f32_16x16x32_bf16 v[88:91], v[146:149], v[222:225], v[88:91]
	v_mfma_f32_16x16x32_bf16 v[80:83], v[174:177], v[222:225], v[80:83]
	v_mfma_f32_16x16x32_bf16 v[16:19], v[170:173], v[194:197], v[16:19]
	v_mfma_f32_16x16x32_bf16 v[20:23], v[178:181], v[194:197], v[20:23]
	v_mfma_f32_16x16x32_bf16 v[40:43], v[170:173], v[210:213], v[40:43]
	v_mfma_f32_16x16x32_bf16 v[32:35], v[178:181], v[210:213], v[32:35]
	v_mfma_f32_16x16x32_bf16 v[64:67], v[170:173], v[218:221], v[64:67]
	v_mfma_f32_16x16x32_bf16 v[56:59], v[178:181], v[218:221], v[56:59]
	s_waitcnt lgkmcnt(0)
	v_mfma_f32_16x16x32_bf16 v[88:91], v[170:173], v[226:229], v[88:91]
	v_mfma_f32_16x16x32_bf16 v[80:83], v[178:181], v[226:229], v[80:83]
	s_setprio 0
	s_barrier
	s_add_i32 s11, 0, 0x1c000
	s_add_i32 s6, s6, s71
	v_add_u32_e32 v169, s11, v156
	v_lshl_add_u64 v[246:247], v[246:247], 0, s[36:37]
	s_mov_b32 m0, s6
	ds_read_b128 v[230:233], v169
	ds_read_b128 v[234:237], v169 offset:1024
	ds_read_b128 v[238:241], v169 offset:2048
	ds_read_b128 v[242:245], v169 offset:3072
	global_load_lds_dwordx4 v[246:247], off
	v_lshl_add_u64 v[246:247], v[248:249], 0, s[36:37]
	s_add_i32 m0, s6, 0x2000
	s_nop 0
	global_load_lds_dwordx4 v[246:247], off
	s_barrier
	s_setprio 1
	s_waitcnt lgkmcnt(3)
	v_mfma_f32_16x16x32_bf16 v[0:3], v[230:233], v[182:185], v[0:3]
	s_waitcnt lgkmcnt(1)
	v_mfma_f32_16x16x32_bf16 v[4:7], v[238:241], v[182:185], v[4:7]
	v_mfma_f32_16x16x32_bf16 v[8:11], v[230:233], v[206:209], v[8:11]
	v_mfma_f32_16x16x32_bf16 v[12:15], v[238:241], v[206:209], v[12:15]
	v_mfma_f32_16x16x32_bf16 v[24:27], v[230:233], v[214:217], v[24:27]
	v_mfma_f32_16x16x32_bf16 v[28:31], v[238:241], v[214:217], v[28:31]
	v_mfma_f32_16x16x32_bf16 v[48:51], v[230:233], v[222:225], v[48:51]
	v_mfma_f32_16x16x32_bf16 v[52:55], v[238:241], v[222:225], v[52:55]
	v_mfma_f32_16x16x32_bf16 v[0:3], v[234:237], v[194:197], v[0:3]
	s_waitcnt lgkmcnt(0)
	v_mfma_f32_16x16x32_bf16 v[4:7], v[242:245], v[194:197], v[4:7]
	v_mfma_f32_16x16x32_bf16 v[8:11], v[234:237], v[210:213], v[8:11]
	v_mfma_f32_16x16x32_bf16 v[12:15], v[242:245], v[210:213], v[12:15]
	v_mfma_f32_16x16x32_bf16 v[24:27], v[234:237], v[218:221], v[24:27]
	v_mfma_f32_16x16x32_bf16 v[28:31], v[242:245], v[218:221], v[28:31]
	v_mfma_f32_16x16x32_bf16 v[48:51], v[234:237], v[226:229], v[48:51]
	v_mfma_f32_16x16x32_bf16 v[52:55], v[242:245], v[226:229], v[52:55]
	s_setprio 0
	s_mov_b32 m0, s82
	v_lshl_add_u64 v[246:247], v[250:251], 0, s[36:37]
	s_barrier
	ds_read_b128 v[182:185], v168 offset:49152
	ds_read_b128 v[194:197], v168 offset:50176
	ds_read_b128 v[206:209], v168 offset:51200
	ds_read_b128 v[210:213], v168 offset:52224
	ds_read_b128 v[214:217], v168 offset:53248
	ds_read_b128 v[218:221], v168 offset:54272
	ds_read_b128 v[222:225], v168 offset:55296
	ds_read_b128 v[226:229], v168 offset:56320
	global_load_lds_dwordx4 v[246:247], off
	v_lshl_add_u64 v[192:193], v[192:193], 0, s[36:37]
	s_mov_b32 m0, s83
	s_nop 0
	global_load_lds_dwordx4 v[192:193], off
	s_barrier
	s_setprio 1
	s_waitcnt lgkmcnt(7)
	v_mfma_f32_16x16x32_bf16 v[76:79], v[146:149], v[182:185], v[76:79]
	v_mfma_f32_16x16x32_bf16 v[72:75], v[174:177], v[182:185], v[72:75]
	s_waitcnt lgkmcnt(5)
	v_mfma_f32_16x16x32_bf16 v[100:103], v[146:149], v[206:209], v[100:103]
	v_mfma_f32_16x16x32_bf16 v[96:99], v[174:177], v[206:209], v[96:99]
	s_waitcnt lgkmcnt(3)
	v_mfma_f32_16x16x32_bf16 v[116:119], v[146:149], v[214:217], v[116:119]
	v_mfma_f32_16x16x32_bf16 v[112:115], v[174:177], v[214:217], v[112:115]
	s_waitcnt lgkmcnt(1)
	v_mfma_f32_16x16x32_bf16 v[124:127], v[146:149], v[222:225], v[124:127]
	v_mfma_f32_16x16x32_bf16 v[120:123], v[174:177], v[222:225], v[120:123]
	v_mfma_f32_16x16x32_bf16 v[76:79], v[170:173], v[194:197], v[76:79]
	v_mfma_f32_16x16x32_bf16 v[72:75], v[178:181], v[194:197], v[72:75]
	v_mfma_f32_16x16x32_bf16 v[100:103], v[170:173], v[210:213], v[100:103]
	v_mfma_f32_16x16x32_bf16 v[96:99], v[178:181], v[210:213], v[96:99]
	v_mfma_f32_16x16x32_bf16 v[116:119], v[170:173], v[218:221], v[116:119]
	v_mfma_f32_16x16x32_bf16 v[112:115], v[178:181], v[218:221], v[112:115]
	s_waitcnt lgkmcnt(0)
	v_mfma_f32_16x16x32_bf16 v[124:127], v[170:173], v[226:229], v[124:127]
	v_mfma_f32_16x16x32_bf16 v[120:123], v[178:181], v[226:229], v[120:123]
	s_setprio 0
	s_barrier
	s_add_u32 s58, s58, 0x40080
	s_addc_u32 s59, s59, 0
	s_add_i32 s6, s11, s71
	v_lshl_add_u64 v[146:147], s[58:59], 0, v[130:131]
	s_mov_b32 m0, s6
	s_nop 0
	global_load_lds_dwordx4 v[146:147], off
	v_lshl_add_u64 v[146:147], s[58:59], 0, v[134:135]
	s_add_i32 m0, s6, 0x2000
	s_nop 0
	global_load_lds_dwordx4 v[146:147], off
	s_waitcnt vmcnt(6)
	s_barrier
	s_setprio 1
	v_mfma_f32_16x16x32_bf16 v[36:39], v[230:233], v[182:185], v[36:39]
	v_mfma_f32_16x16x32_bf16 v[44:47], v[238:241], v[182:185], v[44:47]
	v_mfma_f32_16x16x32_bf16 v[60:63], v[230:233], v[206:209], v[60:63]
	v_mfma_f32_16x16x32_bf16 v[68:71], v[238:241], v[206:209], v[68:71]
	v_mfma_f32_16x16x32_bf16 v[84:87], v[230:233], v[214:217], v[84:87]
	v_mfma_f32_16x16x32_bf16 v[92:95], v[238:241], v[214:217], v[92:95]
	v_mfma_f32_16x16x32_bf16 v[108:111], v[230:233], v[222:225], v[108:111]
	v_mfma_f32_16x16x32_bf16 v[104:107], v[238:241], v[222:225], v[104:107]
	v_mfma_f32_16x16x32_bf16 v[36:39], v[234:237], v[194:197], v[36:39]
	v_mfma_f32_16x16x32_bf16 v[44:47], v[242:245], v[194:197], v[44:47]
	v_mfma_f32_16x16x32_bf16 v[60:63], v[234:237], v[210:213], v[60:63]
	v_mfma_f32_16x16x32_bf16 v[68:71], v[242:245], v[210:213], v[68:71]
	v_mfma_f32_16x16x32_bf16 v[84:87], v[234:237], v[218:221], v[84:87]
	v_mfma_f32_16x16x32_bf16 v[92:95], v[242:245], v[218:221], v[92:95]
	v_mfma_f32_16x16x32_bf16 v[108:111], v[234:237], v[226:229], v[108:111]
	v_mfma_f32_16x16x32_bf16 v[104:107], v[242:245], v[226:229], v[104:107]
	s_setprio 0
	s_add_i32 s10, s10, 2
	s_add_u32 s54, s54, 0x100
	s_addc_u32 s55, s55, 0
	s_cmp_gt_u32 s10, 13
	s_barrier
	s_cbranch_scc0 .LBB0_192
	s_lshl_b32 s6, s84, 10
	v_add_u32_e32 v154, s6, v167
	ds_read_b32 v148, v154
	s_mov_b32 s6, 0xff61b1e6
	v_and_b32_e32 v147, 64, v188
	v_xor_b32_e32 v146, 16, v188
	v_add_u32_e32 v147, 64, v147
	s_waitcnt lgkmcnt(0)
	v_mul_f32_e32 v174, v16, v148
	v_mul_f32_e32 v16, v17, v148
	v_max3_f32 v17, v174, s6, v16
	v_mul_f32_e32 v18, v18, v148
	v_mul_f32_e32 v19, v19, v148
	v_max3_f32 v17, v17, v18, v19
	v_mul_f32_e32 v20, v20, v148
	v_mul_f32_e32 v21, v21, v148
	v_max3_f32 v17, v17, v20, v21
	v_mul_f32_e32 v22, v22, v148
	v_mul_f32_e32 v23, v23, v148
	v_max3_f32 v17, v17, v22, v23
	v_mul_f32_e32 v0, v0, v148
	v_mul_f32_e32 v1, v1, v148
	v_max3_f32 v17, v17, v0, v1
	v_mul_f32_e32 v2, v2, v148
	v_mul_f32_e32 v3, v3, v148
	v_cmp_lt_i32_e32 vcc, v146, v147
	v_max3_f32 v17, v17, v2, v3
	v_mul_f32_e32 v4, v4, v148
	v_mul_f32_e32 v5, v5, v148
	v_cndmask_b32_e32 v146, v188, v146, vcc
	v_max3_f32 v17, v17, v4, v5
	v_mul_f32_e32 v6, v6, v148
	v_mul_f32_e32 v7, v7, v148
	v_lshlrev_b32_e32 v152, 2, v146
	v_max3_f32 v17, v17, v6, v7
	ds_bpermute_b32 v146, v152, v17
	v_xor_b32_e32 v148, 32, v188
	v_cmp_lt_i32_e32 vcc, v148, v147
	s_waitcnt lgkmcnt(0)
	v_max_f32_e32 v146, v146, v146
	v_cndmask_b32_e32 v147, v188, v148, vcc
	v_lshlrev_b32_e32 v153, 2, v147
	v_max_f32_e32 v17, v17, v146
	ds_bpermute_b32 v155, v153, v17
	s_and_saveexec_b64 s[54:55], s[42:43]
	s_cbranch_execz .LBB0_195
	s_waitcnt lgkmcnt(0)
	v_max_f32_e32 v146, v155, v155
	v_max_f32_e32 v17, v17, v17
	v_max_f32_e32 v17, v17, v146
	v_add_u32_e32 v146, s85, v157
	ds_write_b32 v146, v17

.Lm4ap_248:
	s_waitcnt lgkmcnt(0)
	s_barrier
	v_mfma_f32_16x16x32_bf16 v[124:127], v[128:131], v[162:165], 0
	v_mfma_f32_16x16x32_bf16 v[120:123], v[136:139], v[162:165], 0
	v_mfma_f32_16x16x32_bf16 v[108:111], v[128:131], v[170:173], 0
	v_mfma_f32_16x16x32_bf16 v[104:107], v[136:139], v[170:173], 0
	v_mfma_f32_16x16x32_bf16 v[96:99], v[128:131], v[178:181], 0
	v_mfma_f32_16x16x32_bf16 v[88:91], v[136:139], v[178:181], 0
	v_mfma_f32_16x16x32_bf16 v[84:87], v[128:131], v[194:197], 0
	v_mfma_f32_16x16x32_bf16 v[80:83], v[136:139], v[194:197], 0
	v_mfma_f32_16x16x32_bf16 v[124:127], v[132:135], v[166:169], v[124:127]
	v_mfma_f32_16x16x32_bf16 v[120:123], v[146:149], v[166:169], v[120:123]
	v_mfma_f32_16x16x32_bf16 v[108:111], v[132:135], v[174:177], v[108:111]
	v_mfma_f32_16x16x32_bf16 v[104:107], v[146:149], v[174:177], v[104:107]
	v_mfma_f32_16x16x32_bf16 v[96:99], v[132:135], v[182:185], v[96:99]
	v_mfma_f32_16x16x32_bf16 v[88:91], v[146:149], v[182:185], v[88:91]
	v_mfma_f32_16x16x32_bf16 v[84:87], v[132:135], v[210:213], v[84:87]
	v_mfma_f32_16x16x32_bf16 v[80:83], v[146:149], v[210:213], v[80:83]
	v_mfma_f32_16x16x32_bf16 v[116:119], v[214:217], v[162:165], 0
	v_mfma_f32_16x16x32_bf16 v[112:115], v[222:225], v[162:165], 0
	v_mfma_f32_16x16x32_bf16 v[100:103], v[214:217], v[170:173], 0
	v_mfma_f32_16x16x32_bf16 v[92:95], v[222:225], v[170:173], 0
	v_mfma_f32_16x16x32_bf16 v[76:79], v[214:217], v[178:181], 0
	v_mfma_f32_16x16x32_bf16 v[72:75], v[222:225], v[178:181], 0
	v_mfma_f32_16x16x32_bf16 v[68:71], v[214:217], v[194:197], 0
	v_mfma_f32_16x16x32_bf16 v[64:67], v[222:225], v[194:197], 0
	v_mfma_f32_16x16x32_bf16 v[116:119], v[218:221], v[166:169], v[116:119]
	v_mfma_f32_16x16x32_bf16 v[112:115], v[226:229], v[166:169], v[112:115]
	v_mfma_f32_16x16x32_bf16 v[100:103], v[218:221], v[174:177], v[100:103]
	v_mfma_f32_16x16x32_bf16 v[92:95], v[226:229], v[174:177], v[92:95]
	v_mfma_f32_16x16x32_bf16 v[76:79], v[218:221], v[182:185], v[76:79]
	v_mfma_f32_16x16x32_bf16 v[72:75], v[226:229], v[182:185], v[72:75]
	v_mfma_f32_16x16x32_bf16 v[68:71], v[218:221], v[210:213], v[68:71]
	v_mfma_f32_16x16x32_bf16 v[64:67], v[226:229], v[210:213], v[64:67]
	s_add_i32 s19, s23, s57
	v_lshl_add_u64 v[230:231], s[54:55], 0, v[140:141]
	s_mov_b32 m0, s19
	s_barrier
	s_nop 0
	global_load_lds_dwordx4 v[230:231], off
	v_lshl_add_u64 v[232:233], s[54:55], 0, v[150:151]
	s_add_i32 m0, s19, 0x2000
	s_nop 0
	global_load_lds_dwordx4 v[232:233], off
	s_mov_b32 m0, s68
	v_lshl_add_u64 v[234:235], s[58:59], 0, v[154:155]
	ds_read_b128 v[162:165], v208 offset:16384
	ds_read_b128 v[166:169], v208 offset:17408
	ds_read_b128 v[170:173], v208 offset:18432
	ds_read_b128 v[174:177], v208 offset:19456
	ds_read_b128 v[178:181], v208 offset:20480
	ds_read_b128 v[182:185], v208 offset:21504
	ds_read_b128 v[194:197], v208 offset:22528
	ds_read_b128 v[210:213], v208 offset:23552
	global_load_lds_dwordx4 v[234:235], off
	v_lshl_add_u64 v[236:237], s[58:59], 0, v[152:153]
	s_mov_b32 m0, s69
	s_nop 0
	global_load_lds_dwordx4 v[236:237], off
	s_add_u32 s84, s54, 0x40000
	s_addc_u32 s85, s55, 0
	s_add_i32 s6, s6, s57
	v_lshl_add_u64 v[250:251], s[84:85], 0, v[140:141]
	s_mov_b32 m0, s6
	s_nop 0
	global_load_lds_dwordx4 v[250:251], off
	v_lshl_add_u64 v[250:251], s[84:85], 0, v[150:151]
	s_add_i32 m0, s6, 0x2000
	s_nop 0
	global_load_lds_dwordx4 v[250:251], off
	s_waitcnt vmcnt(40)
	s_cmp_lg_u32 s100, 0
	s_cbranch_scc1 .Lm4bp_248
	s_waitcnt vmcnt(8)
.Lm4bp_248:
	s_waitcnt lgkmcnt(0)
	s_mov_b32 s100, 0
	s_barrier
	v_mfma_f32_16x16x32_bf16 v[60:63], v[128:131], v[162:165], 0
	v_mfma_f32_16x16x32_bf16 v[56:59], v[136:139], v[162:165], 0
	v_mfma_f32_16x16x32_bf16 v[48:51], v[128:131], v[170:173], 0
	v_mfma_f32_16x16x32_bf16 v[40:43], v[136:139], v[170:173], 0
	v_mfma_f32_16x16x32_bf16 v[32:35], v[128:131], v[178:181], 0
	v_mfma_f32_16x16x32_bf16 v[24:27], v[136:139], v[178:181], 0
	v_mfma_f32_16x16x32_bf16 v[16:19], v[128:131], v[194:197], 0
	v_mfma_f32_16x16x32_bf16 v[8:11], v[136:139], v[194:197], 0
	v_mfma_f32_16x16x32_bf16 v[60:63], v[132:135], v[166:169], v[60:63]
	v_mfma_f32_16x16x32_bf16 v[56:59], v[146:149], v[166:169], v[56:59]
	v_mfma_f32_16x16x32_bf16 v[48:51], v[132:135], v[174:177], v[48:51]
	v_mfma_f32_16x16x32_bf16 v[40:43], v[146:149], v[174:177], v[40:43]
	v_mfma_f32_16x16x32_bf16 v[32:35], v[132:135], v[182:185], v[32:35]
	v_mfma_f32_16x16x32_bf16 v[24:27], v[146:149], v[182:185], v[24:27]
	v_mfma_f32_16x16x32_bf16 v[16:19], v[132:135], v[210:213], v[16:19]
	v_mfma_f32_16x16x32_bf16 v[8:11], v[146:149], v[210:213], v[8:11]
	v_mfma_f32_16x16x32_bf16 v[52:55], v[214:217], v[162:165], 0
	v_mfma_f32_16x16x32_bf16 v[44:47], v[222:225], v[162:165], 0
	v_mfma_f32_16x16x32_bf16 v[36:39], v[214:217], v[170:173], 0
	v_mfma_f32_16x16x32_bf16 v[28:31], v[222:225], v[170:173], 0
	v_mfma_f32_16x16x32_bf16 v[20:23], v[214:217], v[178:181], 0
	v_mfma_f32_16x16x32_bf16 v[12:15], v[222:225], v[178:181], 0
	v_mfma_f32_16x16x32_bf16 v[4:7], v[214:217], v[194:197], 0
	v_mfma_f32_16x16x32_bf16 v[0:3], v[222:225], v[194:197], 0
	v_mfma_f32_16x16x32_bf16 v[52:55], v[218:221], v[166:169], v[52:55]
	v_mfma_f32_16x16x32_bf16 v[44:47], v[226:229], v[166:169], v[44:47]
	v_mfma_f32_16x16x32_bf16 v[36:39], v[218:221], v[174:177], v[36:39]
	v_mfma_f32_16x16x32_bf16 v[28:31], v[226:229], v[174:177], v[28:31]
	v_mfma_f32_16x16x32_bf16 v[20:23], v[218:221], v[182:185], v[20:23]
	v_mfma_f32_16x16x32_bf16 v[12:15], v[226:229], v[182:185], v[12:15]
	v_mfma_f32_16x16x32_bf16 v[4:7], v[218:221], v[210:213], v[4:7]
	v_mfma_f32_16x16x32_bf16 v[0:3], v[226:229], v[210:213], v[0:3]
	s_add_i32 s6, 0, 0x18000
	s_barrier
	v_add_u32_e32 v146, s6, v206
	ds_read_b128 v[128:131], v146
	ds_read_b128 v[132:135], v146 offset:1024
	ds_read_b128 v[136:139], v146 offset:2048
	ds_read_b128 v[146:149], v146 offset:3072
	s_add_u32 s58, s58, 0x40000
	s_addc_u32 s59, s59, 0
	s_mov_b32 m0, s70
	v_lshl_add_u64 v[214:215], s[58:59], 0, v[154:155]
	ds_read_b128 v[162:165], v208 offset:32768
	ds_read_b128 v[166:169], v208 offset:33792
	ds_read_b128 v[170:173], v208 offset:34816
	ds_read_b128 v[174:177], v208 offset:35840
	ds_read_b128 v[178:181], v208 offset:36864
	ds_read_b128 v[182:185], v208 offset:37888
	ds_read_b128 v[194:197], v208 offset:38912
	ds_read_b128 v[210:213], v208 offset:39936
	global_load_lds_dwordx4 v[214:215], off
	v_lshl_add_u64 v[214:215], s[58:59], 0, v[152:153]
	s_mov_b32 m0, s71
	s_nop 0
	global_load_lds_dwordx4 v[214:215], off
	s_add_i32 s19, 0, 0x1c000
	v_add_u32_e32 v192, s19, v206
	ds_read_b128 v[214:217], v192
	ds_read_b128 v[218:221], v192 offset:1024
	ds_read_b128 v[222:225], v192 offset:2048
	ds_read_b128 v[226:229], v192 offset:3072
	s_waitcnt vmcnt(8)
	s_waitcnt lgkmcnt(0)
	s_barrier
	v_mfma_f32_16x16x32_bf16 v[124:127], v[128:131], v[162:165], v[124:127]
	v_mfma_f32_16x16x32_bf16 v[120:123], v[136:139], v[162:165], v[120:123]
	v_mfma_f32_16x16x32_bf16 v[108:111], v[128:131], v[170:173], v[108:111]
	v_mfma_f32_16x16x32_bf16 v[104:107], v[136:139], v[170:173], v[104:107]
	v_mfma_f32_16x16x32_bf16 v[96:99], v[128:131], v[178:181], v[96:99]
	v_mfma_f32_16x16x32_bf16 v[88:91], v[136:139], v[178:181], v[88:91]
	v_mfma_f32_16x16x32_bf16 v[84:87], v[128:131], v[194:197], v[84:87]
	v_mfma_f32_16x16x32_bf16 v[80:83], v[136:139], v[194:197], v[80:83]
	v_mfma_f32_16x16x32_bf16 v[124:127], v[132:135], v[166:169], v[124:127]
	v_mfma_f32_16x16x32_bf16 v[120:123], v[146:149], v[166:169], v[120:123]
	v_mfma_f32_16x16x32_bf16 v[108:111], v[132:135], v[174:177], v[108:111]
	v_mfma_f32_16x16x32_bf16 v[104:107], v[146:149], v[174:177], v[104:107]
	v_mfma_f32_16x16x32_bf16 v[96:99], v[132:135], v[182:185], v[96:99]
	v_mfma_f32_16x16x32_bf16 v[88:91], v[146:149], v[182:185], v[88:91]
	v_mfma_f32_16x16x32_bf16 v[84:87], v[132:135], v[210:213], v[84:87]
	v_mfma_f32_16x16x32_bf16 v[80:83], v[146:149], v[210:213], v[80:83]
	v_mfma_f32_16x16x32_bf16 v[116:119], v[214:217], v[162:165], v[116:119]
	v_mfma_f32_16x16x32_bf16 v[112:115], v[222:225], v[162:165], v[112:115]
	v_mfma_f32_16x16x32_bf16 v[100:103], v[214:217], v[170:173], v[100:103]
	v_mfma_f32_16x16x32_bf16 v[92:95], v[222:225], v[170:173], v[92:95]
	v_mfma_f32_16x16x32_bf16 v[76:79], v[214:217], v[178:181], v[76:79]
	v_mfma_f32_16x16x32_bf16 v[72:75], v[222:225], v[178:181], v[72:75]
	v_mfma_f32_16x16x32_bf16 v[68:71], v[214:217], v[194:197], v[68:71]
	v_mfma_f32_16x16x32_bf16 v[64:67], v[222:225], v[194:197], v[64:67]
	v_mfma_f32_16x16x32_bf16 v[116:119], v[218:221], v[166:169], v[116:119]
	v_mfma_f32_16x16x32_bf16 v[112:115], v[226:229], v[166:169], v[112:115]
	v_mfma_f32_16x16x32_bf16 v[100:103], v[218:221], v[174:177], v[100:103]
	v_mfma_f32_16x16x32_bf16 v[92:95], v[226:229], v[174:177], v[92:95]
	v_mfma_f32_16x16x32_bf16 v[76:79], v[218:221], v[182:185], v[76:79]
	v_mfma_f32_16x16x32_bf16 v[72:75], v[226:229], v[182:185], v[72:75]
	v_mfma_f32_16x16x32_bf16 v[68:71], v[218:221], v[210:213], v[68:71]
	v_mfma_f32_16x16x32_bf16 v[64:67], v[226:229], v[210:213], v[64:67]
	s_add_i32 s6, s6, s57
	v_lshl_add_u64 v[230:231], v[230:231], 0, s[36:37]
	s_mov_b32 m0, s6
	s_barrier
	s_nop 0
	global_load_lds_dwordx4 v[230:231], off
	v_lshl_add_u64 v[230:231], v[232:233], 0, s[36:37]
	s_add_i32 m0, s6, 0x2000
	s_nop 0
	global_load_lds_dwordx4 v[230:231], off
	s_mov_b32 m0, s72
	v_lshl_add_u64 v[230:231], v[234:235], 0, s[36:37]
	ds_read_b128 v[162:165], v208 offset:49152
	ds_read_b128 v[166:169], v208 offset:50176
	ds_read_b128 v[170:173], v208 offset:51200
	ds_read_b128 v[174:177], v208 offset:52224
	ds_read_b128 v[178:181], v208 offset:53248
	ds_read_b128 v[182:185], v208 offset:54272
	ds_read_b128 v[194:197], v208 offset:55296
	ds_read_b128 v[210:213], v208 offset:56320
	global_load_lds_dwordx4 v[230:231], off
	v_lshl_add_u64 v[230:231], v[236:237], 0, s[36:37]
	s_mov_b32 m0, s73
	s_nop 0
	global_load_lds_dwordx4 v[230:231], off
	s_add_u32 s54, s54, 0x40080
	s_addc_u32 s55, s55, 0
	s_add_i32 s6, s19, s57
	v_lshl_add_u64 v[250:251], s[54:55], 0, v[140:141]
	s_mov_b32 m0, s6
	s_nop 0
	global_load_lds_dwordx4 v[250:251], off
	v_lshl_add_u64 v[250:251], s[54:55], 0, v[150:151]
	s_add_i32 m0, s6, 0x2000
	s_nop 0
	global_load_lds_dwordx4 v[250:251], off
	s_waitcnt vmcnt(8)
	s_waitcnt lgkmcnt(0)
	s_barrier
	v_mfma_f32_16x16x32_bf16 v[60:63], v[128:131], v[162:165], v[60:63]
	v_mfma_f32_16x16x32_bf16 v[56:59], v[136:139], v[162:165], v[56:59]
	v_mfma_f32_16x16x32_bf16 v[48:51], v[128:131], v[170:173], v[48:51]
	v_mfma_f32_16x16x32_bf16 v[40:43], v[136:139], v[170:173], v[40:43]
	v_mfma_f32_16x16x32_bf16 v[32:35], v[128:131], v[178:181], v[32:35]
	v_mfma_f32_16x16x32_bf16 v[24:27], v[136:139], v[178:181], v[24:27]
	v_mfma_f32_16x16x32_bf16 v[16:19], v[128:131], v[194:197], v[16:19]
	v_mfma_f32_16x16x32_bf16 v[8:11], v[136:139], v[194:197], v[8:11]
	v_mfma_f32_16x16x32_bf16 v[60:63], v[132:135], v[166:169], v[60:63]
	v_mfma_f32_16x16x32_bf16 v[56:59], v[146:149], v[166:169], v[56:59]
	v_mfma_f32_16x16x32_bf16 v[48:51], v[132:135], v[174:177], v[48:51]
	v_mfma_f32_16x16x32_bf16 v[40:43], v[146:149], v[174:177], v[40:43]
	v_mfma_f32_16x16x32_bf16 v[32:35], v[132:135], v[182:185], v[32:35]
	v_mfma_f32_16x16x32_bf16 v[24:27], v[146:149], v[182:185], v[24:27]
	v_mfma_f32_16x16x32_bf16 v[16:19], v[132:135], v[210:213], v[16:19]
	v_mfma_f32_16x16x32_bf16 v[8:11], v[146:149], v[210:213], v[8:11]
	v_mfma_f32_16x16x32_bf16 v[52:55], v[214:217], v[162:165], v[52:55]
	v_mfma_f32_16x16x32_bf16 v[44:47], v[222:225], v[162:165], v[44:47]
	v_mfma_f32_16x16x32_bf16 v[36:39], v[214:217], v[170:173], v[36:39]
	v_mfma_f32_16x16x32_bf16 v[28:31], v[222:225], v[170:173], v[28:31]
	v_mfma_f32_16x16x32_bf16 v[20:23], v[214:217], v[178:181], v[20:23]
	v_mfma_f32_16x16x32_bf16 v[12:15], v[222:225], v[178:181], v[12:15]
	v_mfma_f32_16x16x32_bf16 v[4:7], v[214:217], v[194:197], v[4:7]
	v_mfma_f32_16x16x32_bf16 v[0:3], v[222:225], v[194:197], v[0:3]
	v_mfma_f32_16x16x32_bf16 v[52:55], v[218:221], v[166:169], v[52:55]
	v_mfma_f32_16x16x32_bf16 v[44:47], v[226:229], v[166:169], v[44:47]
	v_mfma_f32_16x16x32_bf16 v[36:39], v[218:221], v[174:177], v[36:39]
	v_mfma_f32_16x16x32_bf16 v[28:31], v[226:229], v[174:177], v[28:31]
	v_mfma_f32_16x16x32_bf16 v[20:23], v[218:221], v[182:185], v[20:23]
	v_mfma_f32_16x16x32_bf16 v[12:15], v[226:229], v[182:185], v[12:15]
	v_mfma_f32_16x16x32_bf16 v[4:7], v[218:221], v[210:213], v[4:7]
	v_mfma_f32_16x16x32_bf16 v[0:3], v[226:229], v[210:213], v[0:3]
	s_add_i32 s82, s82, 2
	s_add_u32 s52, s52, 0x100
	s_addc_u32 s53, s53, 0
	s_add_u32 s39, s39, 0x100
	s_addc_u32 s51, s51, 0
	s_cmp_gt_u32 s82, 13
	s_add_u32 s6, s52, 0xfffc0080
	s_addc_u32 s19, s53, -1
	s_add_i32 s23, 0, 0x10000
	s_cmp_eq_u32 s82, 12
	s_cselect_b32 s59, s10, s19
	s_cselect_b32 s58, s11, s6
	s_cselect_b32 s55, s12, s51
	s_cselect_b32 s54, s35, s39
my_head_248:
	s_barrier
.LBB0_248:
	v_add_u32_e32 v146, s23, v206
	ds_read_b128 v[128:131], v146
	ds_read_b128 v[132:135], v146 offset:1024
	ds_read_b128 v[136:139], v146 offset:2048
	ds_read_b128 v[146:149], v146 offset:3072
	v_lshl_add_u64 v[214:215], s[52:53], 0, v[158:159]
	s_add_i32 m0, s68, 0xc000
	ds_read_b128 v[162:165], v208
	ds_read_b128 v[166:169], v208 offset:1024
	ds_read_b128 v[170:173], v208 offset:2048
	ds_read_b128 v[174:177], v208 offset:3072
	ds_read_b128 v[178:181], v208 offset:4096
	ds_read_b128 v[182:185], v208 offset:5120
	ds_read_b128 v[194:197], v208 offset:6144
	ds_read_b128 v[210:213], v208 offset:7168
	global_load_lds_dwordx4 v[214:215], off
	v_lshl_add_u64 v[214:215], s[52:53], 0, v[160:161]
	s_add_i32 m0, s68, 0xe000
	s_nop 0
	global_load_lds_dwordx4 v[214:215], off
	s_add_i32 s6, 0, 0x14000
	v_add_u32_e32 v192, s6, v206
	ds_read_b128 v[214:217], v192
	ds_read_b128 v[218:221], v192 offset:1024
	ds_read_b128 v[222:225], v192 offset:2048
	ds_read_b128 v[226:229], v192 offset:3072
	s_nop 0
	s_waitcnt vmcnt(8)
	s_waitcnt lgkmcnt(0)
	s_barrier
	v_mfma_f32_16x16x32_bf16 v[124:127], v[128:131], v[162:165], v[124:127]
	v_mfma_f32_16x16x32_bf16 v[120:123], v[136:139], v[162:165], v[120:123]
	v_mfma_f32_16x16x32_bf16 v[108:111], v[128:131], v[170:173], v[108:111]
	v_mfma_f32_16x16x32_bf16 v[104:107], v[136:139], v[170:173], v[104:107]
	v_mfma_f32_16x16x32_bf16 v[96:99], v[128:131], v[178:181], v[96:99]
	v_mfma_f32_16x16x32_bf16 v[88:91], v[136:139], v[178:181], v[88:91]
	v_mfma_f32_16x16x32_bf16 v[84:87], v[128:131], v[194:197], v[84:87]
	v_mfma_f32_16x16x32_bf16 v[80:83], v[136:139], v[194:197], v[80:83]
	v_mfma_f32_16x16x32_bf16 v[124:127], v[132:135], v[166:169], v[124:127]
	v_mfma_f32_16x16x32_bf16 v[120:123], v[146:149], v[166:169], v[120:123]
	v_mfma_f32_16x16x32_bf16 v[108:111], v[132:135], v[174:177], v[108:111]
	v_mfma_f32_16x16x32_bf16 v[104:107], v[146:149], v[174:177], v[104:107]
	v_mfma_f32_16x16x32_bf16 v[96:99], v[132:135], v[182:185], v[96:99]
	v_mfma_f32_16x16x32_bf16 v[88:91], v[146:149], v[182:185], v[88:91]
	v_mfma_f32_16x16x32_bf16 v[84:87], v[132:135], v[210:213], v[84:87]
	v_mfma_f32_16x16x32_bf16 v[80:83], v[146:149], v[210:213], v[80:83]
	v_mfma_f32_16x16x32_bf16 v[116:119], v[214:217], v[162:165], v[116:119]
	v_mfma_f32_16x16x32_bf16 v[112:115], v[222:225], v[162:165], v[112:115]
	v_mfma_f32_16x16x32_bf16 v[100:103], v[214:217], v[170:173], v[100:103]
	v_mfma_f32_16x16x32_bf16 v[92:95], v[222:225], v[170:173], v[92:95]
	v_mfma_f32_16x16x32_bf16 v[76:79], v[214:217], v[178:181], v[76:79]
	v_mfma_f32_16x16x32_bf16 v[72:75], v[222:225], v[178:181], v[72:75]
	v_mfma_f32_16x16x32_bf16 v[68:71], v[214:217], v[194:197], v[68:71]
	v_mfma_f32_16x16x32_bf16 v[64:67], v[222:225], v[194:197], v[64:67]
	v_mfma_f32_16x16x32_bf16 v[116:119], v[218:221], v[166:169], v[116:119]
	v_mfma_f32_16x16x32_bf16 v[112:115], v[226:229], v[166:169], v[112:115]
	v_mfma_f32_16x16x32_bf16 v[100:103], v[218:221], v[174:177], v[100:103]
	v_mfma_f32_16x16x32_bf16 v[92:95], v[226:229], v[174:177], v[92:95]
	v_mfma_f32_16x16x32_bf16 v[76:79], v[218:221], v[182:185], v[76:79]
	v_mfma_f32_16x16x32_bf16 v[72:75], v[226:229], v[182:185], v[72:75]
	v_mfma_f32_16x16x32_bf16 v[68:71], v[218:221], v[210:213], v[68:71]
	v_mfma_f32_16x16x32_bf16 v[64:67], v[226:229], v[210:213], v[64:67]
	s_add_i32 s19, s23, s57
	v_lshl_add_u64 v[230:231], s[54:55], 0, v[140:141]
	s_mov_b32 m0, s19
	s_barrier
	s_nop 0
	global_load_lds_dwordx4 v[230:231], off
	v_lshl_add_u64 v[232:233], s[54:55], 0, v[150:151]
	s_add_i32 m0, s19, 0x2000
	s_nop 0
	global_load_lds_dwordx4 v[232:233], off
	s_mov_b32 m0, s68
	v_lshl_add_u64 v[234:235], s[58:59], 0, v[154:155]
	ds_read_b128 v[162:165], v208 offset:16384
	ds_read_b128 v[166:169], v208 offset:17408
	ds_read_b128 v[170:173], v208 offset:18432
	ds_read_b128 v[174:177], v208 offset:19456
	ds_read_b128 v[178:181], v208 offset:20480
	ds_read_b128 v[182:185], v208 offset:21504
	ds_read_b128 v[194:197], v208 offset:22528
	ds_read_b128 v[210:213], v208 offset:23552
	global_load_lds_dwordx4 v[234:235], off
	v_lshl_add_u64 v[236:237], s[58:59], 0, v[152:153]
	s_mov_b32 m0, s69
	s_nop 0
	global_load_lds_dwordx4 v[236:237], off
	s_add_u32 s84, s54, 0x40000
	s_addc_u32 s85, s55, 0
	s_add_i32 s6, s6, s57
	v_lshl_add_u64 v[250:251], s[84:85], 0, v[140:141]
	s_mov_b32 m0, s6
	s_nop 0
	global_load_lds_dwordx4 v[250:251], off
	v_lshl_add_u64 v[250:251], s[84:85], 0, v[150:151]
	s_add_i32 m0, s6, 0x2000
	s_nop 0
	global_load_lds_dwordx4 v[250:251], off
	s_waitcnt vmcnt(8)
	s_waitcnt lgkmcnt(0)
	s_barrier
	v_mfma_f32_16x16x32_bf16 v[60:63], v[128:131], v[162:165], v[60:63]
	v_mfma_f32_16x16x32_bf16 v[56:59], v[136:139], v[162:165], v[56:59]
	v_mfma_f32_16x16x32_bf16 v[48:51], v[128:131], v[170:173], v[48:51]
	v_mfma_f32_16x16x32_bf16 v[40:43], v[136:139], v[170:173], v[40:43]
	v_mfma_f32_16x16x32_bf16 v[32:35], v[128:131], v[178:181], v[32:35]
	v_mfma_f32_16x16x32_bf16 v[24:27], v[136:139], v[178:181], v[24:27]
	v_mfma_f32_16x16x32_bf16 v[16:19], v[128:131], v[194:197], v[16:19]
	v_mfma_f32_16x16x32_bf16 v[8:11], v[136:139], v[194:197], v[8:11]
	v_mfma_f32_16x16x32_bf16 v[60:63], v[132:135], v[166:169], v[60:63]
	v_mfma_f32_16x16x32_bf16 v[56:59], v[146:149], v[166:169], v[56:59]
	v_mfma_f32_16x16x32_bf16 v[48:51], v[132:135], v[174:177], v[48:51]
	v_mfma_f32_16x16x32_bf16 v[40:43], v[146:149], v[174:177], v[40:43]
	v_mfma_f32_16x16x32_bf16 v[32:35], v[132:135], v[182:185], v[32:35]
	v_mfma_f32_16x16x32_bf16 v[24:27], v[146:149], v[182:185], v[24:27]
	v_mfma_f32_16x16x32_bf16 v[16:19], v[132:135], v[210:213], v[16:19]
	v_mfma_f32_16x16x32_bf16 v[8:11], v[146:149], v[210:213], v[8:11]
	v_mfma_f32_16x16x32_bf16 v[52:55], v[214:217], v[162:165], v[52:55]
	v_mfma_f32_16x16x32_bf16 v[44:47], v[222:225], v[162:165], v[44:47]
	v_mfma_f32_16x16x32_bf16 v[36:39], v[214:217], v[170:173], v[36:39]
	v_mfma_f32_16x16x32_bf16 v[28:31], v[222:225], v[170:173], v[28:31]
	v_mfma_f32_16x16x32_bf16 v[20:23], v[214:217], v[178:181], v[20:23]
	v_mfma_f32_16x16x32_bf16 v[12:15], v[222:225], v[178:181], v[12:15]
	v_mfma_f32_16x16x32_bf16 v[4:7], v[214:217], v[194:197], v[4:7]
	v_mfma_f32_16x16x32_bf16 v[0:3], v[222:225], v[194:197], v[0:3]
	v_mfma_f32_16x16x32_bf16 v[52:55], v[218:221], v[166:169], v[52:55]
	v_mfma_f32_16x16x32_bf16 v[44:47], v[226:229], v[166:169], v[44:47]
	v_mfma_f32_16x16x32_bf16 v[36:39], v[218:221], v[174:177], v[36:39]
	v_mfma_f32_16x16x32_bf16 v[28:31], v[226:229], v[174:177], v[28:31]
	v_mfma_f32_16x16x32_bf16 v[20:23], v[218:221], v[182:185], v[20:23]
	v_mfma_f32_16x16x32_bf16 v[12:15], v[226:229], v[182:185], v[12:15]
	v_mfma_f32_16x16x32_bf16 v[4:7], v[218:221], v[210:213], v[4:7]
	v_mfma_f32_16x16x32_bf16 v[0:3], v[226:229], v[210:213], v[0:3]
	s_add_i32 s6, 0, 0x18000
	s_barrier
	v_add_u32_e32 v146, s6, v206
	ds_read_b128 v[128:131], v146
	ds_read_b128 v[132:135], v146 offset:1024
	ds_read_b128 v[136:139], v146 offset:2048
	ds_read_b128 v[146:149], v146 offset:3072
	s_add_u32 s58, s58, 0x40000
	s_addc_u32 s59, s59, 0
	s_mov_b32 m0, s70
	v_lshl_add_u64 v[214:215], s[58:59], 0, v[154:155]
	ds_read_b128 v[162:165], v208 offset:32768
	ds_read_b128 v[166:169], v208 offset:33792
	ds_read_b128 v[170:173], v208 offset:34816
	ds_read_b128 v[174:177], v208 offset:35840
	ds_read_b128 v[178:181], v208 offset:36864
	ds_read_b128 v[182:185], v208 offset:37888
	ds_read_b128 v[194:197], v208 offset:38912
	ds_read_b128 v[210:213], v208 offset:39936
	global_load_lds_dwordx4 v[214:215], off
	v_lshl_add_u64 v[214:215], s[58:59], 0, v[152:153]
	s_mov_b32 m0, s71
	s_nop 0
	global_load_lds_dwordx4 v[214:215], off
	s_add_i32 s19, 0, 0x1c000
	v_add_u32_e32 v192, s19, v206
	ds_read_b128 v[214:217], v192
	ds_read_b128 v[218:221], v192 offset:1024
	ds_read_b128 v[222:225], v192 offset:2048
	ds_read_b128 v[226:229], v192 offset:3072
	s_waitcnt vmcnt(8)
	s_waitcnt lgkmcnt(0)
	s_barrier
	v_mfma_f32_16x16x32_bf16 v[124:127], v[128:131], v[162:165], v[124:127]
	v_mfma_f32_16x16x32_bf16 v[120:123], v[136:139], v[162:165], v[120:123]
	v_mfma_f32_16x16x32_bf16 v[108:111], v[128:131], v[170:173], v[108:111]
	v_mfma_f32_16x16x32_bf16 v[104:107], v[136:139], v[170:173], v[104:107]
	v_mfma_f32_16x16x32_bf16 v[96:99], v[128:131], v[178:181], v[96:99]
	v_mfma_f32_16x16x32_bf16 v[88:91], v[136:139], v[178:181], v[88:91]
	v_mfma_f32_16x16x32_bf16 v[84:87], v[128:131], v[194:197], v[84:87]
	v_mfma_f32_16x16x32_bf16 v[80:83], v[136:139], v[194:197], v[80:83]
	v_mfma_f32_16x16x32_bf16 v[124:127], v[132:135], v[166:169], v[124:127]
	v_mfma_f32_16x16x32_bf16 v[120:123], v[146:149], v[166:169], v[120:123]
	v_mfma_f32_16x16x32_bf16 v[108:111], v[132:135], v[174:177], v[108:111]
	v_mfma_f32_16x16x32_bf16 v[104:107], v[146:149], v[174:177], v[104:107]
	v_mfma_f32_16x16x32_bf16 v[96:99], v[132:135], v[182:185], v[96:99]
	v_mfma_f32_16x16x32_bf16 v[88:91], v[146:149], v[182:185], v[88:91]
	v_mfma_f32_16x16x32_bf16 v[84:87], v[132:135], v[210:213], v[84:87]
	v_mfma_f32_16x16x32_bf16 v[80:83], v[146:149], v[210:213], v[80:83]
	v_mfma_f32_16x16x32_bf16 v[116:119], v[214:217], v[162:165], v[116:119]
	v_mfma_f32_16x16x32_bf16 v[112:115], v[222:225], v[162:165], v[112:115]
	v_mfma_f32_16x16x32_bf16 v[100:103], v[214:217], v[170:173], v[100:103]
	v_mfma_f32_16x16x32_bf16 v[92:95], v[222:225], v[170:173], v[92:95]
	v_mfma_f32_16x16x32_bf16 v[76:79], v[214:217], v[178:181], v[76:79]
	v_mfma_f32_16x16x32_bf16 v[72:75], v[222:225], v[178:181], v[72:75]
	v_mfma_f32_16x16x32_bf16 v[68:71], v[214:217], v[194:197], v[68:71]
	v_mfma_f32_16x16x32_bf16 v[64:67], v[222:225], v[194:197], v[64:67]
	v_mfma_f32_16x16x32_bf16 v[116:119], v[218:221], v[166:169], v[116:119]
	v_mfma_f32_16x16x32_bf16 v[112:115], v[226:229], v[166:169], v[112:115]
	v_mfma_f32_16x16x32_bf16 v[100:103], v[218:221], v[174:177], v[100:103]
	v_mfma_f32_16x16x32_bf16 v[92:95], v[226:229], v[174:177], v[92:95]
	v_mfma_f32_16x16x32_bf16 v[76:79], v[218:221], v[182:185], v[76:79]
	v_mfma_f32_16x16x32_bf16 v[72:75], v[226:229], v[182:185], v[72:75]
	v_mfma_f32_16x16x32_bf16 v[68:71], v[218:221], v[210:213], v[68:71]
	v_mfma_f32_16x16x32_bf16 v[64:67], v[226:229], v[210:213], v[64:67]
	s_add_i32 s6, s6, s57
	v_lshl_add_u64 v[230:231], v[230:231], 0, s[36:37]
	s_mov_b32 m0, s6
	s_barrier
	s_nop 0
	global_load_lds_dwordx4 v[230:231], off
	v_lshl_add_u64 v[230:231], v[232:233], 0, s[36:37]
	s_add_i32 m0, s6, 0x2000
	s_nop 0
	global_load_lds_dwordx4 v[230:231], off
	s_mov_b32 m0, s72
	v_lshl_add_u64 v[230:231], v[234:235], 0, s[36:37]
	ds_read_b128 v[162:165], v208 offset:49152
	ds_read_b128 v[166:169], v208 offset:50176
	ds_read_b128 v[170:173], v208 offset:51200
	ds_read_b128 v[174:177], v208 offset:52224
	ds_read_b128 v[178:181], v208 offset:53248
	ds_read_b128 v[182:185], v208 offset:54272
	ds_read_b128 v[194:197], v208 offset:55296
	ds_read_b128 v[210:213], v208 offset:56320
	global_load_lds_dwordx4 v[230:231], off
	v_lshl_add_u64 v[230:231], v[236:237], 0, s[36:37]
	s_mov_b32 m0, s73
	s_nop 0
	global_load_lds_dwordx4 v[230:231], off
	s_add_u32 s54, s54, 0x40080
	s_addc_u32 s55, s55, 0
	s_add_i32 s6, s19, s57
	v_lshl_add_u64 v[250:251], s[54:55], 0, v[140:141]
	s_mov_b32 m0, s6
	s_nop 0
	global_load_lds_dwordx4 v[250:251], off
	v_lshl_add_u64 v[250:251], s[54:55], 0, v[150:151]
	s_add_i32 m0, s6, 0x2000
	s_nop 0
	global_load_lds_dwordx4 v[250:251], off
	s_waitcnt vmcnt(8)
	s_waitcnt lgkmcnt(0)
	s_barrier
	v_mfma_f32_16x16x32_bf16 v[60:63], v[128:131], v[162:165], v[60:63]
	v_mfma_f32_16x16x32_bf16 v[56:59], v[136:139], v[162:165], v[56:59]
	v_mfma_f32_16x16x32_bf16 v[48:51], v[128:131], v[170:173], v[48:51]
	v_mfma_f32_16x16x32_bf16 v[40:43], v[136:139], v[170:173], v[40:43]
	v_mfma_f32_16x16x32_bf16 v[32:35], v[128:131], v[178:181], v[32:35]
	v_mfma_f32_16x16x32_bf16 v[24:27], v[136:139], v[178:181], v[24:27]
	v_mfma_f32_16x16x32_bf16 v[16:19], v[128:131], v[194:197], v[16:19]
	v_mfma_f32_16x16x32_bf16 v[8:11], v[136:139], v[194:197], v[8:11]
	v_mfma_f32_16x16x32_bf16 v[60:63], v[132:135], v[166:169], v[60:63]
	v_mfma_f32_16x16x32_bf16 v[56:59], v[146:149], v[166:169], v[56:59]
	v_mfma_f32_16x16x32_bf16 v[48:51], v[132:135], v[174:177], v[48:51]
	v_mfma_f32_16x16x32_bf16 v[40:43], v[146:149], v[174:177], v[40:43]
	v_mfma_f32_16x16x32_bf16 v[32:35], v[132:135], v[182:185], v[32:35]
	v_mfma_f32_16x16x32_bf16 v[24:27], v[146:149], v[182:185], v[24:27]
	v_mfma_f32_16x16x32_bf16 v[16:19], v[132:135], v[210:213], v[16:19]
	v_mfma_f32_16x16x32_bf16 v[8:11], v[146:149], v[210:213], v[8:11]
	v_mfma_f32_16x16x32_bf16 v[52:55], v[214:217], v[162:165], v[52:55]
	v_mfma_f32_16x16x32_bf16 v[44:47], v[222:225], v[162:165], v[44:47]
	v_mfma_f32_16x16x32_bf16 v[36:39], v[214:217], v[170:173], v[36:39]
	v_mfma_f32_16x16x32_bf16 v[28:31], v[222:225], v[170:173], v[28:31]
	v_mfma_f32_16x16x32_bf16 v[20:23], v[214:217], v[178:181], v[20:23]
	v_mfma_f32_16x16x32_bf16 v[12:15], v[222:225], v[178:181], v[12:15]
	v_mfma_f32_16x16x32_bf16 v[4:7], v[214:217], v[194:197], v[4:7]
	v_mfma_f32_16x16x32_bf16 v[0:3], v[222:225], v[194:197], v[0:3]
	v_mfma_f32_16x16x32_bf16 v[52:55], v[218:221], v[166:169], v[52:55]
	v_mfma_f32_16x16x32_bf16 v[44:47], v[226:229], v[166:169], v[44:47]
	v_mfma_f32_16x16x32_bf16 v[36:39], v[218:221], v[174:177], v[36:39]
	v_mfma_f32_16x16x32_bf16 v[28:31], v[226:229], v[174:177], v[28:31]
	v_mfma_f32_16x16x32_bf16 v[20:23], v[218:221], v[182:185], v[20:23]
	v_mfma_f32_16x16x32_bf16 v[12:15], v[226:229], v[182:185], v[12:15]
	v_mfma_f32_16x16x32_bf16 v[4:7], v[218:221], v[210:213], v[4:7]
	v_mfma_f32_16x16x32_bf16 v[0:3], v[226:229], v[210:213], v[0:3]
	s_add_i32 s82, s82, 2
	s_add_u32 s52, s52, 0x100
	s_addc_u32 s53, s53, 0
	s_add_u32 s39, s39, 0x100
	s_addc_u32 s51, s51, 0
	s_cmp_gt_u32 s82, 13
	s_cbranch_scc1 my_exit_248
	s_add_u32 s6, s52, 0xfffc0080
	s_addc_u32 s19, s53, -1
	s_add_i32 s23, 0, 0x10000
	s_cmp_eq_u32 s82, 12
	s_cselect_b32 s59, s10, s19
	s_cselect_b32 s58, s11, s6
	s_cselect_b32 s55, s12, s51
	s_cselect_b32 s54, s35, s39
	s_branch my_head_248
my_exit_248:
	s_barrier
	s_mov_b32 s100, 1
	s_ashr_i32 s51, s50, 31
	v_lshl_or_b32 v128, s81, 8, v207
	s_lshl_b64 s[10:11], s[50:51], 8
	v_ashrrev_i32_e32 v129, 31, v128
	v_lshl_add_u64 v[168:169], s[10:11], 0, v[156:157]
	v_lshlrev_b64 v[170:171], 1, v[128:129]
	v_lshl_add_u64 v[174:175], s[28:29], 0, v[170:171]
	v_lshlrev_b64 v[172:173], 11, v[168:169]
	v_lshl_add_u64 v[128:129], v[174:175], 0, v[172:173]
	global_load_dwordx4 v[146:149], v[128:129], off
	global_load_dwordx4 v[182:185], v[128:129], off offset:256
	v_or_b32_e32 v166, 16, v168
	v_mov_b32_e32 v167, v169
	v_lshlrev_b64 v[176:177], 11, v[166:167]
	v_lshl_add_u64 v[128:129], v[174:175], 0, v[176:177]
	global_load_dwordx4 v[194:197], v[128:129], off
	global_load_dwordx4 v[210:213], v[128:129], off offset:256
	v_or_b32_e32 v164, 32, v168
	v_mov_b32_e32 v165, v169
	v_or_b32_e32 v162, 48, v168
	v_mov_b32_e32 v163, v169
	v_lshlrev_b64 v[180:181], 11, v[164:165]
	v_lshlrev_b64 v[178:179], 11, v[162:163]
	v_lshl_add_u64 v[128:129], v[174:175], 0, v[180:181]
	v_lshl_add_u64 v[130:131], v[174:175], 0, v[178:179]
	global_load_dwordx4 v[214:217], v[128:129], off
	global_load_dwordx4 v[136:139], v[128:129], off offset:256
	global_load_dwordx4 v[132:135], v[130:131], off
	s_nop 0
	global_load_dwordx4 v[128:131], v[130:131], off offset:256
	s_mov_b64 s[10:11], 0x90
	v_lshl_add_u64 v[172:173], s[30:31], 0, v[172:173]
	v_lshl_add_u64 v[172:173], v[172:173], 0, v[170:171]
	s_waitcnt vmcnt(0)
	v_lshlrev_b32_e32 v218, 16, v146
	v_and_b32_e32 v219, 0xffff0000, v146
	v_lshlrev_b32_e32 v220, 16, v148
	v_and_b32_e32 v221, 0xffff0000, v148
	v_lshlrev_b32_e32 v146, 16, v147
	v_and_b32_e32 v147, 0xffff0000, v147
	v_lshlrev_b32_e32 v222, 16, v182
	v_and_b32_e32 v223, 0xffff0000, v182
	v_lshlrev_b32_e32 v224, 16, v184
	v_and_b32_e32 v225, 0xffff0000, v184
	v_lshlrev_b32_e32 v182, 16, v183
	v_and_b32_e32 v183, 0xffff0000, v183
	v_pk_add_f32 v[124:125], v[124:125], v[218:219]
	v_pk_add_f32 v[120:121], v[120:121], v[220:221]
	v_pk_add_f32 v[126:127], v[126:127], v[146:147]
	v_pk_add_f32 v[116:117], v[116:117], v[222:223]
	v_pk_add_f32 v[146:147], v[112:113], v[224:225]
	v_pk_add_f32 v[118:119], v[118:119], v[182:183]
	v_pk_mul_f32 v[220:221], v[124:125], v[124:125]
	v_pk_mul_f32 v[222:223], v[126:127], v[126:127]
	v_cvt_pk_bf16_f32 v112, v124, v125
	v_cvt_pk_bf16_f32 v113, v126, v127
	v_pk_mul_f32 v[124:125], v[116:117], v[116:117]
	v_pk_mul_f32 v[126:127], v[118:119], v[118:119]
	v_pk_mul_f32 v[228:229], v[146:147], v[146:147]
	v_cvt_pk_bf16_f32 v116, v116, v117
	v_cvt_pk_bf16_f32 v117, v118, v119
	v_cvt_pk_bf16_f32 v118, v146, v147
	v_add_f32_e32 v146, v220, v221
	v_add_f32_e32 v146, v222, v146
	v_lshlrev_b32_e32 v148, 16, v149
	v_and_b32_e32 v149, 0xffff0000, v149
	v_pk_mul_f32 v[224:225], v[120:121], v[120:121]
	v_add_f32_e32 v146, v223, v146
	v_pk_add_f32 v[122:123], v[122:123], v[148:149]
	v_add_f32_e32 v146, v224, v146
	v_pk_mul_f32 v[226:227], v[122:123], v[122:123]
	v_add_f32_e32 v146, v225, v146
	v_add_f32_e32 v146, v226, v146
	v_add_f32_e32 v146, v227, v146
	v_add_f32_e32 v124, v124, v146
	v_add_f32_e32 v124, v125, v124
	v_add_f32_e32 v124, v126, v124
	v_lshlrev_b32_e32 v184, 16, v185
	v_and_b32_e32 v185, 0xffff0000, v185
	v_add_f32_e32 v124, v127, v124
	v_pk_add_f32 v[148:149], v[114:115], v[184:185]
	v_add_f32_e32 v124, v228, v124
	v_pk_mul_f32 v[230:231], v[148:149], v[148:149]
	v_add_f32_e32 v124, v229, v124
	v_add_f32_e32 v124, v230, v124
	v_add_f32_e32 v209, v231, v124
	v_lshlrev_b32_e32 v124, 16, v212
	v_and_b32_e32 v125, 0xffff0000, v212
	v_pk_add_f32 v[124:125], v[92:93], v[124:125]
	v_lshlrev_b32_e32 v92, 16, v211
	v_and_b32_e32 v93, 0xffff0000, v211
	v_pk_add_f32 v[102:103], v[102:103], v[92:93]
	v_lshlrev_b32_e32 v92, 16, v213
	v_and_b32_e32 v93, 0xffff0000, v213
	v_pk_add_f32 v[126:127], v[94:95], v[92:93]
	v_lshlrev_b32_e32 v92, 16, v214
	v_and_b32_e32 v93, 0xffff0000, v214
	v_pk_add_f32 v[92:93], v[96:97], v[92:93]
	v_lshlrev_b32_e32 v96, 16, v217
	v_and_b32_e32 v97, 0xffff0000, v217
	v_lshlrev_b32_e32 v94, 16, v216
	v_and_b32_e32 v95, 0xffff0000, v216
	v_pk_add_f32 v[90:91], v[90:91], v[96:97]
	v_lshlrev_b32_e32 v96, 16, v136
	v_and_b32_e32 v97, 0xffff0000, v136
	v_lshlrev_b32_e32 v182, 16, v194
	v_and_b32_e32 v183, 0xffff0000, v194
	v_pk_add_f32 v[88:89], v[88:89], v[94:95]
	v_lshlrev_b32_e32 v94, 16, v215
	v_and_b32_e32 v95, 0xffff0000, v215
	v_pk_add_f32 v[96:97], v[76:77], v[96:97]
	v_lshl_add_u64 v[76:77], v[168:169], 0, s[36:37]
	v_lshlrev_b32_e32 v184, 16, v196
	v_and_b32_e32 v185, 0xffff0000, v196
	v_cvt_pk_bf16_f32 v114, v120, v121
	v_pk_add_f32 v[120:121], v[108:109], v[182:183]
	v_pk_add_f32 v[94:95], v[98:99], v[94:95]
	v_lshlrev_b64 v[182:183], 11, v[76:77]
	v_lshlrev_b32_e32 v98, 16, v138
	v_and_b32_e32 v99, 0xffff0000, v138
	v_pk_add_f32 v[108:109], v[104:105], v[184:185]
	v_lshl_add_u64 v[184:185], v[174:175], 0, v[182:183]
	v_pk_add_f32 v[98:99], v[72:73], v[98:99]
	v_lshlrev_b32_e32 v72, 16, v137
	v_and_b32_e32 v73, 0xffff0000, v137
	v_lshlrev_b32_e32 v218, 16, v210
	v_and_b32_e32 v219, 0xffff0000, v210
	global_load_dwordx4 v[210:213], v[184:185], off
	v_pk_add_f32 v[136:137], v[78:79], v[72:73]
	v_lshlrev_b32_e32 v72, 16, v139
	v_and_b32_e32 v73, 0xffff0000, v139
	v_pk_add_f32 v[138:139], v[74:75], v[72:73]
	v_lshlrev_b32_e32 v72, 16, v132
	v_and_b32_e32 v73, 0xffff0000, v132
	v_pk_add_f32 v[74:75], v[84:85], v[72:73]
	v_lshlrev_b32_e32 v72, 16, v134
	v_and_b32_e32 v73, 0xffff0000, v134
	v_pk_add_f32 v[78:79], v[80:81], v[72:73]
	v_lshlrev_b32_e32 v72, 16, v133
	v_and_b32_e32 v73, 0xffff0000, v133
	v_pk_add_f32 v[100:101], v[100:101], v[218:219]
	global_load_dwordx4 v[218:221], v[184:185], off offset:256
	v_pk_add_f32 v[80:81], v[86:87], v[72:73]
	v_lshlrev_b32_e32 v72, 16, v135
	v_and_b32_e32 v73, 0xffff0000, v135
	v_pk_add_f32 v[82:83], v[82:83], v[72:73]
	v_lshl_add_u64 v[72:73], v[168:169], 0, s[10:11]
	v_lshlrev_b64 v[132:133], 11, v[72:73]
	v_lshl_add_u64 v[134:135], v[174:175], 0, v[132:133]
	v_lshlrev_b32_e32 v84, 16, v128
	v_and_b32_e32 v85, 0xffff0000, v128
	global_load_dwordx4 v[226:229], v[134:135], off
	global_load_dwordx4 v[234:237], v[134:135], off offset:256
	v_pk_add_f32 v[84:85], v[68:69], v[84:85]
	v_lshlrev_b32_e32 v68, 16, v130
	v_and_b32_e32 v69, 0xffff0000, v130
	v_pk_add_f32 v[86:87], v[64:65], v[68:69]
	v_lshlrev_b32_e32 v64, 16, v129
	v_and_b32_e32 v65, 0xffff0000, v129
	s_mov_b64 s[10:11], 0xa0
	v_pk_add_f32 v[128:129], v[70:71], v[64:65]
	v_lshl_add_u64 v[70:71], v[168:169], 0, s[10:11]
	s_mov_b64 s[10:11], 0xb0
	v_lshlrev_b32_e32 v64, 16, v131
	v_and_b32_e32 v65, 0xffff0000, v131
	v_lshlrev_b64 v[134:135], 11, v[70:71]
	v_lshl_add_u64 v[68:69], v[168:169], 0, s[10:11]
	v_pk_add_f32 v[130:131], v[66:67], v[64:65]
	v_lshl_add_u64 v[64:65], v[174:175], 0, v[134:135]
	v_lshlrev_b64 v[184:185], 11, v[68:69]
	global_load_dwordx4 v[238:241], v[64:65], off
	global_load_dwordx4 v[242:245], v[64:65], off offset:256
	v_lshl_add_u64 v[64:65], v[174:175], 0, v[184:185]
	global_load_dwordx4 v[246:249], v[64:65], off
	s_nop 0
	global_load_dwordx4 v[64:67], v[64:65], off offset:256
	v_lshlrev_b32_e32 v194, 16, v195
	v_and_b32_e32 v195, 0xffff0000, v195
	v_lshlrev_b32_e32 v196, 16, v197
	v_and_b32_e32 v197, 0xffff0000, v197
	v_cvt_pk_bf16_f32 v115, v122, v123
	v_cvt_pk_bf16_f32 v119, v148, v149
	v_pk_add_f32 v[122:123], v[110:111], v[194:195]
	v_pk_add_f32 v[110:111], v[106:107], v[196:197]
	global_store_dwordx4 v[172:173], v[112:115], off
	global_store_dwordx4 v[172:173], v[116:119], off offset:256
	v_cvt_pk_bf16_f32 v104, v120, v121
	v_lshl_add_u64 v[112:113], s[30:31], 0, v[176:177]
	v_cvt_pk_bf16_f32 v105, v122, v123
	v_cvt_pk_bf16_f32 v106, v108, v109
	v_cvt_pk_bf16_f32 v107, v110, v111
	v_lshl_add_u64 v[112:113], v[112:113], 0, v[170:171]
	v_cvt_pk_bf16_f32 v146, v100, v101
	v_cvt_pk_bf16_f32 v147, v102, v103
	v_cvt_pk_bf16_f32 v148, v124, v125
	v_cvt_pk_bf16_f32 v149, v126, v127
	global_store_dwordx4 v[112:113], v[104:107], off
	global_store_dwordx4 v[112:113], v[146:149], off offset:256
	v_cvt_pk_bf16_f32 v194, v92, v93
	v_lshl_add_u64 v[104:105], s[30:31], 0, v[180:181]
	v_cvt_pk_bf16_f32 v195, v94, v95
	v_cvt_pk_bf16_f32 v196, v88, v89
	v_cvt_pk_bf16_f32 v197, v90, v91
	v_lshl_add_u64 v[104:105], v[104:105], 0, v[170:171]
	v_cvt_pk_bf16_f32 v214, v96, v97
	v_cvt_pk_bf16_f32 v215, v136, v137
	v_cvt_pk_bf16_f32 v216, v98, v99
	v_cvt_pk_bf16_f32 v217, v138, v139
	global_store_dwordx4 v[104:105], v[194:197], off
	global_store_dwordx4 v[104:105], v[214:217], off offset:256
	v_lshl_add_u64 v[104:105], s[30:31], 0, v[178:179]
	v_cvt_pk_bf16_f32 v222, v74, v75
	v_cvt_pk_bf16_f32 v223, v80, v81
	v_cvt_pk_bf16_f32 v224, v78, v79
	v_cvt_pk_bf16_f32 v225, v82, v83
	v_lshl_add_u64 v[104:105], v[104:105], 0, v[170:171]
	v_cvt_pk_bf16_f32 v230, v84, v85
	v_cvt_pk_bf16_f32 v231, v128, v129
	v_cvt_pk_bf16_f32 v232, v86, v87
	v_cvt_pk_bf16_f32 v233, v130, v131
	global_store_dwordx4 v[104:105], v[222:225], off
	global_store_dwordx4 v[104:105], v[230:233], off offset:256
	s_waitcnt vmcnt(0)
	v_lshlrev_b32_e32 v104, 16, v210
	v_and_b32_e32 v105, 0xffff0000, v210
	v_pk_add_f32 v[60:61], v[60:61], v[104:105]
	v_lshlrev_b32_e32 v104, 16, v212
	v_and_b32_e32 v105, 0xffff0000, v212
	v_pk_add_f32 v[56:57], v[56:57], v[104:105]
	v_lshlrev_b32_e32 v104, 16, v211
	v_and_b32_e32 v105, 0xffff0000, v211
	v_pk_add_f32 v[62:63], v[62:63], v[104:105]
	v_lshlrev_b32_e32 v104, 16, v213
	v_and_b32_e32 v105, 0xffff0000, v213
	v_pk_add_f32 v[58:59], v[58:59], v[104:105]
	v_lshlrev_b32_e32 v104, 16, v218
	v_and_b32_e32 v105, 0xffff0000, v218
	v_pk_add_f32 v[52:53], v[52:53], v[104:105]
	v_lshlrev_b32_e32 v104, 16, v220
	v_and_b32_e32 v105, 0xffff0000, v220
	v_pk_add_f32 v[104:105], v[44:45], v[104:105]
	v_lshlrev_b32_e32 v44, 16, v219
	v_and_b32_e32 v45, 0xffff0000, v219
	v_pk_add_f32 v[54:55], v[54:55], v[44:45]
	v_lshlrev_b32_e32 v44, 16, v221
	v_and_b32_e32 v45, 0xffff0000, v221
	v_pk_add_f32 v[106:107], v[46:47], v[44:45]
	v_lshlrev_b32_e32 v44, 16, v226
	v_and_b32_e32 v45, 0xffff0000, v226
	v_pk_add_f32 v[44:45], v[48:49], v[44:45]
	v_lshlrev_b32_e32 v48, 16, v229
	v_and_b32_e32 v49, 0xffff0000, v229
	v_pk_add_f32 v[42:43], v[42:43], v[48:49]
	v_lshlrev_b32_e32 v48, 16, v234
	v_and_b32_e32 v49, 0xffff0000, v234
	v_pk_add_f32 v[36:37], v[36:37], v[48:49]
	v_lshlrev_b32_e32 v48, 16, v236
	v_and_b32_e32 v49, 0xffff0000, v236
	v_lshlrev_b32_e32 v46, 16, v228
	v_and_b32_e32 v47, 0xffff0000, v228
	v_pk_add_f32 v[48:49], v[28:29], v[48:49]
	v_lshlrev_b32_e32 v28, 16, v235
	v_and_b32_e32 v29, 0xffff0000, v235
	v_pk_add_f32 v[40:41], v[40:41], v[46:47]
	v_lshlrev_b32_e32 v46, 16, v227
	v_and_b32_e32 v47, 0xffff0000, v227
	v_pk_add_f32 v[38:39], v[38:39], v[28:29]
	v_lshlrev_b32_e32 v28, 16, v237
	v_and_b32_e32 v29, 0xffff0000, v237
	v_pk_add_f32 v[46:47], v[50:51], v[46:47]
	v_pk_add_f32 v[50:51], v[30:31], v[28:29]
	v_lshlrev_b32_e32 v28, 16, v238
	v_and_b32_e32 v29, 0xffff0000, v238
	v_lshlrev_b32_e32 v180, 16, v64
	v_and_b32_e32 v181, 0xffff0000, v64
	v_pk_add_f32 v[28:29], v[32:33], v[28:29]
	v_lshlrev_b32_e32 v32, 16, v241
	v_and_b32_e32 v33, 0xffff0000, v241
	v_pk_add_f32 v[4:5], v[4:5], v[180:181]
	v_lshlrev_b32_e32 v180, 16, v66
	v_and_b32_e32 v181, 0xffff0000, v66
	v_pk_add_f32 v[26:27], v[26:27], v[32:33]
	v_lshlrev_b32_e32 v32, 16, v242
	v_and_b32_e32 v33, 0xffff0000, v242
	v_pk_add_f32 v[0:1], v[0:1], v[180:181]
	v_lshl_add_u64 v[180:181], s[30:31], 0, v[182:183]
	v_cvt_pk_bf16_f32 v112, v60, v61
	v_cvt_pk_bf16_f32 v113, v62, v63
	v_cvt_pk_bf16_f32 v114, v56, v57
	v_cvt_pk_bf16_f32 v115, v58, v59
	v_pk_add_f32 v[20:21], v[20:21], v[32:33]
	v_lshlrev_b32_e32 v32, 16, v244
	v_and_b32_e32 v33, 0xffff0000, v244
	v_lshl_add_u64 v[180:181], v[180:181], 0, v[170:171]
	v_cvt_pk_bf16_f32 v116, v52, v53
	v_cvt_pk_bf16_f32 v117, v54, v55
	v_cvt_pk_bf16_f32 v118, v104, v105
	v_cvt_pk_bf16_f32 v119, v106, v107
	v_lshlrev_b32_e32 v30, 16, v240
	v_and_b32_e32 v31, 0xffff0000, v240
	v_pk_add_f32 v[32:33], v[12:13], v[32:33]
	v_lshlrev_b32_e32 v12, 16, v243
	v_and_b32_e32 v13, 0xffff0000, v243
	global_store_dwordx4 v[180:181], v[112:115], off
	global_store_dwordx4 v[180:181], v[116:119], off offset:256
	v_cvt_pk_bf16_f32 v146, v44, v45
	v_lshl_add_u64 v[112:113], s[30:31], 0, v[132:133]
	v_cvt_pk_bf16_f32 v147, v46, v47
	v_cvt_pk_bf16_f32 v148, v40, v41
	v_cvt_pk_bf16_f32 v149, v42, v43
	v_pk_add_f32 v[24:25], v[24:25], v[30:31]
	v_lshlrev_b32_e32 v30, 16, v239
	v_and_b32_e32 v31, 0xffff0000, v239
	v_pk_add_f32 v[22:23], v[22:23], v[12:13]
	v_lshlrev_b32_e32 v12, 16, v245
	v_and_b32_e32 v13, 0xffff0000, v245
	v_lshl_add_u64 v[112:113], v[112:113], 0, v[170:171]
	v_cvt_pk_bf16_f32 v172, v36, v37
	v_cvt_pk_bf16_f32 v173, v38, v39
	v_cvt_pk_bf16_f32 v174, v48, v49
	v_cvt_pk_bf16_f32 v175, v50, v51
	v_pk_add_f32 v[30:31], v[34:35], v[30:31]
	v_pk_add_f32 v[34:35], v[14:15], v[12:13]
	v_lshlrev_b32_e32 v12, 16, v246
	v_and_b32_e32 v13, 0xffff0000, v246
	v_lshlrev_b32_e32 v14, 16, v248
	v_and_b32_e32 v15, 0xffff0000, v248
	global_store_dwordx4 v[112:113], v[146:149], off
	global_store_dwordx4 v[112:113], v[172:175], off offset:256
	v_lshl_add_u64 v[112:113], s[30:31], 0, v[134:135]
	v_cvt_pk_bf16_f32 v176, v28, v29
	v_cvt_pk_bf16_f32 v177, v30, v31
	v_cvt_pk_bf16_f32 v178, v24, v25
	v_cvt_pk_bf16_f32 v179, v26, v27
	v_pk_add_f32 v[12:13], v[16:17], v[12:13]
	v_pk_add_f32 v[8:9], v[8:9], v[14:15]
	v_lshlrev_b32_e32 v14, 16, v247
	v_and_b32_e32 v15, 0xffff0000, v247
	v_lshlrev_b32_e32 v16, 16, v249
	v_and_b32_e32 v17, 0xffff0000, v249
	v_lshlrev_b32_e32 v64, 16, v65
	v_and_b32_e32 v65, 0xffff0000, v65
	v_lshl_add_u64 v[112:113], v[112:113], 0, v[170:171]
	v_cvt_pk_bf16_f32 v194, v20, v21
	v_cvt_pk_bf16_f32 v195, v22, v23
	v_cvt_pk_bf16_f32 v196, v32, v33
	v_cvt_pk_bf16_f32 v197, v34, v35
	v_pk_add_f32 v[14:15], v[18:19], v[14:15]
	v_pk_add_f32 v[10:11], v[10:11], v[16:17]
	v_pk_add_f32 v[6:7], v[6:7], v[64:65]
	v_lshlrev_b32_e32 v64, 16, v67
	v_and_b32_e32 v65, 0xffff0000, v67
	global_store_dwordx4 v[112:113], v[176:179], off
	global_store_dwordx4 v[112:113], v[194:197], off offset:256
	v_lshl_add_u64 v[112:113], s[30:31], 0, v[184:185]
	v_cvt_pk_bf16_f32 v16, v12, v13
	v_cvt_pk_bf16_f32 v17, v14, v15
	v_cvt_pk_bf16_f32 v18, v8, v9
	v_cvt_pk_bf16_f32 v19, v10, v11
	v_pk_add_f32 v[2:3], v[2:3], v[64:65]
	v_lshl_add_u64 v[112:113], v[112:113], 0, v[170:171]
	v_cvt_pk_bf16_f32 v64, v4, v5
	v_cvt_pk_bf16_f32 v65, v6, v7
	v_cvt_pk_bf16_f32 v66, v0, v1
	v_cvt_pk_bf16_f32 v67, v2, v3
	global_store_dwordx4 v[112:113], v[16:19], off
	global_store_dwordx4 v[112:113], v[64:67], off offset:256
	s_lshl_b32 s10, s81, 2
	v_and_b32_e32 v17, 64, v188
	v_xor_b32_e32 v16, 16, v188
	v_add_u32_e32 v17, 64, v17
	v_cmp_lt_i32_e32 vcc, v16, v17
	v_xor_b32_e32 v18, 32, v188
	s_ashr_i32 s11, s10, 31
	v_cndmask_b32_e32 v16, v188, v16, vcc
	v_lshlrev_b32_e32 v16, 2, v16
	ds_bpermute_b32 v19, v16, v209
	v_cmp_lt_i32_e32 vcc, v18, v17
	s_lshl_b64 s[10:11], s[10:11], 2
	s_add_u32 s50, s75, s10
	v_cndmask_b32_e32 v17, v188, v18, vcc
	v_lshlrev_b32_e32 v17, 2, v17
	s_waitcnt lgkmcnt(0)
	v_add_f32_e32 v18, v209, v19
	ds_bpermute_b32 v19, v17, v18
	s_addc_u32 s51, s80, s11
	s_and_saveexec_b64 s[52:53], s[42:43]
	s_cbranch_execz .LBB0_251
	s_waitcnt lgkmcnt(0)
	v_add_f32_e32 v64, v18, v19
	v_lshlrev_b64 v[18:19], 6, v[168:169]
	v_lshl_add_u64 v[18:19], s[50:51], 0, v[18:19]
	global_store_dword v[18:19], v64, off

.Lm4ap_295:
	s_waitcnt lgkmcnt(0)
	s_barrier
	v_mfma_f32_16x16x32_bf16 v[124:127], v[146:149], v[170:173], 0
	v_mfma_f32_16x16x32_bf16 v[120:123], v[162:165], v[170:173], 0
	v_mfma_f32_16x16x32_bf16 v[116:119], v[146:149], v[178:181], 0
	v_mfma_f32_16x16x32_bf16 v[112:115], v[162:165], v[178:181], 0
	v_mfma_f32_16x16x32_bf16 v[108:111], v[146:149], v[194:197], 0
	v_mfma_f32_16x16x32_bf16 v[104:107], v[162:165], v[194:197], 0
	v_mfma_f32_16x16x32_bf16 v[100:103], v[146:149], v[210:213], 0
	v_mfma_f32_16x16x32_bf16 v[96:99], v[162:165], v[210:213], 0
	v_mfma_f32_16x16x32_bf16 v[124:127], v[158:161], v[174:177], v[124:127]
	v_mfma_f32_16x16x32_bf16 v[120:123], v[166:169], v[174:177], v[120:123]
	v_mfma_f32_16x16x32_bf16 v[116:119], v[158:161], v[182:185], v[116:119]
	v_mfma_f32_16x16x32_bf16 v[112:115], v[166:169], v[182:185], v[112:115]
	v_mfma_f32_16x16x32_bf16 v[108:111], v[158:161], v[206:209], v[108:111]
	v_mfma_f32_16x16x32_bf16 v[104:107], v[166:169], v[206:209], v[104:107]
	v_mfma_f32_16x16x32_bf16 v[100:103], v[158:161], v[214:217], v[100:103]
	v_mfma_f32_16x16x32_bf16 v[96:99], v[166:169], v[214:217], v[96:99]
	v_mfma_f32_16x16x32_bf16 v[92:95], v[218:221], v[170:173], 0
	v_mfma_f32_16x16x32_bf16 v[88:91], v[226:229], v[170:173], 0
	v_mfma_f32_16x16x32_bf16 v[84:87], v[218:221], v[178:181], 0
	v_mfma_f32_16x16x32_bf16 v[80:83], v[226:229], v[178:181], 0
	v_mfma_f32_16x16x32_bf16 v[76:79], v[218:221], v[194:197], 0
	v_mfma_f32_16x16x32_bf16 v[72:75], v[226:229], v[194:197], 0
	v_mfma_f32_16x16x32_bf16 v[68:71], v[218:221], v[210:213], 0
	v_mfma_f32_16x16x32_bf16 v[64:67], v[226:229], v[210:213], 0
	v_mfma_f32_16x16x32_bf16 v[92:95], v[222:225], v[174:177], v[92:95]
	v_mfma_f32_16x16x32_bf16 v[88:91], v[230:233], v[174:177], v[88:91]
	v_mfma_f32_16x16x32_bf16 v[84:87], v[222:225], v[182:185], v[84:87]
	v_mfma_f32_16x16x32_bf16 v[80:83], v[230:233], v[182:185], v[80:83]
	v_mfma_f32_16x16x32_bf16 v[76:79], v[222:225], v[206:209], v[76:79]
	v_mfma_f32_16x16x32_bf16 v[72:75], v[230:233], v[206:209], v[72:75]
	v_mfma_f32_16x16x32_bf16 v[68:71], v[222:225], v[214:217], v[68:71]
	v_mfma_f32_16x16x32_bf16 v[64:67], v[230:233], v[214:217], v[64:67]
	s_add_i32 s19, s80, s57
	v_lshl_add_u64 v[234:235], s[50:51], 0, v[140:141]
	s_mov_b32 m0, s19
	s_barrier
	s_nop 0
	global_load_lds_dwordx4 v[234:235], off
	v_lshl_add_u64 v[236:237], s[50:51], 0, v[132:133]
	s_add_i32 m0, s19, 0x2000
	s_nop 0
	global_load_lds_dwordx4 v[236:237], off
	s_mov_b32 m0, s58
	v_lshl_add_u64 v[238:239], s[52:53], 0, v[128:129]
	ds_read_b128 v[170:173], v157 offset:16384
	ds_read_b128 v[174:177], v157 offset:17408
	ds_read_b128 v[178:181], v157 offset:18432
	ds_read_b128 v[182:185], v157 offset:19456
	ds_read_b128 v[194:197], v157 offset:20480
	ds_read_b128 v[206:209], v157 offset:21504
	ds_read_b128 v[210:213], v157 offset:22528
	ds_read_b128 v[214:217], v157 offset:23552
	global_load_lds_dwordx4 v[238:239], off
	v_lshl_add_u64 v[240:241], s[52:53], 0, v[130:131]
	s_mov_b32 m0, s59
	s_nop 0
	global_load_lds_dwordx4 v[240:241], off
	s_add_u32 s80, s50, 0x40000
	s_addc_u32 s81, s51, 0
	s_add_i32 s6, s6, s57
	v_lshl_add_u64 v[250:251], s[80:81], 0, v[140:141]
	s_mov_b32 m0, s6
	s_nop 0
	global_load_lds_dwordx4 v[250:251], off
	v_lshl_add_u64 v[250:251], s[80:81], 0, v[132:133]
	s_add_i32 m0, s6, 0x2000
	s_nop 0
	global_load_lds_dwordx4 v[250:251], off
	s_waitcnt vmcnt(24)
	s_cmp_lg_u32 s100, 0
	s_cbranch_scc1 .Lm4bp_295
	s_waitcnt vmcnt(8)
.Lm4bp_295:
	s_waitcnt lgkmcnt(0)
	s_mov_b32 s100, 0
	s_barrier
	v_mfma_f32_16x16x32_bf16 v[60:63], v[146:149], v[170:173], 0
	v_mfma_f32_16x16x32_bf16 v[56:59], v[162:165], v[170:173], 0
	v_mfma_f32_16x16x32_bf16 v[52:55], v[146:149], v[178:181], 0
	v_mfma_f32_16x16x32_bf16 v[48:51], v[162:165], v[178:181], 0
	v_mfma_f32_16x16x32_bf16 v[44:47], v[146:149], v[194:197], 0
	v_mfma_f32_16x16x32_bf16 v[40:43], v[162:165], v[194:197], 0
	v_mfma_f32_16x16x32_bf16 v[36:39], v[146:149], v[210:213], 0
	v_mfma_f32_16x16x32_bf16 v[32:35], v[162:165], v[210:213], 0
	v_mfma_f32_16x16x32_bf16 v[60:63], v[158:161], v[174:177], v[60:63]
	v_mfma_f32_16x16x32_bf16 v[56:59], v[166:169], v[174:177], v[56:59]
	v_mfma_f32_16x16x32_bf16 v[52:55], v[158:161], v[182:185], v[52:55]
	v_mfma_f32_16x16x32_bf16 v[48:51], v[166:169], v[182:185], v[48:51]
	v_mfma_f32_16x16x32_bf16 v[44:47], v[158:161], v[206:209], v[44:47]
	v_mfma_f32_16x16x32_bf16 v[40:43], v[166:169], v[206:209], v[40:43]
	v_mfma_f32_16x16x32_bf16 v[36:39], v[158:161], v[214:217], v[36:39]
	v_mfma_f32_16x16x32_bf16 v[32:35], v[166:169], v[214:217], v[32:35]
	v_mfma_f32_16x16x32_bf16 v[28:31], v[218:221], v[170:173], 0
	v_mfma_f32_16x16x32_bf16 v[24:27], v[226:229], v[170:173], 0
	v_mfma_f32_16x16x32_bf16 v[20:23], v[218:221], v[178:181], 0
	v_mfma_f32_16x16x32_bf16 v[16:19], v[226:229], v[178:181], 0
	v_mfma_f32_16x16x32_bf16 v[12:15], v[218:221], v[194:197], 0
	v_mfma_f32_16x16x32_bf16 v[8:11], v[226:229], v[194:197], 0
	v_mfma_f32_16x16x32_bf16 v[4:7], v[218:221], v[210:213], 0
	v_mfma_f32_16x16x32_bf16 v[0:3], v[226:229], v[210:213], 0
	v_mfma_f32_16x16x32_bf16 v[28:31], v[222:225], v[174:177], v[28:31]
	v_mfma_f32_16x16x32_bf16 v[24:27], v[230:233], v[174:177], v[24:27]
	v_mfma_f32_16x16x32_bf16 v[20:23], v[222:225], v[182:185], v[20:23]
	v_mfma_f32_16x16x32_bf16 v[16:19], v[230:233], v[182:185], v[16:19]
	v_mfma_f32_16x16x32_bf16 v[12:15], v[222:225], v[206:209], v[12:15]
	v_mfma_f32_16x16x32_bf16 v[8:11], v[230:233], v[206:209], v[8:11]
	v_mfma_f32_16x16x32_bf16 v[4:7], v[222:225], v[214:217], v[4:7]
	v_mfma_f32_16x16x32_bf16 v[0:3], v[230:233], v[214:217], v[0:3]
	s_add_i32 s6, 0, 0x18000
	s_barrier
	v_add_u32_e32 v166, s6, v154
	ds_read_b128 v[146:149], v166
	ds_read_b128 v[158:161], v166 offset:1024
	ds_read_b128 v[162:165], v166 offset:2048
	ds_read_b128 v[166:169], v166 offset:3072
	s_add_u32 s52, s52, 0x40000
	s_addc_u32 s53, s53, 0
	s_mov_b32 m0, s68
	v_lshl_add_u64 v[218:219], s[52:53], 0, v[128:129]
	ds_read_b128 v[170:173], v157 offset:32768
	ds_read_b128 v[174:177], v157 offset:33792
	ds_read_b128 v[178:181], v157 offset:34816
	ds_read_b128 v[182:185], v157 offset:35840
	ds_read_b128 v[194:197], v157 offset:36864
	ds_read_b128 v[206:209], v157 offset:37888
	ds_read_b128 v[210:213], v157 offset:38912
	ds_read_b128 v[214:217], v157 offset:39936
	global_load_lds_dwordx4 v[218:219], off
	v_lshl_add_u64 v[218:219], s[52:53], 0, v[130:131]
	s_mov_b32 m0, s69
	s_nop 0
	global_load_lds_dwordx4 v[218:219], off
	s_add_i32 s19, 0, 0x1c000
	v_add_u32_e32 v192, s19, v154
	ds_read_b128 v[218:221], v192
	ds_read_b128 v[222:225], v192 offset:1024
	ds_read_b128 v[226:229], v192 offset:2048
	ds_read_b128 v[230:233], v192 offset:3072
	s_waitcnt vmcnt(8)
	s_waitcnt lgkmcnt(0)
	s_barrier
	v_mfma_f32_16x16x32_bf16 v[124:127], v[146:149], v[170:173], v[124:127]
	v_mfma_f32_16x16x32_bf16 v[120:123], v[162:165], v[170:173], v[120:123]
	v_mfma_f32_16x16x32_bf16 v[116:119], v[146:149], v[178:181], v[116:119]
	v_mfma_f32_16x16x32_bf16 v[112:115], v[162:165], v[178:181], v[112:115]
	v_mfma_f32_16x16x32_bf16 v[108:111], v[146:149], v[194:197], v[108:111]
	v_mfma_f32_16x16x32_bf16 v[104:107], v[162:165], v[194:197], v[104:107]
	v_mfma_f32_16x16x32_bf16 v[100:103], v[146:149], v[210:213], v[100:103]
	v_mfma_f32_16x16x32_bf16 v[96:99], v[162:165], v[210:213], v[96:99]
	v_mfma_f32_16x16x32_bf16 v[124:127], v[158:161], v[174:177], v[124:127]
	v_mfma_f32_16x16x32_bf16 v[120:123], v[166:169], v[174:177], v[120:123]
	v_mfma_f32_16x16x32_bf16 v[116:119], v[158:161], v[182:185], v[116:119]
	v_mfma_f32_16x16x32_bf16 v[112:115], v[166:169], v[182:185], v[112:115]
	v_mfma_f32_16x16x32_bf16 v[108:111], v[158:161], v[206:209], v[108:111]
	v_mfma_f32_16x16x32_bf16 v[104:107], v[166:169], v[206:209], v[104:107]
	v_mfma_f32_16x16x32_bf16 v[100:103], v[158:161], v[214:217], v[100:103]
	v_mfma_f32_16x16x32_bf16 v[96:99], v[166:169], v[214:217], v[96:99]
	v_mfma_f32_16x16x32_bf16 v[92:95], v[218:221], v[170:173], v[92:95]
	v_mfma_f32_16x16x32_bf16 v[88:91], v[226:229], v[170:173], v[88:91]
	v_mfma_f32_16x16x32_bf16 v[84:87], v[218:221], v[178:181], v[84:87]
	v_mfma_f32_16x16x32_bf16 v[80:83], v[226:229], v[178:181], v[80:83]
	v_mfma_f32_16x16x32_bf16 v[76:79], v[218:221], v[194:197], v[76:79]
	v_mfma_f32_16x16x32_bf16 v[72:75], v[226:229], v[194:197], v[72:75]
	v_mfma_f32_16x16x32_bf16 v[68:71], v[218:221], v[210:213], v[68:71]
	v_mfma_f32_16x16x32_bf16 v[64:67], v[226:229], v[210:213], v[64:67]
	v_mfma_f32_16x16x32_bf16 v[92:95], v[222:225], v[174:177], v[92:95]
	v_mfma_f32_16x16x32_bf16 v[88:91], v[230:233], v[174:177], v[88:91]
	v_mfma_f32_16x16x32_bf16 v[84:87], v[222:225], v[182:185], v[84:87]
	v_mfma_f32_16x16x32_bf16 v[80:83], v[230:233], v[182:185], v[80:83]
	v_mfma_f32_16x16x32_bf16 v[76:79], v[222:225], v[206:209], v[76:79]
	v_mfma_f32_16x16x32_bf16 v[72:75], v[230:233], v[206:209], v[72:75]
	v_mfma_f32_16x16x32_bf16 v[68:71], v[222:225], v[214:217], v[68:71]
	v_mfma_f32_16x16x32_bf16 v[64:67], v[230:233], v[214:217], v[64:67]
	s_add_i32 s6, s6, s57
	v_lshl_add_u64 v[234:235], v[234:235], 0, s[36:37]
	s_mov_b32 m0, s6
	s_barrier
	s_nop 0
	global_load_lds_dwordx4 v[234:235], off
	v_lshl_add_u64 v[234:235], v[236:237], 0, s[36:37]
	s_add_i32 m0, s6, 0x2000
	s_nop 0
	global_load_lds_dwordx4 v[234:235], off
	s_mov_b32 m0, s70
	v_lshl_add_u64 v[234:235], v[238:239], 0, s[36:37]
	ds_read_b128 v[170:173], v157 offset:49152
	ds_read_b128 v[174:177], v157 offset:50176
	ds_read_b128 v[178:181], v157 offset:51200
	ds_read_b128 v[182:185], v157 offset:52224
	ds_read_b128 v[194:197], v157 offset:53248
	ds_read_b128 v[206:209], v157 offset:54272
	ds_read_b128 v[210:213], v157 offset:55296
	ds_read_b128 v[214:217], v157 offset:56320
	global_load_lds_dwordx4 v[234:235], off
	v_lshl_add_u64 v[234:235], v[240:241], 0, s[36:37]
	s_mov_b32 m0, s71
	s_nop 0
	global_load_lds_dwordx4 v[234:235], off
	s_add_u32 s50, s50, 0x40080
	s_addc_u32 s51, s51, 0
	s_add_i32 s6, s19, s57
	v_lshl_add_u64 v[250:251], s[50:51], 0, v[140:141]
	s_mov_b32 m0, s6
	s_nop 0
	global_load_lds_dwordx4 v[250:251], off
	v_lshl_add_u64 v[250:251], s[50:51], 0, v[132:133]
	s_add_i32 m0, s6, 0x2000
	s_nop 0
	global_load_lds_dwordx4 v[250:251], off
	s_waitcnt vmcnt(8)
	s_waitcnt lgkmcnt(0)
	s_barrier
	v_mfma_f32_16x16x32_bf16 v[60:63], v[146:149], v[170:173], v[60:63]
	v_mfma_f32_16x16x32_bf16 v[56:59], v[162:165], v[170:173], v[56:59]
	v_mfma_f32_16x16x32_bf16 v[52:55], v[146:149], v[178:181], v[52:55]
	v_mfma_f32_16x16x32_bf16 v[48:51], v[162:165], v[178:181], v[48:51]
	v_mfma_f32_16x16x32_bf16 v[44:47], v[146:149], v[194:197], v[44:47]
	v_mfma_f32_16x16x32_bf16 v[40:43], v[162:165], v[194:197], v[40:43]
	v_mfma_f32_16x16x32_bf16 v[36:39], v[146:149], v[210:213], v[36:39]
	v_mfma_f32_16x16x32_bf16 v[32:35], v[162:165], v[210:213], v[32:35]
	v_mfma_f32_16x16x32_bf16 v[60:63], v[158:161], v[174:177], v[60:63]
	v_mfma_f32_16x16x32_bf16 v[56:59], v[166:169], v[174:177], v[56:59]
	v_mfma_f32_16x16x32_bf16 v[52:55], v[158:161], v[182:185], v[52:55]
	v_mfma_f32_16x16x32_bf16 v[48:51], v[166:169], v[182:185], v[48:51]
	v_mfma_f32_16x16x32_bf16 v[44:47], v[158:161], v[206:209], v[44:47]
	v_mfma_f32_16x16x32_bf16 v[40:43], v[166:169], v[206:209], v[40:43]
	v_mfma_f32_16x16x32_bf16 v[36:39], v[158:161], v[214:217], v[36:39]
	v_mfma_f32_16x16x32_bf16 v[32:35], v[166:169], v[214:217], v[32:35]
	v_mfma_f32_16x16x32_bf16 v[28:31], v[218:221], v[170:173], v[28:31]
	v_mfma_f32_16x16x32_bf16 v[24:27], v[226:229], v[170:173], v[24:27]
	v_mfma_f32_16x16x32_bf16 v[20:23], v[218:221], v[178:181], v[20:23]
	v_mfma_f32_16x16x32_bf16 v[16:19], v[226:229], v[178:181], v[16:19]
	v_mfma_f32_16x16x32_bf16 v[12:15], v[218:221], v[194:197], v[12:15]
	v_mfma_f32_16x16x32_bf16 v[8:11], v[226:229], v[194:197], v[8:11]
	v_mfma_f32_16x16x32_bf16 v[4:7], v[218:221], v[210:213], v[4:7]
	v_mfma_f32_16x16x32_bf16 v[0:3], v[226:229], v[210:213], v[0:3]
	v_mfma_f32_16x16x32_bf16 v[28:31], v[222:225], v[174:177], v[28:31]
	v_mfma_f32_16x16x32_bf16 v[24:27], v[230:233], v[174:177], v[24:27]
	v_mfma_f32_16x16x32_bf16 v[20:23], v[222:225], v[182:185], v[20:23]
	v_mfma_f32_16x16x32_bf16 v[16:19], v[230:233], v[182:185], v[16:19]
	v_mfma_f32_16x16x32_bf16 v[12:15], v[222:225], v[206:209], v[12:15]
	v_mfma_f32_16x16x32_bf16 v[8:11], v[230:233], v[206:209], v[8:11]
	v_mfma_f32_16x16x32_bf16 v[4:7], v[222:225], v[214:217], v[4:7]
	v_mfma_f32_16x16x32_bf16 v[0:3], v[230:233], v[214:217], v[0:3]
	s_add_i32 s75, s75, 2
	s_add_u32 s48, s48, 0x100
	s_addc_u32 s49, s49, 0
	s_cmp_gt_u32 s75, 13
	s_add_u32 s6, s4, s48
	s_addc_u32 s19, s5, s49
	s_add_u32 s6, s6, 0x100
	s_addc_u32 s19, s19, 0
	s_add_u32 s23, s10, s48
	s_addc_u32 s50, s11, s49
	s_add_i32 s80, 0, 0x10000
	s_cmpk_eq_i32 s48, 0x700
	s_cselect_b32 s53, s12, s19
	s_cselect_b32 s52, s29, s6
	s_cselect_b32 s51, s31, s50
	s_cselect_b32 s50, s35, s23
my_head_295:
	s_barrier
.LBB0_295:
	v_add_u32_e32 v166, s80, v154
	ds_read_b128 v[146:149], v166
	ds_read_b128 v[158:161], v166 offset:1024
	ds_read_b128 v[162:165], v166 offset:2048
	ds_read_b128 v[166:169], v166 offset:3072
	v_lshl_add_u64 v[218:219], v[150:151], 0, s[48:49]
	s_add_i32 m0, s58, 0xc000
	ds_read_b128 v[170:173], v157
	ds_read_b128 v[174:177], v157 offset:1024
	ds_read_b128 v[178:181], v157 offset:2048
	ds_read_b128 v[182:185], v157 offset:3072
	ds_read_b128 v[194:197], v157 offset:4096
	ds_read_b128 v[206:209], v157 offset:5120
	ds_read_b128 v[210:213], v157 offset:6144
	ds_read_b128 v[214:217], v157 offset:7168
	global_load_lds_dwordx4 v[218:219], off
	v_lshl_add_u64 v[218:219], v[152:153], 0, s[48:49]
	s_add_i32 m0, s58, 0xe000
	s_nop 0
	global_load_lds_dwordx4 v[218:219], off
	s_add_i32 s6, 0, 0x14000
	v_add_u32_e32 v192, s6, v154
	ds_read_b128 v[218:221], v192
	ds_read_b128 v[222:225], v192 offset:1024
	ds_read_b128 v[226:229], v192 offset:2048
	ds_read_b128 v[230:233], v192 offset:3072
	s_waitcnt vmcnt(8)
	s_waitcnt lgkmcnt(0)
	s_barrier
	v_mfma_f32_16x16x32_bf16 v[124:127], v[146:149], v[170:173], v[124:127]
	v_mfma_f32_16x16x32_bf16 v[120:123], v[162:165], v[170:173], v[120:123]
	v_mfma_f32_16x16x32_bf16 v[116:119], v[146:149], v[178:181], v[116:119]
	v_mfma_f32_16x16x32_bf16 v[112:115], v[162:165], v[178:181], v[112:115]
	v_mfma_f32_16x16x32_bf16 v[108:111], v[146:149], v[194:197], v[108:111]
	v_mfma_f32_16x16x32_bf16 v[104:107], v[162:165], v[194:197], v[104:107]
	v_mfma_f32_16x16x32_bf16 v[100:103], v[146:149], v[210:213], v[100:103]
	v_mfma_f32_16x16x32_bf16 v[96:99], v[162:165], v[210:213], v[96:99]
	v_mfma_f32_16x16x32_bf16 v[124:127], v[158:161], v[174:177], v[124:127]
	v_mfma_f32_16x16x32_bf16 v[120:123], v[166:169], v[174:177], v[120:123]
	v_mfma_f32_16x16x32_bf16 v[116:119], v[158:161], v[182:185], v[116:119]
	v_mfma_f32_16x16x32_bf16 v[112:115], v[166:169], v[182:185], v[112:115]
	v_mfma_f32_16x16x32_bf16 v[108:111], v[158:161], v[206:209], v[108:111]
	v_mfma_f32_16x16x32_bf16 v[104:107], v[166:169], v[206:209], v[104:107]
	v_mfma_f32_16x16x32_bf16 v[100:103], v[158:161], v[214:217], v[100:103]
	v_mfma_f32_16x16x32_bf16 v[96:99], v[166:169], v[214:217], v[96:99]
	v_mfma_f32_16x16x32_bf16 v[92:95], v[218:221], v[170:173], v[92:95]
	v_mfma_f32_16x16x32_bf16 v[88:91], v[226:229], v[170:173], v[88:91]
	v_mfma_f32_16x16x32_bf16 v[84:87], v[218:221], v[178:181], v[84:87]
	v_mfma_f32_16x16x32_bf16 v[80:83], v[226:229], v[178:181], v[80:83]
	v_mfma_f32_16x16x32_bf16 v[76:79], v[218:221], v[194:197], v[76:79]
	v_mfma_f32_16x16x32_bf16 v[72:75], v[226:229], v[194:197], v[72:75]
	v_mfma_f32_16x16x32_bf16 v[68:71], v[218:221], v[210:213], v[68:71]
	v_mfma_f32_16x16x32_bf16 v[64:67], v[226:229], v[210:213], v[64:67]
	v_mfma_f32_16x16x32_bf16 v[92:95], v[222:225], v[174:177], v[92:95]
	v_mfma_f32_16x16x32_bf16 v[88:91], v[230:233], v[174:177], v[88:91]
	v_mfma_f32_16x16x32_bf16 v[84:87], v[222:225], v[182:185], v[84:87]
	v_mfma_f32_16x16x32_bf16 v[80:83], v[230:233], v[182:185], v[80:83]
	v_mfma_f32_16x16x32_bf16 v[76:79], v[222:225], v[206:209], v[76:79]
	v_mfma_f32_16x16x32_bf16 v[72:75], v[230:233], v[206:209], v[72:75]
	v_mfma_f32_16x16x32_bf16 v[68:71], v[222:225], v[214:217], v[68:71]
	v_mfma_f32_16x16x32_bf16 v[64:67], v[230:233], v[214:217], v[64:67]
	s_add_i32 s19, s80, s57
	v_lshl_add_u64 v[234:235], s[50:51], 0, v[140:141]
	s_mov_b32 m0, s19
	s_barrier
	s_nop 0
	global_load_lds_dwordx4 v[234:235], off
	v_lshl_add_u64 v[236:237], s[50:51], 0, v[132:133]
	s_add_i32 m0, s19, 0x2000
	s_nop 0
	global_load_lds_dwordx4 v[236:237], off
	s_mov_b32 m0, s58
	v_lshl_add_u64 v[238:239], s[52:53], 0, v[128:129]
	ds_read_b128 v[170:173], v157 offset:16384
	ds_read_b128 v[174:177], v157 offset:17408
	ds_read_b128 v[178:181], v157 offset:18432
	ds_read_b128 v[182:185], v157 offset:19456
	ds_read_b128 v[194:197], v157 offset:20480
	ds_read_b128 v[206:209], v157 offset:21504
	ds_read_b128 v[210:213], v157 offset:22528
	ds_read_b128 v[214:217], v157 offset:23552
	global_load_lds_dwordx4 v[238:239], off
	v_lshl_add_u64 v[240:241], s[52:53], 0, v[130:131]
	s_mov_b32 m0, s59
	s_nop 0
	global_load_lds_dwordx4 v[240:241], off
	s_add_u32 s80, s50, 0x40000
	s_addc_u32 s81, s51, 0
	s_add_i32 s6, s6, s57
	v_lshl_add_u64 v[250:251], s[80:81], 0, v[140:141]
	s_mov_b32 m0, s6
	s_nop 0
	global_load_lds_dwordx4 v[250:251], off
	v_lshl_add_u64 v[250:251], s[80:81], 0, v[132:133]
	s_add_i32 m0, s6, 0x2000
	s_nop 0
	global_load_lds_dwordx4 v[250:251], off
	s_waitcnt vmcnt(8)
	s_waitcnt lgkmcnt(0)
	s_barrier
	v_mfma_f32_16x16x32_bf16 v[60:63], v[146:149], v[170:173], v[60:63]
	v_mfma_f32_16x16x32_bf16 v[56:59], v[162:165], v[170:173], v[56:59]
	v_mfma_f32_16x16x32_bf16 v[52:55], v[146:149], v[178:181], v[52:55]
	v_mfma_f32_16x16x32_bf16 v[48:51], v[162:165], v[178:181], v[48:51]
	v_mfma_f32_16x16x32_bf16 v[44:47], v[146:149], v[194:197], v[44:47]
	v_mfma_f32_16x16x32_bf16 v[40:43], v[162:165], v[194:197], v[40:43]
	v_mfma_f32_16x16x32_bf16 v[36:39], v[146:149], v[210:213], v[36:39]
	v_mfma_f32_16x16x32_bf16 v[32:35], v[162:165], v[210:213], v[32:35]
	v_mfma_f32_16x16x32_bf16 v[60:63], v[158:161], v[174:177], v[60:63]
	v_mfma_f32_16x16x32_bf16 v[56:59], v[166:169], v[174:177], v[56:59]
	v_mfma_f32_16x16x32_bf16 v[52:55], v[158:161], v[182:185], v[52:55]
	v_mfma_f32_16x16x32_bf16 v[48:51], v[166:169], v[182:185], v[48:51]
	v_mfma_f32_16x16x32_bf16 v[44:47], v[158:161], v[206:209], v[44:47]
	v_mfma_f32_16x16x32_bf16 v[40:43], v[166:169], v[206:209], v[40:43]
	v_mfma_f32_16x16x32_bf16 v[36:39], v[158:161], v[214:217], v[36:39]
	v_mfma_f32_16x16x32_bf16 v[32:35], v[166:169], v[214:217], v[32:35]
	v_mfma_f32_16x16x32_bf16 v[28:31], v[218:221], v[170:173], v[28:31]
	v_mfma_f32_16x16x32_bf16 v[24:27], v[226:229], v[170:173], v[24:27]
	v_mfma_f32_16x16x32_bf16 v[20:23], v[218:221], v[178:181], v[20:23]
	v_mfma_f32_16x16x32_bf16 v[16:19], v[226:229], v[178:181], v[16:19]
	v_mfma_f32_16x16x32_bf16 v[12:15], v[218:221], v[194:197], v[12:15]
	v_mfma_f32_16x16x32_bf16 v[8:11], v[226:229], v[194:197], v[8:11]
	v_mfma_f32_16x16x32_bf16 v[4:7], v[218:221], v[210:213], v[4:7]
	v_mfma_f32_16x16x32_bf16 v[0:3], v[226:229], v[210:213], v[0:3]
	v_mfma_f32_16x16x32_bf16 v[28:31], v[222:225], v[174:177], v[28:31]
	v_mfma_f32_16x16x32_bf16 v[24:27], v[230:233], v[174:177], v[24:27]
	v_mfma_f32_16x16x32_bf16 v[20:23], v[222:225], v[182:185], v[20:23]
	v_mfma_f32_16x16x32_bf16 v[16:19], v[230:233], v[182:185], v[16:19]
	v_mfma_f32_16x16x32_bf16 v[12:15], v[222:225], v[206:209], v[12:15]
	v_mfma_f32_16x16x32_bf16 v[8:11], v[230:233], v[206:209], v[8:11]
	v_mfma_f32_16x16x32_bf16 v[4:7], v[222:225], v[214:217], v[4:7]
	v_mfma_f32_16x16x32_bf16 v[0:3], v[230:233], v[214:217], v[0:3]
	s_add_i32 s6, 0, 0x18000
	s_barrier
	v_add_u32_e32 v166, s6, v154
	ds_read_b128 v[146:149], v166
	ds_read_b128 v[158:161], v166 offset:1024
	ds_read_b128 v[162:165], v166 offset:2048
	ds_read_b128 v[166:169], v166 offset:3072
	s_add_u32 s52, s52, 0x40000
	s_addc_u32 s53, s53, 0
	s_mov_b32 m0, s68
	v_lshl_add_u64 v[218:219], s[52:53], 0, v[128:129]
	ds_read_b128 v[170:173], v157 offset:32768
	ds_read_b128 v[174:177], v157 offset:33792
	ds_read_b128 v[178:181], v157 offset:34816
	ds_read_b128 v[182:185], v157 offset:35840
	ds_read_b128 v[194:197], v157 offset:36864
	ds_read_b128 v[206:209], v157 offset:37888
	ds_read_b128 v[210:213], v157 offset:38912
	ds_read_b128 v[214:217], v157 offset:39936
	global_load_lds_dwordx4 v[218:219], off
	v_lshl_add_u64 v[218:219], s[52:53], 0, v[130:131]
	s_mov_b32 m0, s69
	s_nop 0
	global_load_lds_dwordx4 v[218:219], off
	s_add_i32 s19, 0, 0x1c000
	v_add_u32_e32 v192, s19, v154
	ds_read_b128 v[218:221], v192
	ds_read_b128 v[222:225], v192 offset:1024
	ds_read_b128 v[226:229], v192 offset:2048
	ds_read_b128 v[230:233], v192 offset:3072
	s_waitcnt vmcnt(8)
	s_waitcnt lgkmcnt(0)
	s_barrier
	v_mfma_f32_16x16x32_bf16 v[124:127], v[146:149], v[170:173], v[124:127]
	v_mfma_f32_16x16x32_bf16 v[120:123], v[162:165], v[170:173], v[120:123]
	v_mfma_f32_16x16x32_bf16 v[116:119], v[146:149], v[178:181], v[116:119]
	v_mfma_f32_16x16x32_bf16 v[112:115], v[162:165], v[178:181], v[112:115]
	v_mfma_f32_16x16x32_bf16 v[108:111], v[146:149], v[194:197], v[108:111]
	v_mfma_f32_16x16x32_bf16 v[104:107], v[162:165], v[194:197], v[104:107]
	v_mfma_f32_16x16x32_bf16 v[100:103], v[146:149], v[210:213], v[100:103]
	v_mfma_f32_16x16x32_bf16 v[96:99], v[162:165], v[210:213], v[96:99]
	v_mfma_f32_16x16x32_bf16 v[124:127], v[158:161], v[174:177], v[124:127]
	v_mfma_f32_16x16x32_bf16 v[120:123], v[166:169], v[174:177], v[120:123]
	v_mfma_f32_16x16x32_bf16 v[116:119], v[158:161], v[182:185], v[116:119]
	v_mfma_f32_16x16x32_bf16 v[112:115], v[166:169], v[182:185], v[112:115]
	v_mfma_f32_16x16x32_bf16 v[108:111], v[158:161], v[206:209], v[108:111]
	v_mfma_f32_16x16x32_bf16 v[104:107], v[166:169], v[206:209], v[104:107]
	v_mfma_f32_16x16x32_bf16 v[100:103], v[158:161], v[214:217], v[100:103]
	v_mfma_f32_16x16x32_bf16 v[96:99], v[166:169], v[214:217], v[96:99]
	v_mfma_f32_16x16x32_bf16 v[92:95], v[218:221], v[170:173], v[92:95]
	v_mfma_f32_16x16x32_bf16 v[88:91], v[226:229], v[170:173], v[88:91]
	v_mfma_f32_16x16x32_bf16 v[84:87], v[218:221], v[178:181], v[84:87]
	v_mfma_f32_16x16x32_bf16 v[80:83], v[226:229], v[178:181], v[80:83]
	v_mfma_f32_16x16x32_bf16 v[76:79], v[218:221], v[194:197], v[76:79]
	v_mfma_f32_16x16x32_bf16 v[72:75], v[226:229], v[194:197], v[72:75]
	v_mfma_f32_16x16x32_bf16 v[68:71], v[218:221], v[210:213], v[68:71]
	v_mfma_f32_16x16x32_bf16 v[64:67], v[226:229], v[210:213], v[64:67]
	v_mfma_f32_16x16x32_bf16 v[92:95], v[222:225], v[174:177], v[92:95]
	v_mfma_f32_16x16x32_bf16 v[88:91], v[230:233], v[174:177], v[88:91]
	v_mfma_f32_16x16x32_bf16 v[84:87], v[222:225], v[182:185], v[84:87]
	v_mfma_f32_16x16x32_bf16 v[80:83], v[230:233], v[182:185], v[80:83]
	v_mfma_f32_16x16x32_bf16 v[76:79], v[222:225], v[206:209], v[76:79]
	v_mfma_f32_16x16x32_bf16 v[72:75], v[230:233], v[206:209], v[72:75]
	v_mfma_f32_16x16x32_bf16 v[68:71], v[222:225], v[214:217], v[68:71]
	v_mfma_f32_16x16x32_bf16 v[64:67], v[230:233], v[214:217], v[64:67]
	s_add_i32 s6, s6, s57
	v_lshl_add_u64 v[234:235], v[234:235], 0, s[36:37]
	s_mov_b32 m0, s6
	s_barrier
	s_nop 0
	global_load_lds_dwordx4 v[234:235], off
	v_lshl_add_u64 v[234:235], v[236:237], 0, s[36:37]
	s_add_i32 m0, s6, 0x2000
	s_nop 0
	global_load_lds_dwordx4 v[234:235], off
	s_mov_b32 m0, s70
	v_lshl_add_u64 v[234:235], v[238:239], 0, s[36:37]
	ds_read_b128 v[170:173], v157 offset:49152
	ds_read_b128 v[174:177], v157 offset:50176
	ds_read_b128 v[178:181], v157 offset:51200
	ds_read_b128 v[182:185], v157 offset:52224
	ds_read_b128 v[194:197], v157 offset:53248
	ds_read_b128 v[206:209], v157 offset:54272
	ds_read_b128 v[210:213], v157 offset:55296
	ds_read_b128 v[214:217], v157 offset:56320
	global_load_lds_dwordx4 v[234:235], off
	v_lshl_add_u64 v[234:235], v[240:241], 0, s[36:37]
	s_mov_b32 m0, s71
	s_nop 0
	global_load_lds_dwordx4 v[234:235], off
	s_add_u32 s50, s50, 0x40080
	s_addc_u32 s51, s51, 0
	s_add_i32 s6, s19, s57
	v_lshl_add_u64 v[250:251], s[50:51], 0, v[140:141]
	s_mov_b32 m0, s6
	s_nop 0
	global_load_lds_dwordx4 v[250:251], off
	v_lshl_add_u64 v[250:251], s[50:51], 0, v[132:133]
	s_add_i32 m0, s6, 0x2000
	s_nop 0
	global_load_lds_dwordx4 v[250:251], off
	s_waitcnt vmcnt(8)
	s_waitcnt lgkmcnt(0)
	s_barrier
	v_mfma_f32_16x16x32_bf16 v[60:63], v[146:149], v[170:173], v[60:63]
	v_mfma_f32_16x16x32_bf16 v[56:59], v[162:165], v[170:173], v[56:59]
	v_mfma_f32_16x16x32_bf16 v[52:55], v[146:149], v[178:181], v[52:55]
	v_mfma_f32_16x16x32_bf16 v[48:51], v[162:165], v[178:181], v[48:51]
	v_mfma_f32_16x16x32_bf16 v[44:47], v[146:149], v[194:197], v[44:47]
	v_mfma_f32_16x16x32_bf16 v[40:43], v[162:165], v[194:197], v[40:43]
	v_mfma_f32_16x16x32_bf16 v[36:39], v[146:149], v[210:213], v[36:39]
	v_mfma_f32_16x16x32_bf16 v[32:35], v[162:165], v[210:213], v[32:35]
	v_mfma_f32_16x16x32_bf16 v[60:63], v[158:161], v[174:177], v[60:63]
	v_mfma_f32_16x16x32_bf16 v[56:59], v[166:169], v[174:177], v[56:59]
	v_mfma_f32_16x16x32_bf16 v[52:55], v[158:161], v[182:185], v[52:55]
	v_mfma_f32_16x16x32_bf16 v[48:51], v[166:169], v[182:185], v[48:51]
	v_mfma_f32_16x16x32_bf16 v[44:47], v[158:161], v[206:209], v[44:47]
	v_mfma_f32_16x16x32_bf16 v[40:43], v[166:169], v[206:209], v[40:43]
	v_mfma_f32_16x16x32_bf16 v[36:39], v[158:161], v[214:217], v[36:39]
	v_mfma_f32_16x16x32_bf16 v[32:35], v[166:169], v[214:217], v[32:35]
	v_mfma_f32_16x16x32_bf16 v[28:31], v[218:221], v[170:173], v[28:31]
	v_mfma_f32_16x16x32_bf16 v[24:27], v[226:229], v[170:173], v[24:27]
	v_mfma_f32_16x16x32_bf16 v[20:23], v[218:221], v[178:181], v[20:23]
	v_mfma_f32_16x16x32_bf16 v[16:19], v[226:229], v[178:181], v[16:19]
	v_mfma_f32_16x16x32_bf16 v[12:15], v[218:221], v[194:197], v[12:15]
	v_mfma_f32_16x16x32_bf16 v[8:11], v[226:229], v[194:197], v[8:11]
	v_mfma_f32_16x16x32_bf16 v[4:7], v[218:221], v[210:213], v[4:7]
	v_mfma_f32_16x16x32_bf16 v[0:3], v[226:229], v[210:213], v[0:3]
	v_mfma_f32_16x16x32_bf16 v[28:31], v[222:225], v[174:177], v[28:31]
	v_mfma_f32_16x16x32_bf16 v[24:27], v[230:233], v[174:177], v[24:27]
	v_mfma_f32_16x16x32_bf16 v[20:23], v[222:225], v[182:185], v[20:23]
	v_mfma_f32_16x16x32_bf16 v[16:19], v[230:233], v[182:185], v[16:19]
	v_mfma_f32_16x16x32_bf16 v[12:15], v[222:225], v[206:209], v[12:15]
	v_mfma_f32_16x16x32_bf16 v[8:11], v[230:233], v[206:209], v[8:11]
	v_mfma_f32_16x16x32_bf16 v[4:7], v[222:225], v[214:217], v[4:7]
	v_mfma_f32_16x16x32_bf16 v[0:3], v[230:233], v[214:217], v[0:3]
	s_add_i32 s75, s75, 2
	s_add_u32 s48, s48, 0x100
	s_addc_u32 s49, s49, 0
	s_cmp_gt_u32 s75, 13
	s_cbranch_scc1 my_exit_295
	s_add_u32 s6, s4, s48
	s_addc_u32 s19, s5, s49
	s_add_u32 s6, s6, 0x100
	s_addc_u32 s19, s19, 0
	s_add_u32 s23, s10, s48
	s_addc_u32 s50, s11, s49
	s_add_i32 s80, 0, 0x10000
	s_cmpk_eq_i32 s48, 0x700
	s_cselect_b32 s53, s12, s19
	s_cselect_b32 s52, s29, s6
	s_cselect_b32 s51, s31, s50
	s_cselect_b32 s50, s35, s23
	s_branch my_head_295
my_exit_295:
	s_barrier
	s_mov_b32 s100, 1
	s_add_u32 s48, s10, 0xffffff00
	v_lshl_add_u32 v166, s73, 10, v155
	s_addc_u32 s49, s11, -1
	s_ashr_i32 s29, s28, 31
	v_lshl_or_b32 v146, s72, 8, v156
	ds_read2_b32 v[158:159], v166 offset1:16
	s_lshl_b64 s[10:11], s[28:29], 8
	v_ashrrev_i32_e32 v147, 31, v146
	v_lshl_add_u64 v[148:149], s[10:11], 0, v[134:135]
	v_lshl_add_u64 v[146:147], v[146:147], 1, s[26:27]
	v_mad_u64_u32 v[150:151], s[10:11], v148, s13, v[146:147]
	v_mov_b32_e32 v146, v151
	v_mad_u64_u32 v[152:153], s[10:11], v149, s13, v[146:147]
	s_waitcnt lgkmcnt(0)
	v_pk_mul_f32 v[148:149], v[126:127], v[158:159] op_sel_hi:[1,0]
	v_pk_mul_f32 v[146:147], v[124:125], v[158:159] op_sel_hi:[1,0]
	v_pk_mul_f32 v[160:161], v[122:123], v[158:159] op_sel_hi:[1,0]
	v_pk_mul_f32 v[162:163], v[120:121], v[158:159] op_sel_hi:[1,0]
	v_mov_b32_e32 v151, v152
	v_cvt_pk_bf16_f32 v146, v146, v147
	v_cvt_pk_bf16_f32 v147, v148, v149
	v_cvt_pk_bf16_f32 v148, v162, v163
	v_cvt_pk_bf16_f32 v149, v160, v161
	global_store_dwordx4 v[150:151], v[146:149], off
	v_pk_mul_f32 v[160:161], v[90:91], v[158:159] op_sel_hi:[1,0]
	v_pk_mul_f32 v[162:163], v[88:89], v[158:159] op_sel_hi:[1,0]
	v_pk_mul_f32 v[148:149], v[94:95], v[158:159] op_sel_hi:[1,0]
	v_pk_mul_f32 v[146:147], v[92:93], v[158:159] op_sel_hi:[1,0]
	v_mov_b32_e32 v158, v159
	v_cvt_pk_bf16_f32 v146, v146, v147
	v_cvt_pk_bf16_f32 v147, v148, v149
	v_cvt_pk_bf16_f32 v148, v162, v163
	v_cvt_pk_bf16_f32 v149, v160, v161
	global_store_dwordx4 v[150:151], v[146:149], off offset:256
	v_pk_mul_f32 v[160:161], v[114:115], v[158:159] op_sel_hi:[1,0]
	s_mov_b32 s6, 0x1e000
	v_pk_mul_f32 v[148:149], v[118:119], v[158:159] op_sel_hi:[1,0]
	v_pk_mul_f32 v[146:147], v[116:117], v[158:159] op_sel_hi:[1,0]
	ds_read2_b32 v[164:165], v166 offset0:32 offset1:48
	v_pk_mul_f32 v[162:163], v[112:113], v[158:159] op_sel_hi:[1,0]
	v_cvt_pk_bf16_f32 v146, v146, v147
	v_cvt_pk_bf16_f32 v147, v148, v149
	v_cvt_pk_bf16_f32 v149, v160, v161
	v_add_co_u32_e32 v160, vcc, s6, v150
	v_cvt_pk_bf16_f32 v148, v162, v163
	s_nop 0
	v_addc_co_u32_e32 v161, vcc, 0, v152, vcc
	global_store_dwordx4 v[160:161], v[146:149], off
	v_pk_mul_f32 v[162:163], v[82:83], v[158:159] op_sel_hi:[1,0]
	s_mov_b32 s6, 0x3c000
	v_pk_mul_f32 v[148:149], v[86:87], v[158:159] op_sel_hi:[1,0]
	v_pk_mul_f32 v[146:147], v[84:85], v[158:159] op_sel_hi:[1,0]
	v_pk_mul_f32 v[158:159], v[80:81], v[158:159] op_sel_hi:[1,0]
	v_cvt_pk_bf16_f32 v146, v146, v147
	v_cvt_pk_bf16_f32 v147, v148, v149
	v_cvt_pk_bf16_f32 v148, v158, v159
	v_cvt_pk_bf16_f32 v149, v162, v163
	global_store_dwordx4 v[160:161], v[146:149], off offset:256
	s_waitcnt lgkmcnt(0)
	v_pk_mul_f32 v[158:159], v[106:107], v[164:165] op_sel_hi:[1,0]
	v_pk_mul_f32 v[160:161], v[104:105], v[164:165] op_sel_hi:[1,0]
	v_pk_mul_f32 v[148:149], v[110:111], v[164:165] op_sel_hi:[1,0]
	v_pk_mul_f32 v[146:147], v[108:109], v[164:165] op_sel_hi:[1,0]
	v_pk_mul_f32 v[162:163], v[72:73], v[164:165] op_sel_hi:[1,0]
	v_cvt_pk_bf16_f32 v146, v146, v147
	v_cvt_pk_bf16_f32 v147, v148, v149
	v_cvt_pk_bf16_f32 v149, v158, v159
	v_add_co_u32_e32 v158, vcc, s6, v150
	v_cvt_pk_bf16_f32 v148, v160, v161
	s_nop 0
	v_addc_co_u32_e32 v159, vcc, 0, v152, vcc
	global_store_dwordx4 v[158:159], v[146:149], off
	v_pk_mul_f32 v[160:161], v[74:75], v[164:165] op_sel_hi:[1,0]
	s_mov_b32 s6, 0x5a000
	v_pk_mul_f32 v[148:149], v[78:79], v[164:165] op_sel_hi:[1,0]
	v_pk_mul_f32 v[146:147], v[76:77], v[164:165] op_sel_hi:[1,0]
	s_nop 0
	v_cvt_pk_bf16_f32 v146, v146, v147
	v_cvt_pk_bf16_f32 v147, v148, v149
	v_cvt_pk_bf16_f32 v148, v162, v163
	v_cvt_pk_bf16_f32 v149, v160, v161
	global_store_dwordx4 v[158:159], v[146:149], off offset:256
	v_mov_b32_e32 v158, v165
	v_pk_mul_f32 v[160:161], v[98:99], v[158:159] op_sel_hi:[1,0]
	v_pk_mul_f32 v[148:149], v[102:103], v[158:159] op_sel_hi:[1,0]
	v_pk_mul_f32 v[146:147], v[100:101], v[158:159] op_sel_hi:[1,0]
	ds_read2_b32 v[164:165], v166 offset0:128 offset1:144
	v_pk_mul_f32 v[162:163], v[96:97], v[158:159] op_sel_hi:[1,0]
	v_cvt_pk_bf16_f32 v146, v146, v147
	v_cvt_pk_bf16_f32 v147, v148, v149
	v_cvt_pk_bf16_f32 v149, v160, v161
	v_add_co_u32_e32 v160, vcc, s6, v150
	v_cvt_pk_bf16_f32 v148, v162, v163
	s_nop 0
	v_addc_co_u32_e32 v161, vcc, 0, v152, vcc
	global_store_dwordx4 v[160:161], v[146:149], off
	v_pk_mul_f32 v[162:163], v[66:67], v[158:159] op_sel_hi:[1,0]
	s_mov_b32 s6, 0xf0000
	v_pk_mul_f32 v[148:149], v[70:71], v[158:159] op_sel_hi:[1,0]
	v_pk_mul_f32 v[146:147], v[68:69], v[158:159] op_sel_hi:[1,0]
	v_pk_mul_f32 v[158:159], v[64:65], v[158:159] op_sel_hi:[1,0]
	v_cvt_pk_bf16_f32 v146, v146, v147
	v_cvt_pk_bf16_f32 v147, v148, v149
	v_cvt_pk_bf16_f32 v148, v158, v159
	v_cvt_pk_bf16_f32 v149, v162, v163
	global_store_dwordx4 v[160:161], v[146:149], off offset:256
	s_waitcnt lgkmcnt(0)
	v_pk_mul_f32 v[158:159], v[58:59], v[164:165] op_sel_hi:[1,0]
	v_pk_mul_f32 v[160:161], v[56:57], v[164:165] op_sel_hi:[1,0]
	v_pk_mul_f32 v[148:149], v[62:63], v[164:165] op_sel_hi:[1,0]
	v_pk_mul_f32 v[146:147], v[60:61], v[164:165] op_sel_hi:[1,0]
	v_pk_mul_f32 v[162:163], v[24:25], v[164:165] op_sel_hi:[1,0]
	v_cvt_pk_bf16_f32 v146, v146, v147
	v_cvt_pk_bf16_f32 v147, v148, v149
	v_cvt_pk_bf16_f32 v149, v158, v159
	v_add_co_u32_e32 v158, vcc, s6, v150
	v_cvt_pk_bf16_f32 v148, v160, v161
	s_nop 0
	v_addc_co_u32_e32 v159, vcc, 0, v152, vcc
	global_store_dwordx4 v[158:159], v[146:149], off
	v_pk_mul_f32 v[160:161], v[26:27], v[164:165] op_sel_hi:[1,0]
	s_mov_b32 s6, 0x10e000
	v_pk_mul_f32 v[148:149], v[30:31], v[164:165] op_sel_hi:[1,0]
	v_pk_mul_f32 v[146:147], v[28:29], v[164:165] op_sel_hi:[1,0]
	s_nop 0
	v_cvt_pk_bf16_f32 v146, v146, v147
	v_cvt_pk_bf16_f32 v147, v148, v149
	v_cvt_pk_bf16_f32 v148, v162, v163
	v_cvt_pk_bf16_f32 v149, v160, v161
	global_store_dwordx4 v[158:159], v[146:149], off offset:256
	v_mov_b32_e32 v158, v165
	v_pk_mul_f32 v[160:161], v[50:51], v[158:159] op_sel_hi:[1,0]
	v_pk_mul_f32 v[148:149], v[54:55], v[158:159] op_sel_hi:[1,0]
	v_pk_mul_f32 v[146:147], v[52:53], v[158:159] op_sel_hi:[1,0]
	ds_read2_b32 v[164:165], v166 offset0:160 offset1:176
	v_pk_mul_f32 v[162:163], v[48:49], v[158:159] op_sel_hi:[1,0]
	v_cvt_pk_bf16_f32 v146, v146, v147
	v_cvt_pk_bf16_f32 v147, v148, v149
	v_cvt_pk_bf16_f32 v149, v160, v161
	v_add_co_u32_e32 v160, vcc, s6, v150
	v_cvt_pk_bf16_f32 v148, v162, v163
	s_nop 0
	v_addc_co_u32_e32 v161, vcc, 0, v152, vcc
	global_store_dwordx4 v[160:161], v[146:149], off
	v_pk_mul_f32 v[162:163], v[18:19], v[158:159] op_sel_hi:[1,0]
	s_mov_b32 s6, 0x12c000
	v_pk_mul_f32 v[148:149], v[22:23], v[158:159] op_sel_hi:[1,0]
	v_pk_mul_f32 v[146:147], v[20:21], v[158:159] op_sel_hi:[1,0]
	v_pk_mul_f32 v[158:159], v[16:17], v[158:159] op_sel_hi:[1,0]
	v_cvt_pk_bf16_f32 v146, v146, v147
	v_cvt_pk_bf16_f32 v147, v148, v149
	v_cvt_pk_bf16_f32 v148, v158, v159
	v_cvt_pk_bf16_f32 v149, v162, v163
	global_store_dwordx4 v[160:161], v[146:149], off offset:256
	s_waitcnt lgkmcnt(0)
	v_pk_mul_f32 v[158:159], v[42:43], v[164:165] op_sel_hi:[1,0]
	v_pk_mul_f32 v[160:161], v[40:41], v[164:165] op_sel_hi:[1,0]
	v_pk_mul_f32 v[148:149], v[46:47], v[164:165] op_sel_hi:[1,0]
	v_pk_mul_f32 v[146:147], v[44:45], v[164:165] op_sel_hi:[1,0]
	v_pk_mul_f32 v[162:163], v[8:9], v[164:165] op_sel_hi:[1,0]
	v_cvt_pk_bf16_f32 v146, v146, v147
	v_cvt_pk_bf16_f32 v147, v148, v149
	v_cvt_pk_bf16_f32 v149, v158, v159
	v_add_co_u32_e32 v158, vcc, s6, v150
	v_cvt_pk_bf16_f32 v148, v160, v161
	s_nop 0
	v_addc_co_u32_e32 v159, vcc, 0, v152, vcc
	global_store_dwordx4 v[158:159], v[146:149], off
	v_pk_mul_f32 v[160:161], v[10:11], v[164:165] op_sel_hi:[1,0]
	s_mov_b32 s6, 0x14a000
	v_pk_mul_f32 v[148:149], v[14:15], v[164:165] op_sel_hi:[1,0]
	v_pk_mul_f32 v[146:147], v[12:13], v[164:165] op_sel_hi:[1,0]
	v_add_co_u32_e32 v150, vcc, s6, v150
	v_cvt_pk_bf16_f32 v146, v146, v147
	v_cvt_pk_bf16_f32 v147, v148, v149
	v_cvt_pk_bf16_f32 v148, v162, v163
	v_cvt_pk_bf16_f32 v149, v160, v161
	global_store_dwordx4 v[158:159], v[146:149], off offset:256
	v_mov_b32_e32 v158, v165
	v_pk_mul_f32 v[160:161], v[34:35], v[158:159] op_sel_hi:[1,0]
	v_pk_mul_f32 v[148:149], v[38:39], v[158:159] op_sel_hi:[1,0]
	v_pk_mul_f32 v[146:147], v[36:37], v[158:159] op_sel_hi:[1,0]
	v_pk_mul_f32 v[162:163], v[32:33], v[158:159] op_sel_hi:[1,0]
	v_cvt_pk_bf16_f32 v146, v146, v147
	v_cvt_pk_bf16_f32 v147, v148, v149
	v_cvt_pk_bf16_f32 v148, v162, v163
	v_cvt_pk_bf16_f32 v149, v160, v161
	v_addc_co_u32_e32 v151, vcc, 0, v152, vcc
	global_store_dwordx4 v[150:151], v[146:149], off
	v_pk_mul_f32 v[152:153], v[2:3], v[158:159] op_sel_hi:[1,0]
	s_andn2_b64 vcc, exec, s[44:45]
	v_pk_mul_f32 v[148:149], v[6:7], v[158:159] op_sel_hi:[1,0]
	v_pk_mul_f32 v[146:147], v[4:5], v[158:159] op_sel_hi:[1,0]
	v_pk_mul_f32 v[158:159], v[0:1], v[158:159] op_sel_hi:[1,0]
	v_cvt_pk_bf16_f32 v146, v146, v147
	v_cvt_pk_bf16_f32 v147, v148, v149
	v_cvt_pk_bf16_f32 v148, v158, v159
	v_cvt_pk_bf16_f32 v149, v152, v153
	global_store_dwordx4 v[150:151], v[146:149], off offset:256
	s_cbranch_vccz .LBB0_291
	s_mov_b64 s[38:39], s[48:49]
	s_andn2_b64 vcc, exec, s[42:43]
	s_mov_b64 s[48:49], s[38:39]
	s_cbranch_vccnz .LBB0_292

.Lm4ap_315:
	s_waitcnt lgkmcnt(0)
	s_barrier
	s_nop 0
	v_mfma_f32_16x16x32_bf16 v[124:127], v[146:149], v[170:173], 0
	v_mfma_f32_16x16x32_bf16 v[120:123], v[162:165], v[170:173], 0
	v_mfma_f32_16x16x32_bf16 v[116:119], v[146:149], v[178:181], 0
	v_mfma_f32_16x16x32_bf16 v[112:115], v[162:165], v[178:181], 0
	v_mfma_f32_16x16x32_bf16 v[108:111], v[146:149], v[194:197], 0
	v_mfma_f32_16x16x32_bf16 v[104:107], v[162:165], v[194:197], 0
	v_mfma_f32_16x16x32_bf16 v[100:103], v[146:149], v[210:213], 0
	v_mfma_f32_16x16x32_bf16 v[96:99], v[162:165], v[210:213], 0
	v_mfma_f32_16x16x32_bf16 v[124:127], v[158:161], v[174:177], v[124:127]
	v_mfma_f32_16x16x32_bf16 v[120:123], v[166:169], v[174:177], v[120:123]
	v_mfma_f32_16x16x32_bf16 v[116:119], v[158:161], v[182:185], v[116:119]
	v_mfma_f32_16x16x32_bf16 v[112:115], v[166:169], v[182:185], v[112:115]
	v_mfma_f32_16x16x32_bf16 v[108:111], v[158:161], v[206:209], v[108:111]
	v_mfma_f32_16x16x32_bf16 v[104:107], v[166:169], v[206:209], v[104:107]
	v_mfma_f32_16x16x32_bf16 v[100:103], v[158:161], v[214:217], v[100:103]
	v_mfma_f32_16x16x32_bf16 v[96:99], v[166:169], v[214:217], v[96:99]
	v_mfma_f32_16x16x32_bf16 v[92:95], v[218:221], v[170:173], 0
	v_mfma_f32_16x16x32_bf16 v[88:91], v[226:229], v[170:173], 0
	v_mfma_f32_16x16x32_bf16 v[84:87], v[218:221], v[178:181], 0
	v_mfma_f32_16x16x32_bf16 v[80:83], v[226:229], v[178:181], 0
	v_mfma_f32_16x16x32_bf16 v[76:79], v[218:221], v[194:197], 0
	v_mfma_f32_16x16x32_bf16 v[72:75], v[226:229], v[194:197], 0
	v_mfma_f32_16x16x32_bf16 v[68:71], v[218:221], v[210:213], 0
	v_mfma_f32_16x16x32_bf16 v[64:67], v[226:229], v[210:213], 0
	v_mfma_f32_16x16x32_bf16 v[92:95], v[222:225], v[174:177], v[92:95]
	v_mfma_f32_16x16x32_bf16 v[88:91], v[230:233], v[174:177], v[88:91]
	v_mfma_f32_16x16x32_bf16 v[84:87], v[222:225], v[182:185], v[84:87]
	v_mfma_f32_16x16x32_bf16 v[80:83], v[230:233], v[182:185], v[80:83]
	v_mfma_f32_16x16x32_bf16 v[76:79], v[222:225], v[206:209], v[76:79]
	v_mfma_f32_16x16x32_bf16 v[72:75], v[230:233], v[206:209], v[72:75]
	v_mfma_f32_16x16x32_bf16 v[68:71], v[222:225], v[214:217], v[68:71]
	v_mfma_f32_16x16x32_bf16 v[64:67], v[230:233], v[214:217], v[64:67]
	s_add_i32 s19, s80, s57
	v_lshl_add_u64 v[234:235], s[50:51], 0, v[140:141]
	s_mov_b32 m0, s19
	s_barrier
	s_nop 0
	global_load_lds_dwordx4 v[234:235], off
	v_lshl_add_u64 v[236:237], s[50:51], 0, v[132:133]
	s_add_i32 m0, s19, 0x2000
	s_nop 0
	global_load_lds_dwordx4 v[236:237], off
	s_mov_b32 m0, s58
	v_lshl_add_u64 v[238:239], s[52:53], 0, v[128:129]
	ds_read_b128 v[170:173], v156 offset:16384
	ds_read_b128 v[174:177], v156 offset:17408
	ds_read_b128 v[178:181], v156 offset:18432
	ds_read_b128 v[182:185], v156 offset:19456
	ds_read_b128 v[194:197], v156 offset:20480
	ds_read_b128 v[206:209], v156 offset:21504
	ds_read_b128 v[210:213], v156 offset:22528
	ds_read_b128 v[214:217], v156 offset:23552
	global_load_lds_dwordx4 v[238:239], off
	v_lshl_add_u64 v[240:241], s[52:53], 0, v[130:131]
	s_mov_b32 m0, s59
	s_nop 0
	global_load_lds_dwordx4 v[240:241], off
	s_add_u32 s80, s50, 0x40000
	s_addc_u32 s81, s51, 0
	s_add_i32 s6, s6, s57
	v_lshl_add_u64 v[250:251], s[80:81], 0, v[140:141]
	s_mov_b32 m0, s6
	s_nop 0
	global_load_lds_dwordx4 v[250:251], off
	v_lshl_add_u64 v[250:251], s[80:81], 0, v[132:133]
	s_add_i32 m0, s6, 0x2000
	s_nop 0
	global_load_lds_dwordx4 v[250:251], off
	s_waitcnt vmcnt(24)
	s_cmp_lg_u32 s100, 0
	s_cbranch_scc1 .Lm4bp_315
	s_waitcnt vmcnt(8)
.Lm4bp_315:
	s_waitcnt lgkmcnt(0)
	s_mov_b32 s100, 0
	s_barrier
	v_mfma_f32_16x16x32_bf16 v[60:63], v[146:149], v[170:173], 0
	v_mfma_f32_16x16x32_bf16 v[56:59], v[162:165], v[170:173], 0
	v_mfma_f32_16x16x32_bf16 v[52:55], v[146:149], v[178:181], 0
	v_mfma_f32_16x16x32_bf16 v[48:51], v[162:165], v[178:181], 0
	v_mfma_f32_16x16x32_bf16 v[44:47], v[146:149], v[194:197], 0
	v_mfma_f32_16x16x32_bf16 v[40:43], v[162:165], v[194:197], 0
	v_mfma_f32_16x16x32_bf16 v[36:39], v[146:149], v[210:213], 0
	v_mfma_f32_16x16x32_bf16 v[32:35], v[162:165], v[210:213], 0
	v_mfma_f32_16x16x32_bf16 v[60:63], v[158:161], v[174:177], v[60:63]
	v_mfma_f32_16x16x32_bf16 v[56:59], v[166:169], v[174:177], v[56:59]
	v_mfma_f32_16x16x32_bf16 v[52:55], v[158:161], v[182:185], v[52:55]
	v_mfma_f32_16x16x32_bf16 v[48:51], v[166:169], v[182:185], v[48:51]
	v_mfma_f32_16x16x32_bf16 v[44:47], v[158:161], v[206:209], v[44:47]
	v_mfma_f32_16x16x32_bf16 v[40:43], v[166:169], v[206:209], v[40:43]
	v_mfma_f32_16x16x32_bf16 v[36:39], v[158:161], v[214:217], v[36:39]
	v_mfma_f32_16x16x32_bf16 v[32:35], v[166:169], v[214:217], v[32:35]
	v_mfma_f32_16x16x32_bf16 v[28:31], v[218:221], v[170:173], 0
	v_mfma_f32_16x16x32_bf16 v[24:27], v[226:229], v[170:173], 0
	v_mfma_f32_16x16x32_bf16 v[20:23], v[218:221], v[178:181], 0
	v_mfma_f32_16x16x32_bf16 v[16:19], v[226:229], v[178:181], 0
	v_mfma_f32_16x16x32_bf16 v[12:15], v[218:221], v[194:197], 0
	v_mfma_f32_16x16x32_bf16 v[8:11], v[226:229], v[194:197], 0
	v_mfma_f32_16x16x32_bf16 v[4:7], v[218:221], v[210:213], 0
	v_mfma_f32_16x16x32_bf16 v[0:3], v[226:229], v[210:213], 0
	v_mfma_f32_16x16x32_bf16 v[28:31], v[222:225], v[174:177], v[28:31]
	v_mfma_f32_16x16x32_bf16 v[24:27], v[230:233], v[174:177], v[24:27]
	v_mfma_f32_16x16x32_bf16 v[20:23], v[222:225], v[182:185], v[20:23]
	v_mfma_f32_16x16x32_bf16 v[16:19], v[230:233], v[182:185], v[16:19]
	v_mfma_f32_16x16x32_bf16 v[12:15], v[222:225], v[206:209], v[12:15]
	v_mfma_f32_16x16x32_bf16 v[8:11], v[230:233], v[206:209], v[8:11]
	v_mfma_f32_16x16x32_bf16 v[4:7], v[222:225], v[214:217], v[4:7]
	v_mfma_f32_16x16x32_bf16 v[0:3], v[230:233], v[214:217], v[0:3]
	s_add_i32 s6, 0, 0x18000
	v_add_u32_e32 v157, s6, v154
	s_barrier
	ds_read_b128 v[146:149], v157
	ds_read_b128 v[158:161], v157 offset:1024
	ds_read_b128 v[162:165], v157 offset:2048
	ds_read_b128 v[166:169], v157 offset:3072
	s_add_u32 s52, s52, 0x40000
	s_addc_u32 s53, s53, 0
	s_mov_b32 m0, s68
	v_lshl_add_u64 v[218:219], s[52:53], 0, v[128:129]
	ds_read_b128 v[170:173], v156 offset:32768
	ds_read_b128 v[174:177], v156 offset:33792
	ds_read_b128 v[178:181], v156 offset:34816
	ds_read_b128 v[182:185], v156 offset:35840
	ds_read_b128 v[194:197], v156 offset:36864
	ds_read_b128 v[206:209], v156 offset:37888
	ds_read_b128 v[210:213], v156 offset:38912
	ds_read_b128 v[214:217], v156 offset:39936
	global_load_lds_dwordx4 v[218:219], off
	v_lshl_add_u64 v[218:219], s[52:53], 0, v[130:131]
	s_mov_b32 m0, s69
	s_nop 0
	global_load_lds_dwordx4 v[218:219], off
	s_add_i32 s19, 0, 0x1c000
	v_add_u32_e32 v157, s19, v154
	ds_read_b128 v[218:221], v157
	ds_read_b128 v[222:225], v157 offset:1024
	ds_read_b128 v[226:229], v157 offset:2048
	ds_read_b128 v[230:233], v157 offset:3072
	s_waitcnt vmcnt(8)
	s_waitcnt lgkmcnt(0)
	s_barrier
	v_mfma_f32_16x16x32_bf16 v[124:127], v[146:149], v[170:173], v[124:127]
	v_mfma_f32_16x16x32_bf16 v[120:123], v[162:165], v[170:173], v[120:123]
	v_mfma_f32_16x16x32_bf16 v[116:119], v[146:149], v[178:181], v[116:119]
	v_mfma_f32_16x16x32_bf16 v[112:115], v[162:165], v[178:181], v[112:115]
	v_mfma_f32_16x16x32_bf16 v[108:111], v[146:149], v[194:197], v[108:111]
	v_mfma_f32_16x16x32_bf16 v[104:107], v[162:165], v[194:197], v[104:107]
	v_mfma_f32_16x16x32_bf16 v[100:103], v[146:149], v[210:213], v[100:103]
	v_mfma_f32_16x16x32_bf16 v[96:99], v[162:165], v[210:213], v[96:99]
	v_mfma_f32_16x16x32_bf16 v[124:127], v[158:161], v[174:177], v[124:127]
	v_mfma_f32_16x16x32_bf16 v[120:123], v[166:169], v[174:177], v[120:123]
	v_mfma_f32_16x16x32_bf16 v[116:119], v[158:161], v[182:185], v[116:119]
	v_mfma_f32_16x16x32_bf16 v[112:115], v[166:169], v[182:185], v[112:115]
	v_mfma_f32_16x16x32_bf16 v[108:111], v[158:161], v[206:209], v[108:111]
	v_mfma_f32_16x16x32_bf16 v[104:107], v[166:169], v[206:209], v[104:107]
	v_mfma_f32_16x16x32_bf16 v[100:103], v[158:161], v[214:217], v[100:103]
	v_mfma_f32_16x16x32_bf16 v[96:99], v[166:169], v[214:217], v[96:99]
	v_mfma_f32_16x16x32_bf16 v[92:95], v[218:221], v[170:173], v[92:95]
	v_mfma_f32_16x16x32_bf16 v[88:91], v[226:229], v[170:173], v[88:91]
	v_mfma_f32_16x16x32_bf16 v[84:87], v[218:221], v[178:181], v[84:87]
	v_mfma_f32_16x16x32_bf16 v[80:83], v[226:229], v[178:181], v[80:83]
	v_mfma_f32_16x16x32_bf16 v[76:79], v[218:221], v[194:197], v[76:79]
	v_mfma_f32_16x16x32_bf16 v[72:75], v[226:229], v[194:197], v[72:75]
	v_mfma_f32_16x16x32_bf16 v[68:71], v[218:221], v[210:213], v[68:71]
	v_mfma_f32_16x16x32_bf16 v[64:67], v[226:229], v[210:213], v[64:67]
	v_mfma_f32_16x16x32_bf16 v[92:95], v[222:225], v[174:177], v[92:95]
	v_mfma_f32_16x16x32_bf16 v[88:91], v[230:233], v[174:177], v[88:91]
	v_mfma_f32_16x16x32_bf16 v[84:87], v[222:225], v[182:185], v[84:87]
	v_mfma_f32_16x16x32_bf16 v[80:83], v[230:233], v[182:185], v[80:83]
	v_mfma_f32_16x16x32_bf16 v[76:79], v[222:225], v[206:209], v[76:79]
	v_mfma_f32_16x16x32_bf16 v[72:75], v[230:233], v[206:209], v[72:75]
	v_mfma_f32_16x16x32_bf16 v[68:71], v[222:225], v[214:217], v[68:71]
	v_mfma_f32_16x16x32_bf16 v[64:67], v[230:233], v[214:217], v[64:67]
	s_add_i32 s6, s6, s57
	v_lshl_add_u64 v[234:235], v[234:235], 0, s[36:37]
	s_mov_b32 m0, s6
	s_barrier
	s_nop 0
	global_load_lds_dwordx4 v[234:235], off
	v_lshl_add_u64 v[234:235], v[236:237], 0, s[36:37]
	s_add_i32 m0, s6, 0x2000
	s_nop 0
	global_load_lds_dwordx4 v[234:235], off
	s_mov_b32 m0, s71
	v_lshl_add_u64 v[234:235], v[238:239], 0, s[36:37]
	ds_read_b128 v[170:173], v156 offset:49152
	ds_read_b128 v[174:177], v156 offset:50176
	ds_read_b128 v[178:181], v156 offset:51200
	ds_read_b128 v[182:185], v156 offset:52224
	ds_read_b128 v[194:197], v156 offset:53248
	ds_read_b128 v[206:209], v156 offset:54272
	ds_read_b128 v[210:213], v156 offset:55296
	ds_read_b128 v[214:217], v156 offset:56320
	global_load_lds_dwordx4 v[234:235], off
	v_lshl_add_u64 v[234:235], v[240:241], 0, s[36:37]
	s_mov_b32 m0, s72
	s_nop 0
	global_load_lds_dwordx4 v[234:235], off
	s_add_u32 s50, s50, 0x40080
	s_addc_u32 s51, s51, 0
	s_add_i32 s6, s19, s57
	v_lshl_add_u64 v[250:251], s[50:51], 0, v[140:141]
	s_mov_b32 m0, s6
	s_nop 0
	global_load_lds_dwordx4 v[250:251], off
	v_lshl_add_u64 v[250:251], s[50:51], 0, v[132:133]
	s_add_i32 m0, s6, 0x2000
	s_nop 0
	global_load_lds_dwordx4 v[250:251], off
	s_waitcnt vmcnt(8)
	s_waitcnt lgkmcnt(0)
	s_barrier
	v_mfma_f32_16x16x32_bf16 v[60:63], v[146:149], v[170:173], v[60:63]
	v_mfma_f32_16x16x32_bf16 v[56:59], v[162:165], v[170:173], v[56:59]
	v_mfma_f32_16x16x32_bf16 v[52:55], v[146:149], v[178:181], v[52:55]
	v_mfma_f32_16x16x32_bf16 v[48:51], v[162:165], v[178:181], v[48:51]
	v_mfma_f32_16x16x32_bf16 v[44:47], v[146:149], v[194:197], v[44:47]
	v_mfma_f32_16x16x32_bf16 v[40:43], v[162:165], v[194:197], v[40:43]
	v_mfma_f32_16x16x32_bf16 v[36:39], v[146:149], v[210:213], v[36:39]
	v_mfma_f32_16x16x32_bf16 v[32:35], v[162:165], v[210:213], v[32:35]
	v_mfma_f32_16x16x32_bf16 v[60:63], v[158:161], v[174:177], v[60:63]
	v_mfma_f32_16x16x32_bf16 v[56:59], v[166:169], v[174:177], v[56:59]
	v_mfma_f32_16x16x32_bf16 v[52:55], v[158:161], v[182:185], v[52:55]
	v_mfma_f32_16x16x32_bf16 v[48:51], v[166:169], v[182:185], v[48:51]
	v_mfma_f32_16x16x32_bf16 v[44:47], v[158:161], v[206:209], v[44:47]
	v_mfma_f32_16x16x32_bf16 v[40:43], v[166:169], v[206:209], v[40:43]
	v_mfma_f32_16x16x32_bf16 v[36:39], v[158:161], v[214:217], v[36:39]
	v_mfma_f32_16x16x32_bf16 v[32:35], v[166:169], v[214:217], v[32:35]
	v_mfma_f32_16x16x32_bf16 v[28:31], v[218:221], v[170:173], v[28:31]
	v_mfma_f32_16x16x32_bf16 v[24:27], v[226:229], v[170:173], v[24:27]
	v_mfma_f32_16x16x32_bf16 v[20:23], v[218:221], v[178:181], v[20:23]
	v_mfma_f32_16x16x32_bf16 v[16:19], v[226:229], v[178:181], v[16:19]
	v_mfma_f32_16x16x32_bf16 v[12:15], v[218:221], v[194:197], v[12:15]
	v_mfma_f32_16x16x32_bf16 v[8:11], v[226:229], v[194:197], v[8:11]
	v_mfma_f32_16x16x32_bf16 v[4:7], v[218:221], v[210:213], v[4:7]
	v_mfma_f32_16x16x32_bf16 v[0:3], v[226:229], v[210:213], v[0:3]
	v_mfma_f32_16x16x32_bf16 v[28:31], v[222:225], v[174:177], v[28:31]
	v_mfma_f32_16x16x32_bf16 v[24:27], v[230:233], v[174:177], v[24:27]
	v_mfma_f32_16x16x32_bf16 v[20:23], v[222:225], v[182:185], v[20:23]
	v_mfma_f32_16x16x32_bf16 v[16:19], v[230:233], v[182:185], v[16:19]
	v_mfma_f32_16x16x32_bf16 v[12:15], v[222:225], v[206:209], v[12:15]
	v_mfma_f32_16x16x32_bf16 v[8:11], v[230:233], v[206:209], v[8:11]
	v_mfma_f32_16x16x32_bf16 v[4:7], v[222:225], v[214:217], v[4:7]
	v_mfma_f32_16x16x32_bf16 v[0:3], v[230:233], v[214:217], v[0:3]
	s_add_i32 s75, s75, 2
	s_add_u32 s48, s48, 0x100
	s_addc_u32 s49, s49, 0
	s_cmp_gt_u32 s75, 13
	s_add_u32 s6, s4, s48
	s_addc_u32 s19, s5, s49
	s_add_u32 s6, s6, 0x100
	s_addc_u32 s19, s19, 0
	s_add_u32 s23, s11, s48
	s_addc_u32 s50, s12, s49
	s_add_i32 s80, 0, 0x10000
	s_cmpk_eq_i32 s48, 0x700
	s_cselect_b32 s53, s29, s19
	s_cselect_b32 s52, s31, s6
	s_cselect_b32 s51, s35, s50
	s_cselect_b32 s50, s74, s23
my_head_315:
	s_barrier
.LBB0_315:
	v_add_u32_e32 v157, s80, v154
	ds_read_b128 v[146:149], v157
	ds_read_b128 v[158:161], v157 offset:1024
	ds_read_b128 v[162:165], v157 offset:2048
	ds_read_b128 v[166:169], v157 offset:3072
	v_lshl_add_u64 v[218:219], v[150:151], 0, s[48:49]
	s_add_i32 m0, s58, 0xc000
	ds_read_b128 v[170:173], v156
	ds_read_b128 v[174:177], v156 offset:1024
	ds_read_b128 v[178:181], v156 offset:2048
	ds_read_b128 v[182:185], v156 offset:3072
	ds_read_b128 v[194:197], v156 offset:4096
	ds_read_b128 v[206:209], v156 offset:5120
	ds_read_b128 v[210:213], v156 offset:6144
	ds_read_b128 v[214:217], v156 offset:7168
	global_load_lds_dwordx4 v[218:219], off
	v_lshl_add_u64 v[218:219], v[152:153], 0, s[48:49]
	s_add_i32 m0, s58, 0xe000
	s_nop 0
	global_load_lds_dwordx4 v[218:219], off
	s_add_i32 s6, 0, 0x14000
	v_add_u32_e32 v157, s6, v154
	ds_read_b128 v[218:221], v157
	ds_read_b128 v[222:225], v157 offset:1024
	ds_read_b128 v[226:229], v157 offset:2048
	ds_read_b128 v[230:233], v157 offset:3072
	s_waitcnt vmcnt(8)
	s_waitcnt lgkmcnt(0)
	s_barrier
	v_mfma_f32_16x16x32_bf16 v[124:127], v[146:149], v[170:173], v[124:127]
	v_mfma_f32_16x16x32_bf16 v[120:123], v[162:165], v[170:173], v[120:123]
	v_mfma_f32_16x16x32_bf16 v[116:119], v[146:149], v[178:181], v[116:119]
	v_mfma_f32_16x16x32_bf16 v[112:115], v[162:165], v[178:181], v[112:115]
	v_mfma_f32_16x16x32_bf16 v[108:111], v[146:149], v[194:197], v[108:111]
	v_mfma_f32_16x16x32_bf16 v[104:107], v[162:165], v[194:197], v[104:107]
	v_mfma_f32_16x16x32_bf16 v[100:103], v[146:149], v[210:213], v[100:103]
	v_mfma_f32_16x16x32_bf16 v[96:99], v[162:165], v[210:213], v[96:99]
	v_mfma_f32_16x16x32_bf16 v[124:127], v[158:161], v[174:177], v[124:127]
	v_mfma_f32_16x16x32_bf16 v[120:123], v[166:169], v[174:177], v[120:123]
	v_mfma_f32_16x16x32_bf16 v[116:119], v[158:161], v[182:185], v[116:119]
	v_mfma_f32_16x16x32_bf16 v[112:115], v[166:169], v[182:185], v[112:115]
	v_mfma_f32_16x16x32_bf16 v[108:111], v[158:161], v[206:209], v[108:111]
	v_mfma_f32_16x16x32_bf16 v[104:107], v[166:169], v[206:209], v[104:107]
	v_mfma_f32_16x16x32_bf16 v[100:103], v[158:161], v[214:217], v[100:103]
	v_mfma_f32_16x16x32_bf16 v[96:99], v[166:169], v[214:217], v[96:99]
	v_mfma_f32_16x16x32_bf16 v[92:95], v[218:221], v[170:173], v[92:95]
	v_mfma_f32_16x16x32_bf16 v[88:91], v[226:229], v[170:173], v[88:91]
	v_mfma_f32_16x16x32_bf16 v[84:87], v[218:221], v[178:181], v[84:87]
	v_mfma_f32_16x16x32_bf16 v[80:83], v[226:229], v[178:181], v[80:83]
	v_mfma_f32_16x16x32_bf16 v[76:79], v[218:221], v[194:197], v[76:79]
	v_mfma_f32_16x16x32_bf16 v[72:75], v[226:229], v[194:197], v[72:75]
	v_mfma_f32_16x16x32_bf16 v[68:71], v[218:221], v[210:213], v[68:71]
	v_mfma_f32_16x16x32_bf16 v[64:67], v[226:229], v[210:213], v[64:67]
	v_mfma_f32_16x16x32_bf16 v[92:95], v[222:225], v[174:177], v[92:95]
	v_mfma_f32_16x16x32_bf16 v[88:91], v[230:233], v[174:177], v[88:91]
	v_mfma_f32_16x16x32_bf16 v[84:87], v[222:225], v[182:185], v[84:87]
	v_mfma_f32_16x16x32_bf16 v[80:83], v[230:233], v[182:185], v[80:83]
	v_mfma_f32_16x16x32_bf16 v[76:79], v[222:225], v[206:209], v[76:79]
	v_mfma_f32_16x16x32_bf16 v[72:75], v[230:233], v[206:209], v[72:75]
	v_mfma_f32_16x16x32_bf16 v[68:71], v[222:225], v[214:217], v[68:71]
	v_mfma_f32_16x16x32_bf16 v[64:67], v[230:233], v[214:217], v[64:67]
	s_add_i32 s19, s80, s57
	v_lshl_add_u64 v[234:235], s[50:51], 0, v[140:141]
	s_mov_b32 m0, s19
	s_barrier
	s_nop 0
	global_load_lds_dwordx4 v[234:235], off
	v_lshl_add_u64 v[236:237], s[50:51], 0, v[132:133]
	s_add_i32 m0, s19, 0x2000
	s_nop 0
	global_load_lds_dwordx4 v[236:237], off
	s_mov_b32 m0, s58
	v_lshl_add_u64 v[238:239], s[52:53], 0, v[128:129]
	ds_read_b128 v[170:173], v156 offset:16384
	ds_read_b128 v[174:177], v156 offset:17408
	ds_read_b128 v[178:181], v156 offset:18432
	ds_read_b128 v[182:185], v156 offset:19456
	ds_read_b128 v[194:197], v156 offset:20480
	ds_read_b128 v[206:209], v156 offset:21504
	ds_read_b128 v[210:213], v156 offset:22528
	ds_read_b128 v[214:217], v156 offset:23552
	global_load_lds_dwordx4 v[238:239], off
	v_lshl_add_u64 v[240:241], s[52:53], 0, v[130:131]
	s_mov_b32 m0, s59
	s_nop 0
	global_load_lds_dwordx4 v[240:241], off
	s_add_u32 s80, s50, 0x40000
	s_addc_u32 s81, s51, 0
	s_add_i32 s6, s6, s57
	v_lshl_add_u64 v[250:251], s[80:81], 0, v[140:141]
	s_mov_b32 m0, s6
	s_nop 0
	global_load_lds_dwordx4 v[250:251], off
	v_lshl_add_u64 v[250:251], s[80:81], 0, v[132:133]
	s_add_i32 m0, s6, 0x2000
	s_nop 0
	global_load_lds_dwordx4 v[250:251], off
	s_waitcnt vmcnt(8)
	s_waitcnt lgkmcnt(0)
	s_barrier
	v_mfma_f32_16x16x32_bf16 v[60:63], v[146:149], v[170:173], v[60:63]
	v_mfma_f32_16x16x32_bf16 v[56:59], v[162:165], v[170:173], v[56:59]
	v_mfma_f32_16x16x32_bf16 v[52:55], v[146:149], v[178:181], v[52:55]
	v_mfma_f32_16x16x32_bf16 v[48:51], v[162:165], v[178:181], v[48:51]
	v_mfma_f32_16x16x32_bf16 v[44:47], v[146:149], v[194:197], v[44:47]
	v_mfma_f32_16x16x32_bf16 v[40:43], v[162:165], v[194:197], v[40:43]
	v_mfma_f32_16x16x32_bf16 v[36:39], v[146:149], v[210:213], v[36:39]
	v_mfma_f32_16x16x32_bf16 v[32:35], v[162:165], v[210:213], v[32:35]
	v_mfma_f32_16x16x32_bf16 v[60:63], v[158:161], v[174:177], v[60:63]
	v_mfma_f32_16x16x32_bf16 v[56:59], v[166:169], v[174:177], v[56:59]
	v_mfma_f32_16x16x32_bf16 v[52:55], v[158:161], v[182:185], v[52:55]
	v_mfma_f32_16x16x32_bf16 v[48:51], v[166:169], v[182:185], v[48:51]
	v_mfma_f32_16x16x32_bf16 v[44:47], v[158:161], v[206:209], v[44:47]
	v_mfma_f32_16x16x32_bf16 v[40:43], v[166:169], v[206:209], v[40:43]
	v_mfma_f32_16x16x32_bf16 v[36:39], v[158:161], v[214:217], v[36:39]
	v_mfma_f32_16x16x32_bf16 v[32:35], v[166:169], v[214:217], v[32:35]
	v_mfma_f32_16x16x32_bf16 v[28:31], v[218:221], v[170:173], v[28:31]
	v_mfma_f32_16x16x32_bf16 v[24:27], v[226:229], v[170:173], v[24:27]
	v_mfma_f32_16x16x32_bf16 v[20:23], v[218:221], v[178:181], v[20:23]
	v_mfma_f32_16x16x32_bf16 v[16:19], v[226:229], v[178:181], v[16:19]
	v_mfma_f32_16x16x32_bf16 v[12:15], v[218:221], v[194:197], v[12:15]
	v_mfma_f32_16x16x32_bf16 v[8:11], v[226:229], v[194:197], v[8:11]
	v_mfma_f32_16x16x32_bf16 v[4:7], v[218:221], v[210:213], v[4:7]
	v_mfma_f32_16x16x32_bf16 v[0:3], v[226:229], v[210:213], v[0:3]
	v_mfma_f32_16x16x32_bf16 v[28:31], v[222:225], v[174:177], v[28:31]
	v_mfma_f32_16x16x32_bf16 v[24:27], v[230:233], v[174:177], v[24:27]
	v_mfma_f32_16x16x32_bf16 v[20:23], v[222:225], v[182:185], v[20:23]
	v_mfma_f32_16x16x32_bf16 v[16:19], v[230:233], v[182:185], v[16:19]
	v_mfma_f32_16x16x32_bf16 v[12:15], v[222:225], v[206:209], v[12:15]
	v_mfma_f32_16x16x32_bf16 v[8:11], v[230:233], v[206:209], v[8:11]
	v_mfma_f32_16x16x32_bf16 v[4:7], v[222:225], v[214:217], v[4:7]
	v_mfma_f32_16x16x32_bf16 v[0:3], v[230:233], v[214:217], v[0:3]
	s_add_i32 s6, 0, 0x18000
	v_add_u32_e32 v157, s6, v154
	s_barrier
	ds_read_b128 v[146:149], v157
	ds_read_b128 v[158:161], v157 offset:1024
	ds_read_b128 v[162:165], v157 offset:2048
	ds_read_b128 v[166:169], v157 offset:3072
	s_add_u32 s52, s52, 0x40000
	s_addc_u32 s53, s53, 0
	s_mov_b32 m0, s68
	v_lshl_add_u64 v[218:219], s[52:53], 0, v[128:129]
	ds_read_b128 v[170:173], v156 offset:32768
	ds_read_b128 v[174:177], v156 offset:33792
	ds_read_b128 v[178:181], v156 offset:34816
	ds_read_b128 v[182:185], v156 offset:35840
	ds_read_b128 v[194:197], v156 offset:36864
	ds_read_b128 v[206:209], v156 offset:37888
	ds_read_b128 v[210:213], v156 offset:38912
	ds_read_b128 v[214:217], v156 offset:39936
	global_load_lds_dwordx4 v[218:219], off
	v_lshl_add_u64 v[218:219], s[52:53], 0, v[130:131]
	s_mov_b32 m0, s69
	s_nop 0
	global_load_lds_dwordx4 v[218:219], off
	s_add_i32 s19, 0, 0x1c000
	v_add_u32_e32 v157, s19, v154
	ds_read_b128 v[218:221], v157
	ds_read_b128 v[222:225], v157 offset:1024
	ds_read_b128 v[226:229], v157 offset:2048
	ds_read_b128 v[230:233], v157 offset:3072
	s_waitcnt vmcnt(8)
	s_waitcnt lgkmcnt(0)
	s_barrier
	v_mfma_f32_16x16x32_bf16 v[124:127], v[146:149], v[170:173], v[124:127]
	v_mfma_f32_16x16x32_bf16 v[120:123], v[162:165], v[170:173], v[120:123]
	v_mfma_f32_16x16x32_bf16 v[116:119], v[146:149], v[178:181], v[116:119]
	v_mfma_f32_16x16x32_bf16 v[112:115], v[162:165], v[178:181], v[112:115]
	v_mfma_f32_16x16x32_bf16 v[108:111], v[146:149], v[194:197], v[108:111]
	v_mfma_f32_16x16x32_bf16 v[104:107], v[162:165], v[194:197], v[104:107]
	v_mfma_f32_16x16x32_bf16 v[100:103], v[146:149], v[210:213], v[100:103]
	v_mfma_f32_16x16x32_bf16 v[96:99], v[162:165], v[210:213], v[96:99]
	v_mfma_f32_16x16x32_bf16 v[124:127], v[158:161], v[174:177], v[124:127]
	v_mfma_f32_16x16x32_bf16 v[120:123], v[166:169], v[174:177], v[120:123]
	v_mfma_f32_16x16x32_bf16 v[116:119], v[158:161], v[182:185], v[116:119]
	v_mfma_f32_16x16x32_bf16 v[112:115], v[166:169], v[182:185], v[112:115]
	v_mfma_f32_16x16x32_bf16 v[108:111], v[158:161], v[206:209], v[108:111]
	v_mfma_f32_16x16x32_bf16 v[104:107], v[166:169], v[206:209], v[104:107]
	v_mfma_f32_16x16x32_bf16 v[100:103], v[158:161], v[214:217], v[100:103]
	v_mfma_f32_16x16x32_bf16 v[96:99], v[166:169], v[214:217], v[96:99]
	v_mfma_f32_16x16x32_bf16 v[92:95], v[218:221], v[170:173], v[92:95]
	v_mfma_f32_16x16x32_bf16 v[88:91], v[226:229], v[170:173], v[88:91]
	v_mfma_f32_16x16x32_bf16 v[84:87], v[218:221], v[178:181], v[84:87]
	v_mfma_f32_16x16x32_bf16 v[80:83], v[226:229], v[178:181], v[80:83]
	v_mfma_f32_16x16x32_bf16 v[76:79], v[218:221], v[194:197], v[76:79]
	v_mfma_f32_16x16x32_bf16 v[72:75], v[226:229], v[194:197], v[72:75]
	v_mfma_f32_16x16x32_bf16 v[68:71], v[218:221], v[210:213], v[68:71]
	v_mfma_f32_16x16x32_bf16 v[64:67], v[226:229], v[210:213], v[64:67]
	v_mfma_f32_16x16x32_bf16 v[92:95], v[222:225], v[174:177], v[92:95]
	v_mfma_f32_16x16x32_bf16 v[88:91], v[230:233], v[174:177], v[88:91]
	v_mfma_f32_16x16x32_bf16 v[84:87], v[222:225], v[182:185], v[84:87]
	v_mfma_f32_16x16x32_bf16 v[80:83], v[230:233], v[182:185], v[80:83]
	v_mfma_f32_16x16x32_bf16 v[76:79], v[222:225], v[206:209], v[76:79]
	v_mfma_f32_16x16x32_bf16 v[72:75], v[230:233], v[206:209], v[72:75]
	v_mfma_f32_16x16x32_bf16 v[68:71], v[222:225], v[214:217], v[68:71]
	v_mfma_f32_16x16x32_bf16 v[64:67], v[230:233], v[214:217], v[64:67]
	s_add_i32 s6, s6, s57
	v_lshl_add_u64 v[234:235], v[234:235], 0, s[36:37]
	s_mov_b32 m0, s6
	s_barrier
	s_nop 0
	global_load_lds_dwordx4 v[234:235], off
	v_lshl_add_u64 v[234:235], v[236:237], 0, s[36:37]
	s_add_i32 m0, s6, 0x2000
	s_nop 0
	global_load_lds_dwordx4 v[234:235], off
	s_mov_b32 m0, s71
	v_lshl_add_u64 v[234:235], v[238:239], 0, s[36:37]
	ds_read_b128 v[170:173], v156 offset:49152
	ds_read_b128 v[174:177], v156 offset:50176
	ds_read_b128 v[178:181], v156 offset:51200
	ds_read_b128 v[182:185], v156 offset:52224
	ds_read_b128 v[194:197], v156 offset:53248
	ds_read_b128 v[206:209], v156 offset:54272
	ds_read_b128 v[210:213], v156 offset:55296
	ds_read_b128 v[214:217], v156 offset:56320
	global_load_lds_dwordx4 v[234:235], off
	v_lshl_add_u64 v[234:235], v[240:241], 0, s[36:37]
	s_mov_b32 m0, s72
	s_nop 0
	global_load_lds_dwordx4 v[234:235], off
	s_add_u32 s50, s50, 0x40080
	s_addc_u32 s51, s51, 0
	s_add_i32 s6, s19, s57
	v_lshl_add_u64 v[250:251], s[50:51], 0, v[140:141]
	s_mov_b32 m0, s6
	s_nop 0
	global_load_lds_dwordx4 v[250:251], off
	v_lshl_add_u64 v[250:251], s[50:51], 0, v[132:133]
	s_add_i32 m0, s6, 0x2000
	s_nop 0
	global_load_lds_dwordx4 v[250:251], off
	s_waitcnt vmcnt(8)
	s_waitcnt lgkmcnt(0)
	s_barrier
	v_mfma_f32_16x16x32_bf16 v[60:63], v[146:149], v[170:173], v[60:63]
	v_mfma_f32_16x16x32_bf16 v[56:59], v[162:165], v[170:173], v[56:59]
	v_mfma_f32_16x16x32_bf16 v[52:55], v[146:149], v[178:181], v[52:55]
	v_mfma_f32_16x16x32_bf16 v[48:51], v[162:165], v[178:181], v[48:51]
	v_mfma_f32_16x16x32_bf16 v[44:47], v[146:149], v[194:197], v[44:47]
	v_mfma_f32_16x16x32_bf16 v[40:43], v[162:165], v[194:197], v[40:43]
	v_mfma_f32_16x16x32_bf16 v[36:39], v[146:149], v[210:213], v[36:39]
	v_mfma_f32_16x16x32_bf16 v[32:35], v[162:165], v[210:213], v[32:35]
	v_mfma_f32_16x16x32_bf16 v[60:63], v[158:161], v[174:177], v[60:63]
	v_mfma_f32_16x16x32_bf16 v[56:59], v[166:169], v[174:177], v[56:59]
	v_mfma_f32_16x16x32_bf16 v[52:55], v[158:161], v[182:185], v[52:55]
	v_mfma_f32_16x16x32_bf16 v[48:51], v[166:169], v[182:185], v[48:51]
	v_mfma_f32_16x16x32_bf16 v[44:47], v[158:161], v[206:209], v[44:47]
	v_mfma_f32_16x16x32_bf16 v[40:43], v[166:169], v[206:209], v[40:43]
	v_mfma_f32_16x16x32_bf16 v[36:39], v[158:161], v[214:217], v[36:39]
	v_mfma_f32_16x16x32_bf16 v[32:35], v[166:169], v[214:217], v[32:35]
	v_mfma_f32_16x16x32_bf16 v[28:31], v[218:221], v[170:173], v[28:31]
	v_mfma_f32_16x16x32_bf16 v[24:27], v[226:229], v[170:173], v[24:27]
	v_mfma_f32_16x16x32_bf16 v[20:23], v[218:221], v[178:181], v[20:23]
	v_mfma_f32_16x16x32_bf16 v[16:19], v[226:229], v[178:181], v[16:19]
	v_mfma_f32_16x16x32_bf16 v[12:15], v[218:221], v[194:197], v[12:15]
	v_mfma_f32_16x16x32_bf16 v[8:11], v[226:229], v[194:197], v[8:11]
	v_mfma_f32_16x16x32_bf16 v[4:7], v[218:221], v[210:213], v[4:7]
	v_mfma_f32_16x16x32_bf16 v[0:3], v[226:229], v[210:213], v[0:3]
	v_mfma_f32_16x16x32_bf16 v[28:31], v[222:225], v[174:177], v[28:31]
	v_mfma_f32_16x16x32_bf16 v[24:27], v[230:233], v[174:177], v[24:27]
	v_mfma_f32_16x16x32_bf16 v[20:23], v[222:225], v[182:185], v[20:23]
	v_mfma_f32_16x16x32_bf16 v[16:19], v[230:233], v[182:185], v[16:19]
	v_mfma_f32_16x16x32_bf16 v[12:15], v[222:225], v[206:209], v[12:15]
	v_mfma_f32_16x16x32_bf16 v[8:11], v[230:233], v[206:209], v[8:11]
	v_mfma_f32_16x16x32_bf16 v[4:7], v[222:225], v[214:217], v[4:7]
	v_mfma_f32_16x16x32_bf16 v[0:3], v[230:233], v[214:217], v[0:3]
	s_add_i32 s75, s75, 2
	s_add_u32 s48, s48, 0x100
	s_addc_u32 s49, s49, 0
	s_cmp_gt_u32 s75, 13
	s_cbranch_scc1 my_exit_315
	s_add_u32 s6, s4, s48
	s_addc_u32 s19, s5, s49
	s_add_u32 s6, s6, 0x100
	s_addc_u32 s19, s19, 0
	s_add_u32 s23, s11, s48
	s_addc_u32 s50, s12, s49
	s_add_i32 s80, 0, 0x10000
	s_cmpk_eq_i32 s48, 0x700
	s_cselect_b32 s53, s29, s19
	s_cselect_b32 s52, s31, s6
	s_cselect_b32 s51, s35, s50
	s_cselect_b32 s50, s74, s23
	s_branch my_head_315
my_exit_315:
	s_barrier
	s_mov_b32 s100, 1
	s_add_u32 s48, s11, 0xffffff00
	v_lshl_or_b32 v146, s70, 8, v155
	s_addc_u32 s49, s12, -1
	s_ashr_i32 s29, s28, 31
	v_ashrrev_i32_e32 v147, 31, v146
	v_lshl_add_u64 v[146:147], v[146:147], 1, s[26:27]
	s_lshl_b64 s[50:51], s[28:29], 20
	v_lshl_add_u64 v[146:147], v[146:147], 0, s[50:51]
	v_lshl_add_u64 v[150:151], v[146:147], 0, v[134:135]
	v_cvt_pk_bf16_f32 v146, v124, v125
	v_cvt_pk_bf16_f32 v147, v126, v127
	v_cvt_pk_bf16_f32 v148, v120, v121
	v_cvt_pk_bf16_f32 v149, v122, v123
	global_store_dwordx4 v[150:151], v[146:149], off
	v_add_co_u32_e32 v152, vcc, s66, v150
	s_nop 0
	v_cvt_pk_bf16_f32 v146, v92, v93
	v_cvt_pk_bf16_f32 v147, v94, v95
	v_cvt_pk_bf16_f32 v148, v88, v89
	v_cvt_pk_bf16_f32 v149, v90, v91
	global_store_dwordx4 v[150:151], v[146:149], off offset:256
	v_addc_co_u32_e32 v153, vcc, 0, v151, vcc
	s_nop 0
	v_cvt_pk_bf16_f32 v146, v116, v117
	v_cvt_pk_bf16_f32 v147, v118, v119
	v_cvt_pk_bf16_f32 v148, v112, v113
	v_cvt_pk_bf16_f32 v149, v114, v115
	global_store_dwordx4 v[152:153], v[146:149], off
	s_mov_b32 s6, 0x20000
	s_nop 0
	v_cvt_pk_bf16_f32 v146, v84, v85
	v_cvt_pk_bf16_f32 v147, v86, v87
	v_cvt_pk_bf16_f32 v148, v80, v81
	v_cvt_pk_bf16_f32 v149, v82, v83
	global_store_dwordx4 v[152:153], v[146:149], off offset:256
	v_add_co_u32_e32 v152, vcc, s6, v150
	s_nop 0
	v_cvt_pk_bf16_f32 v146, v108, v109
	v_cvt_pk_bf16_f32 v147, v110, v111
	v_cvt_pk_bf16_f32 v148, v104, v105
	v_cvt_pk_bf16_f32 v149, v106, v107
	v_addc_co_u32_e32 v153, vcc, 0, v151, vcc
	global_store_dwordx4 v[152:153], v[146:149], off
	s_mov_b32 s6, 0x30000
	s_nop 0
	v_cvt_pk_bf16_f32 v146, v76, v77
	v_cvt_pk_bf16_f32 v147, v78, v79
	v_cvt_pk_bf16_f32 v148, v72, v73
	v_cvt_pk_bf16_f32 v149, v74, v75
	global_store_dwordx4 v[152:153], v[146:149], off offset:256
	v_add_co_u32_e32 v152, vcc, s6, v150
	s_nop 0
	v_cvt_pk_bf16_f32 v146, v100, v101
	v_cvt_pk_bf16_f32 v147, v102, v103
	v_cvt_pk_bf16_f32 v148, v96, v97
	v_cvt_pk_bf16_f32 v149, v98, v99
	v_addc_co_u32_e32 v153, vcc, 0, v151, vcc
	global_store_dwordx4 v[152:153], v[146:149], off
	s_mov_b32 s6, 0x80000
	s_nop 0
	v_cvt_pk_bf16_f32 v146, v68, v69
	v_cvt_pk_bf16_f32 v147, v70, v71
	v_cvt_pk_bf16_f32 v148, v64, v65
	v_cvt_pk_bf16_f32 v149, v66, v67
	global_store_dwordx4 v[152:153], v[146:149], off offset:256
	v_add_co_u32_e32 v152, vcc, s6, v150
	s_nop 0
	v_cvt_pk_bf16_f32 v146, v60, v61
	v_cvt_pk_bf16_f32 v147, v62, v63
	v_cvt_pk_bf16_f32 v148, v56, v57
	v_cvt_pk_bf16_f32 v149, v58, v59
	v_addc_co_u32_e32 v153, vcc, 0, v151, vcc
	global_store_dwordx4 v[152:153], v[146:149], off
	s_mov_b32 s6, 0x90000
	s_nop 0
	v_cvt_pk_bf16_f32 v146, v28, v29
	v_cvt_pk_bf16_f32 v147, v30, v31
	v_cvt_pk_bf16_f32 v148, v24, v25
	v_cvt_pk_bf16_f32 v149, v26, v27
	global_store_dwordx4 v[152:153], v[146:149], off offset:256
	v_add_co_u32_e32 v152, vcc, s6, v150
	s_nop 0
	v_cvt_pk_bf16_f32 v146, v52, v53
	v_cvt_pk_bf16_f32 v147, v54, v55
	v_cvt_pk_bf16_f32 v148, v48, v49
	v_cvt_pk_bf16_f32 v149, v50, v51
	v_addc_co_u32_e32 v153, vcc, 0, v151, vcc
	global_store_dwordx4 v[152:153], v[146:149], off
	s_mov_b32 s6, 0xa0000
	s_nop 0
	v_cvt_pk_bf16_f32 v146, v20, v21
	v_cvt_pk_bf16_f32 v147, v22, v23
	v_cvt_pk_bf16_f32 v148, v16, v17
	v_cvt_pk_bf16_f32 v149, v18, v19
	global_store_dwordx4 v[152:153], v[146:149], off offset:256
	v_add_co_u32_e32 v152, vcc, s6, v150
	s_nop 0
	v_cvt_pk_bf16_f32 v146, v44, v45
	v_cvt_pk_bf16_f32 v147, v46, v47
	v_cvt_pk_bf16_f32 v148, v40, v41
	v_cvt_pk_bf16_f32 v149, v42, v43
	v_addc_co_u32_e32 v153, vcc, 0, v151, vcc
	s_mov_b32 s6, 0xb0000
	global_store_dwordx4 v[152:153], v[146:149], off
	v_add_co_u32_e32 v150, vcc, s6, v150
	s_nop 0
	v_cvt_pk_bf16_f32 v146, v12, v13
	v_cvt_pk_bf16_f32 v147, v14, v15
	v_cvt_pk_bf16_f32 v148, v8, v9
	v_cvt_pk_bf16_f32 v149, v10, v11
	global_store_dwordx4 v[152:153], v[146:149], off offset:256
	v_addc_co_u32_e32 v151, vcc, 0, v151, vcc
	s_nop 0
	v_cvt_pk_bf16_f32 v146, v36, v37
	v_cvt_pk_bf16_f32 v147, v38, v39
	v_cvt_pk_bf16_f32 v148, v32, v33
	v_cvt_pk_bf16_f32 v149, v34, v35
	global_store_dwordx4 v[150:151], v[146:149], off
	s_andn2_b64 vcc, exec, s[44:45]
	s_nop 0
	v_cvt_pk_bf16_f32 v146, v4, v5
	v_cvt_pk_bf16_f32 v147, v6, v7
	v_cvt_pk_bf16_f32 v148, v0, v1
	v_cvt_pk_bf16_f32 v149, v2, v3
	global_store_dwordx4 v[150:151], v[146:149], off offset:256
	s_cbranch_vccz .LBB0_307
	s_mov_b64 s[42:43], s[48:49]
	s_andn2_b64 vcc, exec, s[38:39]
	s_mov_b64 s[48:49], s[42:43]
	s_cbranch_vccnz .LBB0_308

my_head_341:
	s_barrier
.LBB0_341:
	v_add_u32_e32 v146, s6, v206
	ds_read_b128 v[128:131], v146
	ds_read_b128 v[132:135], v146 offset:1024
	ds_read_b128 v[136:139], v146 offset:2048
	ds_read_b128 v[146:149], v146 offset:3072
	v_lshl_add_u64 v[214:215], s[50:51], 0, v[158:159]
	s_add_i32 m0, s58, 0xc000
	ds_read_b128 v[162:165], v208
	ds_read_b128 v[166:169], v208 offset:1024
	ds_read_b128 v[170:173], v208 offset:2048
	ds_read_b128 v[174:177], v208 offset:3072
	ds_read_b128 v[178:181], v208 offset:4096
	ds_read_b128 v[182:185], v208 offset:5120
	ds_read_b128 v[194:197], v208 offset:6144
	ds_read_b128 v[210:213], v208 offset:7168
	global_load_lds_dwordx4 v[214:215], off
	v_lshl_add_u64 v[214:215], s[50:51], 0, v[160:161]
	s_add_i32 m0, s58, 0xe000
	s_nop 0
	global_load_lds_dwordx4 v[214:215], off
	s_add_i32 s19, 0, 0x14000
	v_add_u32_e32 v192, s19, v206
	ds_read_b128 v[214:217], v192
	ds_read_b128 v[218:221], v192 offset:1024
	ds_read_b128 v[222:225], v192 offset:2048
	ds_read_b128 v[226:229], v192 offset:3072
	s_nop 0
	s_waitcnt vmcnt(8)
	s_waitcnt lgkmcnt(0)
	s_barrier
	v_mfma_f32_16x16x32_bf16 v[124:127], v[128:131], v[162:165], v[124:127]
	v_mfma_f32_16x16x32_bf16 v[120:123], v[136:139], v[162:165], v[120:123]
	v_mfma_f32_16x16x32_bf16 v[108:111], v[128:131], v[170:173], v[108:111]
	v_mfma_f32_16x16x32_bf16 v[104:107], v[136:139], v[170:173], v[104:107]
	v_mfma_f32_16x16x32_bf16 v[96:99], v[128:131], v[178:181], v[96:99]
	v_mfma_f32_16x16x32_bf16 v[88:91], v[136:139], v[178:181], v[88:91]
	v_mfma_f32_16x16x32_bf16 v[84:87], v[128:131], v[194:197], v[84:87]
	v_mfma_f32_16x16x32_bf16 v[80:83], v[136:139], v[194:197], v[80:83]
	v_mfma_f32_16x16x32_bf16 v[124:127], v[132:135], v[166:169], v[124:127]
	v_mfma_f32_16x16x32_bf16 v[120:123], v[146:149], v[166:169], v[120:123]
	v_mfma_f32_16x16x32_bf16 v[108:111], v[132:135], v[174:177], v[108:111]
	v_mfma_f32_16x16x32_bf16 v[104:107], v[146:149], v[174:177], v[104:107]
	v_mfma_f32_16x16x32_bf16 v[96:99], v[132:135], v[182:185], v[96:99]
	v_mfma_f32_16x16x32_bf16 v[88:91], v[146:149], v[182:185], v[88:91]
	v_mfma_f32_16x16x32_bf16 v[84:87], v[132:135], v[210:213], v[84:87]
	v_mfma_f32_16x16x32_bf16 v[80:83], v[146:149], v[210:213], v[80:83]
	v_mfma_f32_16x16x32_bf16 v[116:119], v[214:217], v[162:165], v[116:119]
	v_mfma_f32_16x16x32_bf16 v[112:115], v[222:225], v[162:165], v[112:115]
	v_mfma_f32_16x16x32_bf16 v[100:103], v[214:217], v[170:173], v[100:103]
	v_mfma_f32_16x16x32_bf16 v[92:95], v[222:225], v[170:173], v[92:95]
	v_mfma_f32_16x16x32_bf16 v[76:79], v[214:217], v[178:181], v[76:79]
	v_mfma_f32_16x16x32_bf16 v[72:75], v[222:225], v[178:181], v[72:75]
	v_mfma_f32_16x16x32_bf16 v[68:71], v[214:217], v[194:197], v[68:71]
	v_mfma_f32_16x16x32_bf16 v[64:67], v[222:225], v[194:197], v[64:67]
	v_mfma_f32_16x16x32_bf16 v[116:119], v[218:221], v[166:169], v[116:119]
	v_mfma_f32_16x16x32_bf16 v[112:115], v[226:229], v[166:169], v[112:115]
	v_mfma_f32_16x16x32_bf16 v[100:103], v[218:221], v[174:177], v[100:103]
	v_mfma_f32_16x16x32_bf16 v[92:95], v[226:229], v[174:177], v[92:95]
	v_mfma_f32_16x16x32_bf16 v[76:79], v[218:221], v[182:185], v[76:79]
	v_mfma_f32_16x16x32_bf16 v[72:75], v[226:229], v[182:185], v[72:75]
	v_mfma_f32_16x16x32_bf16 v[68:71], v[218:221], v[210:213], v[68:71]
	v_mfma_f32_16x16x32_bf16 v[64:67], v[226:229], v[210:213], v[64:67]
	s_add_i32 s6, s6, s57
	v_lshl_add_u64 v[230:231], s[48:49], 0, v[140:141]
	s_mov_b32 m0, s6
	s_barrier
	s_nop 0
	global_load_lds_dwordx4 v[230:231], off
	v_lshl_add_u64 v[232:233], s[48:49], 0, v[150:151]
	s_add_i32 m0, s6, 0x2000
	s_nop 0
	global_load_lds_dwordx4 v[232:233], off
	s_mov_b32 m0, s58
	v_lshl_add_u64 v[234:235], s[52:53], 0, v[154:155]
	ds_read_b128 v[162:165], v208 offset:16384
	ds_read_b128 v[166:169], v208 offset:17408
	ds_read_b128 v[170:173], v208 offset:18432
	ds_read_b128 v[174:177], v208 offset:19456
	ds_read_b128 v[178:181], v208 offset:20480
	ds_read_b128 v[182:185], v208 offset:21504
	ds_read_b128 v[194:197], v208 offset:22528
	ds_read_b128 v[210:213], v208 offset:23552
	global_load_lds_dwordx4 v[234:235], off
	v_lshl_add_u64 v[236:237], s[52:53], 0, v[152:153]
	s_mov_b32 m0, s59
	s_nop 0
	global_load_lds_dwordx4 v[236:237], off
	s_add_u32 s50, s48, 0xb0000
	s_addc_u32 s51, s49, 0
	s_add_i32 s6, s19, s57
	v_lshl_add_u64 v[250:251], s[50:51], 0, v[140:141]
	s_mov_b32 m0, s6
	s_nop 0
	global_load_lds_dwordx4 v[250:251], off
	v_lshl_add_u64 v[250:251], s[50:51], 0, v[150:151]
	s_add_i32 m0, s6, 0x2000
	s_nop 0
	global_load_lds_dwordx4 v[250:251], off
	s_waitcnt vmcnt(8)
	s_waitcnt lgkmcnt(0)
	s_barrier
	v_mfma_f32_16x16x32_bf16 v[60:63], v[128:131], v[162:165], v[60:63]
	v_mfma_f32_16x16x32_bf16 v[56:59], v[136:139], v[162:165], v[56:59]
	v_mfma_f32_16x16x32_bf16 v[48:51], v[128:131], v[170:173], v[48:51]
	v_mfma_f32_16x16x32_bf16 v[40:43], v[136:139], v[170:173], v[40:43]
	v_mfma_f32_16x16x32_bf16 v[32:35], v[128:131], v[178:181], v[32:35]
	v_mfma_f32_16x16x32_bf16 v[24:27], v[136:139], v[178:181], v[24:27]
	v_mfma_f32_16x16x32_bf16 v[16:19], v[128:131], v[194:197], v[16:19]
	v_mfma_f32_16x16x32_bf16 v[8:11], v[136:139], v[194:197], v[8:11]
	v_mfma_f32_16x16x32_bf16 v[60:63], v[132:135], v[166:169], v[60:63]
	v_mfma_f32_16x16x32_bf16 v[56:59], v[146:149], v[166:169], v[56:59]
	v_mfma_f32_16x16x32_bf16 v[48:51], v[132:135], v[174:177], v[48:51]
	v_mfma_f32_16x16x32_bf16 v[40:43], v[146:149], v[174:177], v[40:43]
	v_mfma_f32_16x16x32_bf16 v[32:35], v[132:135], v[182:185], v[32:35]
	v_mfma_f32_16x16x32_bf16 v[24:27], v[146:149], v[182:185], v[24:27]
	v_mfma_f32_16x16x32_bf16 v[16:19], v[132:135], v[210:213], v[16:19]
	v_mfma_f32_16x16x32_bf16 v[8:11], v[146:149], v[210:213], v[8:11]
	v_mfma_f32_16x16x32_bf16 v[52:55], v[214:217], v[162:165], v[52:55]
	v_mfma_f32_16x16x32_bf16 v[44:47], v[222:225], v[162:165], v[44:47]
	v_mfma_f32_16x16x32_bf16 v[36:39], v[214:217], v[170:173], v[36:39]
	v_mfma_f32_16x16x32_bf16 v[28:31], v[222:225], v[170:173], v[28:31]
	v_mfma_f32_16x16x32_bf16 v[20:23], v[214:217], v[178:181], v[20:23]
	v_mfma_f32_16x16x32_bf16 v[12:15], v[222:225], v[178:181], v[12:15]
	v_mfma_f32_16x16x32_bf16 v[4:7], v[214:217], v[194:197], v[4:7]
	v_mfma_f32_16x16x32_bf16 v[0:3], v[222:225], v[194:197], v[0:3]
	v_mfma_f32_16x16x32_bf16 v[52:55], v[218:221], v[166:169], v[52:55]
	v_mfma_f32_16x16x32_bf16 v[44:47], v[226:229], v[166:169], v[44:47]
	v_mfma_f32_16x16x32_bf16 v[36:39], v[218:221], v[174:177], v[36:39]
	v_mfma_f32_16x16x32_bf16 v[28:31], v[226:229], v[174:177], v[28:31]
	v_mfma_f32_16x16x32_bf16 v[20:23], v[218:221], v[182:185], v[20:23]
	v_mfma_f32_16x16x32_bf16 v[12:15], v[226:229], v[182:185], v[12:15]
	v_mfma_f32_16x16x32_bf16 v[4:7], v[218:221], v[210:213], v[4:7]
	v_mfma_f32_16x16x32_bf16 v[0:3], v[226:229], v[210:213], v[0:3]
	s_add_i32 s6, 0, 0x18000
	s_barrier
	v_add_u32_e32 v146, s6, v206
	ds_read_b128 v[128:131], v146
	ds_read_b128 v[132:135], v146 offset:1024
	ds_read_b128 v[136:139], v146 offset:2048
	ds_read_b128 v[146:149], v146 offset:3072
	s_add_u32 s50, s52, 0xb0000
	s_addc_u32 s51, s53, 0
	s_mov_b32 m0, s68
	v_lshl_add_u64 v[214:215], s[50:51], 0, v[154:155]
	ds_read_b128 v[162:165], v208 offset:32768
	ds_read_b128 v[166:169], v208 offset:33792
	ds_read_b128 v[170:173], v208 offset:34816
	ds_read_b128 v[174:177], v208 offset:35840
	ds_read_b128 v[178:181], v208 offset:36864
	ds_read_b128 v[182:185], v208 offset:37888
	ds_read_b128 v[194:197], v208 offset:38912
	ds_read_b128 v[210:213], v208 offset:39936
	global_load_lds_dwordx4 v[214:215], off
	v_lshl_add_u64 v[214:215], s[50:51], 0, v[152:153]
	s_mov_b32 m0, s69
	s_nop 0
	global_load_lds_dwordx4 v[214:215], off
	s_add_i32 s19, 0, 0x1c000
	v_add_u32_e32 v192, s19, v206
	ds_read_b128 v[214:217], v192
	ds_read_b128 v[218:221], v192 offset:1024
	ds_read_b128 v[222:225], v192 offset:2048
	ds_read_b128 v[226:229], v192 offset:3072
	s_waitcnt vmcnt(8)
	s_waitcnt lgkmcnt(0)
	s_barrier
	v_mfma_f32_16x16x32_bf16 v[124:127], v[128:131], v[162:165], v[124:127]
	v_mfma_f32_16x16x32_bf16 v[120:123], v[136:139], v[162:165], v[120:123]
	v_mfma_f32_16x16x32_bf16 v[108:111], v[128:131], v[170:173], v[108:111]
	v_mfma_f32_16x16x32_bf16 v[104:107], v[136:139], v[170:173], v[104:107]
	v_mfma_f32_16x16x32_bf16 v[96:99], v[128:131], v[178:181], v[96:99]
	v_mfma_f32_16x16x32_bf16 v[88:91], v[136:139], v[178:181], v[88:91]
	v_mfma_f32_16x16x32_bf16 v[84:87], v[128:131], v[194:197], v[84:87]
	v_mfma_f32_16x16x32_bf16 v[80:83], v[136:139], v[194:197], v[80:83]
	v_mfma_f32_16x16x32_bf16 v[124:127], v[132:135], v[166:169], v[124:127]
	v_mfma_f32_16x16x32_bf16 v[120:123], v[146:149], v[166:169], v[120:123]
	v_mfma_f32_16x16x32_bf16 v[108:111], v[132:135], v[174:177], v[108:111]
	v_mfma_f32_16x16x32_bf16 v[104:107], v[146:149], v[174:177], v[104:107]
	v_mfma_f32_16x16x32_bf16 v[96:99], v[132:135], v[182:185], v[96:99]
	v_mfma_f32_16x16x32_bf16 v[88:91], v[146:149], v[182:185], v[88:91]
	v_mfma_f32_16x16x32_bf16 v[84:87], v[132:135], v[210:213], v[84:87]
	v_mfma_f32_16x16x32_bf16 v[80:83], v[146:149], v[210:213], v[80:83]
	v_mfma_f32_16x16x32_bf16 v[116:119], v[214:217], v[162:165], v[116:119]
	v_mfma_f32_16x16x32_bf16 v[112:115], v[222:225], v[162:165], v[112:115]
	v_mfma_f32_16x16x32_bf16 v[100:103], v[214:217], v[170:173], v[100:103]
	v_mfma_f32_16x16x32_bf16 v[92:95], v[222:225], v[170:173], v[92:95]
	v_mfma_f32_16x16x32_bf16 v[76:79], v[214:217], v[178:181], v[76:79]
	v_mfma_f32_16x16x32_bf16 v[72:75], v[222:225], v[178:181], v[72:75]
	v_mfma_f32_16x16x32_bf16 v[68:71], v[214:217], v[194:197], v[68:71]
	v_mfma_f32_16x16x32_bf16 v[64:67], v[222:225], v[194:197], v[64:67]
	v_mfma_f32_16x16x32_bf16 v[116:119], v[218:221], v[166:169], v[116:119]
	v_mfma_f32_16x16x32_bf16 v[112:115], v[226:229], v[166:169], v[112:115]
	v_mfma_f32_16x16x32_bf16 v[100:103], v[218:221], v[174:177], v[100:103]
	v_mfma_f32_16x16x32_bf16 v[92:95], v[226:229], v[174:177], v[92:95]
	v_mfma_f32_16x16x32_bf16 v[76:79], v[218:221], v[182:185], v[76:79]
	v_mfma_f32_16x16x32_bf16 v[72:75], v[226:229], v[182:185], v[72:75]
	v_mfma_f32_16x16x32_bf16 v[68:71], v[218:221], v[210:213], v[68:71]
	v_mfma_f32_16x16x32_bf16 v[64:67], v[226:229], v[210:213], v[64:67]
	s_add_i32 s6, s6, s57
	v_lshl_add_u64 v[230:231], v[230:231], 0, s[36:37]
	s_mov_b32 m0, s6
	s_barrier
	s_nop 0
	global_load_lds_dwordx4 v[230:231], off
	v_lshl_add_u64 v[230:231], v[232:233], 0, s[36:37]
	s_add_i32 m0, s6, 0x2000
	s_nop 0
	global_load_lds_dwordx4 v[230:231], off
	s_mov_b32 m0, s70
	v_lshl_add_u64 v[230:231], v[234:235], 0, s[36:37]
	ds_read_b128 v[162:165], v208 offset:49152
	ds_read_b128 v[166:169], v208 offset:50176
	ds_read_b128 v[170:173], v208 offset:51200
	ds_read_b128 v[174:177], v208 offset:52224
	ds_read_b128 v[178:181], v208 offset:53248
	ds_read_b128 v[182:185], v208 offset:54272
	ds_read_b128 v[194:197], v208 offset:55296
	ds_read_b128 v[210:213], v208 offset:56320
	global_load_lds_dwordx4 v[230:231], off
	v_lshl_add_u64 v[230:231], v[236:237], 0, s[36:37]
	s_mov_b32 m0, s71
	s_nop 0
	global_load_lds_dwordx4 v[230:231], off
	s_add_u32 s48, s48, 0xb0080
	s_addc_u32 s49, s49, 0
	s_add_i32 s6, s19, s57
	v_lshl_add_u64 v[250:251], s[48:49], 0, v[140:141]
	s_mov_b32 m0, s6
	s_nop 0
	global_load_lds_dwordx4 v[250:251], off
	v_lshl_add_u64 v[250:251], s[48:49], 0, v[150:151]
	s_add_i32 m0, s6, 0x2000
	s_nop 0
	global_load_lds_dwordx4 v[250:251], off
	s_waitcnt vmcnt(8)
	s_waitcnt lgkmcnt(0)
	s_barrier
	v_mfma_f32_16x16x32_bf16 v[60:63], v[128:131], v[162:165], v[60:63]
	v_mfma_f32_16x16x32_bf16 v[56:59], v[136:139], v[162:165], v[56:59]
	v_mfma_f32_16x16x32_bf16 v[48:51], v[128:131], v[170:173], v[48:51]
	v_mfma_f32_16x16x32_bf16 v[40:43], v[136:139], v[170:173], v[40:43]
	v_mfma_f32_16x16x32_bf16 v[32:35], v[128:131], v[178:181], v[32:35]
	v_mfma_f32_16x16x32_bf16 v[24:27], v[136:139], v[178:181], v[24:27]
	v_mfma_f32_16x16x32_bf16 v[16:19], v[128:131], v[194:197], v[16:19]
	v_mfma_f32_16x16x32_bf16 v[8:11], v[136:139], v[194:197], v[8:11]
	v_mfma_f32_16x16x32_bf16 v[60:63], v[132:135], v[166:169], v[60:63]
	v_mfma_f32_16x16x32_bf16 v[56:59], v[146:149], v[166:169], v[56:59]
	v_mfma_f32_16x16x32_bf16 v[48:51], v[132:135], v[174:177], v[48:51]
	v_mfma_f32_16x16x32_bf16 v[40:43], v[146:149], v[174:177], v[40:43]
	v_mfma_f32_16x16x32_bf16 v[32:35], v[132:135], v[182:185], v[32:35]
	v_mfma_f32_16x16x32_bf16 v[24:27], v[146:149], v[182:185], v[24:27]
	v_mfma_f32_16x16x32_bf16 v[16:19], v[132:135], v[210:213], v[16:19]
	v_mfma_f32_16x16x32_bf16 v[8:11], v[146:149], v[210:213], v[8:11]
	v_mfma_f32_16x16x32_bf16 v[52:55], v[214:217], v[162:165], v[52:55]
	v_mfma_f32_16x16x32_bf16 v[44:47], v[222:225], v[162:165], v[44:47]
	v_mfma_f32_16x16x32_bf16 v[36:39], v[214:217], v[170:173], v[36:39]
	v_mfma_f32_16x16x32_bf16 v[28:31], v[222:225], v[170:173], v[28:31]
	v_mfma_f32_16x16x32_bf16 v[20:23], v[214:217], v[178:181], v[20:23]
	v_mfma_f32_16x16x32_bf16 v[12:15], v[222:225], v[178:181], v[12:15]
	v_mfma_f32_16x16x32_bf16 v[4:7], v[214:217], v[194:197], v[4:7]
	v_mfma_f32_16x16x32_bf16 v[0:3], v[222:225], v[194:197], v[0:3]
	v_mfma_f32_16x16x32_bf16 v[52:55], v[218:221], v[166:169], v[52:55]
	v_mfma_f32_16x16x32_bf16 v[44:47], v[226:229], v[166:169], v[44:47]
	v_mfma_f32_16x16x32_bf16 v[36:39], v[218:221], v[174:177], v[36:39]
	v_mfma_f32_16x16x32_bf16 v[28:31], v[226:229], v[174:177], v[28:31]
	v_mfma_f32_16x16x32_bf16 v[20:23], v[218:221], v[182:185], v[20:23]
	v_mfma_f32_16x16x32_bf16 v[12:15], v[226:229], v[182:185], v[12:15]
	v_mfma_f32_16x16x32_bf16 v[4:7], v[218:221], v[210:213], v[4:7]
	v_mfma_f32_16x16x32_bf16 v[0:3], v[226:229], v[210:213], v[0:3]
	s_add_i32 s12, s12, 2
	s_add_u32 s10, s10, 0x100
	s_addc_u32 s11, s11, 0
	s_cmp_gt_u32 s12, 41
	s_mov_b64 s[50:51], s[46:47]
	s_cbranch_scc1 my_exit_341
	s_add_u32 s46, s50, 0x100
	s_addc_u32 s47, s51, 0
	s_add_i32 s6, 0, 0x10000
	s_cmp_eq_u32 s12, 40
	s_cselect_b32 s53, s31, s47
	s_cselect_b32 s52, s30, s46
	s_cselect_b32 s49, s35, s11
	s_cselect_b32 s48, s34, s10
	s_branch my_head_341
my_exit_341:
	s_barrier
	s_mov_b32 s100, 1
	s_ashr_i32 s39, s38, 31
	v_lshl_or_b32 v128, s81, 8, v207
	s_lshl_b64 s[10:11], s[38:39], 8
	v_ashrrev_i32_e32 v129, 31, v128
	v_lshl_add_u64 v[168:169], s[10:11], 0, v[156:157]
	v_lshlrev_b64 v[170:171], 1, v[128:129]
	v_lshl_add_u64 v[174:175], s[26:27], 0, v[170:171]
	v_lshlrev_b64 v[172:173], 11, v[168:169]
	v_lshl_add_u64 v[128:129], v[174:175], 0, v[172:173]
	global_load_dwordx4 v[182:185], v[128:129], off
	global_load_dwordx4 v[210:213], v[128:129], off offset:256
	v_or_b32_e32 v166, 16, v168
	v_mov_b32_e32 v167, v169
	v_lshlrev_b64 v[176:177], 11, v[166:167]
	v_lshl_add_u64 v[128:129], v[174:175], 0, v[176:177]
	global_load_dwordx4 v[214:217], v[128:129], off
	global_load_dwordx4 v[218:221], v[128:129], off offset:256
	v_or_b32_e32 v164, 32, v168
	v_mov_b32_e32 v165, v169
	v_or_b32_e32 v162, 48, v168
	v_mov_b32_e32 v163, v169
	v_lshlrev_b64 v[180:181], 11, v[164:165]
	v_lshlrev_b64 v[178:179], 11, v[162:163]
	v_lshl_add_u64 v[128:129], v[174:175], 0, v[180:181]
	v_lshl_add_u64 v[130:131], v[174:175], 0, v[178:179]
	global_load_dwordx4 v[222:225], v[128:129], off
	global_load_dwordx4 v[136:139], v[128:129], off offset:256
	global_load_dwordx4 v[132:135], v[130:131], off
	s_nop 0
	global_load_dwordx4 v[128:131], v[130:131], off offset:256
	s_mov_b64 s[10:11], 0x90
	v_lshl_add_u64 v[172:173], s[28:29], 0, v[172:173]
	v_lshl_add_u64 v[172:173], v[172:173], 0, v[170:171]
	s_waitcnt vmcnt(0)
	v_lshlrev_b32_e32 v146, 16, v182
	v_and_b32_e32 v147, 0xffff0000, v182
	v_lshlrev_b32_e32 v148, 16, v184
	v_and_b32_e32 v149, 0xffff0000, v184
	v_lshlrev_b32_e32 v182, 16, v183
	v_and_b32_e32 v183, 0xffff0000, v183
	v_lshlrev_b32_e32 v194, 16, v210
	v_and_b32_e32 v195, 0xffff0000, v210
	v_lshlrev_b32_e32 v196, 16, v212
	v_and_b32_e32 v197, 0xffff0000, v212
	v_lshlrev_b32_e32 v210, 16, v211
	v_and_b32_e32 v211, 0xffff0000, v211
	v_lshlrev_b32_e32 v212, 16, v213
	v_and_b32_e32 v213, 0xffff0000, v213
	v_pk_fma_f32 v[124:125], v[124:125], 0.5, v[146:147] op_sel_hi:[1,0,1]
	v_pk_fma_f32 v[120:121], v[120:121], 0.5, v[148:149] op_sel_hi:[1,0,1]
	v_pk_fma_f32 v[126:127], v[126:127], 0.5, v[182:183] op_sel_hi:[1,0,1]
	v_pk_fma_f32 v[116:117], v[116:117], 0.5, v[194:195] op_sel_hi:[1,0,1]
	v_pk_fma_f32 v[146:147], v[112:113], 0.5, v[196:197] op_sel_hi:[1,0,1]
	v_pk_fma_f32 v[118:119], v[118:119], 0.5, v[210:211] op_sel_hi:[1,0,1]
	v_pk_fma_f32 v[148:149], v[114:115], 0.5, v[212:213] op_sel_hi:[1,0,1]
	v_pk_mul_f32 v[212:213], v[124:125], v[124:125]
	v_lshlrev_b32_e32 v182, 16, v214
	v_and_b32_e32 v183, 0xffff0000, v214
	v_lshlrev_b32_e32 v194, 16, v215
	v_and_b32_e32 v195, 0xffff0000, v215
	v_pk_mul_f32 v[214:215], v[126:127], v[126:127]
	v_cvt_pk_bf16_f32 v112, v124, v125
	v_cvt_pk_bf16_f32 v113, v126, v127
	v_pk_mul_f32 v[124:125], v[116:117], v[116:117]
	v_pk_mul_f32 v[126:127], v[118:119], v[118:119]
	v_pk_mul_f32 v[228:229], v[146:147], v[146:147]
	v_cvt_pk_bf16_f32 v116, v116, v117
	v_cvt_pk_bf16_f32 v117, v118, v119
	v_cvt_pk_bf16_f32 v118, v146, v147
	v_add_f32_e32 v146, v212, v213
	v_lshlrev_b32_e32 v184, 16, v185
	v_and_b32_e32 v185, 0xffff0000, v185
	v_add_f32_e32 v146, v214, v146
	v_pk_fma_f32 v[122:123], v[122:123], 0.5, v[184:185] op_sel_hi:[1,0,1]
	v_lshlrev_b32_e32 v184, 16, v216
	v_and_b32_e32 v185, 0xffff0000, v216
	v_lshlrev_b32_e32 v196, 16, v217
	v_and_b32_e32 v197, 0xffff0000, v217
	v_pk_mul_f32 v[216:217], v[120:121], v[120:121]
	v_add_f32_e32 v146, v215, v146
	v_add_f32_e32 v146, v216, v146
	v_pk_mul_f32 v[226:227], v[122:123], v[122:123]
	v_add_f32_e32 v146, v217, v146
	v_add_f32_e32 v146, v226, v146
	v_add_f32_e32 v146, v227, v146
	v_add_f32_e32 v124, v124, v146
	v_add_f32_e32 v124, v125, v124
	v_add_f32_e32 v124, v126, v124
	v_add_f32_e32 v124, v127, v124
	v_add_f32_e32 v124, v228, v124
	v_pk_mul_f32 v[230:231], v[148:149], v[148:149]
	v_add_f32_e32 v124, v229, v124
	v_add_f32_e32 v124, v230, v124
	v_add_f32_e32 v209, v231, v124
	v_lshlrev_b32_e32 v124, 16, v220
	v_and_b32_e32 v125, 0xffff0000, v220
	v_pk_fma_f32 v[124:125], v[92:93], 0.5, v[124:125] op_sel_hi:[1,0,1]
	v_lshlrev_b32_e32 v92, 16, v219
	v_and_b32_e32 v93, 0xffff0000, v219
	v_pk_fma_f32 v[102:103], v[102:103], 0.5, v[92:93] op_sel_hi:[1,0,1]
	v_lshlrev_b32_e32 v92, 16, v221
	v_and_b32_e32 v93, 0xffff0000, v221
	v_pk_fma_f32 v[126:127], v[94:95], 0.5, v[92:93] op_sel_hi:[1,0,1]
	v_lshlrev_b32_e32 v92, 16, v222
	v_and_b32_e32 v93, 0xffff0000, v222
	v_pk_fma_f32 v[92:93], v[96:97], 0.5, v[92:93] op_sel_hi:[1,0,1]
	v_lshlrev_b32_e32 v96, 16, v225
	v_and_b32_e32 v97, 0xffff0000, v225
	v_lshlrev_b32_e32 v94, 16, v224
	v_and_b32_e32 v95, 0xffff0000, v224
	v_pk_fma_f32 v[90:91], v[90:91], 0.5, v[96:97] op_sel_hi:[1,0,1]
	v_lshlrev_b32_e32 v96, 16, v136
	v_and_b32_e32 v97, 0xffff0000, v136
	v_pk_fma_f32 v[88:89], v[88:89], 0.5, v[94:95] op_sel_hi:[1,0,1]
	v_lshlrev_b32_e32 v94, 16, v223
	v_and_b32_e32 v95, 0xffff0000, v223
	v_pk_fma_f32 v[96:97], v[76:77], 0.5, v[96:97] op_sel_hi:[1,0,1]
	v_lshl_add_u64 v[76:77], v[168:169], 0, s[36:37]
	v_cvt_pk_bf16_f32 v114, v120, v121
	v_pk_fma_f32 v[120:121], v[108:109], 0.5, v[182:183] op_sel_hi:[1,0,1]
	v_pk_fma_f32 v[94:95], v[98:99], 0.5, v[94:95] op_sel_hi:[1,0,1]
	v_lshlrev_b64 v[182:183], 11, v[76:77]
	v_lshlrev_b32_e32 v98, 16, v138
	v_and_b32_e32 v99, 0xffff0000, v138
	v_lshl_add_u64 v[146:147], v[174:175], 0, v[182:183]
	v_pk_fma_f32 v[98:99], v[72:73], 0.5, v[98:99] op_sel_hi:[1,0,1]
	v_lshlrev_b32_e32 v72, 16, v137
	v_and_b32_e32 v73, 0xffff0000, v137
	v_lshlrev_b32_e32 v210, 16, v218
	v_and_b32_e32 v211, 0xffff0000, v218
	global_load_dwordx4 v[218:221], v[146:147], off
	global_load_dwordx4 v[226:229], v[146:147], off offset:256
	v_pk_fma_f32 v[136:137], v[78:79], 0.5, v[72:73] op_sel_hi:[1,0,1]
	v_lshlrev_b32_e32 v72, 16, v139
	v_and_b32_e32 v73, 0xffff0000, v139
	v_pk_fma_f32 v[138:139], v[74:75], 0.5, v[72:73] op_sel_hi:[1,0,1]
	v_lshlrev_b32_e32 v72, 16, v132
	v_and_b32_e32 v73, 0xffff0000, v132
	v_pk_fma_f32 v[74:75], v[84:85], 0.5, v[72:73] op_sel_hi:[1,0,1]
	v_lshlrev_b32_e32 v72, 16, v134
	v_and_b32_e32 v73, 0xffff0000, v134
	v_pk_fma_f32 v[78:79], v[80:81], 0.5, v[72:73] op_sel_hi:[1,0,1]
	v_lshlrev_b32_e32 v72, 16, v133
	v_and_b32_e32 v73, 0xffff0000, v133
	v_pk_fma_f32 v[80:81], v[86:87], 0.5, v[72:73] op_sel_hi:[1,0,1]
	v_lshlrev_b32_e32 v72, 16, v135
	v_and_b32_e32 v73, 0xffff0000, v135
	v_pk_fma_f32 v[82:83], v[82:83], 0.5, v[72:73] op_sel_hi:[1,0,1]
	v_lshl_add_u64 v[72:73], v[168:169], 0, s[10:11]
	v_lshlrev_b64 v[132:133], 11, v[72:73]
	v_lshl_add_u64 v[134:135], v[174:175], 0, v[132:133]
	global_load_dwordx4 v[234:237], v[134:135], off
	global_load_dwordx4 v[242:245], v[134:135], off offset:256
	v_lshlrev_b32_e32 v84, 16, v128
	v_and_b32_e32 v85, 0xffff0000, v128
	v_pk_fma_f32 v[84:85], v[68:69], 0.5, v[84:85] op_sel_hi:[1,0,1]
	v_lshlrev_b32_e32 v68, 16, v130
	v_and_b32_e32 v69, 0xffff0000, v130
	v_pk_fma_f32 v[86:87], v[64:65], 0.5, v[68:69] op_sel_hi:[1,0,1]
	v_lshlrev_b32_e32 v64, 16, v129
	v_and_b32_e32 v65, 0xffff0000, v129
	s_mov_b64 s[10:11], 0xa0
	v_pk_fma_f32 v[128:129], v[70:71], 0.5, v[64:65] op_sel_hi:[1,0,1]
	v_lshl_add_u64 v[70:71], v[168:169], 0, s[10:11]
	v_lshlrev_b32_e32 v64, 16, v131
	v_and_b32_e32 v65, 0xffff0000, v131
	v_lshlrev_b64 v[134:135], 11, v[70:71]
	v_pk_fma_f32 v[130:131], v[66:67], 0.5, v[64:65] op_sel_hi:[1,0,1]
	v_lshl_add_u64 v[64:65], v[174:175], 0, v[134:135]
	v_cvt_pk_bf16_f32 v115, v122, v123
	v_pk_fma_f32 v[122:123], v[110:111], 0.5, v[194:195] op_sel_hi:[1,0,1]
	v_pk_fma_f32 v[110:111], v[106:107], 0.5, v[196:197] op_sel_hi:[1,0,1]
	global_load_dwordx4 v[246:249], v[64:65], off
	global_load_dwordx4 v[194:197], v[64:65], off offset:256
	s_mov_b64 s[10:11], 0xb0
	v_lshl_add_u64 v[68:69], v[168:169], 0, s[10:11]
	v_pk_fma_f32 v[108:109], v[104:105], 0.5, v[184:185] op_sel_hi:[1,0,1]
	v_lshlrev_b64 v[184:185], 11, v[68:69]
	v_lshl_add_u64 v[64:65], v[174:175], 0, v[184:185]
	v_cvt_pk_bf16_f32 v119, v148, v149
	global_load_dwordx4 v[146:149], v[64:65], off
	s_nop 0
	global_load_dwordx4 v[64:67], v[64:65], off offset:256
	global_store_dwordx4 v[172:173], v[112:115], off
	global_store_dwordx4 v[172:173], v[116:119], off offset:256
	v_cvt_pk_bf16_f32 v104, v120, v121
	v_lshl_add_u64 v[112:113], s[28:29], 0, v[176:177]
	v_cvt_pk_bf16_f32 v105, v122, v123
	v_cvt_pk_bf16_f32 v106, v108, v109
	v_cvt_pk_bf16_f32 v107, v110, v111
	v_pk_fma_f32 v[100:101], v[100:101], 0.5, v[210:211] op_sel_hi:[1,0,1]
	v_lshl_add_u64 v[112:113], v[112:113], 0, v[170:171]
	v_cvt_pk_bf16_f32 v210, v100, v101
	v_cvt_pk_bf16_f32 v211, v102, v103
	v_cvt_pk_bf16_f32 v212, v124, v125
	v_cvt_pk_bf16_f32 v213, v126, v127
	global_store_dwordx4 v[112:113], v[104:107], off
	global_store_dwordx4 v[112:113], v[210:213], off offset:256
	v_cvt_pk_bf16_f32 v214, v92, v93
	v_lshl_add_u64 v[104:105], s[28:29], 0, v[180:181]
	v_cvt_pk_bf16_f32 v215, v94, v95
	v_cvt_pk_bf16_f32 v216, v88, v89
	v_cvt_pk_bf16_f32 v217, v90, v91
	v_lshl_add_u64 v[104:105], v[104:105], 0, v[170:171]
	v_cvt_pk_bf16_f32 v222, v96, v97
	v_cvt_pk_bf16_f32 v223, v136, v137
	v_cvt_pk_bf16_f32 v224, v98, v99
	v_cvt_pk_bf16_f32 v225, v138, v139
	global_store_dwordx4 v[104:105], v[214:217], off
	global_store_dwordx4 v[104:105], v[222:225], off offset:256
	v_lshl_add_u64 v[104:105], s[28:29], 0, v[178:179]
	v_cvt_pk_bf16_f32 v230, v74, v75
	v_cvt_pk_bf16_f32 v231, v80, v81
	v_cvt_pk_bf16_f32 v232, v78, v79
	v_cvt_pk_bf16_f32 v233, v82, v83
	v_lshl_add_u64 v[104:105], v[104:105], 0, v[170:171]
	v_cvt_pk_bf16_f32 v238, v84, v85
	v_cvt_pk_bf16_f32 v239, v128, v129
	v_cvt_pk_bf16_f32 v240, v86, v87
	v_cvt_pk_bf16_f32 v241, v130, v131
	global_store_dwordx4 v[104:105], v[230:233], off
	global_store_dwordx4 v[104:105], v[238:241], off offset:256
	s_waitcnt vmcnt(0)
	v_lshlrev_b32_e32 v104, 16, v218
	v_and_b32_e32 v105, 0xffff0000, v218
	v_pk_fma_f32 v[60:61], v[60:61], 0.5, v[104:105] op_sel_hi:[1,0,1]
	v_lshlrev_b32_e32 v104, 16, v220
	v_and_b32_e32 v105, 0xffff0000, v220
	v_pk_fma_f32 v[56:57], v[56:57], 0.5, v[104:105] op_sel_hi:[1,0,1]
	v_lshlrev_b32_e32 v104, 16, v219
	v_and_b32_e32 v105, 0xffff0000, v219
	v_pk_fma_f32 v[62:63], v[62:63], 0.5, v[104:105] op_sel_hi:[1,0,1]
	v_lshlrev_b32_e32 v104, 16, v221
	v_and_b32_e32 v105, 0xffff0000, v221
	v_pk_fma_f32 v[58:59], v[58:59], 0.5, v[104:105] op_sel_hi:[1,0,1]
	v_lshlrev_b32_e32 v104, 16, v226
	v_and_b32_e32 v105, 0xffff0000, v226
	v_pk_fma_f32 v[52:53], v[52:53], 0.5, v[104:105] op_sel_hi:[1,0,1]
	v_lshlrev_b32_e32 v104, 16, v228
	v_and_b32_e32 v105, 0xffff0000, v228
	v_pk_fma_f32 v[104:105], v[44:45], 0.5, v[104:105] op_sel_hi:[1,0,1]
	v_lshlrev_b32_e32 v44, 16, v227
	v_and_b32_e32 v45, 0xffff0000, v227
	v_pk_fma_f32 v[54:55], v[54:55], 0.5, v[44:45] op_sel_hi:[1,0,1]
	v_lshlrev_b32_e32 v44, 16, v229
	v_and_b32_e32 v45, 0xffff0000, v229
	v_pk_fma_f32 v[106:107], v[46:47], 0.5, v[44:45] op_sel_hi:[1,0,1]
	v_lshlrev_b32_e32 v44, 16, v234
	v_and_b32_e32 v45, 0xffff0000, v234
	v_pk_fma_f32 v[44:45], v[48:49], 0.5, v[44:45] op_sel_hi:[1,0,1]
	v_lshlrev_b32_e32 v48, 16, v237
	v_and_b32_e32 v49, 0xffff0000, v237
	v_pk_fma_f32 v[42:43], v[42:43], 0.5, v[48:49] op_sel_hi:[1,0,1]
	v_lshlrev_b32_e32 v48, 16, v242
	v_and_b32_e32 v49, 0xffff0000, v242
	v_pk_fma_f32 v[36:37], v[36:37], 0.5, v[48:49] op_sel_hi:[1,0,1]
	v_lshlrev_b32_e32 v48, 16, v244
	v_and_b32_e32 v49, 0xffff0000, v244
	v_lshlrev_b32_e32 v46, 16, v236
	v_and_b32_e32 v47, 0xffff0000, v236
	v_pk_fma_f32 v[48:49], v[28:29], 0.5, v[48:49] op_sel_hi:[1,0,1]
	v_lshlrev_b32_e32 v28, 16, v243
	v_and_b32_e32 v29, 0xffff0000, v243
	v_pk_fma_f32 v[40:41], v[40:41], 0.5, v[46:47] op_sel_hi:[1,0,1]
	v_lshlrev_b32_e32 v46, 16, v235
	v_and_b32_e32 v47, 0xffff0000, v235
	v_pk_fma_f32 v[38:39], v[38:39], 0.5, v[28:29] op_sel_hi:[1,0,1]
	v_lshlrev_b32_e32 v28, 16, v245
	v_and_b32_e32 v29, 0xffff0000, v245
	v_pk_fma_f32 v[46:47], v[50:51], 0.5, v[46:47] op_sel_hi:[1,0,1]
	v_pk_fma_f32 v[50:51], v[30:31], 0.5, v[28:29] op_sel_hi:[1,0,1]
	v_lshlrev_b32_e32 v28, 16, v246
	v_and_b32_e32 v29, 0xffff0000, v246
	v_pk_fma_f32 v[28:29], v[32:33], 0.5, v[28:29] op_sel_hi:[1,0,1]
	v_lshlrev_b32_e32 v32, 16, v249
	v_and_b32_e32 v33, 0xffff0000, v249
	v_pk_fma_f32 v[26:27], v[26:27], 0.5, v[32:33] op_sel_hi:[1,0,1]
	v_lshlrev_b32_e32 v32, 16, v194
	v_and_b32_e32 v33, 0xffff0000, v194
	v_pk_fma_f32 v[20:21], v[20:21], 0.5, v[32:33] op_sel_hi:[1,0,1]
	v_lshlrev_b32_e32 v32, 16, v196
	v_and_b32_e32 v33, 0xffff0000, v196
	v_lshlrev_b32_e32 v30, 16, v248
	v_and_b32_e32 v31, 0xffff0000, v248
	v_pk_fma_f32 v[32:33], v[12:13], 0.5, v[32:33] op_sel_hi:[1,0,1]
	v_lshlrev_b32_e32 v12, 16, v195
	v_and_b32_e32 v13, 0xffff0000, v195
	v_pk_fma_f32 v[24:25], v[24:25], 0.5, v[30:31] op_sel_hi:[1,0,1]
	v_lshlrev_b32_e32 v30, 16, v247
	v_and_b32_e32 v31, 0xffff0000, v247
	v_pk_fma_f32 v[22:23], v[22:23], 0.5, v[12:13] op_sel_hi:[1,0,1]
	v_lshlrev_b32_e32 v12, 16, v197
	v_and_b32_e32 v13, 0xffff0000, v197
	v_pk_fma_f32 v[30:31], v[34:35], 0.5, v[30:31] op_sel_hi:[1,0,1]
	v_pk_fma_f32 v[34:35], v[14:15], 0.5, v[12:13] op_sel_hi:[1,0,1]
	v_lshlrev_b32_e32 v14, 16, v148
	v_and_b32_e32 v15, 0xffff0000, v148
	v_lshlrev_b32_e32 v12, 16, v146
	v_and_b32_e32 v13, 0xffff0000, v146
	v_pk_fma_f32 v[8:9], v[8:9], 0.5, v[14:15] op_sel_hi:[1,0,1]
	v_lshlrev_b32_e32 v14, 16, v147
	v_and_b32_e32 v15, 0xffff0000, v147
	v_lshlrev_b32_e32 v146, 16, v64
	v_and_b32_e32 v147, 0xffff0000, v64
	v_pk_fma_f32 v[4:5], v[4:5], 0.5, v[146:147] op_sel_hi:[1,0,1]
	v_lshlrev_b32_e32 v146, 16, v66
	v_and_b32_e32 v147, 0xffff0000, v66
	v_pk_fma_f32 v[0:1], v[0:1], 0.5, v[146:147] op_sel_hi:[1,0,1]
	v_lshl_add_u64 v[146:147], s[28:29], 0, v[182:183]
	v_cvt_pk_bf16_f32 v112, v60, v61
	v_cvt_pk_bf16_f32 v113, v62, v63
	v_cvt_pk_bf16_f32 v114, v56, v57
	v_cvt_pk_bf16_f32 v115, v58, v59
	v_lshl_add_u64 v[146:147], v[146:147], 0, v[170:171]
	v_cvt_pk_bf16_f32 v116, v52, v53
	v_cvt_pk_bf16_f32 v117, v54, v55
	v_cvt_pk_bf16_f32 v118, v104, v105
	v_cvt_pk_bf16_f32 v119, v106, v107
	global_store_dwordx4 v[146:147], v[112:115], off
	global_store_dwordx4 v[146:147], v[116:119], off offset:256
	v_cvt_pk_bf16_f32 v172, v44, v45
	v_lshl_add_u64 v[112:113], s[28:29], 0, v[132:133]
	v_cvt_pk_bf16_f32 v173, v46, v47
	v_cvt_pk_bf16_f32 v174, v40, v41
	v_cvt_pk_bf16_f32 v175, v42, v43
	v_lshl_add_u64 v[112:113], v[112:113], 0, v[170:171]
	v_cvt_pk_bf16_f32 v176, v36, v37
	v_cvt_pk_bf16_f32 v177, v38, v39
	v_cvt_pk_bf16_f32 v178, v48, v49
	v_cvt_pk_bf16_f32 v179, v50, v51
	global_store_dwordx4 v[112:113], v[172:175], off
	global_store_dwordx4 v[112:113], v[176:179], off offset:256
	v_lshl_add_u64 v[112:113], s[28:29], 0, v[134:135]
	v_cvt_pk_bf16_f32 v210, v28, v29
	v_cvt_pk_bf16_f32 v211, v30, v31
	v_cvt_pk_bf16_f32 v212, v24, v25
	v_cvt_pk_bf16_f32 v213, v26, v27
	v_pk_fma_f32 v[12:13], v[16:17], 0.5, v[12:13] op_sel_hi:[1,0,1]
	v_lshlrev_b32_e32 v16, 16, v149
	v_and_b32_e32 v17, 0xffff0000, v149
	v_lshlrev_b32_e32 v64, 16, v65
	v_and_b32_e32 v65, 0xffff0000, v65
	v_lshl_add_u64 v[112:113], v[112:113], 0, v[170:171]
	v_cvt_pk_bf16_f32 v194, v20, v21
	v_cvt_pk_bf16_f32 v195, v22, v23
	v_cvt_pk_bf16_f32 v196, v32, v33
	v_cvt_pk_bf16_f32 v197, v34, v35
	v_pk_fma_f32 v[14:15], v[18:19], 0.5, v[14:15] op_sel_hi:[1,0,1]
	v_pk_fma_f32 v[10:11], v[10:11], 0.5, v[16:17] op_sel_hi:[1,0,1]
	v_pk_fma_f32 v[6:7], v[6:7], 0.5, v[64:65] op_sel_hi:[1,0,1]
	v_lshlrev_b32_e32 v64, 16, v67
	v_and_b32_e32 v65, 0xffff0000, v67
	global_store_dwordx4 v[112:113], v[210:213], off
	global_store_dwordx4 v[112:113], v[194:197], off offset:256
	v_lshl_add_u64 v[112:113], s[28:29], 0, v[184:185]
	v_cvt_pk_bf16_f32 v16, v12, v13
	v_cvt_pk_bf16_f32 v17, v14, v15
	v_cvt_pk_bf16_f32 v18, v8, v9
	v_cvt_pk_bf16_f32 v19, v10, v11
	v_pk_fma_f32 v[2:3], v[2:3], 0.5, v[64:65] op_sel_hi:[1,0,1]
	v_lshl_add_u64 v[112:113], v[112:113], 0, v[170:171]
	v_cvt_pk_bf16_f32 v64, v4, v5
	v_cvt_pk_bf16_f32 v65, v6, v7
	v_cvt_pk_bf16_f32 v66, v0, v1
	v_cvt_pk_bf16_f32 v67, v2, v3
	global_store_dwordx4 v[112:113], v[16:19], off
	global_store_dwordx4 v[112:113], v[64:67], off offset:256
	s_lshl_b32 s10, s81, 2
	v_and_b32_e32 v17, 64, v188
	v_xor_b32_e32 v16, 16, v188
	v_add_u32_e32 v17, 64, v17
	v_cmp_lt_i32_e32 vcc, v16, v17
	v_xor_b32_e32 v18, 32, v188
	s_ashr_i32 s11, s10, 31
	v_cndmask_b32_e32 v16, v188, v16, vcc
	v_lshlrev_b32_e32 v16, 2, v16
	ds_bpermute_b32 v19, v16, v209
	v_cmp_lt_i32_e32 vcc, v18, v17
	s_lshl_b64 s[10:11], s[10:11], 2
	s_add_u32 s38, s73, s10
	v_cndmask_b32_e32 v17, v188, v18, vcc
	v_lshlrev_b32_e32 v17, 2, v17
	s_waitcnt lgkmcnt(0)
	v_add_f32_e32 v18, v209, v19
	ds_bpermute_b32 v19, v17, v18
	s_addc_u32 s39, s74, s11
	s_and_saveexec_b64 s[46:47], s[42:43]
	s_cbranch_execz .LBB0_344
	s_waitcnt lgkmcnt(0)
	v_add_f32_e32 v64, v18, v19
	v_lshlrev_b64 v[18:19], 6, v[168:169]
	v_lshl_add_u64 v[18:19], s[38:39], 0, v[18:19]
	global_store_dword v[18:19], v64, off

.Lm4ap_386:
	s_waitcnt lgkmcnt(0)
	s_barrier
	v_mfma_f32_16x16x32_bf16 v[124:127], v[158:161], v[174:177], 0
	v_mfma_f32_16x16x32_bf16 v[120:123], v[166:169], v[174:177], 0
	v_mfma_f32_16x16x32_bf16 v[116:119], v[158:161], v[182:185], 0
	v_mfma_f32_16x16x32_bf16 v[112:115], v[166:169], v[182:185], 0
	v_mfma_f32_16x16x32_bf16 v[108:111], v[158:161], v[210:213], 0
	v_mfma_f32_16x16x32_bf16 v[104:107], v[166:169], v[210:213], 0
	v_mfma_f32_16x16x32_bf16 v[100:103], v[158:161], v[218:221], 0
	v_mfma_f32_16x16x32_bf16 v[96:99], v[166:169], v[218:221], 0
	v_mfma_f32_16x16x32_bf16 v[124:127], v[162:165], v[178:181], v[124:127]
	v_mfma_f32_16x16x32_bf16 v[120:123], v[170:173], v[178:181], v[120:123]
	v_mfma_f32_16x16x32_bf16 v[116:119], v[162:165], v[206:209], v[116:119]
	v_mfma_f32_16x16x32_bf16 v[112:115], v[170:173], v[206:209], v[112:115]
	v_mfma_f32_16x16x32_bf16 v[108:111], v[162:165], v[214:217], v[108:111]
	v_mfma_f32_16x16x32_bf16 v[104:107], v[170:173], v[214:217], v[104:107]
	v_mfma_f32_16x16x32_bf16 v[100:103], v[162:165], v[222:225], v[100:103]
	v_mfma_f32_16x16x32_bf16 v[96:99], v[170:173], v[222:225], v[96:99]
	v_mfma_f32_16x16x32_bf16 v[92:95], v[226:229], v[174:177], 0
	v_mfma_f32_16x16x32_bf16 v[88:91], v[234:237], v[174:177], 0
	v_mfma_f32_16x16x32_bf16 v[84:87], v[226:229], v[182:185], 0
	v_mfma_f32_16x16x32_bf16 v[80:83], v[234:237], v[182:185], 0
	v_mfma_f32_16x16x32_bf16 v[76:79], v[226:229], v[210:213], 0
	v_mfma_f32_16x16x32_bf16 v[72:75], v[234:237], v[210:213], 0
	v_mfma_f32_16x16x32_bf16 v[68:71], v[226:229], v[218:221], 0
	v_mfma_f32_16x16x32_bf16 v[64:67], v[234:237], v[218:221], 0
	v_mfma_f32_16x16x32_bf16 v[92:95], v[230:233], v[178:181], v[92:95]
	v_mfma_f32_16x16x32_bf16 v[88:91], v[238:241], v[178:181], v[88:91]
	v_mfma_f32_16x16x32_bf16 v[84:87], v[230:233], v[206:209], v[84:87]
	v_mfma_f32_16x16x32_bf16 v[80:83], v[238:241], v[206:209], v[80:83]
	v_mfma_f32_16x16x32_bf16 v[76:79], v[230:233], v[214:217], v[76:79]
	v_mfma_f32_16x16x32_bf16 v[72:75], v[238:241], v[214:217], v[72:75]
	v_mfma_f32_16x16x32_bf16 v[68:71], v[230:233], v[222:225], v[68:71]
	v_mfma_f32_16x16x32_bf16 v[64:67], v[238:241], v[222:225], v[64:67]
	s_add_i32 s19, s82, s57
	v_lshl_add_u64 v[146:147], s[54:55], 0, v[140:141]
	s_mov_b32 m0, s19
	v_lshl_add_u64 v[148:149], s[54:55], 0, v[132:133]
	s_barrier
	global_load_lds_dwordx4 v[146:147], off
	s_add_i32 m0, s19, 0x2000
	s_nop 0
	global_load_lds_dwordx4 v[148:149], off
	s_mov_b32 m0, s68
	v_lshl_add_u64 v[194:195], s[58:59], 0, v[128:129]
	ds_read_b128 v[174:177], v157 offset:16384
	ds_read_b128 v[178:181], v157 offset:17408
	ds_read_b128 v[182:185], v157 offset:18432
	ds_read_b128 v[206:209], v157 offset:19456
	ds_read_b128 v[210:213], v157 offset:20480
	ds_read_b128 v[214:217], v157 offset:21504
	ds_read_b128 v[218:221], v157 offset:22528
	ds_read_b128 v[222:225], v157 offset:23552
	global_load_lds_dwordx4 v[194:195], off
	v_lshl_add_u64 v[196:197], s[58:59], 0, v[130:131]
	s_mov_b32 m0, s69
	s_nop 0
	global_load_lds_dwordx4 v[196:197], off
	s_add_u32 s82, s54, 0x40000
	s_addc_u32 s83, s55, 0
	s_add_i32 s6, s6, s57
	v_lshl_add_u64 v[250:251], s[82:83], 0, v[140:141]
	s_mov_b32 m0, s6
	s_nop 0
	global_load_lds_dwordx4 v[250:251], off
	v_lshl_add_u64 v[250:251], s[82:83], 0, v[132:133]
	s_add_i32 m0, s6, 0x2000
	s_nop 0
	global_load_lds_dwordx4 v[250:251], off
	s_waitcnt vmcnt(16)
	s_cmp_lg_u32 s100, 0
	s_cbranch_scc1 .Lm4bp_386
	s_waitcnt vmcnt(8)
.Lm4bp_386:
	s_waitcnt lgkmcnt(0)
	s_mov_b32 s100, 0
	s_barrier
	s_nop 0
	v_mfma_f32_16x16x32_bf16 v[60:63], v[158:161], v[174:177], 0
	v_mfma_f32_16x16x32_bf16 v[56:59], v[166:169], v[174:177], 0
	v_mfma_f32_16x16x32_bf16 v[52:55], v[158:161], v[182:185], 0
	v_mfma_f32_16x16x32_bf16 v[48:51], v[166:169], v[182:185], 0
	v_mfma_f32_16x16x32_bf16 v[44:47], v[158:161], v[210:213], 0
	v_mfma_f32_16x16x32_bf16 v[40:43], v[166:169], v[210:213], 0
	v_mfma_f32_16x16x32_bf16 v[36:39], v[158:161], v[218:221], 0
	v_mfma_f32_16x16x32_bf16 v[32:35], v[166:169], v[218:221], 0
	v_mfma_f32_16x16x32_bf16 v[60:63], v[162:165], v[178:181], v[60:63]
	v_mfma_f32_16x16x32_bf16 v[56:59], v[170:173], v[178:181], v[56:59]
	v_mfma_f32_16x16x32_bf16 v[52:55], v[162:165], v[206:209], v[52:55]
	v_mfma_f32_16x16x32_bf16 v[48:51], v[170:173], v[206:209], v[48:51]
	v_mfma_f32_16x16x32_bf16 v[44:47], v[162:165], v[214:217], v[44:47]
	v_mfma_f32_16x16x32_bf16 v[40:43], v[170:173], v[214:217], v[40:43]
	v_mfma_f32_16x16x32_bf16 v[36:39], v[162:165], v[222:225], v[36:39]
	v_mfma_f32_16x16x32_bf16 v[32:35], v[170:173], v[222:225], v[32:35]
	v_mfma_f32_16x16x32_bf16 v[28:31], v[226:229], v[174:177], 0
	v_mfma_f32_16x16x32_bf16 v[24:27], v[234:237], v[174:177], 0
	v_mfma_f32_16x16x32_bf16 v[20:23], v[226:229], v[182:185], 0
	v_mfma_f32_16x16x32_bf16 v[16:19], v[234:237], v[182:185], 0
	v_mfma_f32_16x16x32_bf16 v[12:15], v[226:229], v[210:213], 0
	v_mfma_f32_16x16x32_bf16 v[8:11], v[234:237], v[210:213], 0
	v_mfma_f32_16x16x32_bf16 v[4:7], v[226:229], v[218:221], 0
	v_mfma_f32_16x16x32_bf16 v[0:3], v[234:237], v[218:221], 0
	v_mfma_f32_16x16x32_bf16 v[28:31], v[230:233], v[178:181], v[28:31]
	v_mfma_f32_16x16x32_bf16 v[24:27], v[238:241], v[178:181], v[24:27]
	v_mfma_f32_16x16x32_bf16 v[20:23], v[230:233], v[206:209], v[20:23]
	v_mfma_f32_16x16x32_bf16 v[16:19], v[238:241], v[206:209], v[16:19]
	v_mfma_f32_16x16x32_bf16 v[12:15], v[230:233], v[214:217], v[12:15]
	v_mfma_f32_16x16x32_bf16 v[8:11], v[238:241], v[214:217], v[8:11]
	v_mfma_f32_16x16x32_bf16 v[4:7], v[230:233], v[222:225], v[4:7]
	v_mfma_f32_16x16x32_bf16 v[0:3], v[238:241], v[222:225], v[0:3]
	s_add_i32 s6, 0, 0x18000
	s_barrier
	v_add_u32_e32 v170, s6, v154
	ds_read_b128 v[158:161], v170
	ds_read_b128 v[162:165], v170 offset:1024
	ds_read_b128 v[166:169], v170 offset:2048
	ds_read_b128 v[170:173], v170 offset:3072
	s_add_u32 s58, s58, 0x40000
	s_addc_u32 s59, s59, 0
	s_mov_b32 m0, s70
	v_lshl_add_u64 v[226:227], s[58:59], 0, v[128:129]
	ds_read_b128 v[174:177], v157 offset:32768
	ds_read_b128 v[178:181], v157 offset:33792
	ds_read_b128 v[182:185], v157 offset:34816
	ds_read_b128 v[206:209], v157 offset:35840
	ds_read_b128 v[210:213], v157 offset:36864
	ds_read_b128 v[214:217], v157 offset:37888
	ds_read_b128 v[218:221], v157 offset:38912
	ds_read_b128 v[222:225], v157 offset:39936
	global_load_lds_dwordx4 v[226:227], off
	v_lshl_add_u64 v[226:227], s[58:59], 0, v[130:131]
	s_mov_b32 m0, s71
	s_nop 0
	global_load_lds_dwordx4 v[226:227], off
	s_add_i32 s19, 0, 0x1c000
	v_add_u32_e32 v192, s19, v154
	ds_read_b128 v[226:229], v192
	ds_read_b128 v[230:233], v192 offset:1024
	ds_read_b128 v[234:237], v192 offset:2048
	ds_read_b128 v[238:241], v192 offset:3072
	s_waitcnt vmcnt(8)
	s_waitcnt lgkmcnt(0)
	s_barrier
	v_mfma_f32_16x16x32_bf16 v[124:127], v[158:161], v[174:177], v[124:127]
	v_mfma_f32_16x16x32_bf16 v[120:123], v[166:169], v[174:177], v[120:123]
	v_mfma_f32_16x16x32_bf16 v[116:119], v[158:161], v[182:185], v[116:119]
	v_mfma_f32_16x16x32_bf16 v[112:115], v[166:169], v[182:185], v[112:115]
	v_mfma_f32_16x16x32_bf16 v[108:111], v[158:161], v[210:213], v[108:111]
	v_mfma_f32_16x16x32_bf16 v[104:107], v[166:169], v[210:213], v[104:107]
	v_mfma_f32_16x16x32_bf16 v[100:103], v[158:161], v[218:221], v[100:103]
	v_mfma_f32_16x16x32_bf16 v[96:99], v[166:169], v[218:221], v[96:99]
	v_mfma_f32_16x16x32_bf16 v[124:127], v[162:165], v[178:181], v[124:127]
	v_mfma_f32_16x16x32_bf16 v[120:123], v[170:173], v[178:181], v[120:123]
	v_mfma_f32_16x16x32_bf16 v[116:119], v[162:165], v[206:209], v[116:119]
	v_mfma_f32_16x16x32_bf16 v[112:115], v[170:173], v[206:209], v[112:115]
	v_mfma_f32_16x16x32_bf16 v[108:111], v[162:165], v[214:217], v[108:111]
	v_mfma_f32_16x16x32_bf16 v[104:107], v[170:173], v[214:217], v[104:107]
	v_mfma_f32_16x16x32_bf16 v[100:103], v[162:165], v[222:225], v[100:103]
	v_mfma_f32_16x16x32_bf16 v[96:99], v[170:173], v[222:225], v[96:99]
	v_mfma_f32_16x16x32_bf16 v[92:95], v[226:229], v[174:177], v[92:95]
	v_mfma_f32_16x16x32_bf16 v[88:91], v[234:237], v[174:177], v[88:91]
	v_mfma_f32_16x16x32_bf16 v[84:87], v[226:229], v[182:185], v[84:87]
	v_mfma_f32_16x16x32_bf16 v[80:83], v[234:237], v[182:185], v[80:83]
	v_mfma_f32_16x16x32_bf16 v[76:79], v[226:229], v[210:213], v[76:79]
	v_mfma_f32_16x16x32_bf16 v[72:75], v[234:237], v[210:213], v[72:75]
	v_mfma_f32_16x16x32_bf16 v[68:71], v[226:229], v[218:221], v[68:71]
	v_mfma_f32_16x16x32_bf16 v[64:67], v[234:237], v[218:221], v[64:67]
	v_mfma_f32_16x16x32_bf16 v[92:95], v[230:233], v[178:181], v[92:95]
	v_mfma_f32_16x16x32_bf16 v[88:91], v[238:241], v[178:181], v[88:91]
	v_mfma_f32_16x16x32_bf16 v[84:87], v[230:233], v[206:209], v[84:87]
	v_mfma_f32_16x16x32_bf16 v[80:83], v[238:241], v[206:209], v[80:83]
	v_mfma_f32_16x16x32_bf16 v[76:79], v[230:233], v[214:217], v[76:79]
	v_mfma_f32_16x16x32_bf16 v[72:75], v[238:241], v[214:217], v[72:75]
	v_mfma_f32_16x16x32_bf16 v[68:71], v[230:233], v[222:225], v[68:71]
	v_mfma_f32_16x16x32_bf16 v[64:67], v[238:241], v[222:225], v[64:67]
	s_add_i32 s6, s6, s57
	v_lshl_add_u64 v[146:147], v[146:147], 0, s[36:37]
	s_mov_b32 m0, s6
	s_barrier
	s_nop 0
	global_load_lds_dwordx4 v[146:147], off
	v_lshl_add_u64 v[146:147], v[148:149], 0, s[36:37]
	s_add_i32 m0, s6, 0x2000
	s_nop 0
	global_load_lds_dwordx4 v[146:147], off
	s_mov_b32 m0, s72
	v_lshl_add_u64 v[146:147], v[194:195], 0, s[36:37]
	ds_read_b128 v[174:177], v157 offset:49152
	ds_read_b128 v[178:181], v157 offset:50176
	ds_read_b128 v[182:185], v157 offset:51200
	ds_read_b128 v[206:209], v157 offset:52224
	ds_read_b128 v[210:213], v157 offset:53248
	ds_read_b128 v[214:217], v157 offset:54272
	ds_read_b128 v[218:221], v157 offset:55296
	ds_read_b128 v[222:225], v157 offset:56320
	global_load_lds_dwordx4 v[146:147], off
	v_lshl_add_u64 v[146:147], v[196:197], 0, s[36:37]
	s_mov_b32 m0, s73
	s_nop 0
	global_load_lds_dwordx4 v[146:147], off
	s_add_u32 s54, s54, 0x40080
	s_addc_u32 s55, s55, 0
	s_add_i32 s6, s19, s57
	v_lshl_add_u64 v[146:147], s[54:55], 0, v[140:141]
	s_mov_b32 m0, s6
	s_nop 0
	global_load_lds_dwordx4 v[146:147], off
	v_lshl_add_u64 v[146:147], s[54:55], 0, v[132:133]
	s_add_i32 m0, s6, 0x2000
	s_nop 0
	global_load_lds_dwordx4 v[146:147], off
	s_waitcnt vmcnt(8)
	s_waitcnt lgkmcnt(0)
	s_barrier
	v_mfma_f32_16x16x32_bf16 v[60:63], v[158:161], v[174:177], v[60:63]
	v_mfma_f32_16x16x32_bf16 v[56:59], v[166:169], v[174:177], v[56:59]
	v_mfma_f32_16x16x32_bf16 v[52:55], v[158:161], v[182:185], v[52:55]
	v_mfma_f32_16x16x32_bf16 v[48:51], v[166:169], v[182:185], v[48:51]
	v_mfma_f32_16x16x32_bf16 v[44:47], v[158:161], v[210:213], v[44:47]
	v_mfma_f32_16x16x32_bf16 v[40:43], v[166:169], v[210:213], v[40:43]
	v_mfma_f32_16x16x32_bf16 v[36:39], v[158:161], v[218:221], v[36:39]
	v_mfma_f32_16x16x32_bf16 v[32:35], v[166:169], v[218:221], v[32:35]
	v_mfma_f32_16x16x32_bf16 v[60:63], v[162:165], v[178:181], v[60:63]
	v_mfma_f32_16x16x32_bf16 v[56:59], v[170:173], v[178:181], v[56:59]
	v_mfma_f32_16x16x32_bf16 v[52:55], v[162:165], v[206:209], v[52:55]
	v_mfma_f32_16x16x32_bf16 v[48:51], v[170:173], v[206:209], v[48:51]
	v_mfma_f32_16x16x32_bf16 v[44:47], v[162:165], v[214:217], v[44:47]
	v_mfma_f32_16x16x32_bf16 v[40:43], v[170:173], v[214:217], v[40:43]
	v_mfma_f32_16x16x32_bf16 v[36:39], v[162:165], v[222:225], v[36:39]
	v_mfma_f32_16x16x32_bf16 v[32:35], v[170:173], v[222:225], v[32:35]
	v_mfma_f32_16x16x32_bf16 v[28:31], v[226:229], v[174:177], v[28:31]
	v_mfma_f32_16x16x32_bf16 v[24:27], v[234:237], v[174:177], v[24:27]
	v_mfma_f32_16x16x32_bf16 v[20:23], v[226:229], v[182:185], v[20:23]
	v_mfma_f32_16x16x32_bf16 v[16:19], v[234:237], v[182:185], v[16:19]
	v_mfma_f32_16x16x32_bf16 v[12:15], v[226:229], v[210:213], v[12:15]
	v_mfma_f32_16x16x32_bf16 v[8:11], v[234:237], v[210:213], v[8:11]
	v_mfma_f32_16x16x32_bf16 v[4:7], v[226:229], v[218:221], v[4:7]
	v_mfma_f32_16x16x32_bf16 v[0:3], v[234:237], v[218:221], v[0:3]
	v_mfma_f32_16x16x32_bf16 v[28:31], v[230:233], v[178:181], v[28:31]
	v_mfma_f32_16x16x32_bf16 v[24:27], v[238:241], v[178:181], v[24:27]
	v_mfma_f32_16x16x32_bf16 v[20:23], v[230:233], v[206:209], v[20:23]
	v_mfma_f32_16x16x32_bf16 v[16:19], v[238:241], v[206:209], v[16:19]
	v_mfma_f32_16x16x32_bf16 v[12:15], v[230:233], v[214:217], v[12:15]
	v_mfma_f32_16x16x32_bf16 v[8:11], v[238:241], v[214:217], v[8:11]
	v_mfma_f32_16x16x32_bf16 v[4:7], v[230:233], v[222:225], v[4:7]
	v_mfma_f32_16x16x32_bf16 v[0:3], v[238:241], v[222:225], v[0:3]
	s_add_i32 s81, s81, 2
	s_add_u32 s52, s52, 0x100
	s_addc_u32 s53, s53, 0
	s_cmp_gt_u32 s81, 13
	s_add_u32 s6, s28, s52
	s_addc_u32 s19, s29, s53
	s_add_u32 s6, s6, 0x100
	s_addc_u32 s19, s19, 0
	s_add_u32 s23, s10, s52
	s_addc_u32 s54, s11, s53
	s_add_i32 s82, 0, 0x10000
	s_cmpk_eq_i32 s52, 0x700
	s_cselect_b32 s59, s12, s19
	s_cselect_b32 s58, s35, s6
	s_cselect_b32 s55, s39, s54
	s_cselect_b32 s54, s47, s23
my_head_386:
	s_barrier
.LBB0_386:
	v_add_u32_e32 v146, s82, v154
	ds_read_b128 v[158:161], v146
	ds_read_b128 v[162:165], v146 offset:1024
	ds_read_b128 v[166:169], v146 offset:2048
	ds_read_b128 v[170:173], v146 offset:3072
	v_lshl_add_u64 v[146:147], v[150:151], 0, s[52:53]
	s_add_i32 m0, s68, 0xc000
	ds_read_b128 v[174:177], v157
	ds_read_b128 v[178:181], v157 offset:1024
	ds_read_b128 v[182:185], v157 offset:2048
	ds_read_b128 v[206:209], v157 offset:3072
	ds_read_b128 v[210:213], v157 offset:4096
	ds_read_b128 v[214:217], v157 offset:5120
	ds_read_b128 v[218:221], v157 offset:6144
	ds_read_b128 v[222:225], v157 offset:7168
	global_load_lds_dwordx4 v[146:147], off
	v_lshl_add_u64 v[146:147], v[152:153], 0, s[52:53]
	s_add_i32 m0, s68, 0xe000
	s_nop 0
	global_load_lds_dwordx4 v[146:147], off
	s_add_i32 s6, 0, 0x14000
	v_add_u32_e32 v146, s6, v154
	ds_read_b128 v[226:229], v146
	ds_read_b128 v[230:233], v146 offset:1024
	ds_read_b128 v[234:237], v146 offset:2048
	ds_read_b128 v[238:241], v146 offset:3072
	s_waitcnt vmcnt(8)
	s_waitcnt lgkmcnt(0)
	s_barrier
	v_mfma_f32_16x16x32_bf16 v[124:127], v[158:161], v[174:177], v[124:127]
	v_mfma_f32_16x16x32_bf16 v[120:123], v[166:169], v[174:177], v[120:123]
	v_mfma_f32_16x16x32_bf16 v[116:119], v[158:161], v[182:185], v[116:119]
	v_mfma_f32_16x16x32_bf16 v[112:115], v[166:169], v[182:185], v[112:115]
	v_mfma_f32_16x16x32_bf16 v[108:111], v[158:161], v[210:213], v[108:111]
	v_mfma_f32_16x16x32_bf16 v[104:107], v[166:169], v[210:213], v[104:107]
	v_mfma_f32_16x16x32_bf16 v[100:103], v[158:161], v[218:221], v[100:103]
	v_mfma_f32_16x16x32_bf16 v[96:99], v[166:169], v[218:221], v[96:99]
	v_mfma_f32_16x16x32_bf16 v[124:127], v[162:165], v[178:181], v[124:127]
	v_mfma_f32_16x16x32_bf16 v[120:123], v[170:173], v[178:181], v[120:123]
	v_mfma_f32_16x16x32_bf16 v[116:119], v[162:165], v[206:209], v[116:119]
	v_mfma_f32_16x16x32_bf16 v[112:115], v[170:173], v[206:209], v[112:115]
	v_mfma_f32_16x16x32_bf16 v[108:111], v[162:165], v[214:217], v[108:111]
	v_mfma_f32_16x16x32_bf16 v[104:107], v[170:173], v[214:217], v[104:107]
	v_mfma_f32_16x16x32_bf16 v[100:103], v[162:165], v[222:225], v[100:103]
	v_mfma_f32_16x16x32_bf16 v[96:99], v[170:173], v[222:225], v[96:99]
	v_mfma_f32_16x16x32_bf16 v[92:95], v[226:229], v[174:177], v[92:95]
	v_mfma_f32_16x16x32_bf16 v[88:91], v[234:237], v[174:177], v[88:91]
	v_mfma_f32_16x16x32_bf16 v[84:87], v[226:229], v[182:185], v[84:87]
	v_mfma_f32_16x16x32_bf16 v[80:83], v[234:237], v[182:185], v[80:83]
	v_mfma_f32_16x16x32_bf16 v[76:79], v[226:229], v[210:213], v[76:79]
	v_mfma_f32_16x16x32_bf16 v[72:75], v[234:237], v[210:213], v[72:75]
	v_mfma_f32_16x16x32_bf16 v[68:71], v[226:229], v[218:221], v[68:71]
	v_mfma_f32_16x16x32_bf16 v[64:67], v[234:237], v[218:221], v[64:67]
	v_mfma_f32_16x16x32_bf16 v[92:95], v[230:233], v[178:181], v[92:95]
	v_mfma_f32_16x16x32_bf16 v[88:91], v[238:241], v[178:181], v[88:91]
	v_mfma_f32_16x16x32_bf16 v[84:87], v[230:233], v[206:209], v[84:87]
	v_mfma_f32_16x16x32_bf16 v[80:83], v[238:241], v[206:209], v[80:83]
	v_mfma_f32_16x16x32_bf16 v[76:79], v[230:233], v[214:217], v[76:79]
	v_mfma_f32_16x16x32_bf16 v[72:75], v[238:241], v[214:217], v[72:75]
	v_mfma_f32_16x16x32_bf16 v[68:71], v[230:233], v[222:225], v[68:71]
	v_mfma_f32_16x16x32_bf16 v[64:67], v[238:241], v[222:225], v[64:67]
	s_add_i32 s19, s82, s57
	v_lshl_add_u64 v[146:147], s[54:55], 0, v[140:141]
	s_mov_b32 m0, s19
	v_lshl_add_u64 v[148:149], s[54:55], 0, v[132:133]
	s_barrier
	global_load_lds_dwordx4 v[146:147], off
	s_add_i32 m0, s19, 0x2000
	s_nop 0
	global_load_lds_dwordx4 v[148:149], off
	s_mov_b32 m0, s68
	v_lshl_add_u64 v[194:195], s[58:59], 0, v[128:129]
	ds_read_b128 v[174:177], v157 offset:16384
	ds_read_b128 v[178:181], v157 offset:17408
	ds_read_b128 v[182:185], v157 offset:18432
	ds_read_b128 v[206:209], v157 offset:19456
	ds_read_b128 v[210:213], v157 offset:20480
	ds_read_b128 v[214:217], v157 offset:21504
	ds_read_b128 v[218:221], v157 offset:22528
	ds_read_b128 v[222:225], v157 offset:23552
	global_load_lds_dwordx4 v[194:195], off
	v_lshl_add_u64 v[196:197], s[58:59], 0, v[130:131]
	s_mov_b32 m0, s69
	s_nop 0
	global_load_lds_dwordx4 v[196:197], off
	s_add_u32 s82, s54, 0x40000
	s_addc_u32 s83, s55, 0
	s_add_i32 s6, s6, s57
	v_lshl_add_u64 v[250:251], s[82:83], 0, v[140:141]
	s_mov_b32 m0, s6
	s_nop 0
	global_load_lds_dwordx4 v[250:251], off
	v_lshl_add_u64 v[250:251], s[82:83], 0, v[132:133]
	s_add_i32 m0, s6, 0x2000
	s_nop 0
	global_load_lds_dwordx4 v[250:251], off
	s_nop 0
	s_waitcnt vmcnt(8)
	s_waitcnt lgkmcnt(0)
	s_barrier
	v_mfma_f32_16x16x32_bf16 v[60:63], v[158:161], v[174:177], v[60:63]
	v_mfma_f32_16x16x32_bf16 v[56:59], v[166:169], v[174:177], v[56:59]
	v_mfma_f32_16x16x32_bf16 v[52:55], v[158:161], v[182:185], v[52:55]
	v_mfma_f32_16x16x32_bf16 v[48:51], v[166:169], v[182:185], v[48:51]
	v_mfma_f32_16x16x32_bf16 v[44:47], v[158:161], v[210:213], v[44:47]
	v_mfma_f32_16x16x32_bf16 v[40:43], v[166:169], v[210:213], v[40:43]
	v_mfma_f32_16x16x32_bf16 v[36:39], v[158:161], v[218:221], v[36:39]
	v_mfma_f32_16x16x32_bf16 v[32:35], v[166:169], v[218:221], v[32:35]
	v_mfma_f32_16x16x32_bf16 v[60:63], v[162:165], v[178:181], v[60:63]
	v_mfma_f32_16x16x32_bf16 v[56:59], v[170:173], v[178:181], v[56:59]
	v_mfma_f32_16x16x32_bf16 v[52:55], v[162:165], v[206:209], v[52:55]
	v_mfma_f32_16x16x32_bf16 v[48:51], v[170:173], v[206:209], v[48:51]
	v_mfma_f32_16x16x32_bf16 v[44:47], v[162:165], v[214:217], v[44:47]
	v_mfma_f32_16x16x32_bf16 v[40:43], v[170:173], v[214:217], v[40:43]
	v_mfma_f32_16x16x32_bf16 v[36:39], v[162:165], v[222:225], v[36:39]
	v_mfma_f32_16x16x32_bf16 v[32:35], v[170:173], v[222:225], v[32:35]
	v_mfma_f32_16x16x32_bf16 v[28:31], v[226:229], v[174:177], v[28:31]
	v_mfma_f32_16x16x32_bf16 v[24:27], v[234:237], v[174:177], v[24:27]
	v_mfma_f32_16x16x32_bf16 v[20:23], v[226:229], v[182:185], v[20:23]
	v_mfma_f32_16x16x32_bf16 v[16:19], v[234:237], v[182:185], v[16:19]
	v_mfma_f32_16x16x32_bf16 v[12:15], v[226:229], v[210:213], v[12:15]
	v_mfma_f32_16x16x32_bf16 v[8:11], v[234:237], v[210:213], v[8:11]
	v_mfma_f32_16x16x32_bf16 v[4:7], v[226:229], v[218:221], v[4:7]
	v_mfma_f32_16x16x32_bf16 v[0:3], v[234:237], v[218:221], v[0:3]
	v_mfma_f32_16x16x32_bf16 v[28:31], v[230:233], v[178:181], v[28:31]
	v_mfma_f32_16x16x32_bf16 v[24:27], v[238:241], v[178:181], v[24:27]
	v_mfma_f32_16x16x32_bf16 v[20:23], v[230:233], v[206:209], v[20:23]
	v_mfma_f32_16x16x32_bf16 v[16:19], v[238:241], v[206:209], v[16:19]
	v_mfma_f32_16x16x32_bf16 v[12:15], v[230:233], v[214:217], v[12:15]
	v_mfma_f32_16x16x32_bf16 v[8:11], v[238:241], v[214:217], v[8:11]
	v_mfma_f32_16x16x32_bf16 v[4:7], v[230:233], v[222:225], v[4:7]
	v_mfma_f32_16x16x32_bf16 v[0:3], v[238:241], v[222:225], v[0:3]
	s_add_i32 s6, 0, 0x18000
	s_barrier
	v_add_u32_e32 v170, s6, v154
	ds_read_b128 v[158:161], v170
	ds_read_b128 v[162:165], v170 offset:1024
	ds_read_b128 v[166:169], v170 offset:2048
	ds_read_b128 v[170:173], v170 offset:3072
	s_add_u32 s58, s58, 0x40000
	s_addc_u32 s59, s59, 0
	s_mov_b32 m0, s70
	v_lshl_add_u64 v[226:227], s[58:59], 0, v[128:129]
	ds_read_b128 v[174:177], v157 offset:32768
	ds_read_b128 v[178:181], v157 offset:33792
	ds_read_b128 v[182:185], v157 offset:34816
	ds_read_b128 v[206:209], v157 offset:35840
	ds_read_b128 v[210:213], v157 offset:36864
	ds_read_b128 v[214:217], v157 offset:37888
	ds_read_b128 v[218:221], v157 offset:38912
	ds_read_b128 v[222:225], v157 offset:39936
	global_load_lds_dwordx4 v[226:227], off
	v_lshl_add_u64 v[226:227], s[58:59], 0, v[130:131]
	s_mov_b32 m0, s71
	s_nop 0
	global_load_lds_dwordx4 v[226:227], off
	s_add_i32 s19, 0, 0x1c000
	v_add_u32_e32 v192, s19, v154
	ds_read_b128 v[226:229], v192
	ds_read_b128 v[230:233], v192 offset:1024
	ds_read_b128 v[234:237], v192 offset:2048
	ds_read_b128 v[238:241], v192 offset:3072
	s_waitcnt vmcnt(8)
	s_waitcnt lgkmcnt(0)
	s_barrier
	v_mfma_f32_16x16x32_bf16 v[124:127], v[158:161], v[174:177], v[124:127]
	v_mfma_f32_16x16x32_bf16 v[120:123], v[166:169], v[174:177], v[120:123]
	v_mfma_f32_16x16x32_bf16 v[116:119], v[158:161], v[182:185], v[116:119]
	v_mfma_f32_16x16x32_bf16 v[112:115], v[166:169], v[182:185], v[112:115]
	v_mfma_f32_16x16x32_bf16 v[108:111], v[158:161], v[210:213], v[108:111]
	v_mfma_f32_16x16x32_bf16 v[104:107], v[166:169], v[210:213], v[104:107]
	v_mfma_f32_16x16x32_bf16 v[100:103], v[158:161], v[218:221], v[100:103]
	v_mfma_f32_16x16x32_bf16 v[96:99], v[166:169], v[218:221], v[96:99]
	v_mfma_f32_16x16x32_bf16 v[124:127], v[162:165], v[178:181], v[124:127]
	v_mfma_f32_16x16x32_bf16 v[120:123], v[170:173], v[178:181], v[120:123]
	v_mfma_f32_16x16x32_bf16 v[116:119], v[162:165], v[206:209], v[116:119]
	v_mfma_f32_16x16x32_bf16 v[112:115], v[170:173], v[206:209], v[112:115]
	v_mfma_f32_16x16x32_bf16 v[108:111], v[162:165], v[214:217], v[108:111]
	v_mfma_f32_16x16x32_bf16 v[104:107], v[170:173], v[214:217], v[104:107]
	v_mfma_f32_16x16x32_bf16 v[100:103], v[162:165], v[222:225], v[100:103]
	v_mfma_f32_16x16x32_bf16 v[96:99], v[170:173], v[222:225], v[96:99]
	v_mfma_f32_16x16x32_bf16 v[92:95], v[226:229], v[174:177], v[92:95]
	v_mfma_f32_16x16x32_bf16 v[88:91], v[234:237], v[174:177], v[88:91]
	v_mfma_f32_16x16x32_bf16 v[84:87], v[226:229], v[182:185], v[84:87]
	v_mfma_f32_16x16x32_bf16 v[80:83], v[234:237], v[182:185], v[80:83]
	v_mfma_f32_16x16x32_bf16 v[76:79], v[226:229], v[210:213], v[76:79]
	v_mfma_f32_16x16x32_bf16 v[72:75], v[234:237], v[210:213], v[72:75]
	v_mfma_f32_16x16x32_bf16 v[68:71], v[226:229], v[218:221], v[68:71]
	v_mfma_f32_16x16x32_bf16 v[64:67], v[234:237], v[218:221], v[64:67]
	v_mfma_f32_16x16x32_bf16 v[92:95], v[230:233], v[178:181], v[92:95]
	v_mfma_f32_16x16x32_bf16 v[88:91], v[238:241], v[178:181], v[88:91]
	v_mfma_f32_16x16x32_bf16 v[84:87], v[230:233], v[206:209], v[84:87]
	v_mfma_f32_16x16x32_bf16 v[80:83], v[238:241], v[206:209], v[80:83]
	v_mfma_f32_16x16x32_bf16 v[76:79], v[230:233], v[214:217], v[76:79]
	v_mfma_f32_16x16x32_bf16 v[72:75], v[238:241], v[214:217], v[72:75]
	v_mfma_f32_16x16x32_bf16 v[68:71], v[230:233], v[222:225], v[68:71]
	v_mfma_f32_16x16x32_bf16 v[64:67], v[238:241], v[222:225], v[64:67]
	s_add_i32 s6, s6, s57
	v_lshl_add_u64 v[146:147], v[146:147], 0, s[36:37]
	s_mov_b32 m0, s6
	s_barrier
	s_nop 0
	global_load_lds_dwordx4 v[146:147], off
	v_lshl_add_u64 v[146:147], v[148:149], 0, s[36:37]
	s_add_i32 m0, s6, 0x2000
	s_nop 0
	global_load_lds_dwordx4 v[146:147], off
	s_mov_b32 m0, s72
	v_lshl_add_u64 v[146:147], v[194:195], 0, s[36:37]
	ds_read_b128 v[174:177], v157 offset:49152
	ds_read_b128 v[178:181], v157 offset:50176
	ds_read_b128 v[182:185], v157 offset:51200
	ds_read_b128 v[206:209], v157 offset:52224
	ds_read_b128 v[210:213], v157 offset:53248
	ds_read_b128 v[214:217], v157 offset:54272
	ds_read_b128 v[218:221], v157 offset:55296
	ds_read_b128 v[222:225], v157 offset:56320
	global_load_lds_dwordx4 v[146:147], off
	v_lshl_add_u64 v[146:147], v[196:197], 0, s[36:37]
	s_mov_b32 m0, s73
	s_nop 0
	global_load_lds_dwordx4 v[146:147], off
	s_add_u32 s54, s54, 0x40080
	s_addc_u32 s55, s55, 0
	s_add_i32 s6, s19, s57
	v_lshl_add_u64 v[146:147], s[54:55], 0, v[140:141]
	s_mov_b32 m0, s6
	s_nop 0
	global_load_lds_dwordx4 v[146:147], off
	v_lshl_add_u64 v[146:147], s[54:55], 0, v[132:133]
	s_add_i32 m0, s6, 0x2000
	s_nop 0
	global_load_lds_dwordx4 v[146:147], off
	s_waitcnt vmcnt(8)
	s_waitcnt lgkmcnt(0)
	s_barrier
	v_mfma_f32_16x16x32_bf16 v[60:63], v[158:161], v[174:177], v[60:63]
	v_mfma_f32_16x16x32_bf16 v[56:59], v[166:169], v[174:177], v[56:59]
	v_mfma_f32_16x16x32_bf16 v[52:55], v[158:161], v[182:185], v[52:55]
	v_mfma_f32_16x16x32_bf16 v[48:51], v[166:169], v[182:185], v[48:51]
	v_mfma_f32_16x16x32_bf16 v[44:47], v[158:161], v[210:213], v[44:47]
	v_mfma_f32_16x16x32_bf16 v[40:43], v[166:169], v[210:213], v[40:43]
	v_mfma_f32_16x16x32_bf16 v[36:39], v[158:161], v[218:221], v[36:39]
	v_mfma_f32_16x16x32_bf16 v[32:35], v[166:169], v[218:221], v[32:35]
	v_mfma_f32_16x16x32_bf16 v[60:63], v[162:165], v[178:181], v[60:63]
	v_mfma_f32_16x16x32_bf16 v[56:59], v[170:173], v[178:181], v[56:59]
	v_mfma_f32_16x16x32_bf16 v[52:55], v[162:165], v[206:209], v[52:55]
	v_mfma_f32_16x16x32_bf16 v[48:51], v[170:173], v[206:209], v[48:51]
	v_mfma_f32_16x16x32_bf16 v[44:47], v[162:165], v[214:217], v[44:47]
	v_mfma_f32_16x16x32_bf16 v[40:43], v[170:173], v[214:217], v[40:43]
	v_mfma_f32_16x16x32_bf16 v[36:39], v[162:165], v[222:225], v[36:39]
	v_mfma_f32_16x16x32_bf16 v[32:35], v[170:173], v[222:225], v[32:35]
	v_mfma_f32_16x16x32_bf16 v[28:31], v[226:229], v[174:177], v[28:31]
	v_mfma_f32_16x16x32_bf16 v[24:27], v[234:237], v[174:177], v[24:27]
	v_mfma_f32_16x16x32_bf16 v[20:23], v[226:229], v[182:185], v[20:23]
	v_mfma_f32_16x16x32_bf16 v[16:19], v[234:237], v[182:185], v[16:19]
	v_mfma_f32_16x16x32_bf16 v[12:15], v[226:229], v[210:213], v[12:15]
	v_mfma_f32_16x16x32_bf16 v[8:11], v[234:237], v[210:213], v[8:11]
	v_mfma_f32_16x16x32_bf16 v[4:7], v[226:229], v[218:221], v[4:7]
	v_mfma_f32_16x16x32_bf16 v[0:3], v[234:237], v[218:221], v[0:3]
	v_mfma_f32_16x16x32_bf16 v[28:31], v[230:233], v[178:181], v[28:31]
	v_mfma_f32_16x16x32_bf16 v[24:27], v[238:241], v[178:181], v[24:27]
	v_mfma_f32_16x16x32_bf16 v[20:23], v[230:233], v[206:209], v[20:23]
	v_mfma_f32_16x16x32_bf16 v[16:19], v[238:241], v[206:209], v[16:19]
	v_mfma_f32_16x16x32_bf16 v[12:15], v[230:233], v[214:217], v[12:15]
	v_mfma_f32_16x16x32_bf16 v[8:11], v[238:241], v[214:217], v[8:11]
	v_mfma_f32_16x16x32_bf16 v[4:7], v[230:233], v[222:225], v[4:7]
	v_mfma_f32_16x16x32_bf16 v[0:3], v[238:241], v[222:225], v[0:3]
	s_add_i32 s81, s81, 2
	s_add_u32 s52, s52, 0x100
	s_addc_u32 s53, s53, 0
	s_cmp_gt_u32 s81, 13
	s_cbranch_scc1 my_exit_386
	s_add_u32 s6, s28, s52
	s_addc_u32 s19, s29, s53
	s_add_u32 s6, s6, 0x100
	s_addc_u32 s19, s19, 0
	s_add_u32 s23, s10, s52
	s_addc_u32 s54, s11, s53
	s_add_i32 s82, 0, 0x10000
	s_cmpk_eq_i32 s52, 0x700
	s_cselect_b32 s59, s12, s19
	s_cselect_b32 s58, s35, s6
	s_cselect_b32 s55, s39, s54
	s_cselect_b32 s54, s47, s23
	s_branch my_head_386
my_exit_386:
	s_barrier
	s_mov_b32 s100, 1
	v_lshl_add_u32 v158, s75, 10, v155
	ds_read2_b32 v[146:147], v158 offset1:16
	s_add_u32 s52, s10, 0xffffff00
	s_addc_u32 s53, s11, -1
	s_ashr_i32 s35, s34, 31
	s_lshl_b64 s[10:11], s[34:35], 8
	s_waitcnt lgkmcnt(0)
	v_mul_f32_e32 v184, 0xbfb8aa3b, v146
	v_mul_f32_e32 v206, v146, v146
	v_pk_mul_f32 v[168:169], v[124:125], v[184:185] op_sel_hi:[1,0]
	v_pk_mul_f32 v[170:171], v[126:127], v[184:185] op_sel_hi:[1,0]
	v_pk_mul_f32 v[172:173], v[120:121], v[184:185] op_sel_hi:[1,0]
	v_pk_mul_f32 v[174:175], v[122:123], v[184:185] op_sel_hi:[1,0]
	v_exp_f32_e32 v168, v168
	v_exp_f32_e32 v169, v169
	v_exp_f32_e32 v170, v170
	v_exp_f32_e32 v171, v171
	v_exp_f32_e32 v172, v172
	v_exp_f32_e32 v173, v173
	v_exp_f32_e32 v174, v174
	v_exp_f32_e32 v175, v175
	v_pk_mul_f32 v[176:177], v[124:125], v[92:93]
	v_pk_mul_f32 v[178:179], v[126:127], v[94:95]
	v_pk_mul_f32 v[180:181], v[120:121], v[88:89]
	v_pk_mul_f32 v[182:183], v[122:123], v[90:91]
	v_pk_add_f32 v[168:169], v[168:169], 1.0 op_sel_hi:[1,0]
	v_pk_add_f32 v[170:171], v[170:171], 1.0 op_sel_hi:[1,0]
	v_pk_add_f32 v[172:173], v[172:173], 1.0 op_sel_hi:[1,0]
	v_pk_add_f32 v[174:175], v[174:175], 1.0 op_sel_hi:[1,0]
	v_rcp_f32_e32 v168, v168
	v_rcp_f32_e32 v169, v169
	v_rcp_f32_e32 v170, v170
	v_rcp_f32_e32 v171, v171
	v_rcp_f32_e32 v172, v172
	v_rcp_f32_e32 v173, v173
	v_rcp_f32_e32 v174, v174
	v_rcp_f32_e32 v175, v175
	v_pk_mul_f32 v[176:177], v[176:177], v[206:207] op_sel_hi:[1,0]
	v_pk_mul_f32 v[178:179], v[178:179], v[206:207] op_sel_hi:[1,0]
	v_pk_mul_f32 v[180:181], v[180:181], v[206:207] op_sel_hi:[1,0]
	v_pk_mul_f32 v[182:183], v[182:183], v[206:207] op_sel_hi:[1,0]
	v_pk_mul_f32 v[176:177], v[176:177], v[168:169]
	v_pk_mul_f32 v[178:179], v[178:179], v[170:171]
	v_pk_mul_f32 v[180:181], v[180:181], v[172:173]
	v_pk_mul_f32 v[182:183], v[182:183], v[174:175]
	v_cvt_pk_bf16_f32 v160, v176, v177
	v_cvt_pk_bf16_f32 v161, v178, v179
	v_cvt_pk_bf16_f32 v162, v180, v181
	v_cvt_pk_bf16_f32 v163, v182, v183
	v_lshl_add_u64 v[152:153], v[134:135], 0, s[10:11]
	s_movk_i32 s6, 0x1600
	v_lshl_or_b32 v150, s74, 7, v156
	v_ashrrev_i32_e32 v151, 31, v150
	s_nop 1
	v_mov_b64_e32 v[148:149], s[30:31]
	v_mad_u64_u32 v[148:149], s[10:11], v152, s6, v[148:149]
	v_mov_b32_e32 v146, v149
	v_mad_u64_u32 v[152:153], s[10:11], v153, s6, v[146:147]
	v_mov_b32_e32 v149, v152
	v_mov_b32_e32 v146, v147
	v_lshl_add_u64 v[150:151], v[150:151], 1, v[148:149]
	global_store_dwordx4 v[150:151], v[160:163], off
	v_mul_f32_e32 v184, 0xbfb8aa3b, v146
	v_mul_f32_e32 v206, v146, v146
	v_pk_mul_f32 v[168:169], v[116:117], v[184:185] op_sel_hi:[1,0]
	v_pk_mul_f32 v[170:171], v[118:119], v[184:185] op_sel_hi:[1,0]
	v_pk_mul_f32 v[172:173], v[112:113], v[184:185] op_sel_hi:[1,0]
	v_pk_mul_f32 v[174:175], v[114:115], v[184:185] op_sel_hi:[1,0]
	v_exp_f32_e32 v168, v168
	v_exp_f32_e32 v169, v169
	v_exp_f32_e32 v170, v170
	v_exp_f32_e32 v171, v171
	v_exp_f32_e32 v172, v172
	v_exp_f32_e32 v173, v173
	v_exp_f32_e32 v174, v174
	v_exp_f32_e32 v175, v175
	v_pk_mul_f32 v[176:177], v[116:117], v[84:85]
	v_pk_mul_f32 v[178:179], v[118:119], v[86:87]
	v_pk_mul_f32 v[180:181], v[112:113], v[80:81]
	v_pk_mul_f32 v[182:183], v[114:115], v[82:83]
	v_pk_add_f32 v[168:169], v[168:169], 1.0 op_sel_hi:[1,0]
	v_pk_add_f32 v[170:171], v[170:171], 1.0 op_sel_hi:[1,0]
	v_pk_add_f32 v[172:173], v[172:173], 1.0 op_sel_hi:[1,0]
	v_pk_add_f32 v[174:175], v[174:175], 1.0 op_sel_hi:[1,0]
	v_rcp_f32_e32 v168, v168
	v_rcp_f32_e32 v169, v169
	v_rcp_f32_e32 v170, v170
	v_rcp_f32_e32 v171, v171
	v_rcp_f32_e32 v172, v172
	v_rcp_f32_e32 v173, v173
	v_rcp_f32_e32 v174, v174
	v_rcp_f32_e32 v175, v175
	v_pk_mul_f32 v[176:177], v[176:177], v[206:207] op_sel_hi:[1,0]
	v_pk_mul_f32 v[178:179], v[178:179], v[206:207] op_sel_hi:[1,0]
	v_pk_mul_f32 v[180:181], v[180:181], v[206:207] op_sel_hi:[1,0]
	v_pk_mul_f32 v[182:183], v[182:183], v[206:207] op_sel_hi:[1,0]
	v_pk_mul_f32 v[176:177], v[176:177], v[168:169]
	v_pk_mul_f32 v[178:179], v[178:179], v[170:171]
	v_pk_mul_f32 v[180:181], v[180:181], v[172:173]
	v_pk_mul_f32 v[182:183], v[182:183], v[174:175]
	v_cvt_pk_bf16_f32 v160, v176, v177
	v_cvt_pk_bf16_f32 v161, v178, v179
	v_cvt_pk_bf16_f32 v162, v180, v181
	v_cvt_pk_bf16_f32 v163, v182, v183
	s_mov_b32 s6, 0x16000
	s_nop 1
	v_add_co_u32_e32 v146, vcc, s6, v150
	s_nop 0
	v_addc_co_u32_e32 v147, vcc, 0, v151, vcc
	global_store_dwordx4 v[146:147], v[160:163], off
	ds_read2_b32 v[146:147], v158 offset0:32 offset1:48
	s_mov_b32 s6, 0x2c000
	s_waitcnt lgkmcnt(0)
	v_mul_f32_e32 v184, 0xbfb8aa3b, v146
	v_mul_f32_e32 v206, v146, v146
	v_pk_mul_f32 v[168:169], v[108:109], v[184:185] op_sel_hi:[1,0]
	v_pk_mul_f32 v[170:171], v[110:111], v[184:185] op_sel_hi:[1,0]
	v_pk_mul_f32 v[172:173], v[104:105], v[184:185] op_sel_hi:[1,0]
	v_pk_mul_f32 v[174:175], v[106:107], v[184:185] op_sel_hi:[1,0]
	v_exp_f32_e32 v168, v168
	v_exp_f32_e32 v169, v169
	v_exp_f32_e32 v170, v170
	v_exp_f32_e32 v171, v171
	v_exp_f32_e32 v172, v172
	v_exp_f32_e32 v173, v173
	v_exp_f32_e32 v174, v174
	v_exp_f32_e32 v175, v175
	v_pk_mul_f32 v[176:177], v[108:109], v[76:77]
	v_pk_mul_f32 v[178:179], v[110:111], v[78:79]
	v_pk_mul_f32 v[180:181], v[104:105], v[72:73]
	v_pk_mul_f32 v[182:183], v[106:107], v[74:75]
	v_pk_add_f32 v[168:169], v[168:169], 1.0 op_sel_hi:[1,0]
	v_pk_add_f32 v[170:171], v[170:171], 1.0 op_sel_hi:[1,0]
	v_pk_add_f32 v[172:173], v[172:173], 1.0 op_sel_hi:[1,0]
	v_pk_add_f32 v[174:175], v[174:175], 1.0 op_sel_hi:[1,0]
	v_rcp_f32_e32 v168, v168
	v_rcp_f32_e32 v169, v169
	v_rcp_f32_e32 v170, v170
	v_rcp_f32_e32 v171, v171
	v_rcp_f32_e32 v172, v172
	v_rcp_f32_e32 v173, v173
	v_rcp_f32_e32 v174, v174
	v_rcp_f32_e32 v175, v175
	v_pk_mul_f32 v[176:177], v[176:177], v[206:207] op_sel_hi:[1,0]
	v_pk_mul_f32 v[178:179], v[178:179], v[206:207] op_sel_hi:[1,0]
	v_pk_mul_f32 v[180:181], v[180:181], v[206:207] op_sel_hi:[1,0]
	v_pk_mul_f32 v[182:183], v[182:183], v[206:207] op_sel_hi:[1,0]
	v_pk_mul_f32 v[176:177], v[176:177], v[168:169]
	v_pk_mul_f32 v[178:179], v[178:179], v[170:171]
	v_pk_mul_f32 v[180:181], v[180:181], v[172:173]
	v_pk_mul_f32 v[182:183], v[182:183], v[174:175]
	v_cvt_pk_bf16_f32 v160, v176, v177
	v_cvt_pk_bf16_f32 v161, v178, v179
	v_cvt_pk_bf16_f32 v162, v180, v181
	v_cvt_pk_bf16_f32 v163, v182, v183
	s_nop 1
	v_mov_b32_e32 v146, v147
	v_add_co_u32_e32 v148, vcc, s6, v150
	v_addc_co_u32_e32 v149, vcc, 0, v151, vcc
	global_store_dwordx4 v[148:149], v[160:163], off
	v_mul_f32_e32 v184, 0xbfb8aa3b, v146
	v_mul_f32_e32 v206, v146, v146
	v_pk_mul_f32 v[168:169], v[100:101], v[184:185] op_sel_hi:[1,0]
	v_pk_mul_f32 v[170:171], v[102:103], v[184:185] op_sel_hi:[1,0]
	v_pk_mul_f32 v[172:173], v[96:97], v[184:185] op_sel_hi:[1,0]
	v_pk_mul_f32 v[174:175], v[98:99], v[184:185] op_sel_hi:[1,0]
	v_exp_f32_e32 v168, v168
	v_exp_f32_e32 v169, v169
	v_exp_f32_e32 v170, v170
	v_exp_f32_e32 v171, v171
	v_exp_f32_e32 v172, v172
	v_exp_f32_e32 v173, v173
	v_exp_f32_e32 v174, v174
	v_exp_f32_e32 v175, v175
	v_pk_mul_f32 v[176:177], v[100:101], v[68:69]
	v_pk_mul_f32 v[178:179], v[102:103], v[70:71]
	v_pk_mul_f32 v[180:181], v[96:97], v[64:65]
	v_pk_mul_f32 v[182:183], v[98:99], v[66:67]
	v_pk_add_f32 v[168:169], v[168:169], 1.0 op_sel_hi:[1,0]
	v_pk_add_f32 v[170:171], v[170:171], 1.0 op_sel_hi:[1,0]
	v_pk_add_f32 v[172:173], v[172:173], 1.0 op_sel_hi:[1,0]
	v_pk_add_f32 v[174:175], v[174:175], 1.0 op_sel_hi:[1,0]
	v_rcp_f32_e32 v168, v168
	v_rcp_f32_e32 v169, v169
	v_rcp_f32_e32 v170, v170
	v_rcp_f32_e32 v171, v171
	v_rcp_f32_e32 v172, v172
	v_rcp_f32_e32 v173, v173
	v_rcp_f32_e32 v174, v174
	v_rcp_f32_e32 v175, v175
	v_pk_mul_f32 v[176:177], v[176:177], v[206:207] op_sel_hi:[1,0]
	v_pk_mul_f32 v[178:179], v[178:179], v[206:207] op_sel_hi:[1,0]
	v_pk_mul_f32 v[180:181], v[180:181], v[206:207] op_sel_hi:[1,0]
	v_pk_mul_f32 v[182:183], v[182:183], v[206:207] op_sel_hi:[1,0]
	v_pk_mul_f32 v[176:177], v[176:177], v[168:169]
	v_pk_mul_f32 v[178:179], v[178:179], v[170:171]
	v_pk_mul_f32 v[180:181], v[180:181], v[172:173]
	v_pk_mul_f32 v[182:183], v[182:183], v[174:175]
	v_cvt_pk_bf16_f32 v160, v176, v177
	v_cvt_pk_bf16_f32 v161, v178, v179
	v_cvt_pk_bf16_f32 v162, v180, v181
	v_cvt_pk_bf16_f32 v163, v182, v183
	s_mov_b32 s6, 0x42000
	s_nop 1
	v_add_co_u32_e32 v146, vcc, s6, v150
	s_nop 0
	v_addc_co_u32_e32 v147, vcc, 0, v151, vcc
	global_store_dwordx4 v[146:147], v[160:163], off
	ds_read2_b32 v[146:147], v158 offset0:128 offset1:144
	s_mov_b32 s6, 0xb0000
	s_waitcnt lgkmcnt(0)
	v_mul_f32_e32 v184, 0xbfb8aa3b, v146
	v_mul_f32_e32 v206, v146, v146
	v_pk_mul_f32 v[168:169], v[60:61], v[184:185] op_sel_hi:[1,0]
	v_pk_mul_f32 v[170:171], v[62:63], v[184:185] op_sel_hi:[1,0]
	v_pk_mul_f32 v[172:173], v[56:57], v[184:185] op_sel_hi:[1,0]
	v_pk_mul_f32 v[174:175], v[58:59], v[184:185] op_sel_hi:[1,0]
	v_exp_f32_e32 v168, v168
	v_exp_f32_e32 v169, v169
	v_exp_f32_e32 v170, v170
	v_exp_f32_e32 v171, v171
	v_exp_f32_e32 v172, v172
	v_exp_f32_e32 v173, v173
	v_exp_f32_e32 v174, v174
	v_exp_f32_e32 v175, v175
	v_pk_mul_f32 v[176:177], v[60:61], v[28:29]
	v_pk_mul_f32 v[178:179], v[62:63], v[30:31]
	v_pk_mul_f32 v[180:181], v[56:57], v[24:25]
	v_pk_mul_f32 v[182:183], v[58:59], v[26:27]
	v_pk_add_f32 v[168:169], v[168:169], 1.0 op_sel_hi:[1,0]
	v_pk_add_f32 v[170:171], v[170:171], 1.0 op_sel_hi:[1,0]
	v_pk_add_f32 v[172:173], v[172:173], 1.0 op_sel_hi:[1,0]
	v_pk_add_f32 v[174:175], v[174:175], 1.0 op_sel_hi:[1,0]
	v_rcp_f32_e32 v168, v168
	v_rcp_f32_e32 v169, v169
	v_rcp_f32_e32 v170, v170
	v_rcp_f32_e32 v171, v171
	v_rcp_f32_e32 v172, v172
	v_rcp_f32_e32 v173, v173
	v_rcp_f32_e32 v174, v174
	v_rcp_f32_e32 v175, v175
	v_pk_mul_f32 v[176:177], v[176:177], v[206:207] op_sel_hi:[1,0]
	v_pk_mul_f32 v[178:179], v[178:179], v[206:207] op_sel_hi:[1,0]
	v_pk_mul_f32 v[180:181], v[180:181], v[206:207] op_sel_hi:[1,0]
	v_pk_mul_f32 v[182:183], v[182:183], v[206:207] op_sel_hi:[1,0]
	v_pk_mul_f32 v[176:177], v[176:177], v[168:169]
	v_pk_mul_f32 v[178:179], v[178:179], v[170:171]
	v_pk_mul_f32 v[180:181], v[180:181], v[172:173]
	v_pk_mul_f32 v[182:183], v[182:183], v[174:175]
	v_cvt_pk_bf16_f32 v160, v176, v177
	v_cvt_pk_bf16_f32 v161, v178, v179
	v_cvt_pk_bf16_f32 v162, v180, v181
	v_cvt_pk_bf16_f32 v163, v182, v183
	s_nop 1
	v_mov_b32_e32 v146, v147
	v_add_co_u32_e32 v148, vcc, s6, v150
	v_addc_co_u32_e32 v149, vcc, 0, v151, vcc
	global_store_dwordx4 v[148:149], v[160:163], off
	v_mul_f32_e32 v184, 0xbfb8aa3b, v146
	v_mul_f32_e32 v206, v146, v146
	v_pk_mul_f32 v[168:169], v[52:53], v[184:185] op_sel_hi:[1,0]
	v_pk_mul_f32 v[170:171], v[54:55], v[184:185] op_sel_hi:[1,0]
	v_pk_mul_f32 v[172:173], v[48:49], v[184:185] op_sel_hi:[1,0]
	v_pk_mul_f32 v[174:175], v[50:51], v[184:185] op_sel_hi:[1,0]
	v_exp_f32_e32 v168, v168
	v_exp_f32_e32 v169, v169
	v_exp_f32_e32 v170, v170
	v_exp_f32_e32 v171, v171
	v_exp_f32_e32 v172, v172
	v_exp_f32_e32 v173, v173
	v_exp_f32_e32 v174, v174
	v_exp_f32_e32 v175, v175
	v_pk_mul_f32 v[176:177], v[52:53], v[20:21]
	v_pk_mul_f32 v[178:179], v[54:55], v[22:23]
	v_pk_mul_f32 v[180:181], v[48:49], v[16:17]
	v_pk_mul_f32 v[182:183], v[50:51], v[18:19]
	v_pk_add_f32 v[168:169], v[168:169], 1.0 op_sel_hi:[1,0]
	v_pk_add_f32 v[170:171], v[170:171], 1.0 op_sel_hi:[1,0]
	v_pk_add_f32 v[172:173], v[172:173], 1.0 op_sel_hi:[1,0]
	v_pk_add_f32 v[174:175], v[174:175], 1.0 op_sel_hi:[1,0]
	v_rcp_f32_e32 v168, v168
	v_rcp_f32_e32 v169, v169
	v_rcp_f32_e32 v170, v170
	v_rcp_f32_e32 v171, v171
	v_rcp_f32_e32 v172, v172
	v_rcp_f32_e32 v173, v173
	v_rcp_f32_e32 v174, v174
	v_rcp_f32_e32 v175, v175
	v_pk_mul_f32 v[176:177], v[176:177], v[206:207] op_sel_hi:[1,0]
	v_pk_mul_f32 v[178:179], v[178:179], v[206:207] op_sel_hi:[1,0]
	v_pk_mul_f32 v[180:181], v[180:181], v[206:207] op_sel_hi:[1,0]
	v_pk_mul_f32 v[182:183], v[182:183], v[206:207] op_sel_hi:[1,0]
	v_pk_mul_f32 v[176:177], v[176:177], v[168:169]
	v_pk_mul_f32 v[178:179], v[178:179], v[170:171]
	v_pk_mul_f32 v[180:181], v[180:181], v[172:173]
	v_pk_mul_f32 v[182:183], v[182:183], v[174:175]
	v_cvt_pk_bf16_f32 v160, v176, v177
	v_cvt_pk_bf16_f32 v161, v178, v179
	v_cvt_pk_bf16_f32 v162, v180, v181
	v_cvt_pk_bf16_f32 v163, v182, v183
	s_mov_b32 s6, 0xc6000
	s_nop 1
	v_add_co_u32_e32 v146, vcc, s6, v150
	s_nop 0
	v_addc_co_u32_e32 v147, vcc, 0, v151, vcc
	global_store_dwordx4 v[146:147], v[160:163], off
	ds_read2_b32 v[146:147], v158 offset0:160 offset1:176
	s_mov_b32 s6, 0xdc000
	s_waitcnt lgkmcnt(0)
	v_mul_f32_e32 v184, 0xbfb8aa3b, v146
	v_mul_f32_e32 v206, v146, v146
	v_pk_mul_f32 v[168:169], v[44:45], v[184:185] op_sel_hi:[1,0]
	v_pk_mul_f32 v[170:171], v[46:47], v[184:185] op_sel_hi:[1,0]
	v_pk_mul_f32 v[172:173], v[40:41], v[184:185] op_sel_hi:[1,0]
	v_pk_mul_f32 v[174:175], v[42:43], v[184:185] op_sel_hi:[1,0]
	v_exp_f32_e32 v168, v168
	v_exp_f32_e32 v169, v169
	v_exp_f32_e32 v170, v170
	v_exp_f32_e32 v171, v171
	v_exp_f32_e32 v172, v172
	v_exp_f32_e32 v173, v173
	v_exp_f32_e32 v174, v174
	v_exp_f32_e32 v175, v175
	v_pk_mul_f32 v[176:177], v[44:45], v[12:13]
	v_pk_mul_f32 v[178:179], v[46:47], v[14:15]
	v_pk_mul_f32 v[180:181], v[40:41], v[8:9]
	v_pk_mul_f32 v[182:183], v[42:43], v[10:11]
	v_pk_add_f32 v[168:169], v[168:169], 1.0 op_sel_hi:[1,0]
	v_pk_add_f32 v[170:171], v[170:171], 1.0 op_sel_hi:[1,0]
	v_pk_add_f32 v[172:173], v[172:173], 1.0 op_sel_hi:[1,0]
	v_pk_add_f32 v[174:175], v[174:175], 1.0 op_sel_hi:[1,0]
	v_rcp_f32_e32 v168, v168
	v_rcp_f32_e32 v169, v169
	v_rcp_f32_e32 v170, v170
	v_rcp_f32_e32 v171, v171
	v_rcp_f32_e32 v172, v172
	v_rcp_f32_e32 v173, v173
	v_rcp_f32_e32 v174, v174
	v_rcp_f32_e32 v175, v175
	v_pk_mul_f32 v[176:177], v[176:177], v[206:207] op_sel_hi:[1,0]
	v_pk_mul_f32 v[178:179], v[178:179], v[206:207] op_sel_hi:[1,0]
	v_pk_mul_f32 v[180:181], v[180:181], v[206:207] op_sel_hi:[1,0]
	v_pk_mul_f32 v[182:183], v[182:183], v[206:207] op_sel_hi:[1,0]
	v_pk_mul_f32 v[176:177], v[176:177], v[168:169]
	v_pk_mul_f32 v[178:179], v[178:179], v[170:171]
	v_pk_mul_f32 v[180:181], v[180:181], v[172:173]
	v_pk_mul_f32 v[182:183], v[182:183], v[174:175]
	v_cvt_pk_bf16_f32 v158, v176, v177
	v_cvt_pk_bf16_f32 v159, v178, v179
	v_cvt_pk_bf16_f32 v160, v180, v181
	v_cvt_pk_bf16_f32 v161, v182, v183
	s_nop 1
	v_mov_b32_e32 v146, v147
	v_add_co_u32_e32 v148, vcc, s6, v150
	v_addc_co_u32_e32 v149, vcc, 0, v151, vcc
	global_store_dwordx4 v[148:149], v[158:161], off
	v_mul_f32_e32 v184, 0xbfb8aa3b, v146
	v_mul_f32_e32 v206, v146, v146
	v_pk_mul_f32 v[168:169], v[36:37], v[184:185] op_sel_hi:[1,0]
	v_pk_mul_f32 v[170:171], v[38:39], v[184:185] op_sel_hi:[1,0]
	v_pk_mul_f32 v[172:173], v[32:33], v[184:185] op_sel_hi:[1,0]
	v_pk_mul_f32 v[174:175], v[34:35], v[184:185] op_sel_hi:[1,0]
	v_exp_f32_e32 v168, v168
	v_exp_f32_e32 v169, v169
	v_exp_f32_e32 v170, v170
	v_exp_f32_e32 v171, v171
	v_exp_f32_e32 v172, v172
	v_exp_f32_e32 v173, v173
	v_exp_f32_e32 v174, v174
	v_exp_f32_e32 v175, v175
	v_pk_mul_f32 v[176:177], v[36:37], v[4:5]
	v_pk_mul_f32 v[178:179], v[38:39], v[6:7]
	v_pk_mul_f32 v[180:181], v[32:33], v[0:1]
	v_pk_mul_f32 v[182:183], v[34:35], v[2:3]
	v_pk_add_f32 v[168:169], v[168:169], 1.0 op_sel_hi:[1,0]
	v_pk_add_f32 v[170:171], v[170:171], 1.0 op_sel_hi:[1,0]
	v_pk_add_f32 v[172:173], v[172:173], 1.0 op_sel_hi:[1,0]
	v_pk_add_f32 v[174:175], v[174:175], 1.0 op_sel_hi:[1,0]
	v_rcp_f32_e32 v168, v168
	v_rcp_f32_e32 v169, v169
	v_rcp_f32_e32 v170, v170
	v_rcp_f32_e32 v171, v171
	v_rcp_f32_e32 v172, v172
	v_rcp_f32_e32 v173, v173
	v_rcp_f32_e32 v174, v174
	v_rcp_f32_e32 v175, v175
	v_pk_mul_f32 v[176:177], v[176:177], v[206:207] op_sel_hi:[1,0]
	v_pk_mul_f32 v[178:179], v[178:179], v[206:207] op_sel_hi:[1,0]
	v_pk_mul_f32 v[180:181], v[180:181], v[206:207] op_sel_hi:[1,0]
	v_pk_mul_f32 v[182:183], v[182:183], v[206:207] op_sel_hi:[1,0]
	v_pk_mul_f32 v[176:177], v[176:177], v[168:169]
	v_pk_mul_f32 v[178:179], v[178:179], v[170:171]
	v_pk_mul_f32 v[180:181], v[180:181], v[172:173]
	v_pk_mul_f32 v[182:183], v[182:183], v[174:175]
	v_cvt_pk_bf16_f32 v158, v176, v177
	v_cvt_pk_bf16_f32 v159, v178, v179
	v_cvt_pk_bf16_f32 v160, v180, v181
	v_cvt_pk_bf16_f32 v161, v182, v183
	s_nop 1
	v_add_co_u32_e32 v146, vcc, 0xf2000, v150
	s_nop 0
	v_addc_co_u32_e32 v147, vcc, 0, v151, vcc
	s_andn2_b64 vcc, exec, s[44:45]
	global_store_dwordx4 v[146:147], v[158:161], off
	s_cbranch_vccz .LBB0_382
	s_mov_b64 s[48:49], s[52:53]
	s_andn2_b64 vcc, exec, s[42:43]
	s_mov_b64 s[52:53], s[48:49]
	s_cbranch_vccnz .LBB0_383

.LBB0_773:
	s_add_u32 s12, s26, s6
	s_addc_u32 s19, s27, 0
	s_add_u32 s23, s12, 0x100
	s_addc_u32 s29, s19, 0
	s_and_b64 s[10:11], s[46:47], exec
	s_cselect_b32 s53, s35, s29
	s_cselect_b32 s52, s34, s23
	s_add_u32 s6, s4, s6
	s_addc_u32 s10, s5, 0
	s_add_u32 s6, s6, 0x100
	s_addc_u32 s23, s10, 0
	s_add_i32 s84, 0, 0x10000
	s_and_b64 s[10:11], s[46:47], exec
	s_cselect_b32 s55, s39, s23
	s_cselect_b32 s54, s38, s6
	s_add_u32 s58, s12, 0x80080
	s_addc_u32 s59, s19, 0
	s_add_i32 s88, s84, s68
	s_add_i32 m0, s69, 0xc000
	s_add_i32 s23, s69, 0xe000
	s_add_i32 s87, 0, 0x14000
	s_add_i32 s86, s88, 0x2000
	s_add_u32 s50, s54, 0x40000
	v_add_u32_e32 v136, s84, v138
	s_addc_u32 s51, s55, 0
	s_add_i32 s29, s87, s68
	ds_read_b128 v[146:149], v136
	ds_read_b128 v[152:155], v136 offset:1024
	ds_read_b128 v[156:159], v136 offset:2048
	ds_read_b128 v[160:163], v136 offset:3072
	s_add_i32 s19, s29, 0x2000
	s_add_i32 s12, 0, 0x18000
	s_add_u32 s48, s52, 0x80000
	s_addc_u32 s49, s53, 0
	s_add_i32 s11, s12, s68
	s_add_i32 s10, 0, 0x1c000
	s_add_i32 s6, s11, 0x2000
	s_add_u32 s46, s54, 0x40080
	s_addc_u32 s47, s55, 0
	s_add_i32 s85, s10, s68
	s_add_i32 s84, s85, 0x2000
	v_lshl_add_u64 v[136:137], s[58:59], 0, v[132:133]
	ds_read_b128 v[164:167], v150
	ds_read_b128 v[168:171], v150 offset:1024
	ds_read_b128 v[172:175], v150 offset:2048
	ds_read_b128 v[176:179], v150 offset:3072
	ds_read_b128 v[180:183], v150 offset:4096
	ds_read_b128 v[194:197], v150 offset:5120
	ds_read_b128 v[206:209], v150 offset:6144
	ds_read_b128 v[210:213], v150 offset:7168
	global_load_lds_dwordx4 v[136:137], off
	v_lshl_add_u64 v[136:137], s[58:59], 0, v[130:131]
	s_mov_b32 m0, s23
	s_nop 0
	global_load_lds_dwordx4 v[136:137], off
	s_waitcnt lgkmcnt(8)
	s_barrier
	s_setprio 1
	s_waitcnt lgkmcnt(7)
	v_mfma_f32_16x16x32_bf16 v[124:127], v[146:149], v[164:167], v[124:127]
	v_mfma_f32_16x16x32_bf16 v[120:123], v[156:159], v[164:167], v[120:123]
	s_waitcnt lgkmcnt(5)
	v_mfma_f32_16x16x32_bf16 v[116:119], v[146:149], v[172:175], v[116:119]
	v_mfma_f32_16x16x32_bf16 v[112:115], v[156:159], v[172:175], v[112:115]
	s_waitcnt lgkmcnt(3)
	v_mfma_f32_16x16x32_bf16 v[108:111], v[146:149], v[180:183], v[108:111]
	v_mfma_f32_16x16x32_bf16 v[104:107], v[156:159], v[180:183], v[104:107]
	s_waitcnt lgkmcnt(1)
	v_mfma_f32_16x16x32_bf16 v[100:103], v[146:149], v[206:209], v[100:103]
	v_mfma_f32_16x16x32_bf16 v[96:99], v[156:159], v[206:209], v[96:99]
	v_mfma_f32_16x16x32_bf16 v[124:127], v[152:155], v[168:171], v[124:127]
	v_mfma_f32_16x16x32_bf16 v[120:123], v[160:163], v[168:171], v[120:123]
	v_mfma_f32_16x16x32_bf16 v[116:119], v[152:155], v[176:179], v[116:119]
	v_mfma_f32_16x16x32_bf16 v[112:115], v[160:163], v[176:179], v[112:115]
	v_mfma_f32_16x16x32_bf16 v[108:111], v[152:155], v[194:197], v[108:111]
	v_mfma_f32_16x16x32_bf16 v[104:107], v[160:163], v[194:197], v[104:107]
	s_waitcnt lgkmcnt(0)
	v_mfma_f32_16x16x32_bf16 v[100:103], v[152:155], v[210:213], v[100:103]
	v_mfma_f32_16x16x32_bf16 v[96:99], v[160:163], v[210:213], v[96:99]
	s_setprio 0
	s_barrier
	v_add_u32_e32 v136, s87, v138
	s_mov_b32 m0, s88
	ds_read_b128 v[214:217], v136
	ds_read_b128 v[218:221], v136 offset:1024
	ds_read_b128 v[222:225], v136 offset:2048
	ds_read_b128 v[226:229], v136 offset:3072
	v_lshl_add_u64 v[136:137], s[54:55], 0, v[140:141]
	global_load_lds_dwordx4 v[136:137], off
	v_lshl_add_u64 v[184:185], s[54:55], 0, v[128:129]
	s_mov_b32 m0, s86
	s_nop 0
	global_load_lds_dwordx4 v[184:185], off
	s_barrier
	s_setprio 1
	s_waitcnt lgkmcnt(3)
	v_mfma_f32_16x16x32_bf16 v[92:95], v[214:217], v[164:167], v[92:95]
	s_waitcnt lgkmcnt(1)
	v_mfma_f32_16x16x32_bf16 v[88:91], v[222:225], v[164:167], v[88:91]
	v_mfma_f32_16x16x32_bf16 v[84:87], v[214:217], v[172:175], v[84:87]
	v_mfma_f32_16x16x32_bf16 v[80:83], v[222:225], v[172:175], v[80:83]
	v_mfma_f32_16x16x32_bf16 v[76:79], v[214:217], v[180:183], v[76:79]
	v_mfma_f32_16x16x32_bf16 v[72:75], v[222:225], v[180:183], v[72:75]
	v_mfma_f32_16x16x32_bf16 v[68:71], v[214:217], v[206:209], v[68:71]
	v_mfma_f32_16x16x32_bf16 v[64:67], v[222:225], v[206:209], v[64:67]
	v_mfma_f32_16x16x32_bf16 v[92:95], v[218:221], v[168:171], v[92:95]
	s_waitcnt lgkmcnt(0)
	v_mfma_f32_16x16x32_bf16 v[88:91], v[226:229], v[168:171], v[88:91]
	v_mfma_f32_16x16x32_bf16 v[84:87], v[218:221], v[176:179], v[84:87]
	v_mfma_f32_16x16x32_bf16 v[80:83], v[226:229], v[176:179], v[80:83]
	v_mfma_f32_16x16x32_bf16 v[76:79], v[218:221], v[194:197], v[76:79]
	v_mfma_f32_16x16x32_bf16 v[72:75], v[226:229], v[194:197], v[72:75]
	v_mfma_f32_16x16x32_bf16 v[68:71], v[218:221], v[210:213], v[68:71]
	v_mfma_f32_16x16x32_bf16 v[64:67], v[226:229], v[210:213], v[64:67]
	s_setprio 0
	s_mov_b32 m0, s69
	v_lshl_add_u64 v[192:193], s[52:53], 0, v[132:133]
	s_barrier
	ds_read_b128 v[164:167], v150 offset:16384
	ds_read_b128 v[168:171], v150 offset:17408
	ds_read_b128 v[172:175], v150 offset:18432
	ds_read_b128 v[176:179], v150 offset:19456
	ds_read_b128 v[180:183], v150 offset:20480
	ds_read_b128 v[194:197], v150 offset:21504
	ds_read_b128 v[206:209], v150 offset:22528
	ds_read_b128 v[210:213], v150 offset:23552
	global_load_lds_dwordx4 v[192:193], off
	v_lshl_add_u64 v[230:231], s[52:53], 0, v[130:131]
	s_mov_b32 m0, s70
	s_nop 0
	global_load_lds_dwordx4 v[230:231], off
	s_barrier
	s_setprio 1
	s_waitcnt lgkmcnt(7)
	v_mfma_f32_16x16x32_bf16 v[60:63], v[146:149], v[164:167], v[60:63]
	v_mfma_f32_16x16x32_bf16 v[56:59], v[156:159], v[164:167], v[56:59]
	s_waitcnt lgkmcnt(5)
	v_mfma_f32_16x16x32_bf16 v[52:55], v[146:149], v[172:175], v[52:55]
	v_mfma_f32_16x16x32_bf16 v[48:51], v[156:159], v[172:175], v[48:51]
	s_waitcnt lgkmcnt(3)
	v_mfma_f32_16x16x32_bf16 v[44:47], v[146:149], v[180:183], v[44:47]
	v_mfma_f32_16x16x32_bf16 v[40:43], v[156:159], v[180:183], v[40:43]
	s_waitcnt lgkmcnt(1)
	v_mfma_f32_16x16x32_bf16 v[36:39], v[146:149], v[206:209], v[36:39]
	v_mfma_f32_16x16x32_bf16 v[32:35], v[156:159], v[206:209], v[32:35]
	v_mfma_f32_16x16x32_bf16 v[60:63], v[152:155], v[168:171], v[60:63]
	v_mfma_f32_16x16x32_bf16 v[56:59], v[160:163], v[168:171], v[56:59]
	v_mfma_f32_16x16x32_bf16 v[52:55], v[152:155], v[176:179], v[52:55]
	v_mfma_f32_16x16x32_bf16 v[48:51], v[160:163], v[176:179], v[48:51]
	v_mfma_f32_16x16x32_bf16 v[44:47], v[152:155], v[194:197], v[44:47]
	v_mfma_f32_16x16x32_bf16 v[40:43], v[160:163], v[194:197], v[40:43]
	s_waitcnt lgkmcnt(0)
	v_mfma_f32_16x16x32_bf16 v[36:39], v[152:155], v[210:213], v[36:39]
	v_mfma_f32_16x16x32_bf16 v[32:35], v[160:163], v[210:213], v[32:35]
	s_setprio 0
	s_barrier
	s_mov_b32 m0, s29
	v_lshl_add_u64 v[146:147], s[50:51], 0, v[140:141]
	global_load_lds_dwordx4 v[146:147], off
	v_lshl_add_u64 v[146:147], s[50:51], 0, v[128:129]
	s_mov_b32 m0, s19
	s_nop 0
	global_load_lds_dwordx4 v[146:147], off
	s_nop 0
	s_waitcnt vmcnt(6)
	s_barrier
	s_setprio 1
	v_mfma_f32_16x16x32_bf16 v[28:31], v[214:217], v[164:167], v[28:31]
	v_mfma_f32_16x16x32_bf16 v[24:27], v[222:225], v[164:167], v[24:27]
	v_mfma_f32_16x16x32_bf16 v[20:23], v[214:217], v[172:175], v[20:23]
	v_mfma_f32_16x16x32_bf16 v[16:19], v[222:225], v[172:175], v[16:19]
	v_mfma_f32_16x16x32_bf16 v[12:15], v[214:217], v[180:183], v[12:15]
	v_mfma_f32_16x16x32_bf16 v[8:11], v[222:225], v[180:183], v[8:11]
	v_mfma_f32_16x16x32_bf16 v[4:7], v[214:217], v[206:209], v[4:7]
	v_mfma_f32_16x16x32_bf16 v[0:3], v[222:225], v[206:209], v[0:3]
	v_mfma_f32_16x16x32_bf16 v[28:31], v[218:221], v[168:171], v[28:31]
	v_mfma_f32_16x16x32_bf16 v[24:27], v[226:229], v[168:171], v[24:27]
	v_mfma_f32_16x16x32_bf16 v[20:23], v[218:221], v[176:179], v[20:23]
	v_mfma_f32_16x16x32_bf16 v[16:19], v[226:229], v[176:179], v[16:19]
	v_mfma_f32_16x16x32_bf16 v[12:15], v[218:221], v[194:197], v[12:15]
	v_mfma_f32_16x16x32_bf16 v[8:11], v[226:229], v[194:197], v[8:11]
	v_mfma_f32_16x16x32_bf16 v[4:7], v[218:221], v[210:213], v[4:7]
	v_mfma_f32_16x16x32_bf16 v[0:3], v[226:229], v[210:213], v[0:3]
	s_setprio 0
	v_add_u32_e32 v151, s12, v138
	s_barrier
	ds_read_b128 v[146:149], v151
	ds_read_b128 v[152:155], v151 offset:1024
	ds_read_b128 v[156:159], v151 offset:2048
	ds_read_b128 v[160:163], v151 offset:3072
	s_mov_b32 m0, s71
	v_lshl_add_u64 v[214:215], s[48:49], 0, v[132:133]
	ds_read_b128 v[164:167], v150 offset:32768
	ds_read_b128 v[168:171], v150 offset:33792
	ds_read_b128 v[172:175], v150 offset:34816
	ds_read_b128 v[176:179], v150 offset:35840
	ds_read_b128 v[180:183], v150 offset:36864
	ds_read_b128 v[194:197], v150 offset:37888
	ds_read_b128 v[206:209], v150 offset:38912
	ds_read_b128 v[210:213], v150 offset:39936
	global_load_lds_dwordx4 v[214:215], off
	v_lshl_add_u64 v[214:215], s[48:49], 0, v[130:131]
	s_mov_b32 m0, s72
	s_nop 0
	global_load_lds_dwordx4 v[214:215], off
	s_waitcnt lgkmcnt(8)
	s_barrier
	s_setprio 1
	s_waitcnt lgkmcnt(7)
	v_mfma_f32_16x16x32_bf16 v[124:127], v[146:149], v[164:167], v[124:127]
	v_mfma_f32_16x16x32_bf16 v[120:123], v[156:159], v[164:167], v[120:123]
	s_waitcnt lgkmcnt(5)
	v_mfma_f32_16x16x32_bf16 v[116:119], v[146:149], v[172:175], v[116:119]
	v_mfma_f32_16x16x32_bf16 v[112:115], v[156:159], v[172:175], v[112:115]
	s_waitcnt lgkmcnt(3)
	v_mfma_f32_16x16x32_bf16 v[108:111], v[146:149], v[180:183], v[108:111]
	v_mfma_f32_16x16x32_bf16 v[104:107], v[156:159], v[180:183], v[104:107]
	s_waitcnt lgkmcnt(1)
	v_mfma_f32_16x16x32_bf16 v[100:103], v[146:149], v[206:209], v[100:103]
	v_mfma_f32_16x16x32_bf16 v[96:99], v[156:159], v[206:209], v[96:99]
	v_mfma_f32_16x16x32_bf16 v[124:127], v[152:155], v[168:171], v[124:127]
	v_mfma_f32_16x16x32_bf16 v[120:123], v[160:163], v[168:171], v[120:123]
	v_mfma_f32_16x16x32_bf16 v[116:119], v[152:155], v[176:179], v[116:119]
	v_mfma_f32_16x16x32_bf16 v[112:115], v[160:163], v[176:179], v[112:115]
	v_mfma_f32_16x16x32_bf16 v[108:111], v[152:155], v[194:197], v[108:111]
	v_mfma_f32_16x16x32_bf16 v[104:107], v[160:163], v[194:197], v[104:107]
	s_waitcnt lgkmcnt(0)
	v_mfma_f32_16x16x32_bf16 v[100:103], v[152:155], v[210:213], v[100:103]
	v_mfma_f32_16x16x32_bf16 v[96:99], v[160:163], v[210:213], v[96:99]
	s_setprio 0
	s_barrier
	s_mov_b32 m0, s11
	v_add_u32_e32 v151, s10, v138
	v_lshl_add_u64 v[136:137], v[136:137], 0, s[36:37]
	ds_read_b128 v[214:217], v151
	ds_read_b128 v[218:221], v151 offset:1024
	ds_read_b128 v[222:225], v151 offset:2048
	ds_read_b128 v[226:229], v151 offset:3072
	global_load_lds_dwordx4 v[136:137], off
	v_lshl_add_u64 v[136:137], v[184:185], 0, s[36:37]
	s_mov_b32 m0, s6
	s_nop 0
	global_load_lds_dwordx4 v[136:137], off
	s_barrier
	s_setprio 1
	s_waitcnt lgkmcnt(3)
	v_mfma_f32_16x16x32_bf16 v[92:95], v[214:217], v[164:167], v[92:95]
	s_waitcnt lgkmcnt(1)
	v_mfma_f32_16x16x32_bf16 v[88:91], v[222:225], v[164:167], v[88:91]
	v_mfma_f32_16x16x32_bf16 v[84:87], v[214:217], v[172:175], v[84:87]
	v_mfma_f32_16x16x32_bf16 v[80:83], v[222:225], v[172:175], v[80:83]
	v_mfma_f32_16x16x32_bf16 v[76:79], v[214:217], v[180:183], v[76:79]
	v_mfma_f32_16x16x32_bf16 v[72:75], v[222:225], v[180:183], v[72:75]
	v_mfma_f32_16x16x32_bf16 v[68:71], v[214:217], v[206:209], v[68:71]
	v_mfma_f32_16x16x32_bf16 v[64:67], v[222:225], v[206:209], v[64:67]
	v_mfma_f32_16x16x32_bf16 v[92:95], v[218:221], v[168:171], v[92:95]
	s_waitcnt lgkmcnt(0)
	v_mfma_f32_16x16x32_bf16 v[88:91], v[226:229], v[168:171], v[88:91]
	v_mfma_f32_16x16x32_bf16 v[84:87], v[218:221], v[176:179], v[84:87]
	v_mfma_f32_16x16x32_bf16 v[80:83], v[226:229], v[176:179], v[80:83]
	v_mfma_f32_16x16x32_bf16 v[76:79], v[218:221], v[194:197], v[76:79]
	v_mfma_f32_16x16x32_bf16 v[72:75], v[226:229], v[194:197], v[72:75]
	v_mfma_f32_16x16x32_bf16 v[68:71], v[218:221], v[210:213], v[68:71]
	v_mfma_f32_16x16x32_bf16 v[64:67], v[226:229], v[210:213], v[64:67]
	s_setprio 0
	s_mov_b32 m0, s75
	v_lshl_add_u64 v[136:137], v[192:193], 0, s[36:37]
	s_barrier
	ds_read_b128 v[164:167], v150 offset:49152
	ds_read_b128 v[168:171], v150 offset:50176
	ds_read_b128 v[172:175], v150 offset:51200
	ds_read_b128 v[176:179], v150 offset:52224
	ds_read_b128 v[180:183], v150 offset:53248
	ds_read_b128 v[194:197], v150 offset:54272
	ds_read_b128 v[206:209], v150 offset:55296
	ds_read_b128 v[210:213], v150 offset:56320
	global_load_lds_dwordx4 v[136:137], off
	v_lshl_add_u64 v[136:137], v[230:231], 0, s[36:37]
	s_mov_b32 m0, s76
	s_nop 0
	global_load_lds_dwordx4 v[136:137], off
	s_barrier
	s_setprio 1
	s_waitcnt lgkmcnt(7)
	v_mfma_f32_16x16x32_bf16 v[60:63], v[146:149], v[164:167], v[60:63]
	v_mfma_f32_16x16x32_bf16 v[56:59], v[156:159], v[164:167], v[56:59]
	s_waitcnt lgkmcnt(5)
	v_mfma_f32_16x16x32_bf16 v[52:55], v[146:149], v[172:175], v[52:55]
	v_mfma_f32_16x16x32_bf16 v[48:51], v[156:159], v[172:175], v[48:51]
	s_waitcnt lgkmcnt(3)
	v_mfma_f32_16x16x32_bf16 v[44:47], v[146:149], v[180:183], v[44:47]
	v_mfma_f32_16x16x32_bf16 v[40:43], v[156:159], v[180:183], v[40:43]
	s_waitcnt lgkmcnt(1)
	v_mfma_f32_16x16x32_bf16 v[36:39], v[146:149], v[206:209], v[36:39]
	v_mfma_f32_16x16x32_bf16 v[32:35], v[156:159], v[206:209], v[32:35]
	v_mfma_f32_16x16x32_bf16 v[60:63], v[152:155], v[168:171], v[60:63]
	v_mfma_f32_16x16x32_bf16 v[56:59], v[160:163], v[168:171], v[56:59]
	v_mfma_f32_16x16x32_bf16 v[52:55], v[152:155], v[176:179], v[52:55]
	v_mfma_f32_16x16x32_bf16 v[48:51], v[160:163], v[176:179], v[48:51]
	v_mfma_f32_16x16x32_bf16 v[44:47], v[152:155], v[194:197], v[44:47]
	v_mfma_f32_16x16x32_bf16 v[40:43], v[160:163], v[194:197], v[40:43]
	s_waitcnt lgkmcnt(0)
	v_mfma_f32_16x16x32_bf16 v[36:39], v[152:155], v[210:213], v[36:39]
	v_mfma_f32_16x16x32_bf16 v[32:35], v[160:163], v[210:213], v[32:35]
	s_setprio 0
	s_barrier
	s_mov_b32 m0, s85
	v_lshl_add_u64 v[136:137], s[46:47], 0, v[140:141]
	global_load_lds_dwordx4 v[136:137], off
	v_lshl_add_u64 v[136:137], s[46:47], 0, v[128:129]
	s_mov_b32 m0, s84
	s_nop 0
	global_load_lds_dwordx4 v[136:137], off
	s_nop 0
	s_waitcnt vmcnt(6)
	s_barrier
	s_setprio 1
	v_mfma_f32_16x16x32_bf16 v[28:31], v[214:217], v[164:167], v[28:31]
	v_mfma_f32_16x16x32_bf16 v[24:27], v[222:225], v[164:167], v[24:27]
	v_mfma_f32_16x16x32_bf16 v[20:23], v[214:217], v[172:175], v[20:23]
	v_mfma_f32_16x16x32_bf16 v[16:19], v[222:225], v[172:175], v[16:19]
	v_mfma_f32_16x16x32_bf16 v[12:15], v[214:217], v[180:183], v[12:15]
	v_mfma_f32_16x16x32_bf16 v[8:11], v[222:225], v[180:183], v[8:11]
	v_mfma_f32_16x16x32_bf16 v[4:7], v[214:217], v[206:209], v[4:7]
	v_mfma_f32_16x16x32_bf16 v[0:3], v[222:225], v[206:209], v[0:3]
	v_mfma_f32_16x16x32_bf16 v[28:31], v[218:221], v[168:171], v[28:31]
	v_mfma_f32_16x16x32_bf16 v[24:27], v[226:229], v[168:171], v[24:27]
	v_mfma_f32_16x16x32_bf16 v[20:23], v[218:221], v[176:179], v[20:23]
	v_mfma_f32_16x16x32_bf16 v[16:19], v[226:229], v[176:179], v[16:19]
	v_mfma_f32_16x16x32_bf16 v[12:15], v[218:221], v[194:197], v[12:15]
	v_mfma_f32_16x16x32_bf16 v[8:11], v[226:229], v[194:197], v[8:11]
	v_mfma_f32_16x16x32_bf16 v[4:7], v[218:221], v[210:213], v[4:7]
	v_mfma_f32_16x16x32_bf16 v[0:3], v[226:229], v[210:213], v[0:3]
	s_setprio 0
	s_movk_i32 s6, 0x100
	s_andn2_b64 vcc, exec, s[44:45]
	s_mov_b64 s[46:47], -1
	s_mov_b64 s[44:45], 0
	s_barrier
	s_cbranch_vccz .LBB0_773
	s_ashr_i32 s10, s81, 2
	s_ashr_i32 s11, s10, 31
	s_lshl_b64 s[10:11], s[10:11], 21
	s_add_u32 s6, s73, s10
	s_addc_u32 s11, s74, s11
	s_lshl_b32 s10, s81, 19
	s_and_b32 s10, s10, 0x180000
	s_add_u32 s10, s6, s10
	v_lshl_or_b32 v136, s77, 8, v139
	s_addc_u32 s11, s11, 0
	v_ashrrev_i32_e32 v137, 31, v136
	v_lshl_add_u64 v[136:137], v[136:137], 1, s[10:11]
	v_pk_mul_f32 v[148:149], v[126:127], s[40:41] op_sel_hi:[1,0]
	v_pk_mul_f32 v[146:147], v[124:125], s[40:41] op_sel_hi:[1,0]
	v_pk_mul_f32 v[152:153], v[122:123], s[40:41] op_sel_hi:[1,0]
	v_pk_mul_f32 v[154:155], v[120:121], s[40:41] op_sel_hi:[1,0]
	v_lshl_add_u64 v[136:137], v[136:137], 0, v[134:135]
	v_cvt_pk_bf16_f32 v146, v146, v147
	v_cvt_pk_bf16_f32 v147, v148, v149
	v_cvt_pk_bf16_f32 v148, v154, v155
	v_cvt_pk_bf16_f32 v149, v152, v153
	global_store_dwordx4 v[136:137], v[146:149], off
	v_pk_mul_f32 v[152:153], v[90:91], s[40:41] op_sel_hi:[1,0]
	v_pk_mul_f32 v[154:155], v[88:89], s[40:41] op_sel_hi:[1,0]
	v_pk_mul_f32 v[148:149], v[94:95], s[40:41] op_sel_hi:[1,0]
	v_pk_mul_f32 v[146:147], v[92:93], s[40:41] op_sel_hi:[1,0]
	v_pk_mul_f32 v[156:157], v[80:81], s[40:41] op_sel_hi:[1,0]
	v_cvt_pk_bf16_f32 v146, v146, v147
	v_cvt_pk_bf16_f32 v147, v148, v149
	v_cvt_pk_bf16_f32 v148, v154, v155
	v_cvt_pk_bf16_f32 v149, v152, v153
	global_store_dwordx4 v[136:137], v[146:149], off offset:256
	v_pk_mul_f32 v[152:153], v[114:115], s[40:41] op_sel_hi:[1,0]
	v_pk_mul_f32 v[154:155], v[112:113], s[40:41] op_sel_hi:[1,0]
	v_pk_mul_f32 v[148:149], v[118:119], s[40:41] op_sel_hi:[1,0]
	v_pk_mul_f32 v[146:147], v[116:117], s[40:41] op_sel_hi:[1,0]
	s_mov_b32 s6, 0x40000
	v_cvt_pk_bf16_f32 v146, v146, v147
	v_cvt_pk_bf16_f32 v147, v148, v149
	v_cvt_pk_bf16_f32 v149, v152, v153
	v_add_co_u32_e32 v152, vcc, s65, v136
	v_cvt_pk_bf16_f32 v148, v154, v155
	s_nop 0
	v_addc_co_u32_e32 v153, vcc, 0, v137, vcc
	global_store_dwordx4 v[152:153], v[146:149], off
	v_pk_mul_f32 v[154:155], v[82:83], s[40:41] op_sel_hi:[1,0]
	s_nop 0
	v_pk_mul_f32 v[148:149], v[86:87], s[40:41] op_sel_hi:[1,0]
	v_pk_mul_f32 v[146:147], v[84:85], s[40:41] op_sel_hi:[1,0]
	s_nop 0
	v_cvt_pk_bf16_f32 v146, v146, v147
	v_cvt_pk_bf16_f32 v147, v148, v149
	v_cvt_pk_bf16_f32 v148, v156, v157
	v_cvt_pk_bf16_f32 v149, v154, v155
	global_store_dwordx4 v[152:153], v[146:149], off offset:256
	v_pk_mul_f32 v[152:153], v[106:107], s[40:41] op_sel_hi:[1,0]
	v_pk_mul_f32 v[154:155], v[104:105], s[40:41] op_sel_hi:[1,0]
	v_pk_mul_f32 v[148:149], v[110:111], s[40:41] op_sel_hi:[1,0]
	v_pk_mul_f32 v[146:147], v[108:109], s[40:41] op_sel_hi:[1,0]
	v_pk_mul_f32 v[156:157], v[72:73], s[40:41] op_sel_hi:[1,0]
	v_cvt_pk_bf16_f32 v146, v146, v147
	v_cvt_pk_bf16_f32 v147, v148, v149
	v_cvt_pk_bf16_f32 v149, v152, v153
	v_add_co_u32_e32 v152, vcc, s66, v136
	v_cvt_pk_bf16_f32 v148, v154, v155
	s_nop 0
	v_addc_co_u32_e32 v153, vcc, 0, v137, vcc
	global_store_dwordx4 v[152:153], v[146:149], off
	v_pk_mul_f32 v[154:155], v[74:75], s[40:41] op_sel_hi:[1,0]
	s_nop 0
	v_pk_mul_f32 v[148:149], v[78:79], s[40:41] op_sel_hi:[1,0]
	v_pk_mul_f32 v[146:147], v[76:77], s[40:41] op_sel_hi:[1,0]
	s_nop 0
	v_cvt_pk_bf16_f32 v146, v146, v147
	v_cvt_pk_bf16_f32 v147, v148, v149
	v_cvt_pk_bf16_f32 v148, v156, v157
	v_cvt_pk_bf16_f32 v149, v154, v155
	global_store_dwordx4 v[152:153], v[146:149], off offset:256
	v_pk_mul_f32 v[152:153], v[98:99], s[40:41] op_sel_hi:[1,0]
	v_pk_mul_f32 v[154:155], v[96:97], s[40:41] op_sel_hi:[1,0]
	v_pk_mul_f32 v[148:149], v[102:103], s[40:41] op_sel_hi:[1,0]
	v_pk_mul_f32 v[146:147], v[100:101], s[40:41] op_sel_hi:[1,0]
	v_pk_mul_f32 v[156:157], v[64:65], s[40:41] op_sel_hi:[1,0]
	v_cvt_pk_bf16_f32 v146, v146, v147
	v_cvt_pk_bf16_f32 v147, v148, v149
	v_cvt_pk_bf16_f32 v149, v152, v153
	v_add_co_u32_e32 v152, vcc, s64, v136
	v_cvt_pk_bf16_f32 v148, v154, v155
	s_nop 0
	v_addc_co_u32_e32 v153, vcc, 0, v137, vcc
	global_store_dwordx4 v[152:153], v[146:149], off
	v_pk_mul_f32 v[154:155], v[66:67], s[40:41] op_sel_hi:[1,0]
	s_nop 0
	v_pk_mul_f32 v[148:149], v[70:71], s[40:41] op_sel_hi:[1,0]
	v_pk_mul_f32 v[146:147], v[68:69], s[40:41] op_sel_hi:[1,0]
	s_nop 0
	v_cvt_pk_bf16_f32 v146, v146, v147
	v_cvt_pk_bf16_f32 v147, v148, v149
	v_cvt_pk_bf16_f32 v148, v156, v157
	v_cvt_pk_bf16_f32 v149, v154, v155
	global_store_dwordx4 v[152:153], v[146:149], off offset:256
	v_pk_mul_f32 v[152:153], v[58:59], s[40:41] op_sel_hi:[1,0]
	v_pk_mul_f32 v[154:155], v[56:57], s[40:41] op_sel_hi:[1,0]
	v_pk_mul_f32 v[148:149], v[62:63], s[40:41] op_sel_hi:[1,0]
	v_pk_mul_f32 v[146:147], v[60:61], s[40:41] op_sel_hi:[1,0]
	v_pk_mul_f32 v[156:157], v[24:25], s[40:41] op_sel_hi:[1,0]
	v_cvt_pk_bf16_f32 v146, v146, v147
	v_cvt_pk_bf16_f32 v147, v148, v149
	v_cvt_pk_bf16_f32 v149, v152, v153
	v_add_co_u32_e32 v152, vcc, s6, v136
	v_cvt_pk_bf16_f32 v148, v154, v155
	s_nop 0
	v_addc_co_u32_e32 v153, vcc, 0, v137, vcc
	global_store_dwordx4 v[152:153], v[146:149], off
	v_pk_mul_f32 v[154:155], v[26:27], s[40:41] op_sel_hi:[1,0]
	s_mov_b32 s6, 0x48000
	v_pk_mul_f32 v[148:149], v[30:31], s[40:41] op_sel_hi:[1,0]
	v_pk_mul_f32 v[146:147], v[28:29], s[40:41] op_sel_hi:[1,0]
	s_nop 0
	v_cvt_pk_bf16_f32 v146, v146, v147
	v_cvt_pk_bf16_f32 v147, v148, v149
	v_cvt_pk_bf16_f32 v148, v156, v157
	v_cvt_pk_bf16_f32 v149, v154, v155
	global_store_dwordx4 v[152:153], v[146:149], off offset:256
	v_pk_mul_f32 v[152:153], v[50:51], s[40:41] op_sel_hi:[1,0]
	v_pk_mul_f32 v[154:155], v[48:49], s[40:41] op_sel_hi:[1,0]
	v_pk_mul_f32 v[148:149], v[54:55], s[40:41] op_sel_hi:[1,0]
	v_pk_mul_f32 v[146:147], v[52:53], s[40:41] op_sel_hi:[1,0]
	v_pk_mul_f32 v[156:157], v[16:17], s[40:41] op_sel_hi:[1,0]
	v_cvt_pk_bf16_f32 v146, v146, v147
	v_cvt_pk_bf16_f32 v147, v148, v149
	v_cvt_pk_bf16_f32 v149, v152, v153
	v_add_co_u32_e32 v152, vcc, s6, v136
	v_cvt_pk_bf16_f32 v148, v154, v155
	s_nop 0
	v_addc_co_u32_e32 v153, vcc, 0, v137, vcc
	global_store_dwordx4 v[152:153], v[146:149], off
	v_pk_mul_f32 v[154:155], v[18:19], s[40:41] op_sel_hi:[1,0]
	s_mov_b32 s6, 0x50000
	v_pk_mul_f32 v[148:149], v[22:23], s[40:41] op_sel_hi:[1,0]
	v_pk_mul_f32 v[146:147], v[20:21], s[40:41] op_sel_hi:[1,0]
	s_nop 0
	v_cvt_pk_bf16_f32 v146, v146, v147
	v_cvt_pk_bf16_f32 v147, v148, v149
	v_cvt_pk_bf16_f32 v148, v156, v157
	v_cvt_pk_bf16_f32 v149, v154, v155
	global_store_dwordx4 v[152:153], v[146:149], off offset:256
	v_pk_mul_f32 v[152:153], v[42:43], s[40:41] op_sel_hi:[1,0]
	v_pk_mul_f32 v[154:155], v[40:41], s[40:41] op_sel_hi:[1,0]
	v_pk_mul_f32 v[148:149], v[46:47], s[40:41] op_sel_hi:[1,0]
	v_pk_mul_f32 v[146:147], v[44:45], s[40:41] op_sel_hi:[1,0]
	v_pk_mul_f32 v[156:157], v[8:9], s[40:41] op_sel_hi:[1,0]
	v_cvt_pk_bf16_f32 v146, v146, v147
	v_cvt_pk_bf16_f32 v147, v148, v149
	v_cvt_pk_bf16_f32 v149, v152, v153
	v_add_co_u32_e32 v152, vcc, s6, v136
	v_cvt_pk_bf16_f32 v148, v154, v155
	s_nop 0
	v_addc_co_u32_e32 v153, vcc, 0, v137, vcc
	global_store_dwordx4 v[152:153], v[146:149], off
	v_pk_mul_f32 v[154:155], v[10:11], s[40:41] op_sel_hi:[1,0]
	s_mov_b32 s6, 0x58000
	v_pk_mul_f32 v[148:149], v[14:15], s[40:41] op_sel_hi:[1,0]
	v_pk_mul_f32 v[146:147], v[12:13], s[40:41] op_sel_hi:[1,0]
	v_add_co_u32_e32 v136, vcc, s6, v136
	v_cvt_pk_bf16_f32 v146, v146, v147
	v_cvt_pk_bf16_f32 v147, v148, v149
	v_cvt_pk_bf16_f32 v148, v156, v157
	v_cvt_pk_bf16_f32 v149, v154, v155
	global_store_dwordx4 v[152:153], v[146:149], off offset:256
	v_pk_mul_f32 v[152:153], v[34:35], s[40:41] op_sel_hi:[1,0]
	v_pk_mul_f32 v[154:155], v[32:33], s[40:41] op_sel_hi:[1,0]
	v_pk_mul_f32 v[148:149], v[38:39], s[40:41] op_sel_hi:[1,0]
	v_pk_mul_f32 v[146:147], v[36:37], s[40:41] op_sel_hi:[1,0]
	v_addc_co_u32_e32 v137, vcc, 0, v137, vcc
	v_cvt_pk_bf16_f32 v146, v146, v147
	v_cvt_pk_bf16_f32 v147, v148, v149
	v_cvt_pk_bf16_f32 v148, v154, v155
	v_cvt_pk_bf16_f32 v149, v152, v153
	global_store_dwordx4 v[136:137], v[146:149], off
	v_pk_mul_f32 v[152:153], v[2:3], s[40:41] op_sel_hi:[1,0]
	v_pk_mul_f32 v[154:155], v[0:1], s[40:41] op_sel_hi:[1,0]
	v_pk_mul_f32 v[148:149], v[6:7], s[40:41] op_sel_hi:[1,0]
	v_pk_mul_f32 v[146:147], v[4:5], s[40:41] op_sel_hi:[1,0]
	s_and_b64 vcc, exec, s[42:43]
	v_cvt_pk_bf16_f32 v146, v146, v147
	v_cvt_pk_bf16_f32 v147, v148, v149
	v_cvt_pk_bf16_f32 v148, v154, v155
	v_cvt_pk_bf16_f32 v149, v152, v153
	global_store_dwordx4 v[136:137], v[146:149], off offset:256
	s_cbranch_vccnz .LBB0_761
	v_mov_b32_e32 v0, 0
	s_mov_b32 s77, s28
	s_mov_b32 s81, s82
	s_mov_b64 s[4:5], s[38:39]
	s_mov_b64 s[26:27], s[34:35]
	s_mov_b32 s80, s83
	v_mov_b32_e32 v1, v0
	v_mov_b32_e32 v2, v0
	v_mov_b32_e32 v3, v0
	v_mov_b32_e32 v4, v0
	v_mov_b32_e32 v5, v0
	v_mov_b32_e32 v6, v0
	v_mov_b32_e32 v7, v0
	v_mov_b32_e32 v8, v0
	v_mov_b32_e32 v9, v0
	v_mov_b32_e32 v10, v0
	v_mov_b32_e32 v11, v0
	v_mov_b32_e32 v12, v0
	v_mov_b32_e32 v13, v0
	v_mov_b32_e32 v14, v0
	v_mov_b32_e32 v15, v0
	v_mov_b32_e32 v16, v0
	v_mov_b32_e32 v17, v0
	v_mov_b32_e32 v18, v0
	v_mov_b32_e32 v19, v0
	v_mov_b32_e32 v20, v0
	v_mov_b32_e32 v21, v0
	v_mov_b32_e32 v22, v0
	v_mov_b32_e32 v23, v0
	v_mov_b32_e32 v24, v0
	v_mov_b32_e32 v25, v0
	v_mov_b32_e32 v26, v0
	v_mov_b32_e32 v27, v0
	v_mov_b32_e32 v28, v0
	v_mov_b32_e32 v29, v0
	v_mov_b32_e32 v30, v0
	v_mov_b32_e32 v31, v0
	v_mov_b32_e32 v32, v0
	v_mov_b32_e32 v33, v0
	v_mov_b32_e32 v34, v0
	v_mov_b32_e32 v35, v0
	v_mov_b32_e32 v36, v0
	v_mov_b32_e32 v37, v0
	v_mov_b32_e32 v38, v0
	v_mov_b32_e32 v39, v0
	v_mov_b32_e32 v40, v0
	v_mov_b32_e32 v41, v0
	v_mov_b32_e32 v42, v0
	v_mov_b32_e32 v43, v0
	v_mov_b32_e32 v44, v0
	v_mov_b32_e32 v45, v0
	v_mov_b32_e32 v46, v0
	v_mov_b32_e32 v47, v0
	v_mov_b32_e32 v48, v0
	v_mov_b32_e32 v49, v0
	v_mov_b32_e32 v50, v0
	v_mov_b32_e32 v51, v0
	v_mov_b32_e32 v52, v0
	v_mov_b32_e32 v53, v0
	v_mov_b32_e32 v54, v0
	v_mov_b32_e32 v55, v0
	v_mov_b32_e32 v56, v0
	v_mov_b32_e32 v57, v0
	v_mov_b32_e32 v58, v0
	v_mov_b32_e32 v59, v0
	v_mov_b32_e32 v60, v0
	v_mov_b32_e32 v61, v0
	v_mov_b32_e32 v62, v0
	v_mov_b32_e32 v63, v0
	v_mov_b32_e32 v64, v0
	v_mov_b32_e32 v65, v0
	v_mov_b32_e32 v66, v0
	v_mov_b32_e32 v67, v0
	v_mov_b32_e32 v68, v0
	v_mov_b32_e32 v69, v0
	v_mov_b32_e32 v70, v0
	v_mov_b32_e32 v71, v0
	v_mov_b32_e32 v72, v0
	v_mov_b32_e32 v73, v0
	v_mov_b32_e32 v74, v0
	v_mov_b32_e32 v75, v0
	v_mov_b32_e32 v76, v0
	v_mov_b32_e32 v77, v0
	v_mov_b32_e32 v78, v0
	v_mov_b32_e32 v79, v0
	v_mov_b32_e32 v80, v0
	v_mov_b32_e32 v81, v0
	v_mov_b32_e32 v82, v0
	v_mov_b32_e32 v83, v0
	v_mov_b32_e32 v84, v0
	v_mov_b32_e32 v85, v0
	v_mov_b32_e32 v86, v0
	v_mov_b32_e32 v87, v0
	v_mov_b32_e32 v88, v0
	v_mov_b32_e32 v89, v0
	v_mov_b32_e32 v90, v0
	v_mov_b32_e32 v91, v0
	v_mov_b32_e32 v92, v0
	v_mov_b32_e32 v93, v0
	v_mov_b32_e32 v94, v0
	v_mov_b32_e32 v95, v0
	v_mov_b32_e32 v96, v0
	v_mov_b32_e32 v97, v0
	v_mov_b32_e32 v98, v0
	v_mov_b32_e32 v99, v0
	v_mov_b32_e32 v100, v0
	v_mov_b32_e32 v101, v0
	v_mov_b32_e32 v102, v0
	v_mov_b32_e32 v103, v0
	v_mov_b32_e32 v104, v0
	v_mov_b32_e32 v105, v0
	v_mov_b32_e32 v106, v0
	v_mov_b32_e32 v107, v0
	v_mov_b32_e32 v108, v0
	v_mov_b32_e32 v109, v0
	v_mov_b32_e32 v110, v0
	v_mov_b32_e32 v111, v0
	v_mov_b32_e32 v112, v0
	v_mov_b32_e32 v113, v0
	v_mov_b32_e32 v114, v0
	v_mov_b32_e32 v115, v0
	v_mov_b32_e32 v116, v0
	v_mov_b32_e32 v117, v0
	v_mov_b32_e32 v118, v0
	v_mov_b32_e32 v119, v0
	v_mov_b32_e32 v120, v0
	v_mov_b32_e32 v121, v0
	v_mov_b32_e32 v122, v0
	v_mov_b32_e32 v123, v0
	v_mov_b32_e32 v124, v0
	v_mov_b32_e32 v125, v0
	v_mov_b32_e32 v126, v0
	v_mov_b32_e32 v127, v0
	s_branch .LBB0_761
